# GEMM K-loops: s_setprio 1 issued before the pre-MFMA barrier and s_setprio 0 after the post-MFMA barrier, taking both flips off the MFMA wave critical path
# speedup vs baseline: 1.0077x; 1.0077x over previous
; #define PG8_STAGE(bufoff, gbase, voff) do { _Pragma("unroll") for (int _i = 0; _i < 2; ++_i) \
;         __builtin_amdgcn_global_load_lds((const unsigned*)((const char*)(gbase) + (voff)[_i]), (LAS unsigned*)(lds + (bufoff) + ldsw + _i * 8192), 16, 0, 0); } while (0)
; #define PG8_LDA(dst, b, h) do { _Pragma("unroll") for (int m = 0; m < 4; ++m) _Pragma("unroll") for (int k = 0; k < 2; ++k) dst[m][k] = *(const LAS bf16x8*)(lds + PG8_SA(b, h) + aoff + m * 2048 + k * 1024); } while (0)
; #define PG8_LDB(dst, b, h) do { _Pragma("unroll") for (int n = 0; n < 2; ++n) _Pragma("unroll") for (int k = 0; k < 2; ++k) dst[n][k] = *(const LAS bf16x8*)(lds + PG8_SB(b, h) + boff + n * 2048 + k * 1024); } while (0)
; #define PG8_MMA(ai, bj, At, Bt) do { __builtin_amdgcn_s_setprio(1); _Pragma("unroll") for (int m = 0; m < 4; ++m) _Pragma("unroll") for (int n = 0; n < 2; ++n) _Pragma("unroll") for (int k = 0; k < 2; ++k) \
;         acc[ai][bj][m][n] = __builtin_amdgcn_mfma_f32_16x16x32_bf16(Bt[n][k], At[m][k], acc[ai][bj][m][n], 0, 0, 0); __builtin_amdgcn_s_setprio(0); } while (0)
; #define PG8_WAIT_V(n) asm volatile("s_waitcnt vmcnt(" #n ")" ::: "memory")
; #define PG8_WAIT_L(n) asm volatile("s_waitcnt lgkmcnt(" #n ")" ::: "memory")
; template <class Map, class Epi>
; DI void gemm_phase(LAS unsigned char* lds, const Map& MP, const Epi& E, const int nM, const int nN, const int K, const int lda, const int ldb) {
;     ...
;         for (int t = 0; t < nt; t += 2) {
;             const bool last = (t == nt - 2);
;             const char* a1 = cA + (size_t)(t + 1) * kstep;
;             const char* a2 = last ? nA : cA + (size_t)(t + 2) * kstep; const char* b2 = last ? nB : cB + (size_t)(t + 2) * kstep;
;             const char* a3 = a2 + kstep; const char* b3 = b2 + kstep;
;             PG8_LDB(B0, 0, 0); PG8_SCHED; PG8_LDA(At, 0, 0); PG8_STAGE(PG8_SA(1, 1), a1 + hstepA, voffA);
;             PG8_WAIT_L(8); PG8_BAR; PG8_WAIT_L(0); PG8_MMA(0, 0, At, B0); PG8_BAR; PG8_SCHED;
;             PG8_LDB(B1, 0, 1); PG8_STAGE(PG8_SB(0, 0), b2, voffB);
;             PG8_BAR; PG8_WAIT_L(0); PG8_MMA(0, 1, At, B1); PG8_BAR;
;             PG8_LDA(At, 0, 1); PG8_STAGE(PG8_SA(0, 0), a2, voffA);
;             PG8_BAR; PG8_WAIT_L(0); PG8_MMA(1, 0, At, B0); PG8_BAR; PG8_SCHED;
;             PG8_STAGE(PG8_SB(0, 1), b2 + hstepB, voffB);
;             PG8_WAIT_V(6); PG8_BAR; PG8_MMA(1, 1, At, B1); PG8_BAR;
.LBB1_229:
	s_add_u32 s26, s24, 0xfff80080
	s_addc_u32 s27, s25, -1
	s_cmp_eq_u32 s57, 4
	s_cselect_b32 s29, s17, s27
	s_cselect_b32 s28, s43, s26
	s_cselect_b32 s27, s53, s56
	s_cselect_b32 s26, s54, s55
	s_add_i32 m0, s2, 0xc000
	ds_read_b128 v[160:163], v168
	ds_read_b128 v[170:173], v168 offset:1024
	ds_read_b128 v[174:177], v168 offset:2048
	ds_read_b128 v[178:181], v168 offset:3072
	ds_read_b128 v[182:185], v168 offset:4096
	ds_read_b128 v[186:189], v168 offset:5120
	ds_read_b128 v[190:193], v168 offset:6144
	ds_read_b128 v[198:201], v168 offset:7168
	global_load_lds_dwordx4 v154, s[24:25]
	s_add_i32 m0, s2, 0xe000
	s_nop 0
	global_load_lds_dwordx4 v152, s[24:25]
	s_waitcnt lgkmcnt(8)
	s_setprio 1
	s_barrier
	s_waitcnt lgkmcnt(7)
	v_mfma_f32_16x16x32_bf16 v[140:143], v[72:75], v[160:163], v[140:143]
	v_mfma_f32_16x16x32_bf16 v[136:139], v[80:83], v[160:163], v[136:139]
	s_waitcnt lgkmcnt(5)
	v_mfma_f32_16x16x32_bf16 v[124:127], v[72:75], v[174:177], v[124:127]
	v_mfma_f32_16x16x32_bf16 v[120:123], v[80:83], v[174:177], v[120:123]
	s_waitcnt lgkmcnt(3)
	v_mfma_f32_16x16x32_bf16 v[108:111], v[72:75], v[182:185], v[108:111]
	v_mfma_f32_16x16x32_bf16 v[104:107], v[80:83], v[182:185], v[104:107]
	s_waitcnt lgkmcnt(1)
	v_mfma_f32_16x16x32_bf16 v[92:95], v[72:75], v[190:193], v[92:95]
	v_mfma_f32_16x16x32_bf16 v[88:91], v[80:83], v[190:193], v[88:91]
	v_mfma_f32_16x16x32_bf16 v[140:143], v[76:79], v[170:173], v[140:143]
	v_mfma_f32_16x16x32_bf16 v[136:139], v[84:87], v[170:173], v[136:139]
	v_mfma_f32_16x16x32_bf16 v[124:127], v[76:79], v[178:181], v[124:127]
	v_mfma_f32_16x16x32_bf16 v[120:123], v[84:87], v[178:181], v[120:123]
	v_mfma_f32_16x16x32_bf16 v[108:111], v[76:79], v[186:189], v[108:111]
	v_mfma_f32_16x16x32_bf16 v[104:107], v[84:87], v[186:189], v[104:107]
	s_waitcnt lgkmcnt(0)
	v_mfma_f32_16x16x32_bf16 v[92:95], v[76:79], v[198:201], v[92:95]
	v_mfma_f32_16x16x32_bf16 v[88:91], v[84:87], v[198:201], v[88:91]
	s_barrier
	s_setprio 0
	s_add_i32 s58, s48, s34
	v_lshl_add_u64 v[194:195], s[26:27], 0, v[148:149]
	s_mov_b32 m0, s58
	ds_read_b128 v[202:205], v169
	ds_read_b128 v[206:209], v169 offset:1024
	ds_read_b128 v[210:213], v169 offset:2048
	ds_read_b128 v[214:217], v169 offset:3072
	global_load_lds_dwordx4 v[194:195], off
	v_lshl_add_u64 v[218:219], s[26:27], 0, v[144:145]
	s_add_i32 m0, s58, 0x2000
	s_nop 0
	global_load_lds_dwordx4 v[218:219], off
	s_setprio 1
	s_barrier
	s_waitcnt lgkmcnt(3)
	v_mfma_f32_16x16x32_bf16 v[132:135], v[202:205], v[160:163], v[132:135]
	s_waitcnt lgkmcnt(1)
	v_mfma_f32_16x16x32_bf16 v[128:131], v[210:213], v[160:163], v[128:131]
	v_mfma_f32_16x16x32_bf16 v[116:119], v[202:205], v[174:177], v[116:119]
	v_mfma_f32_16x16x32_bf16 v[112:115], v[210:213], v[174:177], v[112:115]
	v_mfma_f32_16x16x32_bf16 v[100:103], v[202:205], v[182:185], v[100:103]
	v_mfma_f32_16x16x32_bf16 v[96:99], v[210:213], v[182:185], v[96:99]
	v_mfma_f32_16x16x32_bf16 v[68:71], v[202:205], v[190:193], v[68:71]
	v_mfma_f32_16x16x32_bf16 v[64:67], v[210:213], v[190:193], v[64:67]
	v_mfma_f32_16x16x32_bf16 v[132:135], v[206:209], v[170:173], v[132:135]
	s_mov_b32 m0, s2
	s_waitcnt lgkmcnt(0)
	v_mfma_f32_16x16x32_bf16 v[128:131], v[214:217], v[170:173], v[128:131]
	v_lshl_add_u64 v[220:221], s[28:29], 0, v[150:151]
	v_mfma_f32_16x16x32_bf16 v[116:119], v[206:209], v[178:181], v[116:119]
	v_mfma_f32_16x16x32_bf16 v[112:115], v[214:217], v[178:181], v[112:115]
	v_mfma_f32_16x16x32_bf16 v[100:103], v[206:209], v[186:189], v[100:103]
	v_mfma_f32_16x16x32_bf16 v[96:99], v[214:217], v[186:189], v[96:99]
	v_mfma_f32_16x16x32_bf16 v[68:71], v[206:209], v[198:201], v[68:71]
	v_mfma_f32_16x16x32_bf16 v[64:67], v[214:217], v[198:201], v[64:67]
	s_barrier
	s_setprio 0
	ds_read_b128 v[160:163], v168 offset:16384
	ds_read_b128 v[170:173], v168 offset:17408
	ds_read_b128 v[174:177], v168 offset:18432
	ds_read_b128 v[178:181], v168 offset:19456
	ds_read_b128 v[182:185], v168 offset:20480
	ds_read_b128 v[186:189], v168 offset:21504
	ds_read_b128 v[190:193], v168 offset:22528
	ds_read_b128 v[198:201], v168 offset:23552
	global_load_lds_dwordx4 v[220:221], off
	v_lshl_add_u64 v[222:223], s[28:29], 0, v[146:147]
	s_mov_b32 m0, s4
	s_nop 0
	global_load_lds_dwordx4 v[222:223], off
	s_waitcnt vmcnt(10)
	s_setprio 1
	s_barrier
	s_waitcnt lgkmcnt(7)
	v_mfma_f32_16x16x32_bf16 v[60:63], v[72:75], v[160:163], v[60:63]
	v_mfma_f32_16x16x32_bf16 v[56:59], v[80:83], v[160:163], v[56:59]
	s_waitcnt lgkmcnt(5)
	v_mfma_f32_16x16x32_bf16 v[44:47], v[72:75], v[174:177], v[44:47]
	v_mfma_f32_16x16x32_bf16 v[40:43], v[80:83], v[174:177], v[40:43]
	s_waitcnt lgkmcnt(3)
	v_mfma_f32_16x16x32_bf16 v[28:31], v[72:75], v[182:185], v[28:31]
	v_mfma_f32_16x16x32_bf16 v[24:27], v[80:83], v[182:185], v[24:27]
	s_waitcnt lgkmcnt(1)
	v_mfma_f32_16x16x32_bf16 v[12:15], v[72:75], v[190:193], v[12:15]
	v_mfma_f32_16x16x32_bf16 v[8:11], v[80:83], v[190:193], v[8:11]
	v_mfma_f32_16x16x32_bf16 v[60:63], v[76:79], v[170:173], v[60:63]
	v_mfma_f32_16x16x32_bf16 v[56:59], v[84:87], v[170:173], v[56:59]
	v_mfma_f32_16x16x32_bf16 v[44:47], v[76:79], v[178:181], v[44:47]
	v_mfma_f32_16x16x32_bf16 v[40:43], v[84:87], v[178:181], v[40:43]
	v_mfma_f32_16x16x32_bf16 v[28:31], v[76:79], v[186:189], v[28:31]
	v_mfma_f32_16x16x32_bf16 v[24:27], v[84:87], v[186:189], v[24:27]
	s_waitcnt lgkmcnt(0)
	v_mfma_f32_16x16x32_bf16 v[12:15], v[76:79], v[198:201], v[12:15]
	v_mfma_f32_16x16x32_bf16 v[8:11], v[84:87], v[198:201], v[8:11]
	s_barrier
	s_setprio 0
	s_add_u32 s58, s26, 0x20000
	s_addc_u32 s59, s27, 0
	s_add_i32 s60, s49, s34
	s_mov_b32 m0, s60
	s_nop 0
	global_load_lds_dwordx4 v148, s[58:59]
	s_add_i32 m0, s60, 0x2000
	s_nop 0
	global_load_lds_dwordx4 v144, s[58:59]
	s_waitcnt vmcnt(6)
	s_setprio 1
	s_barrier
; #define PG8_STAGE(bufoff, gbase, voff) do { _Pragma("unroll") for (int _i = 0; _i < 2; ++_i) \
;         __builtin_amdgcn_global_load_lds((const unsigned*)((const char*)(gbase) + (voff)[_i]), (LAS unsigned*)(lds + (bufoff) + ldsw + _i * 8192), 16, 0, 0); } while (0)
; #define PG8_LDA(dst, b, h) do { _Pragma("unroll") for (int m = 0; m < 4; ++m) _Pragma("unroll") for (int k = 0; k < 2; ++k) dst[m][k] = *(const LAS bf16x8*)(lds + PG8_SA(b, h) + aoff + m * 2048 + k * 1024); } while (0)
; #define PG8_LDB(dst, b, h) do { _Pragma("unroll") for (int n = 0; n < 2; ++n) _Pragma("unroll") for (int k = 0; k < 2; ++k) dst[n][k] = *(const LAS bf16x8*)(lds + PG8_SB(b, h) + boff + n * 2048 + k * 1024); } while (0)
; #define PG8_MMA(ai, bj, At, Bt) do { __builtin_amdgcn_s_setprio(1); _Pragma("unroll") for (int m = 0; m < 4; ++m) _Pragma("unroll") for (int n = 0; n < 2; ++n) _Pragma("unroll") for (int k = 0; k < 2; ++k) \
;         acc[ai][bj][m][n] = __builtin_amdgcn_mfma_f32_16x16x32_bf16(Bt[n][k], At[m][k], acc[ai][bj][m][n], 0, 0, 0); __builtin_amdgcn_s_setprio(0); } while (0)
; #define PG8_WAIT_V(n) asm volatile("s_waitcnt vmcnt(" #n ")" ::: "memory")
; #define PG8_WAIT_L(n) asm volatile("s_waitcnt lgkmcnt(" #n ")" ::: "memory")
; #define PG8_BAR __builtin_amdgcn_s_barrier()
; #define PG8_SCHED __builtin_amdgcn_sched_barrier(0)
; template <class Map, class Epi>
; DI void gemm_phase(LAS unsigned char* lds, const Map& MP, const Epi& E, const int nM, const int nN, const int K, const int lda, const int ldb) {
;     ...
;             PG8_WAIT_V(6); PG8_BAR; PG8_MMA(1, 1, At, B1); PG8_BAR;
;             PG8_LDB(B0, 1, 0); PG8_SCHED; PG8_LDA(At, 1, 0); PG8_STAGE(PG8_SA(0, 1), a2 + hstepA, voffA);
;             PG8_WAIT_L(8); PG8_BAR; PG8_WAIT_L(0); PG8_MMA(0, 0, At, B0); PG8_BAR; PG8_SCHED;
;             PG8_LDB(B1, 1, 1); PG8_STAGE(PG8_SB(1, 0), b3, voffB);
;             PG8_BAR; PG8_WAIT_L(0); PG8_MMA(0, 1, At, B1); PG8_BAR;
;             PG8_LDA(At, 1, 1); PG8_STAGE(PG8_SA(1, 0), a3, voffA);
;             PG8_BAR; PG8_WAIT_L(0); PG8_MMA(1, 0, At, B0); PG8_BAR; PG8_SCHED;
	v_mfma_f32_16x16x32_bf16 v[52:55], v[202:205], v[160:163], v[52:55]
	v_mfma_f32_16x16x32_bf16 v[48:51], v[210:213], v[160:163], v[48:51]
	s_add_i32 s58, 0, 0x18000
	v_add_u32_e32 v84, s58, v166
	ds_read_b128 v[72:75], v84
	v_mfma_f32_16x16x32_bf16 v[36:39], v[202:205], v[174:177], v[36:39]
	v_mfma_f32_16x16x32_bf16 v[32:35], v[210:213], v[174:177], v[32:35]
	ds_read_b128 v[76:79], v84 offset:1024
	v_mfma_f32_16x16x32_bf16 v[20:23], v[202:205], v[182:185], v[20:23]
	v_mfma_f32_16x16x32_bf16 v[16:19], v[210:213], v[182:185], v[16:19]
	ds_read_b128 v[80:83], v84 offset:2048
	v_mfma_f32_16x16x32_bf16 v[4:7], v[202:205], v[190:193], v[4:7]
	v_mfma_f32_16x16x32_bf16 v[0:3], v[210:213], v[190:193], v[0:3]
	ds_read_b128 v[84:87], v84 offset:3072
	v_mfma_f32_16x16x32_bf16 v[52:55], v[206:209], v[170:173], v[52:55]
	v_mfma_f32_16x16x32_bf16 v[48:51], v[214:217], v[170:173], v[48:51]
	v_mfma_f32_16x16x32_bf16 v[36:39], v[206:209], v[178:181], v[36:39]
	v_mfma_f32_16x16x32_bf16 v[32:35], v[214:217], v[178:181], v[32:35]
	v_mfma_f32_16x16x32_bf16 v[20:23], v[206:209], v[186:189], v[20:23]
	v_mfma_f32_16x16x32_bf16 v[16:19], v[214:217], v[186:189], v[16:19]
	v_mfma_f32_16x16x32_bf16 v[4:7], v[206:209], v[198:201], v[4:7]
	v_mfma_f32_16x16x32_bf16 v[0:3], v[214:217], v[198:201], v[0:3]
	s_barrier
	s_setprio 0
	s_add_u32 s28, s28, 0x80000
	s_addc_u32 s29, s29, 0
	s_mov_b32 m0, s5
	ds_read_b128 v[160:163], v168 offset:32768
	ds_read_b128 v[170:173], v168 offset:33792
	ds_read_b128 v[174:177], v168 offset:34816
	ds_read_b128 v[178:181], v168 offset:35840
	ds_read_b128 v[182:185], v168 offset:36864
	ds_read_b128 v[186:189], v168 offset:37888
	ds_read_b128 v[190:193], v168 offset:38912
	ds_read_b128 v[198:201], v168 offset:39936
	global_load_lds_dwordx4 v150, s[28:29]
	s_mov_b32 m0, s23
	s_nop 0
	global_load_lds_dwordx4 v146, s[28:29]
	s_waitcnt lgkmcnt(8)
	s_setprio 1
	s_barrier
	s_waitcnt lgkmcnt(7)
	v_mfma_f32_16x16x32_bf16 v[140:143], v[72:75], v[160:163], v[140:143]
	v_mfma_f32_16x16x32_bf16 v[136:139], v[80:83], v[160:163], v[136:139]
	s_waitcnt lgkmcnt(5)
	v_mfma_f32_16x16x32_bf16 v[124:127], v[72:75], v[174:177], v[124:127]
	v_mfma_f32_16x16x32_bf16 v[120:123], v[80:83], v[174:177], v[120:123]
	s_waitcnt lgkmcnt(3)
	v_mfma_f32_16x16x32_bf16 v[108:111], v[72:75], v[182:185], v[108:111]
	v_mfma_f32_16x16x32_bf16 v[104:107], v[80:83], v[182:185], v[104:107]
	s_waitcnt lgkmcnt(1)
	v_mfma_f32_16x16x32_bf16 v[92:95], v[72:75], v[190:193], v[92:95]
	v_mfma_f32_16x16x32_bf16 v[88:91], v[80:83], v[190:193], v[88:91]
	v_mfma_f32_16x16x32_bf16 v[140:143], v[76:79], v[170:173], v[140:143]
	v_mfma_f32_16x16x32_bf16 v[136:139], v[84:87], v[170:173], v[136:139]
	v_mfma_f32_16x16x32_bf16 v[124:127], v[76:79], v[178:181], v[124:127]
	v_mfma_f32_16x16x32_bf16 v[120:123], v[84:87], v[178:181], v[120:123]
	v_mfma_f32_16x16x32_bf16 v[108:111], v[76:79], v[186:189], v[108:111]
	v_mfma_f32_16x16x32_bf16 v[104:107], v[84:87], v[186:189], v[104:107]
	s_waitcnt lgkmcnt(0)
	v_mfma_f32_16x16x32_bf16 v[92:95], v[76:79], v[198:201], v[92:95]
	v_mfma_f32_16x16x32_bf16 v[88:91], v[84:87], v[198:201], v[88:91]
	s_barrier
	s_setprio 0
	s_add_i32 s28, 0, 0x1c000
	s_add_i32 s29, s58, s34
	v_add_u32_e32 v196, s28, v166
	v_lshl_add_u64 v[194:195], v[194:195], 0, s[12:13]
	s_mov_b32 m0, s29
	ds_read_b128 v[202:205], v196
	ds_read_b128 v[206:209], v196 offset:1024
	ds_read_b128 v[210:213], v196 offset:2048
	ds_read_b128 v[214:217], v196 offset:3072
	global_load_lds_dwordx4 v[194:195], off
	v_lshl_add_u64 v[194:195], v[218:219], 0, s[12:13]
	s_add_i32 m0, s29, 0x2000
	s_nop 0
	global_load_lds_dwordx4 v[194:195], off
	s_setprio 1
	s_barrier
	s_waitcnt lgkmcnt(3)
	v_mfma_f32_16x16x32_bf16 v[132:135], v[202:205], v[160:163], v[132:135]
	s_waitcnt lgkmcnt(1)
	v_mfma_f32_16x16x32_bf16 v[128:131], v[210:213], v[160:163], v[128:131]
	v_mfma_f32_16x16x32_bf16 v[116:119], v[202:205], v[174:177], v[116:119]
	v_mfma_f32_16x16x32_bf16 v[112:115], v[210:213], v[174:177], v[112:115]
	v_mfma_f32_16x16x32_bf16 v[100:103], v[202:205], v[182:185], v[100:103]
	v_mfma_f32_16x16x32_bf16 v[96:99], v[210:213], v[182:185], v[96:99]
	v_mfma_f32_16x16x32_bf16 v[68:71], v[202:205], v[190:193], v[68:71]
	v_mfma_f32_16x16x32_bf16 v[64:67], v[210:213], v[190:193], v[64:67]
	v_mfma_f32_16x16x32_bf16 v[132:135], v[206:209], v[170:173], v[132:135]
	s_mov_b32 m0, s39
	s_waitcnt lgkmcnt(0)
	v_mfma_f32_16x16x32_bf16 v[128:131], v[214:217], v[170:173], v[128:131]
	v_lshl_add_u64 v[194:195], v[220:221], 0, s[12:13]
	v_mfma_f32_16x16x32_bf16 v[116:119], v[206:209], v[178:181], v[116:119]
	v_mfma_f32_16x16x32_bf16 v[112:115], v[214:217], v[178:181], v[112:115]
	v_mfma_f32_16x16x32_bf16 v[100:103], v[206:209], v[186:189], v[100:103]
	v_mfma_f32_16x16x32_bf16 v[96:99], v[214:217], v[186:189], v[96:99]
	v_mfma_f32_16x16x32_bf16 v[68:71], v[206:209], v[198:201], v[68:71]
	v_mfma_f32_16x16x32_bf16 v[64:67], v[214:217], v[198:201], v[64:67]
	s_barrier
; #define PG8_STAGE(bufoff, gbase, voff) do { _Pragma("unroll") for (int _i = 0; _i < 2; ++_i) \
;         __builtin_amdgcn_global_load_lds((const unsigned*)((const char*)(gbase) + (voff)[_i]), (LAS unsigned*)(lds + (bufoff) + ldsw + _i * 8192), 16, 0, 0); } while (0)
; #define PG8_MMA(ai, bj, At, Bt) do { __builtin_amdgcn_s_setprio(1); _Pragma("unroll") for (int m = 0; m < 4; ++m) _Pragma("unroll") for (int n = 0; n < 2; ++n) _Pragma("unroll") for (int k = 0; k < 2; ++k) \
;         acc[ai][bj][m][n] = __builtin_amdgcn_mfma_f32_16x16x32_bf16(Bt[n][k], At[m][k], acc[ai][bj][m][n], 0, 0, 0); __builtin_amdgcn_s_setprio(0); } while (0)
; #define PG8_WAIT_V(n) asm volatile("s_waitcnt vmcnt(" #n ")" ::: "memory")
; #define PG8_WAIT_L(n) asm volatile("s_waitcnt lgkmcnt(" #n ")" ::: "memory")
; #define PG8_BAR __builtin_amdgcn_s_barrier()
; #define PG8_SCHED __builtin_amdgcn_sched_barrier(0)
;     DI void operator()(const f32x4 (&acc)[2][2][4][2], const Unit& u, int wr, int wc, int fr, int fq) const {
;         const int row0 = u.pm * BM + wr * 64 + fr, col0 = u.pn * BM + wc * 32 + 8 * fq;
;         f32x4 sc[2][2];
; #pragma unroll
;         for (int bj = 0; bj < 2; ++bj)
; #pragma unroll
;             for (int n = 0; n < 2; ++n) sc[bj][n] = scale ? *(const f32x4*)(scale + col0 + bj * HALF + 4 * n) : (f32x4){1.f, 1.f, 1.f, 1.f};
; #pragma unroll
; template <class Map, class Epi>
; DI void gemm_phase(LAS unsigned char* lds, const Map& MP, const Epi& E, const int nM, const int nN, const int K, const int lda, const int ldb) {
;     ...
;             PG8_BAR; PG8_WAIT_L(0); PG8_MMA(1, 0, At, B0); PG8_BAR; PG8_SCHED;
;             PG8_STAGE(PG8_SB(1, 1), b3 + hstepB, voffB);
;             PG8_WAIT_V(6); PG8_BAR; PG8_MMA(1, 1, At, B1); PG8_BAR;
;         }
	s_setprio 0
	ds_read_b128 v[160:163], v168 offset:49152
	ds_read_b128 v[170:173], v168 offset:50176
	ds_read_b128 v[174:177], v168 offset:51200
	ds_read_b128 v[178:181], v168 offset:52224
	ds_read_b128 v[182:185], v168 offset:53248
	ds_read_b128 v[186:189], v168 offset:54272
	ds_read_b128 v[190:193], v168 offset:55296
	ds_read_b128 v[198:201], v168 offset:56320
	global_load_lds_dwordx4 v[194:195], off
	v_lshl_add_u64 v[194:195], v[222:223], 0, s[12:13]
	s_mov_b32 m0, s46
	s_nop 0
	global_load_lds_dwordx4 v[194:195], off
	s_waitcnt vmcnt(10)
	s_setprio 1
	s_barrier
	s_waitcnt lgkmcnt(7)
	v_mfma_f32_16x16x32_bf16 v[60:63], v[72:75], v[160:163], v[60:63]
	v_mfma_f32_16x16x32_bf16 v[56:59], v[80:83], v[160:163], v[56:59]
	s_waitcnt lgkmcnt(5)
	v_mfma_f32_16x16x32_bf16 v[44:47], v[72:75], v[174:177], v[44:47]
	v_mfma_f32_16x16x32_bf16 v[40:43], v[80:83], v[174:177], v[40:43]
	s_waitcnt lgkmcnt(3)
	v_mfma_f32_16x16x32_bf16 v[28:31], v[72:75], v[182:185], v[28:31]
	v_mfma_f32_16x16x32_bf16 v[24:27], v[80:83], v[182:185], v[24:27]
	s_waitcnt lgkmcnt(1)
	v_mfma_f32_16x16x32_bf16 v[12:15], v[72:75], v[190:193], v[12:15]
	v_mfma_f32_16x16x32_bf16 v[8:11], v[80:83], v[190:193], v[8:11]
	v_mfma_f32_16x16x32_bf16 v[60:63], v[76:79], v[170:173], v[60:63]
	v_mfma_f32_16x16x32_bf16 v[56:59], v[84:87], v[170:173], v[56:59]
	v_mfma_f32_16x16x32_bf16 v[44:47], v[76:79], v[178:181], v[44:47]
	v_mfma_f32_16x16x32_bf16 v[40:43], v[84:87], v[178:181], v[40:43]
	v_mfma_f32_16x16x32_bf16 v[28:31], v[76:79], v[186:189], v[28:31]
	v_mfma_f32_16x16x32_bf16 v[24:27], v[84:87], v[186:189], v[24:27]
	s_waitcnt lgkmcnt(0)
	v_mfma_f32_16x16x32_bf16 v[12:15], v[76:79], v[198:201], v[12:15]
	v_mfma_f32_16x16x32_bf16 v[8:11], v[84:87], v[198:201], v[8:11]
	s_barrier
	s_setprio 0
	s_add_u32 s26, s26, 0x20080
	s_addc_u32 s27, s27, 0
	s_add_i32 s28, s28, s34
	s_mov_b32 m0, s28
	s_nop 0
	global_load_lds_dwordx4 v148, s[26:27]
	s_add_i32 m0, s28, 0x2000
	s_nop 0
	global_load_lds_dwordx4 v144, s[26:27]
	s_waitcnt vmcnt(6)
	s_setprio 1
	s_barrier
	v_mfma_f32_16x16x32_bf16 v[52:55], v[202:205], v[160:163], v[52:55]
	v_mfma_f32_16x16x32_bf16 v[48:51], v[210:213], v[160:163], v[48:51]
	ds_read_b128 v[72:75], v167
	v_mfma_f32_16x16x32_bf16 v[36:39], v[202:205], v[174:177], v[36:39]
	v_mfma_f32_16x16x32_bf16 v[32:35], v[210:213], v[174:177], v[32:35]
	ds_read_b128 v[76:79], v167 offset:1024
	v_mfma_f32_16x16x32_bf16 v[20:23], v[202:205], v[182:185], v[20:23]
	v_mfma_f32_16x16x32_bf16 v[16:19], v[210:213], v[182:185], v[16:19]
	ds_read_b128 v[80:83], v167 offset:2048
	v_mfma_f32_16x16x32_bf16 v[4:7], v[202:205], v[190:193], v[4:7]
	v_mfma_f32_16x16x32_bf16 v[0:3], v[210:213], v[190:193], v[0:3]
	ds_read_b128 v[84:87], v167 offset:3072
	v_mfma_f32_16x16x32_bf16 v[52:55], v[206:209], v[170:173], v[52:55]
	s_add_i32 s57, s57, 2
	v_mfma_f32_16x16x32_bf16 v[48:51], v[214:217], v[170:173], v[48:51]
	s_add_u32 s55, s55, 0x100
	s_addc_u32 s56, s56, 0
	v_mfma_f32_16x16x32_bf16 v[36:39], v[206:209], v[178:181], v[36:39]
	s_add_u32 s24, s24, 0x100
	s_addc_u32 s25, s25, 0
	v_mfma_f32_16x16x32_bf16 v[32:35], v[214:217], v[178:181], v[32:35]
	s_cmp_gt_u32 s57, 5
	v_mfma_f32_16x16x32_bf16 v[20:23], v[206:209], v[186:189], v[20:23]
	v_mfma_f32_16x16x32_bf16 v[16:19], v[214:217], v[186:189], v[16:19]
	v_mfma_f32_16x16x32_bf16 v[4:7], v[206:209], v[198:201], v[4:7]
	v_mfma_f32_16x16x32_bf16 v[0:3], v[214:217], v[198:201], v[0:3]
	s_barrier
	s_setprio 0
	s_cbranch_scc0 .LBB1_229
	s_waitcnt lgkmcnt(0)
	s_lshl_b32 s17, s42, 8
	v_mov_b32_e32 v170, v164
	v_mov_b32_e32 v72, v165
	s_or_b32 s17, s17, s38
	v_mov_b32_e32 v80, 1.0
	v_lshl_add_u32 v160, v72, 3, s17
	v_ashrrev_i32_e32 v161, 31, v160
	v_cndmask_b32_e64 v72, 0, 1, s[14:15]
	v_lshl_add_u64 v[162:163], v[160:161], 2, s[8:9]
	v_cmp_ne_u32_e64 s[42:43], 1, v72
	s_andn2_b64 vcc, exec, s[14:15]
	v_mov_b32_e32 v84, 1.0
	v_mov_b32_e32 v85, 1.0
	v_mov_b32_e32 v86, 1.0
	v_mov_b32_e32 v87, 1.0
	s_cbranch_vccnz .LBB1_232
	global_load_dwordx4 v[84:87], v[162:163], off

; #define PG8_STAGE(bufoff, gbase, voff) do { _Pragma("unroll") for (int _i = 0; _i < 2; ++_i) \
;         __builtin_amdgcn_global_load_lds((const unsigned*)((const char*)(gbase) + (voff)[_i]), (LAS unsigned*)(lds + (bufoff) + ldsw + _i * 8192), 16, 0, 0); } while (0)
; #define PG8_LDA(dst, b, h) do { _Pragma("unroll") for (int m = 0; m < 4; ++m) _Pragma("unroll") for (int k = 0; k < 2; ++k) dst[m][k] = *(const LAS bf16x8*)(lds + PG8_SA(b, h) + aoff + m * 2048 + k * 1024); } while (0)
; #define PG8_LDB(dst, b, h) do { _Pragma("unroll") for (int n = 0; n < 2; ++n) _Pragma("unroll") for (int k = 0; k < 2; ++k) dst[n][k] = *(const LAS bf16x8*)(lds + PG8_SB(b, h) + boff + n * 2048 + k * 1024); } while (0)
; #define PG8_MMA(ai, bj, At, Bt) do { __builtin_amdgcn_s_setprio(1); _Pragma("unroll") for (int m = 0; m < 4; ++m) _Pragma("unroll") for (int n = 0; n < 2; ++n) _Pragma("unroll") for (int k = 0; k < 2; ++k) \
;         acc[ai][bj][m][n] = __builtin_amdgcn_mfma_f32_16x16x32_bf16(Bt[n][k], At[m][k], acc[ai][bj][m][n], 0, 0, 0); __builtin_amdgcn_s_setprio(0); } while (0)
; #define PG8_WAIT_V(n) asm volatile("s_waitcnt vmcnt(" #n ")" ::: "memory")
; #define PG8_WAIT_L(n) asm volatile("s_waitcnt lgkmcnt(" #n ")" ::: "memory")
; template <class Map, class Epi>
; DI void gemm_phase(LAS unsigned char* lds, const Map& MP, const Epi& E, const int nM, const int nN, const int K, const int lda, const int ldb) {
;     ...
;         for (int t = 0; t < nt; t += 2) {
;             const bool last = (t == nt - 2);
;             const char* a1 = cA + (size_t)(t + 1) * kstep;
;             const char* a2 = last ? nA : cA + (size_t)(t + 2) * kstep; const char* b2 = last ? nB : cB + (size_t)(t + 2) * kstep;
;             const char* a3 = a2 + kstep; const char* b3 = b2 + kstep;
;             PG8_LDB(B0, 0, 0); PG8_SCHED; PG8_LDA(At, 0, 0); PG8_STAGE(PG8_SA(1, 1), a1 + hstepA, voffA);
;             PG8_WAIT_L(8); PG8_BAR; PG8_WAIT_L(0); PG8_MMA(0, 0, At, B0); PG8_BAR; PG8_SCHED;
;             PG8_LDB(B1, 0, 1); PG8_STAGE(PG8_SB(0, 0), b2, voffB);
;             PG8_BAR; PG8_WAIT_L(0); PG8_MMA(0, 1, At, B1); PG8_BAR;
;             PG8_LDA(At, 0, 1); PG8_STAGE(PG8_SA(0, 0), a2, voffA);
;             PG8_BAR; PG8_WAIT_L(0); PG8_MMA(1, 0, At, B0); PG8_BAR; PG8_SCHED;
;             PG8_STAGE(PG8_SB(0, 1), b2 + hstepB, voffB);
;             PG8_WAIT_V(6); PG8_BAR; PG8_MMA(1, 1, At, B1); PG8_BAR;
.LBB1_380:
	s_add_u32 s28, s44, 0xfff80080
	s_addc_u32 s29, s45, -1
	s_cmp_eq_u32 vcc_hi, 28
	s_cselect_b32 s47, s23, s29
	s_cselect_b32 s46, s61, s28
	s_cselect_b32 s29, s21, vcc_lo
	s_cselect_b32 s28, s58, s59
	s_add_i32 m0, s38, 0xc000
	ds_read_b128 v[96:99], v190
	ds_read_b128 v[100:103], v190 offset:1024
	ds_read_b128 v[108:111], v190 offset:2048
	ds_read_b128 v[112:115], v190 offset:3072
	ds_read_b128 v[160:163], v190 offset:4096
	ds_read_b128 v[164:167], v190 offset:5120
	ds_read_b128 v[198:201], v190 offset:6144
	ds_read_b128 v[202:205], v190 offset:7168
	global_load_lds_dwordx4 v178, s[44:45]
	s_add_i32 m0, s38, 0xe000
	s_nop 0
	global_load_lds_dwordx4 v176, s[44:45]
	s_waitcnt lgkmcnt(8)
	s_setprio 1
	s_barrier
	s_waitcnt lgkmcnt(7)
	v_mfma_f32_16x16x32_bf16 v[148:151], v[80:83], v[96:99], v[148:151]
	v_mfma_f32_16x16x32_bf16 v[144:147], v[88:91], v[96:99], v[144:147]
	s_waitcnt lgkmcnt(5)
	v_mfma_f32_16x16x32_bf16 v[136:139], v[80:83], v[108:111], v[136:139]
	v_mfma_f32_16x16x32_bf16 v[128:131], v[88:91], v[108:111], v[128:131]
	s_waitcnt lgkmcnt(3)
	v_mfma_f32_16x16x32_bf16 v[120:123], v[80:83], v[160:163], v[120:123]
	v_mfma_f32_16x16x32_bf16 v[104:107], v[88:91], v[160:163], v[104:107]
	s_waitcnt lgkmcnt(1)
	v_mfma_f32_16x16x32_bf16 v[76:79], v[80:83], v[198:201], v[76:79]
	v_mfma_f32_16x16x32_bf16 v[72:75], v[88:91], v[198:201], v[72:75]
	v_mfma_f32_16x16x32_bf16 v[148:151], v[84:87], v[100:103], v[148:151]
	v_mfma_f32_16x16x32_bf16 v[144:147], v[92:95], v[100:103], v[144:147]
	v_mfma_f32_16x16x32_bf16 v[136:139], v[84:87], v[112:115], v[136:139]
	v_mfma_f32_16x16x32_bf16 v[128:131], v[92:95], v[112:115], v[128:131]
	v_mfma_f32_16x16x32_bf16 v[120:123], v[84:87], v[164:167], v[120:123]
	v_mfma_f32_16x16x32_bf16 v[104:107], v[92:95], v[164:167], v[104:107]
	s_waitcnt lgkmcnt(0)
	v_mfma_f32_16x16x32_bf16 v[76:79], v[84:87], v[202:205], v[76:79]
	v_mfma_f32_16x16x32_bf16 v[72:75], v[92:95], v[202:205], v[72:75]
	s_barrier
	s_setprio 0
	s_add_i32 s68, s5, s37
	v_lshl_add_u64 v[184:185], s[28:29], 0, v[172:173]
	s_mov_b32 m0, s68
	ds_read_b128 v[206:209], v191
	ds_read_b128 v[210:213], v191 offset:1024
	ds_read_b128 v[214:217], v191 offset:2048
	ds_read_b128 v[218:221], v191 offset:3072
	global_load_lds_dwordx4 v[184:185], off
	v_lshl_add_u64 v[194:195], s[28:29], 0, v[168:169]
	s_add_i32 m0, s68, 0x2000
	s_nop 0
	global_load_lds_dwordx4 v[194:195], off
	s_setprio 1
	s_barrier
	s_waitcnt lgkmcnt(3)
	v_mfma_f32_16x16x32_bf16 v[156:159], v[206:209], v[96:99], v[156:159]
	s_waitcnt lgkmcnt(1)
	v_mfma_f32_16x16x32_bf16 v[96:99], v[214:217], v[96:99], v[152:155]
	v_mfma_f32_16x16x32_bf16 v[156:159], v[210:213], v[100:103], v[156:159]
	s_waitcnt lgkmcnt(0)
	v_mfma_f32_16x16x32_bf16 v[96:99], v[218:221], v[100:103], v[96:99]
	v_mfma_f32_16x16x32_bf16 v[100:103], v[206:209], v[108:111], v[140:143]
	v_mfma_f32_16x16x32_bf16 v[108:111], v[214:217], v[108:111], v[132:135]
	v_mfma_f32_16x16x32_bf16 v[116:119], v[214:217], v[160:163], v[116:119]
	v_mfma_f32_16x16x32_bf16 v[68:71], v[206:209], v[198:201], v[68:71]
	v_mfma_f32_16x16x32_bf16 v[64:67], v[214:217], v[198:201], v[64:67]
	s_mov_b32 m0, s38
	v_mfma_f32_16x16x32_bf16 v[100:103], v[210:213], v[112:115], v[100:103]
	v_lshl_add_u64 v[226:227], s[46:47], 0, v[174:175]
	v_mfma_f32_16x16x32_bf16 v[108:111], v[218:221], v[112:115], v[108:111]
	v_mfma_f32_16x16x32_bf16 v[112:115], v[206:209], v[160:163], v[124:127]
	v_mfma_f32_16x16x32_bf16 v[116:119], v[218:221], v[164:167], v[116:119]
	v_mfma_f32_16x16x32_bf16 v[68:71], v[210:213], v[202:205], v[68:71]
	v_mfma_f32_16x16x32_bf16 v[64:67], v[218:221], v[202:205], v[64:67]
	v_mfma_f32_16x16x32_bf16 v[112:115], v[210:213], v[164:167], v[112:115]
	s_barrier
	s_setprio 0
	ds_read_b128 v[124:127], v190 offset:16384
	ds_read_b128 v[132:135], v190 offset:17408
	ds_read_b128 v[140:143], v190 offset:18432
	ds_read_b128 v[152:155], v190 offset:19456
	ds_read_b128 v[160:163], v190 offset:20480
	ds_read_b128 v[164:167], v190 offset:21504
	ds_read_b128 v[198:201], v190 offset:22528
	ds_read_b128 v[202:205], v190 offset:23552
	global_load_lds_dwordx4 v[226:227], off
	v_lshl_add_u64 v[234:235], s[46:47], 0, v[170:171]
	s_mov_b32 m0, s39
	s_nop 0
	global_load_lds_dwordx4 v[234:235], off
	s_waitcnt vmcnt(10)
	s_setprio 1
	s_barrier
	s_waitcnt lgkmcnt(7)
	v_mfma_f32_16x16x32_bf16 v[60:63], v[80:83], v[124:127], v[60:63]
	v_mfma_f32_16x16x32_bf16 v[48:51], v[88:91], v[124:127], v[48:51]
	s_waitcnt lgkmcnt(5)
	v_mfma_f32_16x16x32_bf16 v[40:43], v[80:83], v[140:143], v[40:43]
	v_mfma_f32_16x16x32_bf16 v[32:35], v[88:91], v[140:143], v[32:35]
	s_waitcnt lgkmcnt(3)
	v_mfma_f32_16x16x32_bf16 v[24:27], v[80:83], v[160:163], v[24:27]
	v_mfma_f32_16x16x32_bf16 v[16:19], v[88:91], v[160:163], v[16:19]
	s_waitcnt lgkmcnt(1)
	v_mfma_f32_16x16x32_bf16 v[12:15], v[80:83], v[198:201], v[12:15]
	v_mfma_f32_16x16x32_bf16 v[8:11], v[88:91], v[198:201], v[8:11]
	v_mfma_f32_16x16x32_bf16 v[60:63], v[84:87], v[132:135], v[60:63]
	v_mfma_f32_16x16x32_bf16 v[48:51], v[92:95], v[132:135], v[48:51]
	v_mfma_f32_16x16x32_bf16 v[40:43], v[84:87], v[152:155], v[40:43]
	v_mfma_f32_16x16x32_bf16 v[32:35], v[92:95], v[152:155], v[32:35]
	v_mfma_f32_16x16x32_bf16 v[24:27], v[84:87], v[164:167], v[24:27]
	v_mfma_f32_16x16x32_bf16 v[16:19], v[92:95], v[164:167], v[16:19]
	s_waitcnt lgkmcnt(0)
	v_mfma_f32_16x16x32_bf16 v[12:15], v[84:87], v[202:205], v[12:15]
	v_mfma_f32_16x16x32_bf16 v[8:11], v[92:95], v[202:205], v[8:11]
	s_barrier
	s_setprio 0
	s_add_u32 s68, s28, 0x80000
	s_addc_u32 s69, s29, 0
	s_add_i32 s70, s2, s37
	s_mov_b32 m0, s70
	s_nop 0
	global_load_lds_dwordx4 v172, s[68:69]
	s_add_i32 m0, s70, 0x2000
	s_nop 0
	global_load_lds_dwordx4 v168, s[68:69]
	s_waitcnt vmcnt(6)
	s_setprio 1
	s_barrier
; #define PG8_STAGE(bufoff, gbase, voff) do { _Pragma("unroll") for (int _i = 0; _i < 2; ++_i) \
;         __builtin_amdgcn_global_load_lds((const unsigned*)((const char*)(gbase) + (voff)[_i]), (LAS unsigned*)(lds + (bufoff) + ldsw + _i * 8192), 16, 0, 0); } while (0)
; #define PG8_LDA(dst, b, h) do { _Pragma("unroll") for (int m = 0; m < 4; ++m) _Pragma("unroll") for (int k = 0; k < 2; ++k) dst[m][k] = *(const LAS bf16x8*)(lds + PG8_SA(b, h) + aoff + m * 2048 + k * 1024); } while (0)
; #define PG8_LDB(dst, b, h) do { _Pragma("unroll") for (int n = 0; n < 2; ++n) _Pragma("unroll") for (int k = 0; k < 2; ++k) dst[n][k] = *(const LAS bf16x8*)(lds + PG8_SB(b, h) + boff + n * 2048 + k * 1024); } while (0)
; #define PG8_MMA(ai, bj, At, Bt) do { __builtin_amdgcn_s_setprio(1); _Pragma("unroll") for (int m = 0; m < 4; ++m) _Pragma("unroll") for (int n = 0; n < 2; ++n) _Pragma("unroll") for (int k = 0; k < 2; ++k) \
;         acc[ai][bj][m][n] = __builtin_amdgcn_mfma_f32_16x16x32_bf16(Bt[n][k], At[m][k], acc[ai][bj][m][n], 0, 0, 0); __builtin_amdgcn_s_setprio(0); } while (0)
; #define PG8_WAIT_V(n) asm volatile("s_waitcnt vmcnt(" #n ")" ::: "memory")
; #define PG8_WAIT_L(n) asm volatile("s_waitcnt lgkmcnt(" #n ")" ::: "memory")
; #define PG8_BAR __builtin_amdgcn_s_barrier()
; #define PG8_SCHED __builtin_amdgcn_sched_barrier(0)
; template <class Map, class Epi>
; DI void gemm_phase(LAS unsigned char* lds, const Map& MP, const Epi& E, const int nM, const int nN, const int K, const int lda, const int ldb) {
;     ...
;             PG8_WAIT_V(6); PG8_BAR; PG8_MMA(1, 1, At, B1); PG8_BAR;
;             PG8_LDB(B0, 1, 0); PG8_SCHED; PG8_LDA(At, 1, 0); PG8_STAGE(PG8_SA(0, 1), a2 + hstepA, voffA);
;             PG8_WAIT_L(8); PG8_BAR; PG8_WAIT_L(0); PG8_MMA(0, 0, At, B0); PG8_BAR; PG8_SCHED;
;             PG8_LDB(B1, 1, 1); PG8_STAGE(PG8_SB(1, 0), b3, voffB);
;             PG8_BAR; PG8_WAIT_L(0); PG8_MMA(0, 1, At, B1); PG8_BAR;
;             PG8_LDA(At, 1, 1); PG8_STAGE(PG8_SA(1, 0), a3, voffA);
;             PG8_BAR; PG8_WAIT_L(0); PG8_MMA(1, 0, At, B0); PG8_BAR; PG8_SCHED;
;             PG8_STAGE(PG8_SB(1, 1), b3 + hstepB, voffB);
	v_mfma_f32_16x16x32_bf16 v[56:59], v[206:209], v[124:127], v[56:59]
	v_mfma_f32_16x16x32_bf16 v[52:55], v[214:217], v[124:127], v[52:55]
	s_add_i32 s68, 0, 0x18000
	v_add_u32_e32 v92, s68, v188
	ds_read_b128 v[80:83], v92
	v_mfma_f32_16x16x32_bf16 v[44:47], v[206:209], v[140:143], v[44:47]
	v_mfma_f32_16x16x32_bf16 v[36:39], v[214:217], v[140:143], v[36:39]
	ds_read_b128 v[84:87], v92 offset:1024
	v_mfma_f32_16x16x32_bf16 v[28:31], v[206:209], v[160:163], v[28:31]
	v_mfma_f32_16x16x32_bf16 v[20:23], v[214:217], v[160:163], v[20:23]
	ds_read_b128 v[88:91], v92 offset:2048
	v_mfma_f32_16x16x32_bf16 v[4:7], v[206:209], v[198:201], v[4:7]
	v_mfma_f32_16x16x32_bf16 v[0:3], v[214:217], v[198:201], v[0:3]
	ds_read_b128 v[92:95], v92 offset:3072
	v_mfma_f32_16x16x32_bf16 v[56:59], v[210:213], v[132:135], v[56:59]
	v_mfma_f32_16x16x32_bf16 v[52:55], v[218:221], v[132:135], v[52:55]
	v_mfma_f32_16x16x32_bf16 v[44:47], v[210:213], v[152:155], v[44:47]
	v_mfma_f32_16x16x32_bf16 v[36:39], v[218:221], v[152:155], v[36:39]
	v_mfma_f32_16x16x32_bf16 v[28:31], v[210:213], v[164:167], v[28:31]
	v_mfma_f32_16x16x32_bf16 v[20:23], v[218:221], v[164:167], v[20:23]
	v_mfma_f32_16x16x32_bf16 v[4:7], v[210:213], v[202:205], v[4:7]
	v_mfma_f32_16x16x32_bf16 v[0:3], v[218:221], v[202:205], v[0:3]
	s_barrier
	s_setprio 0
	s_add_u32 s46, s46, 0x80000
	s_addc_u32 s47, s47, 0
	s_mov_b32 m0, s56
	ds_read_b128 v[124:127], v190 offset:32768
	ds_read_b128 v[132:135], v190 offset:33792
	ds_read_b128 v[160:163], v190 offset:34816
	ds_read_b128 v[164:167], v190 offset:35840
	ds_read_b128 v[198:201], v190 offset:36864
	ds_read_b128 v[202:205], v190 offset:37888
	ds_read_b128 v[206:209], v190 offset:38912
	ds_read_b128 v[210:213], v190 offset:39936
	global_load_lds_dwordx4 v174, s[46:47]
	s_mov_b32 m0, s57
	s_nop 0
	global_load_lds_dwordx4 v170, s[46:47]
	s_waitcnt lgkmcnt(8)
	s_setprio 1
	s_barrier
	s_waitcnt lgkmcnt(7)
	v_mfma_f32_16x16x32_bf16 v[140:143], v[80:83], v[124:127], v[148:151]
	s_waitcnt lgkmcnt(6)
	v_mfma_f32_16x16x32_bf16 v[148:151], v[84:87], v[132:135], v[140:143]
	v_mfma_f32_16x16x32_bf16 v[140:143], v[88:91], v[124:127], v[144:147]
	s_waitcnt lgkmcnt(5)
	v_mfma_f32_16x16x32_bf16 v[136:139], v[80:83], v[160:163], v[136:139]
	v_mfma_f32_16x16x32_bf16 v[128:131], v[88:91], v[160:163], v[128:131]
	s_waitcnt lgkmcnt(3)
	v_mfma_f32_16x16x32_bf16 v[120:123], v[80:83], v[198:201], v[120:123]
	v_mfma_f32_16x16x32_bf16 v[104:107], v[88:91], v[198:201], v[104:107]
	s_waitcnt lgkmcnt(1)
	v_mfma_f32_16x16x32_bf16 v[76:79], v[80:83], v[206:209], v[76:79]
	v_mfma_f32_16x16x32_bf16 v[72:75], v[88:91], v[206:209], v[72:75]
	v_mfma_f32_16x16x32_bf16 v[144:147], v[92:95], v[132:135], v[140:143]
	v_mfma_f32_16x16x32_bf16 v[136:139], v[84:87], v[164:167], v[136:139]
	v_mfma_f32_16x16x32_bf16 v[128:131], v[92:95], v[164:167], v[128:131]
	v_mfma_f32_16x16x32_bf16 v[120:123], v[84:87], v[202:205], v[120:123]
	v_mfma_f32_16x16x32_bf16 v[104:107], v[92:95], v[202:205], v[104:107]
	s_waitcnt lgkmcnt(0)
	v_mfma_f32_16x16x32_bf16 v[76:79], v[84:87], v[210:213], v[76:79]
	v_mfma_f32_16x16x32_bf16 v[72:75], v[92:95], v[210:213], v[72:75]
	s_barrier
	s_setprio 0
	s_add_i32 s46, 0, 0x1c000
	v_add_u32_e32 v140, s46, v188
	s_add_i32 s47, s68, s37
	ds_read_b128 v[214:217], v140
	ds_read_b128 v[218:221], v140 offset:1024
	ds_read_b128 v[222:225], v140 offset:2048
	ds_read_b128 v[230:233], v140 offset:3072
	v_lshl_add_u64 v[140:141], v[184:185], 0, s[14:15]
	s_mov_b32 m0, s47
	s_nop 0
	global_load_lds_dwordx4 v[140:141], off
	v_lshl_add_u64 v[140:141], v[194:195], 0, s[14:15]
	s_add_i32 m0, s47, 0x2000
	s_nop 0
	global_load_lds_dwordx4 v[140:141], off
	s_setprio 1
	s_barrier
	s_waitcnt lgkmcnt(1)
	v_mfma_f32_16x16x32_bf16 v[96:99], v[222:225], v[124:127], v[96:99]
	v_mfma_f32_16x16x32_bf16 v[140:143], v[214:217], v[124:127], v[156:159]
	s_waitcnt lgkmcnt(0)
	v_mfma_f32_16x16x32_bf16 v[152:155], v[230:233], v[132:135], v[96:99]
	v_mfma_f32_16x16x32_bf16 v[96:99], v[214:217], v[160:163], v[100:103]
	v_mfma_f32_16x16x32_bf16 v[156:159], v[218:221], v[132:135], v[140:143]
	v_mfma_f32_16x16x32_bf16 v[140:143], v[218:221], v[164:167], v[96:99]
	v_mfma_f32_16x16x32_bf16 v[96:99], v[222:225], v[160:163], v[108:111]
	v_mfma_f32_16x16x32_bf16 v[132:135], v[230:233], v[164:167], v[96:99]
	v_mfma_f32_16x16x32_bf16 v[96:99], v[214:217], v[198:201], v[112:115]
	s_mov_b32 m0, s62
	v_mfma_f32_16x16x32_bf16 v[124:127], v[218:221], v[202:205], v[96:99]
	v_lshl_add_u64 v[184:185], v[226:227], 0, s[14:15]
	v_mfma_f32_16x16x32_bf16 v[96:99], v[222:225], v[198:201], v[116:119]
	v_mfma_f32_16x16x32_bf16 v[68:71], v[214:217], v[206:209], v[68:71]
	v_mfma_f32_16x16x32_bf16 v[64:67], v[222:225], v[206:209], v[64:67]
	v_mfma_f32_16x16x32_bf16 v[116:119], v[230:233], v[202:205], v[96:99]
	v_mfma_f32_16x16x32_bf16 v[68:71], v[218:221], v[210:213], v[68:71]
	v_mfma_f32_16x16x32_bf16 v[64:67], v[230:233], v[210:213], v[64:67]
	s_barrier
	s_setprio 0
	ds_read_b128 v[96:99], v190 offset:49152
	ds_read_b128 v[100:103], v190 offset:50176
	ds_read_b128 v[108:111], v190 offset:51200
	ds_read_b128 v[112:115], v190 offset:52224
	ds_read_b128 v[160:163], v190 offset:53248
	ds_read_b128 v[164:167], v190 offset:54272
	ds_read_b128 v[198:201], v190 offset:55296
	ds_read_b128 v[202:205], v190 offset:56320
	global_load_lds_dwordx4 v[184:185], off
	v_lshl_add_u64 v[184:185], v[234:235], 0, s[14:15]
	s_mov_b32 m0, s63
	s_nop 0
	global_load_lds_dwordx4 v[184:185], off
	s_waitcnt vmcnt(10)
	s_setprio 1
	s_barrier
; #define PG8_STAGE(bufoff, gbase, voff) do { _Pragma("unroll") for (int _i = 0; _i < 2; ++_i) \
;         __builtin_amdgcn_global_load_lds((const unsigned*)((const char*)(gbase) + (voff)[_i]), (LAS unsigned*)(lds + (bufoff) + ldsw + _i * 8192), 16, 0, 0); } while (0)
; #define PG8_MMA(ai, bj, At, Bt) do { __builtin_amdgcn_s_setprio(1); _Pragma("unroll") for (int m = 0; m < 4; ++m) _Pragma("unroll") for (int n = 0; n < 2; ++n) _Pragma("unroll") for (int k = 0; k < 2; ++k) \
;         acc[ai][bj][m][n] = __builtin_amdgcn_mfma_f32_16x16x32_bf16(Bt[n][k], At[m][k], acc[ai][bj][m][n], 0, 0, 0); __builtin_amdgcn_s_setprio(0); } while (0)
; #define PG8_WAIT_V(n) asm volatile("s_waitcnt vmcnt(" #n ")" ::: "memory")
; #define PG8_WAIT_L(n) asm volatile("s_waitcnt lgkmcnt(" #n ")" ::: "memory")
; #define PG8_BAR __builtin_amdgcn_s_barrier()
; #define PG8_SCHED __builtin_amdgcn_sched_barrier(0)
; template <class Map, class Epi>
; DI void gemm_phase(LAS unsigned char* lds, const Map& MP, const Epi& E, const int nM, const int nN, const int K, const int lda, const int ldb) {
;     ...
;             PG8_BAR; PG8_WAIT_L(0); PG8_MMA(1, 0, At, B0); PG8_BAR; PG8_SCHED;
;             PG8_STAGE(PG8_SB(1, 1), b3 + hstepB, voffB);
;             PG8_WAIT_V(6); PG8_BAR; PG8_MMA(1, 1, At, B1); PG8_BAR;
;         }
	s_waitcnt lgkmcnt(7)
	v_mfma_f32_16x16x32_bf16 v[60:63], v[80:83], v[96:99], v[60:63]
	v_mfma_f32_16x16x32_bf16 v[48:51], v[88:91], v[96:99], v[48:51]
	s_waitcnt lgkmcnt(5)
	v_mfma_f32_16x16x32_bf16 v[40:43], v[80:83], v[108:111], v[40:43]
	v_mfma_f32_16x16x32_bf16 v[32:35], v[88:91], v[108:111], v[32:35]
	s_waitcnt lgkmcnt(3)
	v_mfma_f32_16x16x32_bf16 v[24:27], v[80:83], v[160:163], v[24:27]
	v_mfma_f32_16x16x32_bf16 v[16:19], v[88:91], v[160:163], v[16:19]
	s_waitcnt lgkmcnt(1)
	v_mfma_f32_16x16x32_bf16 v[12:15], v[80:83], v[198:201], v[12:15]
	v_mfma_f32_16x16x32_bf16 v[8:11], v[88:91], v[198:201], v[8:11]
	v_mfma_f32_16x16x32_bf16 v[60:63], v[84:87], v[100:103], v[60:63]
	v_mfma_f32_16x16x32_bf16 v[48:51], v[92:95], v[100:103], v[48:51]
	v_mfma_f32_16x16x32_bf16 v[40:43], v[84:87], v[112:115], v[40:43]
	v_mfma_f32_16x16x32_bf16 v[32:35], v[92:95], v[112:115], v[32:35]
	v_mfma_f32_16x16x32_bf16 v[24:27], v[84:87], v[164:167], v[24:27]
	v_mfma_f32_16x16x32_bf16 v[16:19], v[92:95], v[164:167], v[16:19]
	s_waitcnt lgkmcnt(0)
	v_mfma_f32_16x16x32_bf16 v[12:15], v[84:87], v[202:205], v[12:15]
	v_mfma_f32_16x16x32_bf16 v[8:11], v[92:95], v[202:205], v[8:11]
	s_barrier
	s_setprio 0
	s_add_u32 s28, s28, 0x80080
	s_addc_u32 s29, s29, 0
	s_add_i32 s46, s46, s37
	s_mov_b32 m0, s46
	s_nop 0
	global_load_lds_dwordx4 v172, s[28:29]
	s_add_i32 m0, s46, 0x2000
	s_nop 0
	global_load_lds_dwordx4 v168, s[28:29]
	s_waitcnt vmcnt(6)
	s_setprio 1
	s_barrier
	v_mfma_f32_16x16x32_bf16 v[56:59], v[214:217], v[96:99], v[56:59]
	v_mfma_f32_16x16x32_bf16 v[52:55], v[222:225], v[96:99], v[52:55]
	ds_read_b128 v[80:83], v189
	v_mfma_f32_16x16x32_bf16 v[44:47], v[214:217], v[108:111], v[44:47]
	v_mfma_f32_16x16x32_bf16 v[36:39], v[222:225], v[108:111], v[36:39]
	ds_read_b128 v[84:87], v189 offset:1024
	v_mfma_f32_16x16x32_bf16 v[28:31], v[214:217], v[160:163], v[28:31]
	v_mfma_f32_16x16x32_bf16 v[20:23], v[222:225], v[160:163], v[20:23]
	ds_read_b128 v[88:91], v189 offset:2048
	v_mfma_f32_16x16x32_bf16 v[4:7], v[214:217], v[198:201], v[4:7]
	v_mfma_f32_16x16x32_bf16 v[0:3], v[222:225], v[198:201], v[0:3]
	ds_read_b128 v[92:95], v189 offset:3072
	v_mfma_f32_16x16x32_bf16 v[56:59], v[218:221], v[100:103], v[56:59]
	s_add_i32 vcc_hi, vcc_hi, 2
	v_mfma_f32_16x16x32_bf16 v[52:55], v[230:233], v[100:103], v[52:55]
	s_add_u32 s59, s59, 0x100
	s_addc_u32 vcc_lo, vcc_lo, 0
	v_mfma_f32_16x16x32_bf16 v[44:47], v[218:221], v[112:115], v[44:47]
	s_add_u32 s44, s44, 0x100
	s_addc_u32 s45, s45, 0
	v_mfma_f32_16x16x32_bf16 v[36:39], v[230:233], v[112:115], v[36:39]
	s_cmp_gt_u32 vcc_hi, 29
	v_mfma_f32_16x16x32_bf16 v[28:31], v[218:221], v[164:167], v[28:31]
	v_mfma_f32_16x16x32_bf16 v[20:23], v[230:233], v[164:167], v[20:23]
	v_mfma_f32_16x16x32_bf16 v[4:7], v[218:221], v[202:205], v[4:7]
	v_mfma_f32_16x16x32_bf16 v[0:3], v[230:233], v[202:205], v[0:3]
	s_barrier
	s_setprio 0
	s_cbranch_scc0 .LBB1_380
; DI float silu_mul(float g, float v) { return g * v * __builtin_amdgcn_rcpf(1.0f + __builtin_amdgcn_exp2f(-LOG2E * g)); }
;     DI void operator()(const f32x4 (&acc)[2][2][4][2], const Unit& u, int wr, int wc, int fr, int fq) const {
;         const int row0 = u.pm * BM + wr * 64 + fr, ch0 = u.pn * 128 + wc * 32 + 8 * fq;
;         f32x4 w0[2], w1[2], w2[2], bb[2];
; #pragma unroll
;         for (int n = 0; n < 2; ++n) { w0[n] = *(const f32x4*)(cw + ch0 + 4 * n); w1[n] = *(const f32x4*)(cw + DFF + ch0 + 4 * n); w2[n] = *(const f32x4*)(cw + 2 * DFF + ch0 + 4 * n); bb[n] = *(const f32x4*)(cb + ch0 + 4 * n); }
; #pragma unroll
;         for (int ai = 0; ai < 2; ++ai)
; #pragma unroll
;             for (int m = 0; m < 4; ++m) {
;                 const bool efirst = (m == 0) && (fr == 0), elast = (m == 3) && (fr == 15);
;                 const int row = row0 + ai * HALF + m * 16;
;                 f32x4 gc[2];
; #pragma unroll
;                 for (int n = 0; n < 2; ++n) {
;                     const f32x4 g = acc[ai][0][m][n];
;                     const f32x4 gprev = acc[ai][0][m > 0 ? m - 1 : 0][n], gnext = acc[ai][0][m < 3 ? m + 1 : 3][n];
;                     f32x4 up, dn;
; #pragma unroll
;                     for (int e = 0; e < 4; ++e) {
;                         const float pu = (m > 0 && fr == 15) ? gprev[e] : g[e];
;                         const float pd = (m < 3 && fr == 0) ? gnext[e] : g[e];
;                         up[e] = dpp_ror1(pu); dn[e] = dpp_ror15(pd);
;                     }
;                     if (efirst) up = (f32x4){0.f, 0.f, 0.f, 0.f};
;                     if (elast) dn = (f32x4){0.f, 0.f, 0.f, 0.f};
;                     gc[n] = w0[n] * up + w1[n] * g + w2[n] * dn + bb[n];
;                 }
;                 if (efirst || elast) {
;                     const size_t eo = (size_t)((row >> 6) * 2 + (elast ? 1 : 0)) * DFF + ch0;
; #pragma unroll
;                     for (int n = 0; n < 2; ++n) { *(f32x4*)(EP + eo + 4 * n) = gc[n]; *(f32x4*)(ER + eo + 4 * n) = acc[ai][0][m][n]; *(f32x4*)(EV + eo + 4 * n) = acc[ai][1][m][n]; }
;                 } else {
;                     const f32x4 v0 = acc[ai][1][m][0], v1 = acc[ai][1][m][1];
;                     u32x4 o;
;                     o[0] = pack2(silu_mul(gc[0][0], v0[0]), silu_mul(gc[0][1], v0[1])); o[1] = pack2(silu_mul(gc[0][2], v0[2]), silu_mul(gc[0][3], v0[3]));
	s_waitcnt lgkmcnt(0)
	s_lshl_b32 s23, s43, 7
	v_mov_b32_e32 v194, v186
	v_mov_b32_e32 v80, v187
	s_or_b32 s23, s23, s67
	v_mov_b32_e32 v160, 0
	v_lshl_add_u32 v184, v80, 3, s23
	v_ashrrev_i32_e32 v185, 31, v184
	v_lshlrev_b64 v[80:81], 2, v[184:185]
	v_lshl_add_u64 v[84:85], s[52:53], 0, v[80:81]
	v_lshl_add_u64 v[88:89], s[16:17], 0, v[80:81]
	v_lshl_add_u64 v[92:93], s[18:19], 0, v[80:81]
	v_lshl_add_u64 v[112:113], s[54:55], 0, v[80:81]
	global_load_dwordx4 v[80:83], v[84:85], off offset:16
	global_load_dwordx4 v[96:99], v[84:85], off
	s_nop 0
	global_load_dwordx4 v[84:87], v[88:89], off offset:16
	global_load_dwordx4 v[100:103], v[88:89], off
	s_nop 0
	global_load_dwordx4 v[88:91], v[92:93], off offset:16
	global_load_dwordx4 v[108:111], v[92:93], off
	s_nop 0
	global_load_dwordx4 v[92:95], v[112:113], off offset:16
	s_nop 0
	global_load_dwordx4 v[112:115], v[112:113], off
	v_cmp_eq_u32_e32 vcc, 0, v194
	v_mov_b32_e32 v164, 0
	v_mov_b32_e32 v195, 0
	v_cndmask_b32_e32 v161, v148, v136, vcc
	v_cndmask_b32_e32 v162, v149, v137, vcc
	v_cndmask_b32_e32 v163, v150, v138, vcc
	v_mov_b32_dpp v160, v161 row_ror:15 row_mask:0xf bank_mask:0xf
	v_mov_b32_e32 v161, 0
	v_mov_b32_e32 v166, 0
	v_mov_b32_e32 v167, 0
	v_mov_b32_dpp v161, v162 row_ror:15 row_mask:0xf bank_mask:0xf
	v_mov_b32_e32 v162, 0
	v_mov_b32_dpp v164, v150 row_ror:1 row_mask:0xf bank_mask:0xf
	v_cndmask_b32_e32 v165, v151, v139, vcc
	v_mov_b32_dpp v162, v163 row_ror:15 row_mask:0xf bank_mask:0xf
	v_mov_b32_dpp v195, v151 row_ror:1 row_mask:0xf bank_mask:0xf
	v_mov_b32_e32 v163, 0
	v_mov_b32_dpp v166, v148 row_ror:1 row_mask:0xf bank_mask:0xf
	v_mov_b32_dpp v167, v149 row_ror:1 row_mask:0xf bank_mask:0xf
	v_mov_b32_dpp v163, v165 row_ror:15 row_mask:0xf bank_mask:0xf
	v_cndmask_b32_e64 v165, v195, 0, vcc
	v_cndmask_b32_e64 v164, v164, 0, vcc
	v_cndmask_b32_e64 v167, v167, 0, vcc
	v_cndmask_b32_e64 v166, v166, 0, vcc
	v_mov_b32_e32 v195, 0
	v_mov_b32_e32 v196, 0
	v_mov_b32_e32 v198, 0
	v_mov_b32_e32 v200, 0
	v_mov_b32_dpp v195, v144 row_ror:1 row_mask:0xf bank_mask:0xf
	v_mov_b32_dpp v196, v145 row_ror:1 row_mask:0xf bank_mask:0xf
	v_mov_b32_dpp v198, v146 row_ror:1 row_mask:0xf bank_mask:0xf
	v_cndmask_b32_e32 v199, v147, v131, vcc
	v_mov_b32_dpp v200, v147 row_ror:1 row_mask:0xf bank_mask:0xf
	v_cndmask_b32_e64 v198, v198, 0, vcc
	v_cndmask_b32_e64 v201, v196, 0, vcc
	s_lshl_b32 s21, s42, 8
	s_add_i32 s21, s21, s49
	v_add_u32_e32 v193, s21, v194
	v_cmp_ne_u32_e64 s[46:47], 0, v194
	s_waitcnt vmcnt(0)
	v_pk_mul_f32 v[164:165], v[98:99], v[164:165]
	v_pk_mul_f32 v[166:167], v[96:97], v[166:167]
	v_pk_fma_f32 v[164:165], v[150:151], v[102:103], v[164:165]
	v_pk_fma_f32 v[166:167], v[148:149], v[100:101], v[166:167]
	v_pk_fma_f32 v[162:163], v[110:111], v[162:163], v[164:165]
	v_cndmask_b32_e32 v165, v144, v128, vcc
	v_mov_b32_e32 v164, 0
	v_pk_fma_f32 v[160:161], v[108:109], v[160:161], v[166:167]
	v_cndmask_b32_e32 v166, v145, v129, vcc
	v_mov_b32_dpp v164, v165 row_ror:15 row_mask:0xf bank_mask:0xf
	v_mov_b32_e32 v165, 0
	v_cndmask_b32_e32 v167, v146, v130, vcc
	v_pk_add_f32 v[162:163], v[114:115], v[162:163]
	v_mov_b32_dpp v165, v166 row_ror:15 row_mask:0xf bank_mask:0xf
	v_mov_b32_e32 v166, 0
	v_pk_add_f32 v[160:161], v[112:113], v[160:161]
	s_nop 0
	v_mov_b32_dpp v166, v167 row_ror:15 row_mask:0xf bank_mask:0xf
	v_mov_b32_e32 v167, 0
	s_nop 1
	v_mov_b32_dpp v167, v199 row_ror:15 row_mask:0xf bank_mask:0xf
	v_cndmask_b32_e64 v199, v200, 0, vcc
	v_cndmask_b32_e64 v200, v195, 0, vcc
	v_pk_mul_f32 v[200:201], v[80:81], v[200:201]
	v_pk_mul_f32 v[198:199], v[82:83], v[198:199]
	v_pk_fma_f32 v[200:201], v[144:145], v[84:85], v[200:201]
	v_pk_fma_f32 v[198:199], v[146:147], v[86:87], v[198:199]
	v_pk_fma_f32 v[164:165], v[88:89], v[164:165], v[200:201]
	v_pk_fma_f32 v[166:167], v[90:91], v[166:167], v[198:199]
	v_pk_add_f32 v[164:165], v[92:93], v[164:165]
	v_pk_add_f32 v[166:167], v[94:95], v[166:167]
	s_and_saveexec_b64 s[28:29], s[46:47]
	s_xor_b64 s[28:29], exec, s[28:29]
	s_cbranch_execz .LBB1_383
	v_mul_f32_e32 v195, 0xbfb8aa3b, v160
	v_exp_f32_e32 v195, v195
	v_mul_f32_e32 v196, 0xbfb8aa3b, v161
	v_exp_f32_e32 v196, v196
	v_pk_mul_f32 v[160:161], v[156:157], v[160:161]
	v_add_f32_e32 v195, 1.0, v195
	v_rcp_f32_e32 v198, v195
	v_add_f32_e32 v196, 1.0, v196
	v_mul_f32_e32 v195, 0xbfb8aa3b, v162
	v_rcp_f32_e32 v199, v196
	v_exp_f32_e32 v195, v195
	v_mul_f32_e32 v196, 0xbfb8aa3b, v163
	v_exp_f32_e32 v196, v196
	v_pk_mul_f32 v[160:161], v[160:161], v[198:199]
	v_add_f32_e32 v195, 1.0, v195
	v_rcp_f32_e32 v200, v195
	v_add_f32_e32 v195, 1.0, v196
	v_rcp_f32_e32 v201, v195
	v_cvt_pk_bf16_f32 v160, v160, v161
	v_mul_f32_e32 v161, 0xbfb8aa3b, v164
	v_exp_f32_e32 v195, v161
	v_mul_f32_e32 v161, 0xbfb8aa3b, v165
	v_exp_f32_e32 v196, v161
	v_pk_mul_f32 v[162:163], v[158:159], v[162:163]
	v_pk_mul_f32 v[164:165], v[152:153], v[164:165]
	v_pk_mul_f32 v[162:163], v[162:163], v[200:201]
	s_nop 0
	v_cvt_pk_bf16_f32 v161, v162, v163
	v_add_f32_e32 v162, 1.0, v195
	v_mul_f32_e32 v195, 0xbfb8aa3b, v166
	v_add_f32_e32 v163, 1.0, v196
	v_exp_f32_e32 v195, v195
	v_mul_f32_e32 v196, 0xbfb8aa3b, v167
	v_exp_f32_e32 v196, v196
	v_rcp_f32_e32 v162, v162
	v_add_f32_e32 v195, 1.0, v195
	v_rcp_f32_e32 v198, v195
	v_add_f32_e32 v195, 1.0, v196
	v_rcp_f32_e32 v163, v163
	v_rcp_f32_e32 v199, v195
	v_pk_mul_f32 v[166:167], v[154:155], v[166:167]
	v_pk_mul_f32 v[162:163], v[164:165], v[162:163]
	v_pk_mul_f32 v[164:165], v[166:167], v[198:199]
	v_cvt_pk_bf16_f32 v162, v162, v163
	v_cvt_pk_bf16_f32 v163, v164, v165
	v_mov_b64_e32 v[164:165], s[6:7]
	v_mad_i64_i32 v[164:165], s[42:43], v193, s30, v[164:165]
	v_lshl_add_u64 v[164:165], v[184:185], 1, v[164:165]
	global_store_dwordx4 v[164:165], v[160:163], off

; #define PG8_STAGE(bufoff, gbase, voff) do { _Pragma("unroll") for (int _i = 0; _i < 2; ++_i) \
;         __builtin_amdgcn_global_load_lds((const unsigned*)((const char*)(gbase) + (voff)[_i]), (LAS unsigned*)(lds + (bufoff) + ldsw + _i * 8192), 16, 0, 0); } while (0)
; #define PG8_LDA(dst, b, h) do { _Pragma("unroll") for (int m = 0; m < 4; ++m) _Pragma("unroll") for (int k = 0; k < 2; ++k) dst[m][k] = *(const LAS bf16x8*)(lds + PG8_SA(b, h) + aoff + m * 2048 + k * 1024); } while (0)
; #define PG8_LDB(dst, b, h) do { _Pragma("unroll") for (int n = 0; n < 2; ++n) _Pragma("unroll") for (int k = 0; k < 2; ++k) dst[n][k] = *(const LAS bf16x8*)(lds + PG8_SB(b, h) + boff + n * 2048 + k * 1024); } while (0)
; #define PG8_MMA(ai, bj, At, Bt) do { __builtin_amdgcn_s_setprio(1); _Pragma("unroll") for (int m = 0; m < 4; ++m) _Pragma("unroll") for (int n = 0; n < 2; ++n) _Pragma("unroll") for (int k = 0; k < 2; ++k) \
;         acc[ai][bj][m][n] = __builtin_amdgcn_mfma_f32_16x16x32_bf16(Bt[n][k], At[m][k], acc[ai][bj][m][n], 0, 0, 0); __builtin_amdgcn_s_setprio(0); } while (0)
; #define PG8_WAIT_V(n) asm volatile("s_waitcnt vmcnt(" #n ")" ::: "memory")
; #define PG8_WAIT_L(n) asm volatile("s_waitcnt lgkmcnt(" #n ")" ::: "memory")
; template <class Map, class Epi>
; DI void gemm_phase(LAS unsigned char* lds, const Map& MP, const Epi& E, const int nM, const int nN, const int K, const int lda, const int ldb) {
;     ...
;         for (int t = 0; t < nt; t += 2) {
;             const bool last = (t == nt - 2);
;             const char* a1 = cA + (size_t)(t + 1) * kstep;
;             const char* a2 = last ? nA : cA + (size_t)(t + 2) * kstep; const char* b2 = last ? nB : cB + (size_t)(t + 2) * kstep;
;             const char* a3 = a2 + kstep; const char* b3 = b2 + kstep;
;             PG8_LDB(B0, 0, 0); PG8_SCHED; PG8_LDA(At, 0, 0); PG8_STAGE(PG8_SA(1, 1), a1 + hstepA, voffA);
;             PG8_WAIT_L(8); PG8_BAR; PG8_WAIT_L(0); PG8_MMA(0, 0, At, B0); PG8_BAR; PG8_SCHED;
;             PG8_LDB(B1, 0, 1); PG8_STAGE(PG8_SB(0, 0), b2, voffB);
;             PG8_BAR; PG8_WAIT_L(0); PG8_MMA(0, 1, At, B1); PG8_BAR;
;             PG8_LDA(At, 0, 1); PG8_STAGE(PG8_SA(0, 0), a2, voffA);
;             PG8_BAR; PG8_WAIT_L(0); PG8_MMA(1, 0, At, B0); PG8_BAR; PG8_SCHED;
;             PG8_STAGE(PG8_SB(0, 1), b2 + hstepB, voffB);
;             PG8_WAIT_V(6); PG8_BAR; PG8_MMA(1, 1, At, B1); PG8_BAR;
.LBB1_550:
	s_add_u32 s10, s8, 0x100
	s_addc_u32 s11, s9, 0
	s_cmpk_eq_i32 s3, 0x54
	s_cselect_b32 s15, s43, s11
	s_cselect_b32 s14, s42, s10
	s_cselect_b32 s13, s7, s38
	s_cselect_b32 s12, s6, s5
	s_add_i32 m0, s24, 0xc000
	ds_read_b128 v[168:171], v150
	ds_read_b128 v[172:175], v150 offset:1024
	ds_read_b128 v[176:179], v150 offset:2048
	ds_read_b128 v[180:183], v150 offset:3072
	ds_read_b128 v[184:187], v150 offset:4096
	ds_read_b128 v[188:191], v150 offset:5120
	ds_read_b128 v[192:195], v150 offset:6144
	ds_read_b128 v[198:201], v150 offset:7168
	global_load_lds_dwordx4 v138, s[8:9]
	s_add_i32 m0, s24, 0xe000
	s_nop 0
	global_load_lds_dwordx4 v136, s[8:9]
	s_waitcnt lgkmcnt(8)
	s_setprio 1
	s_barrier
	s_waitcnt lgkmcnt(7)
	v_mfma_f32_16x16x32_bf16 v[124:127], v[152:155], v[168:171], v[124:127]
	v_mfma_f32_16x16x32_bf16 v[120:123], v[160:163], v[168:171], v[120:123]
	s_waitcnt lgkmcnt(5)
	v_mfma_f32_16x16x32_bf16 v[108:111], v[152:155], v[176:179], v[108:111]
	v_mfma_f32_16x16x32_bf16 v[104:107], v[160:163], v[176:179], v[104:107]
	s_waitcnt lgkmcnt(3)
	v_mfma_f32_16x16x32_bf16 v[92:95], v[152:155], v[184:187], v[92:95]
	v_mfma_f32_16x16x32_bf16 v[88:91], v[160:163], v[184:187], v[88:91]
	s_waitcnt lgkmcnt(1)
	v_mfma_f32_16x16x32_bf16 v[76:79], v[152:155], v[192:195], v[76:79]
	v_mfma_f32_16x16x32_bf16 v[72:75], v[160:163], v[192:195], v[72:75]
	v_mfma_f32_16x16x32_bf16 v[124:127], v[156:159], v[172:175], v[124:127]
	v_mfma_f32_16x16x32_bf16 v[120:123], v[164:167], v[172:175], v[120:123]
	v_mfma_f32_16x16x32_bf16 v[108:111], v[156:159], v[180:183], v[108:111]
	v_mfma_f32_16x16x32_bf16 v[104:107], v[164:167], v[180:183], v[104:107]
	v_mfma_f32_16x16x32_bf16 v[92:95], v[156:159], v[188:191], v[92:95]
	v_mfma_f32_16x16x32_bf16 v[88:91], v[164:167], v[188:191], v[88:91]
	s_waitcnt lgkmcnt(0)
	v_mfma_f32_16x16x32_bf16 v[76:79], v[156:159], v[198:201], v[76:79]
	v_mfma_f32_16x16x32_bf16 v[72:75], v[164:167], v[198:201], v[72:75]
	s_barrier
	s_setprio 0
	s_add_i32 s8, s35, s22
	v_lshl_add_u64 v[144:145], s[12:13], 0, v[132:133]
	s_mov_b32 m0, s8
	ds_read_b128 v[202:205], v151
	ds_read_b128 v[206:209], v151 offset:1024
	ds_read_b128 v[210:213], v151 offset:2048
	ds_read_b128 v[214:217], v151 offset:3072
	global_load_lds_dwordx4 v[144:145], off
	v_lshl_add_u64 v[218:219], s[12:13], 0, v[128:129]
	s_add_i32 m0, s8, 0x2000
	s_nop 0
	global_load_lds_dwordx4 v[218:219], off
	s_setprio 1
	s_barrier
	s_waitcnt lgkmcnt(3)
	v_mfma_f32_16x16x32_bf16 v[116:119], v[202:205], v[168:171], v[116:119]
	s_waitcnt lgkmcnt(1)
	v_mfma_f32_16x16x32_bf16 v[112:115], v[210:213], v[168:171], v[112:115]
	v_mfma_f32_16x16x32_bf16 v[100:103], v[202:205], v[176:179], v[100:103]
	v_mfma_f32_16x16x32_bf16 v[96:99], v[210:213], v[176:179], v[96:99]
	v_mfma_f32_16x16x32_bf16 v[84:87], v[202:205], v[184:187], v[84:87]
	v_mfma_f32_16x16x32_bf16 v[80:83], v[210:213], v[184:187], v[80:83]
	v_mfma_f32_16x16x32_bf16 v[68:71], v[202:205], v[192:195], v[68:71]
	v_mfma_f32_16x16x32_bf16 v[64:67], v[210:213], v[192:195], v[64:67]
	v_mfma_f32_16x16x32_bf16 v[116:119], v[206:209], v[172:175], v[116:119]
	s_mov_b32 m0, s24
	s_waitcnt lgkmcnt(0)
	v_mfma_f32_16x16x32_bf16 v[112:115], v[214:217], v[172:175], v[112:115]
	v_lshl_add_u64 v[220:221], s[14:15], 0, v[134:135]
	v_mfma_f32_16x16x32_bf16 v[100:103], v[206:209], v[180:183], v[100:103]
	v_mfma_f32_16x16x32_bf16 v[96:99], v[214:217], v[180:183], v[96:99]
	v_mfma_f32_16x16x32_bf16 v[84:87], v[206:209], v[188:191], v[84:87]
	v_mfma_f32_16x16x32_bf16 v[80:83], v[214:217], v[188:191], v[80:83]
	v_mfma_f32_16x16x32_bf16 v[68:71], v[206:209], v[198:201], v[68:71]
	v_mfma_f32_16x16x32_bf16 v[64:67], v[214:217], v[198:201], v[64:67]
	s_barrier
	s_setprio 0
	ds_read_b128 v[168:171], v150 offset:16384
	ds_read_b128 v[172:175], v150 offset:17408
	ds_read_b128 v[176:179], v150 offset:18432
	ds_read_b128 v[180:183], v150 offset:19456
	ds_read_b128 v[184:187], v150 offset:20480
	ds_read_b128 v[188:191], v150 offset:21504
	ds_read_b128 v[192:195], v150 offset:22528
	ds_read_b128 v[198:201], v150 offset:23552
	global_load_lds_dwordx4 v[220:221], off
	v_lshl_add_u64 v[222:223], s[14:15], 0, v[130:131]
	s_mov_b32 m0, s25
	s_nop 0
	global_load_lds_dwordx4 v[222:223], off
	s_waitcnt vmcnt(10)
	s_setprio 1
	s_barrier
	s_waitcnt lgkmcnt(7)
	v_mfma_f32_16x16x32_bf16 v[60:63], v[152:155], v[168:171], v[60:63]
	v_mfma_f32_16x16x32_bf16 v[56:59], v[160:163], v[168:171], v[56:59]
	s_waitcnt lgkmcnt(5)
	v_mfma_f32_16x16x32_bf16 v[44:47], v[152:155], v[176:179], v[44:47]
	v_mfma_f32_16x16x32_bf16 v[40:43], v[160:163], v[176:179], v[40:43]
	s_waitcnt lgkmcnt(3)
	v_mfma_f32_16x16x32_bf16 v[28:31], v[152:155], v[184:187], v[28:31]
	v_mfma_f32_16x16x32_bf16 v[24:27], v[160:163], v[184:187], v[24:27]
	s_waitcnt lgkmcnt(1)
	v_mfma_f32_16x16x32_bf16 v[12:15], v[152:155], v[192:195], v[12:15]
	v_mfma_f32_16x16x32_bf16 v[8:11], v[160:163], v[192:195], v[8:11]
	v_mfma_f32_16x16x32_bf16 v[60:63], v[156:159], v[172:175], v[60:63]
	v_mfma_f32_16x16x32_bf16 v[56:59], v[164:167], v[172:175], v[56:59]
	v_mfma_f32_16x16x32_bf16 v[44:47], v[156:159], v[180:183], v[44:47]
	v_mfma_f32_16x16x32_bf16 v[40:43], v[164:167], v[180:183], v[40:43]
	v_mfma_f32_16x16x32_bf16 v[28:31], v[156:159], v[188:191], v[28:31]
	v_mfma_f32_16x16x32_bf16 v[24:27], v[164:167], v[188:191], v[24:27]
	s_waitcnt lgkmcnt(0)
	v_mfma_f32_16x16x32_bf16 v[12:15], v[156:159], v[198:201], v[12:15]
	v_mfma_f32_16x16x32_bf16 v[8:11], v[164:167], v[198:201], v[8:11]
	s_barrier
	s_setprio 0
	s_add_u32 s8, s12, 0x160000
	s_addc_u32 s9, s13, 0
	s_add_i32 s39, s36, s22
	s_mov_b32 m0, s39
	s_nop 0
	global_load_lds_dwordx4 v132, s[8:9]
	s_add_i32 m0, s39, 0x2000
	s_nop 0
	global_load_lds_dwordx4 v128, s[8:9]
	s_waitcnt vmcnt(6)
	s_setprio 1
	s_barrier
; #define PG8_STAGE(bufoff, gbase, voff) do { _Pragma("unroll") for (int _i = 0; _i < 2; ++_i) \
;         __builtin_amdgcn_global_load_lds((const unsigned*)((const char*)(gbase) + (voff)[_i]), (LAS unsigned*)(lds + (bufoff) + ldsw + _i * 8192), 16, 0, 0); } while (0)
; #define PG8_LDA(dst, b, h) do { _Pragma("unroll") for (int m = 0; m < 4; ++m) _Pragma("unroll") for (int k = 0; k < 2; ++k) dst[m][k] = *(const LAS bf16x8*)(lds + PG8_SA(b, h) + aoff + m * 2048 + k * 1024); } while (0)
; #define PG8_LDB(dst, b, h) do { _Pragma("unroll") for (int n = 0; n < 2; ++n) _Pragma("unroll") for (int k = 0; k < 2; ++k) dst[n][k] = *(const LAS bf16x8*)(lds + PG8_SB(b, h) + boff + n * 2048 + k * 1024); } while (0)
; #define PG8_WAIT_V(n) asm volatile("s_waitcnt vmcnt(" #n ")" ::: "memory")
; #define PG8_WAIT_L(n) asm volatile("s_waitcnt lgkmcnt(" #n ")" ::: "memory")
; #define PG8_BAR __builtin_amdgcn_s_barrier()
; #define PG8_SCHED __builtin_amdgcn_sched_barrier(0)
; template <class Map, class Epi>
; DI void gemm_phase(LAS unsigned char* lds, const Map& MP, const Epi& E, const int nM, const int nN, const int K, const int lda, const int ldb) {
;     ...
;             PG8_LDB(B0, 0, 0); PG8_SCHED; PG8_LDA(At, 0, 0); PG8_STAGE(PG8_SA(1, 1), a1 + hstepA, voffA);
;             PG8_WAIT_L(8); PG8_BAR; PG8_WAIT_L(0); PG8_MMA(0, 0, At, B0); PG8_BAR; PG8_SCHED;
;             PG8_LDB(B1, 0, 1); PG8_STAGE(PG8_SB(0, 0), b2, voffB);
;             PG8_BAR; PG8_WAIT_L(0); PG8_MMA(0, 1, At, B1); PG8_BAR;
;             PG8_LDA(At, 0, 1); PG8_STAGE(PG8_SA(0, 0), a2, voffA);
;             PG8_BAR; PG8_WAIT_L(0); PG8_MMA(1, 0, At, B0); PG8_BAR; PG8_SCHED;
;             PG8_STAGE(PG8_SB(0, 1), b2 + hstepB, voffB);
;             PG8_WAIT_V(6); PG8_BAR; PG8_MMA(1, 1, At, B1); PG8_BAR;
;             PG8_LDB(B0, 1, 0); PG8_SCHED; PG8_LDA(At, 1, 0); PG8_STAGE(PG8_SA(0, 1), a2 + hstepA, voffA);
;             PG8_WAIT_L(8); PG8_BAR; PG8_WAIT_L(0); PG8_MMA(0, 0, At, B0); PG8_BAR; PG8_SCHED;
;             PG8_LDB(B1, 1, 1); PG8_STAGE(PG8_SB(1, 0), b3, voffB);
;             PG8_BAR; PG8_WAIT_L(0); PG8_MMA(0, 1, At, B1); PG8_BAR;
;             PG8_LDA(At, 1, 1); PG8_STAGE(PG8_SA(1, 0), a3, voffA);
;             PG8_BAR; PG8_WAIT_L(0); PG8_MMA(1, 0, At, B0); PG8_BAR; PG8_SCHED;
;             PG8_STAGE(PG8_SB(1, 1), b3 + hstepB, voffB);
;             PG8_WAIT_V(6); PG8_BAR; PG8_MMA(1, 1, At, B1); PG8_BAR;
	v_mfma_f32_16x16x32_bf16 v[52:55], v[202:205], v[168:171], v[52:55]
	v_mfma_f32_16x16x32_bf16 v[48:51], v[210:213], v[168:171], v[48:51]
	s_add_i32 s39, 0, 0x18000
	v_add_u32_e32 v164, s39, v148
	ds_read_b128 v[152:155], v164
	v_mfma_f32_16x16x32_bf16 v[36:39], v[202:205], v[176:179], v[36:39]
	v_mfma_f32_16x16x32_bf16 v[32:35], v[210:213], v[176:179], v[32:35]
	ds_read_b128 v[156:159], v164 offset:1024
	v_mfma_f32_16x16x32_bf16 v[20:23], v[202:205], v[184:187], v[20:23]
	v_mfma_f32_16x16x32_bf16 v[16:19], v[210:213], v[184:187], v[16:19]
	ds_read_b128 v[160:163], v164 offset:2048
	v_mfma_f32_16x16x32_bf16 v[4:7], v[202:205], v[192:195], v[4:7]
	v_mfma_f32_16x16x32_bf16 v[0:3], v[210:213], v[192:195], v[0:3]
	ds_read_b128 v[164:167], v164 offset:3072
	v_mfma_f32_16x16x32_bf16 v[52:55], v[206:209], v[172:175], v[52:55]
	v_mfma_f32_16x16x32_bf16 v[48:51], v[214:217], v[172:175], v[48:51]
	v_mfma_f32_16x16x32_bf16 v[36:39], v[206:209], v[180:183], v[36:39]
	v_mfma_f32_16x16x32_bf16 v[32:35], v[214:217], v[180:183], v[32:35]
	v_mfma_f32_16x16x32_bf16 v[20:23], v[206:209], v[188:191], v[20:23]
	v_mfma_f32_16x16x32_bf16 v[16:19], v[214:217], v[188:191], v[16:19]
	v_mfma_f32_16x16x32_bf16 v[4:7], v[206:209], v[198:201], v[4:7]
	v_mfma_f32_16x16x32_bf16 v[0:3], v[214:217], v[198:201], v[0:3]
	s_barrier
	s_setprio 0
	s_add_u32 s8, s14, 0x160000
	s_addc_u32 s9, s15, 0
	s_mov_b32 m0, s26
	ds_read_b128 v[168:171], v150 offset:32768
	ds_read_b128 v[172:175], v150 offset:33792
	ds_read_b128 v[176:179], v150 offset:34816
	ds_read_b128 v[180:183], v150 offset:35840
	ds_read_b128 v[184:187], v150 offset:36864
	ds_read_b128 v[188:191], v150 offset:37888
	ds_read_b128 v[192:195], v150 offset:38912
	ds_read_b128 v[198:201], v150 offset:39936
	global_load_lds_dwordx4 v134, s[8:9]
	s_mov_b32 m0, s27
	s_nop 0
	global_load_lds_dwordx4 v130, s[8:9]
	s_waitcnt lgkmcnt(8)
	s_setprio 1
	s_barrier
	s_waitcnt lgkmcnt(7)
	v_mfma_f32_16x16x32_bf16 v[124:127], v[152:155], v[168:171], v[124:127]
	v_mfma_f32_16x16x32_bf16 v[120:123], v[160:163], v[168:171], v[120:123]
	s_waitcnt lgkmcnt(5)
	v_mfma_f32_16x16x32_bf16 v[108:111], v[152:155], v[176:179], v[108:111]
	v_mfma_f32_16x16x32_bf16 v[104:107], v[160:163], v[176:179], v[104:107]
	s_waitcnt lgkmcnt(3)
	v_mfma_f32_16x16x32_bf16 v[92:95], v[152:155], v[184:187], v[92:95]
	v_mfma_f32_16x16x32_bf16 v[88:91], v[160:163], v[184:187], v[88:91]
	s_waitcnt lgkmcnt(1)
	v_mfma_f32_16x16x32_bf16 v[76:79], v[152:155], v[192:195], v[76:79]
	v_mfma_f32_16x16x32_bf16 v[72:75], v[160:163], v[192:195], v[72:75]
	v_mfma_f32_16x16x32_bf16 v[124:127], v[156:159], v[172:175], v[124:127]
	v_mfma_f32_16x16x32_bf16 v[120:123], v[164:167], v[172:175], v[120:123]
	v_mfma_f32_16x16x32_bf16 v[108:111], v[156:159], v[180:183], v[108:111]
	v_mfma_f32_16x16x32_bf16 v[104:107], v[164:167], v[180:183], v[104:107]
	v_mfma_f32_16x16x32_bf16 v[92:95], v[156:159], v[188:191], v[92:95]
	v_mfma_f32_16x16x32_bf16 v[88:91], v[164:167], v[188:191], v[88:91]
	s_waitcnt lgkmcnt(0)
	v_mfma_f32_16x16x32_bf16 v[76:79], v[156:159], v[198:201], v[76:79]
	v_mfma_f32_16x16x32_bf16 v[72:75], v[164:167], v[198:201], v[72:75]
	s_barrier
	s_setprio 0
	s_add_i32 s14, 0, 0x1c000
	s_add_i32 s8, s39, s22
	v_add_u32_e32 v196, s14, v148
	v_lshl_add_u64 v[144:145], v[144:145], 0, s[52:53]
	s_mov_b32 m0, s8
	ds_read_b128 v[202:205], v196
	ds_read_b128 v[206:209], v196 offset:1024
	ds_read_b128 v[210:213], v196 offset:2048
	ds_read_b128 v[214:217], v196 offset:3072
	global_load_lds_dwordx4 v[144:145], off
	v_lshl_add_u64 v[144:145], v[218:219], 0, s[52:53]
	s_add_i32 m0, s8, 0x2000
	s_nop 0
	global_load_lds_dwordx4 v[144:145], off
	s_setprio 1
	s_barrier
	s_waitcnt lgkmcnt(3)
	v_mfma_f32_16x16x32_bf16 v[116:119], v[202:205], v[168:171], v[116:119]
	s_waitcnt lgkmcnt(1)
	v_mfma_f32_16x16x32_bf16 v[112:115], v[210:213], v[168:171], v[112:115]
	v_mfma_f32_16x16x32_bf16 v[100:103], v[202:205], v[176:179], v[100:103]
	v_mfma_f32_16x16x32_bf16 v[96:99], v[210:213], v[176:179], v[96:99]
	v_mfma_f32_16x16x32_bf16 v[84:87], v[202:205], v[184:187], v[84:87]
	v_mfma_f32_16x16x32_bf16 v[80:83], v[210:213], v[184:187], v[80:83]
	v_mfma_f32_16x16x32_bf16 v[68:71], v[202:205], v[192:195], v[68:71]
	v_mfma_f32_16x16x32_bf16 v[64:67], v[210:213], v[192:195], v[64:67]
	v_mfma_f32_16x16x32_bf16 v[116:119], v[206:209], v[172:175], v[116:119]
	s_mov_b32 m0, s30
	s_waitcnt lgkmcnt(0)
	v_mfma_f32_16x16x32_bf16 v[112:115], v[214:217], v[172:175], v[112:115]
	v_lshl_add_u64 v[144:145], v[220:221], 0, s[52:53]
	v_mfma_f32_16x16x32_bf16 v[100:103], v[206:209], v[180:183], v[100:103]
	v_mfma_f32_16x16x32_bf16 v[96:99], v[214:217], v[180:183], v[96:99]
	v_mfma_f32_16x16x32_bf16 v[84:87], v[206:209], v[188:191], v[84:87]
	v_mfma_f32_16x16x32_bf16 v[80:83], v[214:217], v[188:191], v[80:83]
	v_mfma_f32_16x16x32_bf16 v[68:71], v[206:209], v[198:201], v[68:71]
	v_mfma_f32_16x16x32_bf16 v[64:67], v[214:217], v[198:201], v[64:67]
	s_barrier
	s_setprio 0
	ds_read_b128 v[168:171], v150 offset:49152
	ds_read_b128 v[172:175], v150 offset:50176
	ds_read_b128 v[176:179], v150 offset:51200
	ds_read_b128 v[180:183], v150 offset:52224
	ds_read_b128 v[184:187], v150 offset:53248
	ds_read_b128 v[188:191], v150 offset:54272
	ds_read_b128 v[192:195], v150 offset:55296
	ds_read_b128 v[198:201], v150 offset:56320
	global_load_lds_dwordx4 v[144:145], off
	v_lshl_add_u64 v[144:145], v[222:223], 0, s[52:53]
	s_mov_b32 m0, s31
	s_nop 0
	global_load_lds_dwordx4 v[144:145], off
	s_waitcnt vmcnt(10)
	s_setprio 1
	s_barrier
; DI float bflo(unsigned w) { return __uint_as_float(w << 16); }
; DI float bfhi(unsigned w) { return __uint_as_float(w & 0xffff0000u); }
;     DI void operator()(const f32x4 (&acc)[2][2][4][2], const Unit& u, int wr, int wc, int fr, int fq) const {
;     ...
;         for (int ai = 0; ai < 2; ++ai)
; #pragma unroll
;             for (int m = 0; m < 4; ++m) { const size_t ro = (size_t)(row0 + ai * HALF + m * 16) * D + col0;
; #pragma unroll
;                 for (int bj = 0; bj < 2; ++bj) {
;                     f32x4 x0, x1;
;                     if constexpr (IB) { const u32x4 w = *(const u32x4*)((const bf16_t*)Xin + ro + bj * HALF);
;                         x0 = (f32x4){bflo(w[0]), bfhi(w[0]), bflo(w[1]), bfhi(w[1])}; x1 = (f32x4){bflo(w[2]), bfhi(w[2]), bflo(w[3]), bfhi(w[3])}; }
;                     else { x0 = *(const f32x4*)((const float*)Xin + ro + bj * HALF); x1 = *(const f32x4*)((const float*)Xin + ro + bj * HALF + 4); }
;                     x0 += acc[ai][bj][m][0] * sc[bj][0]; x1 += acc[ai][bj][m][1] * sc[bj][1];
;                     if constexpr (OB) { u32x4 o; o[0] = pack2(x0[0], x0[1]); o[1] = pack2(x0[2], x0[3]); o[2] = pack2(x1[0], x1[1]); o[3] = pack2(x1[2], x1[3]);
;                         *(u32x4*)((bf16_t*)Xout + ro + bj * HALF) = o; }
;                     else { *(f32x4*)((float*)Xout + ro + bj * HALF) = x0; *(f32x4*)((float*)Xout + ro + bj * HALF + 4) = x1; } } }
; template <class Map, class Epi>
; DI void gemm_phase(LAS unsigned char* lds, const Map& MP, const Epi& E, const int nM, const int nN, const int K, const int lda, const int ldb) {
;     ...
;             PG8_WAIT_V(6); PG8_BAR; PG8_MMA(1, 1, At, B1); PG8_BAR;
;             PG8_LDB(B0, 1, 0); PG8_SCHED; PG8_LDA(At, 1, 0); PG8_STAGE(PG8_SA(0, 1), a2 + hstepA, voffA);
;             PG8_WAIT_L(8); PG8_BAR; PG8_WAIT_L(0); PG8_MMA(0, 0, At, B0); PG8_BAR; PG8_SCHED;
;             PG8_LDB(B1, 1, 1); PG8_STAGE(PG8_SB(1, 0), b3, voffB);
;             PG8_BAR; PG8_WAIT_L(0); PG8_MMA(0, 1, At, B1); PG8_BAR;
;             PG8_LDA(At, 1, 1); PG8_STAGE(PG8_SA(1, 0), a3, voffA);
;             PG8_BAR; PG8_WAIT_L(0); PG8_MMA(1, 0, At, B0); PG8_BAR; PG8_SCHED;
;             PG8_STAGE(PG8_SB(1, 1), b3 + hstepB, voffB);
;             PG8_WAIT_V(6); PG8_BAR; PG8_MMA(1, 1, At, B1); PG8_BAR;
;         }
;         { int frr = fr, fqq = fq; asm volatile("" : "+v"(frr), "+v"(fqq)); E(acc, cur, wr, wc, frr, fqq); }
	s_waitcnt lgkmcnt(7)
	v_mfma_f32_16x16x32_bf16 v[60:63], v[152:155], v[168:171], v[60:63]
	v_mfma_f32_16x16x32_bf16 v[56:59], v[160:163], v[168:171], v[56:59]
	s_waitcnt lgkmcnt(5)
	v_mfma_f32_16x16x32_bf16 v[44:47], v[152:155], v[176:179], v[44:47]
	v_mfma_f32_16x16x32_bf16 v[40:43], v[160:163], v[176:179], v[40:43]
	s_waitcnt lgkmcnt(3)
	v_mfma_f32_16x16x32_bf16 v[28:31], v[152:155], v[184:187], v[28:31]
	v_mfma_f32_16x16x32_bf16 v[24:27], v[160:163], v[184:187], v[24:27]
	s_waitcnt lgkmcnt(1)
	v_mfma_f32_16x16x32_bf16 v[12:15], v[152:155], v[192:195], v[12:15]
	v_mfma_f32_16x16x32_bf16 v[8:11], v[160:163], v[192:195], v[8:11]
	v_mfma_f32_16x16x32_bf16 v[60:63], v[156:159], v[172:175], v[60:63]
	v_mfma_f32_16x16x32_bf16 v[56:59], v[164:167], v[172:175], v[56:59]
	v_mfma_f32_16x16x32_bf16 v[44:47], v[156:159], v[180:183], v[44:47]
	v_mfma_f32_16x16x32_bf16 v[40:43], v[164:167], v[180:183], v[40:43]
	v_mfma_f32_16x16x32_bf16 v[28:31], v[156:159], v[188:191], v[28:31]
	v_mfma_f32_16x16x32_bf16 v[24:27], v[164:167], v[188:191], v[24:27]
	s_waitcnt lgkmcnt(0)
	v_mfma_f32_16x16x32_bf16 v[12:15], v[156:159], v[198:201], v[12:15]
	v_mfma_f32_16x16x32_bf16 v[8:11], v[164:167], v[198:201], v[8:11]
	s_barrier
	s_setprio 0
	s_add_u32 s8, s12, 0x160080
	s_addc_u32 s9, s13, 0
	s_add_i32 s12, s14, s22
	s_mov_b32 m0, s12
	s_nop 0
	global_load_lds_dwordx4 v132, s[8:9]
	s_add_i32 m0, s12, 0x2000
	s_nop 0
	global_load_lds_dwordx4 v128, s[8:9]
	s_waitcnt vmcnt(6)
	s_setprio 1
	s_barrier
	v_mfma_f32_16x16x32_bf16 v[52:55], v[202:205], v[168:171], v[52:55]
	v_mfma_f32_16x16x32_bf16 v[48:51], v[210:213], v[168:171], v[48:51]
	ds_read_b128 v[152:155], v149
	v_mfma_f32_16x16x32_bf16 v[36:39], v[202:205], v[176:179], v[36:39]
	v_mfma_f32_16x16x32_bf16 v[32:35], v[210:213], v[176:179], v[32:35]
	ds_read_b128 v[156:159], v149 offset:1024
	v_mfma_f32_16x16x32_bf16 v[20:23], v[202:205], v[184:187], v[20:23]
	v_mfma_f32_16x16x32_bf16 v[16:19], v[210:213], v[184:187], v[16:19]
	ds_read_b128 v[160:163], v149 offset:2048
	v_mfma_f32_16x16x32_bf16 v[4:7], v[202:205], v[192:195], v[4:7]
	v_mfma_f32_16x16x32_bf16 v[0:3], v[210:213], v[192:195], v[0:3]
	ds_read_b128 v[164:167], v149 offset:3072
	v_mfma_f32_16x16x32_bf16 v[52:55], v[206:209], v[172:175], v[52:55]
	s_add_i32 s3, s3, 2
	v_mfma_f32_16x16x32_bf16 v[48:51], v[214:217], v[172:175], v[48:51]
	s_add_u32 s5, s5, 0x100
	s_addc_u32 s38, s38, 0
	v_mfma_f32_16x16x32_bf16 v[36:39], v[206:209], v[180:183], v[36:39]
	s_cmpk_gt_u32 s3, 0x55
	v_mfma_f32_16x16x32_bf16 v[32:35], v[214:217], v[180:183], v[32:35]
	s_mov_b64 s[8:9], s[10:11]
	v_mfma_f32_16x16x32_bf16 v[20:23], v[206:209], v[188:191], v[20:23]
	v_mfma_f32_16x16x32_bf16 v[16:19], v[214:217], v[188:191], v[16:19]
	v_mfma_f32_16x16x32_bf16 v[4:7], v[206:209], v[198:201], v[4:7]
	v_mfma_f32_16x16x32_bf16 v[0:3], v[214:217], v[198:201], v[0:3]
	s_barrier
	s_setprio 0
	s_cbranch_scc0 .LBB1_550
	s_waitcnt lgkmcnt(0)
	v_mov_b32_e32 v144, v146
	v_mov_b32_e32 v152, v147
	s_lshl_b32 s2, s2, 8
	s_add_i32 s2, s2, s29
	s_lshl_b32 s3, s4, 8
	v_add_u32_e32 v152, s2, v152
	s_or_b32 s3, s3, s54
	v_ashrrev_i32_e32 v153, 31, v152
	v_lshl_add_u32 v144, v144, 3, s3
	v_lshlrev_b64 v[152:153], 12, v[152:153]
	v_ashrrev_i32_e32 v145, 31, v144
	v_lshl_add_u64 v[152:153], s[46:47], 0, v[152:153]
	v_lshl_add_u64 v[144:145], v[144:145], 1, v[152:153]
	global_load_dwordx4 v[160:163], v[144:145], off
	global_load_dwordx4 v[164:167], v[144:145], off offset:256
	s_mov_b64 s[98:99], 0x10000
	v_lshl_add_u64 v[154:155], v[144:145], 0, s[98:99]
	global_load_dwordx4 v[168:171], v[154:155], off
	global_load_dwordx4 v[172:175], v[154:155], off offset:256
	s_mov_b64 s[98:99], 0x20000
	v_lshl_add_u64 v[154:155], v[144:145], 0, s[98:99]
	global_load_dwordx4 v[176:179], v[154:155], off
	global_load_dwordx4 v[180:183], v[154:155], off offset:256
	s_mov_b64 s[98:99], 0x30000
	v_lshl_add_u64 v[154:155], v[144:145], 0, s[98:99]
	global_load_dwordx4 v[184:187], v[154:155], off
	global_load_dwordx4 v[188:191], v[154:155], off offset:256
	s_mov_b64 s[98:99], 0x80000
	v_lshl_add_u64 v[154:155], v[144:145], 0, s[98:99]
	global_load_dwordx4 v[192:195], v[154:155], off
	global_load_dwordx4 v[198:201], v[154:155], off offset:256
	s_mov_b64 s[98:99], 0x90000
	v_lshl_add_u64 v[154:155], v[144:145], 0, s[98:99]
	global_load_dwordx4 v[202:205], v[154:155], off
	global_load_dwordx4 v[206:209], v[154:155], off offset:256
	s_mov_b64 s[98:99], 0xa0000
	v_lshl_add_u64 v[154:155], v[144:145], 0, s[98:99]
	global_load_dwordx4 v[210:213], v[154:155], off
	global_load_dwordx4 v[214:217], v[154:155], off offset:256
	s_mov_b64 s[98:99], 0xb0000
	v_lshl_add_u64 v[154:155], v[144:145], 0, s[98:99]
	global_load_dwordx4 v[248:251], v[154:155], off
	global_load_dwordx4 v[252:255], v[154:155], off offset:256
	s_waitcnt vmcnt(15)
	s_nop 1
	v_mov_b32_e32 v152, v160
	v_mov_b32_e32 v153, v161
	v_mov_b32_e32 v154, v162
	v_mov_b32_e32 v155, v163
	s_mov_b64 s[2:3], 0x10000
	s_mov_b32 s4, s37
	s_mov_b64 s[10:11], s[6:7]
	s_mov_b64 s[8:9], s[42:43]
	s_waitcnt lgkmcnt(0)
	v_lshlrev_b32_e32 v156, 16, v152
	v_and_b32_e32 v157, 0xffff0000, v152
	v_lshlrev_b32_e32 v152, 16, v153
	v_and_b32_e32 v153, 0xffff0000, v153
	v_lshlrev_b32_e32 v158, 16, v154
	v_and_b32_e32 v159, 0xffff0000, v154
	v_lshlrev_b32_e32 v154, 16, v155
	v_and_b32_e32 v155, 0xffff0000, v155
	v_pk_add_f32 v[126:127], v[126:127], v[152:153]
	v_pk_add_f32 v[124:125], v[124:125], v[156:157]
	v_pk_add_f32 v[152:153], v[122:123], v[154:155]
	v_pk_add_f32 v[122:123], v[120:121], v[158:159]
	v_cvt_pk_bf16_f32 v120, v124, v125
	v_cvt_pk_bf16_f32 v121, v126, v127
	v_cvt_pk_bf16_f32 v122, v122, v123
	v_cvt_pk_bf16_f32 v123, v152, v153
	global_store_dwordx4 v[144:145], v[120:123], off
	s_waitcnt vmcnt(15)
; DI unsigned pack2(float a, float b) { f32x2 v = {a, b}; hwbf16x2 r = __builtin_convertvector(v, hwbf16x2); return __builtin_bit_cast(unsigned, r); }
; DI float bflo(unsigned w) { return __uint_as_float(w << 16); }
; DI float bfhi(unsigned w) { return __uint_as_float(w & 0xffff0000u); }
;     DI void operator()(const f32x4 (&acc)[2][2][4][2], const Unit& u, int wr, int wc, int fr, int fq) const {
;     ...
;         for (int ai = 0; ai < 2; ++ai)
; #pragma unroll
;             for (int m = 0; m < 4; ++m) { const size_t ro = (size_t)(row0 + ai * HALF + m * 16) * D + col0;
; #pragma unroll
;                 for (int bj = 0; bj < 2; ++bj) {
;                     f32x4 x0, x1;
;                     if constexpr (IB) { const u32x4 w = *(const u32x4*)((const bf16_t*)Xin + ro + bj * HALF);
;                         x0 = (f32x4){bflo(w[0]), bfhi(w[0]), bflo(w[1]), bfhi(w[1])}; x1 = (f32x4){bflo(w[2]), bfhi(w[2]), bflo(w[3]), bfhi(w[3])}; }
;                     else { x0 = *(const f32x4*)((const float*)Xin + ro + bj * HALF); x1 = *(const f32x4*)((const float*)Xin + ro + bj * HALF + 4); }
;                     x0 += acc[ai][bj][m][0] * sc[bj][0]; x1 += acc[ai][bj][m][1] * sc[bj][1];
;                     if constexpr (OB) { u32x4 o; o[0] = pack2(x0[0], x0[1]); o[1] = pack2(x0[2], x0[3]); o[2] = pack2(x1[0], x1[1]); o[3] = pack2(x1[2], x1[3]);
;                         *(u32x4*)((bf16_t*)Xout + ro + bj * HALF) = o; }
;                     else { *(f32x4*)((float*)Xout + ro + bj * HALF) = x0; *(f32x4*)((float*)Xout + ro + bj * HALF + 4) = x1; } } }
	s_nop 1
	v_mov_b32_e32 v120, v164
	v_mov_b32_e32 v121, v165
	v_mov_b32_e32 v122, v166
	v_mov_b32_e32 v123, v167
	s_waitcnt lgkmcnt(0)
	v_lshlrev_b32_e32 v124, 16, v120
	v_and_b32_e32 v125, 0xffff0000, v120
	v_lshlrev_b32_e32 v120, 16, v121
	v_and_b32_e32 v121, 0xffff0000, v121
	v_lshlrev_b32_e32 v126, 16, v122
	v_and_b32_e32 v127, 0xffff0000, v122
	v_lshlrev_b32_e32 v122, 16, v123
	v_and_b32_e32 v123, 0xffff0000, v123
	v_pk_add_f32 v[116:117], v[116:117], v[124:125]
	v_pk_add_f32 v[118:119], v[118:119], v[120:121]
	v_pk_add_f32 v[120:121], v[114:115], v[122:123]
	v_pk_add_f32 v[114:115], v[112:113], v[126:127]
	v_cvt_pk_bf16_f32 v112, v116, v117
	v_lshl_add_u64 v[116:117], v[144:145], 0, s[2:3]
	s_mov_b32 s2, 0x10000
	v_cvt_pk_bf16_f32 v113, v118, v119
	v_add_co_u32_e32 v118, vcc, s2, v144
	v_cvt_pk_bf16_f32 v114, v114, v115
	v_cvt_pk_bf16_f32 v115, v120, v121
	v_addc_co_u32_e32 v119, vcc, 0, v145, vcc
	global_store_dwordx4 v[144:145], v[112:115], off offset:256
	s_waitcnt vmcnt(15)
	s_nop 1
	v_mov_b32_e32 v112, v168
	v_mov_b32_e32 v113, v169
	v_mov_b32_e32 v114, v170
	v_mov_b32_e32 v115, v171
	s_mov_b64 s[2:3], 0x20000
	s_waitcnt lgkmcnt(0)
	v_lshlrev_b32_e32 v120, 16, v112
	v_and_b32_e32 v121, 0xffff0000, v112
	v_lshlrev_b32_e32 v112, 16, v113
	v_and_b32_e32 v113, 0xffff0000, v113
	v_lshlrev_b32_e32 v122, 16, v114
	v_and_b32_e32 v123, 0xffff0000, v114
	v_lshlrev_b32_e32 v114, 16, v115
	v_and_b32_e32 v115, 0xffff0000, v115
	v_pk_add_f32 v[110:111], v[110:111], v[112:113]
	v_pk_add_f32 v[108:109], v[108:109], v[120:121]
	v_pk_add_f32 v[112:113], v[106:107], v[114:115]
	v_pk_add_f32 v[106:107], v[104:105], v[122:123]
	v_cvt_pk_bf16_f32 v104, v108, v109
	v_cvt_pk_bf16_f32 v105, v110, v111
	v_cvt_pk_bf16_f32 v106, v106, v107
	v_cvt_pk_bf16_f32 v107, v112, v113
	global_store_dwordx4 v[118:119], v[104:107], off
	s_waitcnt vmcnt(15)
	s_nop 1
	v_mov_b32_e32 v104, v172
	v_mov_b32_e32 v105, v173
	v_mov_b32_e32 v106, v174
	v_mov_b32_e32 v107, v175
	s_waitcnt lgkmcnt(0)
	v_lshlrev_b32_e32 v108, 16, v104
	v_and_b32_e32 v109, 0xffff0000, v104
	v_lshlrev_b32_e32 v104, 16, v105
	v_and_b32_e32 v105, 0xffff0000, v105
	v_lshlrev_b32_e32 v110, 16, v106
	v_and_b32_e32 v111, 0xffff0000, v106
	v_lshlrev_b32_e32 v106, 16, v107
	v_and_b32_e32 v107, 0xffff0000, v107
	v_pk_add_f32 v[100:101], v[100:101], v[108:109]
	v_pk_add_f32 v[102:103], v[102:103], v[104:105]
	v_pk_add_f32 v[104:105], v[98:99], v[106:107]
	v_pk_add_f32 v[98:99], v[96:97], v[110:111]
	v_cvt_pk_bf16_f32 v96, v100, v101
	v_lshl_add_u64 v[100:101], v[144:145], 0, s[2:3]
	s_mov_b32 s2, 0x20000
	v_cvt_pk_bf16_f32 v97, v102, v103
	v_add_co_u32_e32 v102, vcc, s2, v144
	v_cvt_pk_bf16_f32 v98, v98, v99
	v_cvt_pk_bf16_f32 v99, v104, v105
	v_addc_co_u32_e32 v103, vcc, 0, v145, vcc
	global_store_dwordx4 v[116:117], v[96:99], off offset:256
	s_waitcnt vmcnt(15)
	s_nop 1
	v_mov_b32_e32 v96, v176
	v_mov_b32_e32 v97, v177
	v_mov_b32_e32 v98, v178
	v_mov_b32_e32 v99, v179
	s_mov_b64 s[2:3], 0x30000
	s_waitcnt lgkmcnt(0)
	v_lshlrev_b32_e32 v104, 16, v96
	v_and_b32_e32 v105, 0xffff0000, v96
	v_lshlrev_b32_e32 v96, 16, v97
	v_and_b32_e32 v97, 0xffff0000, v97
	v_lshlrev_b32_e32 v106, 16, v98
	v_and_b32_e32 v107, 0xffff0000, v98
	v_lshlrev_b32_e32 v98, 16, v99
	v_and_b32_e32 v99, 0xffff0000, v99
	v_pk_add_f32 v[94:95], v[94:95], v[96:97]
	v_pk_add_f32 v[92:93], v[92:93], v[104:105]
	v_pk_add_f32 v[96:97], v[90:91], v[98:99]
	v_pk_add_f32 v[90:91], v[88:89], v[106:107]
	v_cvt_pk_bf16_f32 v88, v92, v93
	v_cvt_pk_bf16_f32 v89, v94, v95
	v_cvt_pk_bf16_f32 v90, v90, v91
	v_cvt_pk_bf16_f32 v91, v96, v97
	global_store_dwordx4 v[102:103], v[88:91], off
	s_waitcnt vmcnt(15)
	s_nop 1
	v_mov_b32_e32 v88, v180
	v_mov_b32_e32 v89, v181
	v_mov_b32_e32 v90, v182
	v_mov_b32_e32 v91, v183
	s_waitcnt lgkmcnt(0)
	v_lshlrev_b32_e32 v92, 16, v88
	v_and_b32_e32 v93, 0xffff0000, v88
	v_lshlrev_b32_e32 v88, 16, v89
	v_and_b32_e32 v89, 0xffff0000, v89
	v_lshlrev_b32_e32 v94, 16, v90
	v_and_b32_e32 v95, 0xffff0000, v90
	v_lshlrev_b32_e32 v90, 16, v91
	v_and_b32_e32 v91, 0xffff0000, v91
	v_pk_add_f32 v[86:87], v[86:87], v[88:89]
	v_pk_add_f32 v[84:85], v[84:85], v[92:93]
	v_pk_add_f32 v[88:89], v[82:83], v[90:91]
	v_pk_add_f32 v[82:83], v[80:81], v[94:95]
	v_cvt_pk_bf16_f32 v80, v84, v85
	v_cvt_pk_bf16_f32 v81, v86, v87
	v_cvt_pk_bf16_f32 v82, v82, v83
	v_cvt_pk_bf16_f32 v83, v88, v89
	global_store_dwordx4 v[100:101], v[80:83], off offset:256
	s_nop 1
	v_lshl_add_u64 v[80:81], v[144:145], 0, s[2:3]
	s_mov_b32 s2, 0x30000
	v_add_co_u32_e32 v86, vcc, s2, v144
	s_mov_b64 s[2:3], 0x80000
	s_nop 0
	v_addc_co_u32_e32 v87, vcc, 0, v145, vcc
	s_waitcnt vmcnt(15)
	s_nop 1
	v_mov_b32_e32 v82, v184
	v_mov_b32_e32 v83, v185
	v_mov_b32_e32 v84, v186
	v_mov_b32_e32 v85, v187
	s_waitcnt lgkmcnt(0)
	v_lshlrev_b32_e32 v88, 16, v82
	v_and_b32_e32 v89, 0xffff0000, v82
	v_lshlrev_b32_e32 v82, 16, v83
	v_and_b32_e32 v83, 0xffff0000, v83
	v_lshlrev_b32_e32 v90, 16, v84
	v_and_b32_e32 v91, 0xffff0000, v84
	v_lshlrev_b32_e32 v84, 16, v85
	v_and_b32_e32 v85, 0xffff0000, v85
	v_pk_add_f32 v[78:79], v[78:79], v[82:83]
	v_pk_add_f32 v[76:77], v[76:77], v[88:89]
	v_pk_add_f32 v[82:83], v[74:75], v[84:85]
	v_pk_add_f32 v[74:75], v[72:73], v[90:91]
	v_cvt_pk_bf16_f32 v72, v76, v77
	v_cvt_pk_bf16_f32 v73, v78, v79
	v_cvt_pk_bf16_f32 v74, v74, v75
	v_cvt_pk_bf16_f32 v75, v82, v83
	global_store_dwordx4 v[86:87], v[72:75], off
	s_waitcnt vmcnt(15)
	s_nop 1
	v_mov_b32_e32 v72, v188
	v_mov_b32_e32 v73, v189
	v_mov_b32_e32 v74, v190
	v_mov_b32_e32 v75, v191
	s_waitcnt lgkmcnt(0)
; DI unsigned pack2(float a, float b) { f32x2 v = {a, b}; hwbf16x2 r = __builtin_convertvector(v, hwbf16x2); return __builtin_bit_cast(unsigned, r); }
; DI float bflo(unsigned w) { return __uint_as_float(w << 16); }
; DI float bfhi(unsigned w) { return __uint_as_float(w & 0xffff0000u); }
;     DI void operator()(const f32x4 (&acc)[2][2][4][2], const Unit& u, int wr, int wc, int fr, int fq) const {
;     ...
;         for (int ai = 0; ai < 2; ++ai)
; #pragma unroll
;             for (int m = 0; m < 4; ++m) { const size_t ro = (size_t)(row0 + ai * HALF + m * 16) * D + col0;
; #pragma unroll
;                 for (int bj = 0; bj < 2; ++bj) {
;                     f32x4 x0, x1;
;                     if constexpr (IB) { const u32x4 w = *(const u32x4*)((const bf16_t*)Xin + ro + bj * HALF);
;                         x0 = (f32x4){bflo(w[0]), bfhi(w[0]), bflo(w[1]), bfhi(w[1])}; x1 = (f32x4){bflo(w[2]), bfhi(w[2]), bflo(w[3]), bfhi(w[3])}; }
;                     else { x0 = *(const f32x4*)((const float*)Xin + ro + bj * HALF); x1 = *(const f32x4*)((const float*)Xin + ro + bj * HALF + 4); }
;                     x0 += acc[ai][bj][m][0] * sc[bj][0]; x1 += acc[ai][bj][m][1] * sc[bj][1];
;                     if constexpr (OB) { u32x4 o; o[0] = pack2(x0[0], x0[1]); o[1] = pack2(x0[2], x0[3]); o[2] = pack2(x1[0], x1[1]); o[3] = pack2(x1[2], x1[3]);
;                         *(u32x4*)((bf16_t*)Xout + ro + bj * HALF) = o; }
;                     else { *(f32x4*)((float*)Xout + ro + bj * HALF) = x0; *(f32x4*)((float*)Xout + ro + bj * HALF + 4) = x1; } } }
	v_lshlrev_b32_e32 v76, 16, v72
	v_and_b32_e32 v77, 0xffff0000, v72
	v_lshlrev_b32_e32 v72, 16, v73
	v_and_b32_e32 v73, 0xffff0000, v73
	v_lshlrev_b32_e32 v78, 16, v74
	v_and_b32_e32 v79, 0xffff0000, v74
	v_lshlrev_b32_e32 v74, 16, v75
	v_and_b32_e32 v75, 0xffff0000, v75
	v_pk_add_f32 v[70:71], v[70:71], v[72:73]
	v_pk_add_f32 v[68:69], v[68:69], v[76:77]
	v_pk_add_f32 v[72:73], v[66:67], v[74:75]
	v_pk_add_f32 v[66:67], v[64:65], v[78:79]
	v_cvt_pk_bf16_f32 v64, v68, v69
	v_cvt_pk_bf16_f32 v65, v70, v71
	v_cvt_pk_bf16_f32 v66, v66, v67
	v_cvt_pk_bf16_f32 v67, v72, v73
	global_store_dwordx4 v[80:81], v[64:67], off offset:256
	s_nop 1
	v_lshl_add_u64 v[64:65], v[144:145], 0, s[2:3]
	s_mov_b32 s2, 0x80000
	v_add_co_u32_e32 v70, vcc, s2, v144
	s_mov_b64 s[2:3], 0x90000
	s_nop 0
	v_addc_co_u32_e32 v71, vcc, 0, v145, vcc
	s_waitcnt vmcnt(15)
	s_nop 1
	v_mov_b32_e32 v66, v192
	v_mov_b32_e32 v67, v193
	v_mov_b32_e32 v68, v194
	v_mov_b32_e32 v69, v195
	s_waitcnt lgkmcnt(0)
	v_lshlrev_b32_e32 v72, 16, v66
	v_and_b32_e32 v73, 0xffff0000, v66
	v_lshlrev_b32_e32 v66, 16, v67
	v_and_b32_e32 v67, 0xffff0000, v67
	v_lshlrev_b32_e32 v74, 16, v68
	v_and_b32_e32 v75, 0xffff0000, v68
	v_lshlrev_b32_e32 v68, 16, v69
	v_and_b32_e32 v69, 0xffff0000, v69
	v_pk_add_f32 v[62:63], v[62:63], v[66:67]
	v_pk_add_f32 v[60:61], v[60:61], v[72:73]
	v_pk_add_f32 v[66:67], v[58:59], v[68:69]
	v_pk_add_f32 v[58:59], v[56:57], v[74:75]
	v_cvt_pk_bf16_f32 v56, v60, v61
	v_cvt_pk_bf16_f32 v57, v62, v63
	v_cvt_pk_bf16_f32 v58, v58, v59
	v_cvt_pk_bf16_f32 v59, v66, v67
	global_store_dwordx4 v[70:71], v[56:59], off
	s_waitcnt vmcnt(15)
	s_nop 1
	v_mov_b32_e32 v56, v198
	v_mov_b32_e32 v57, v199
	v_mov_b32_e32 v58, v200
	v_mov_b32_e32 v59, v201
	s_waitcnt lgkmcnt(0)
	v_lshlrev_b32_e32 v60, 16, v56
	v_and_b32_e32 v61, 0xffff0000, v56
	v_lshlrev_b32_e32 v56, 16, v57
	v_and_b32_e32 v57, 0xffff0000, v57
	v_lshlrev_b32_e32 v62, 16, v58
	v_and_b32_e32 v63, 0xffff0000, v58
	v_lshlrev_b32_e32 v58, 16, v59
	v_and_b32_e32 v59, 0xffff0000, v59
	v_pk_add_f32 v[54:55], v[54:55], v[56:57]
	v_pk_add_f32 v[52:53], v[52:53], v[60:61]
	v_pk_add_f32 v[56:57], v[50:51], v[58:59]
	v_pk_add_f32 v[50:51], v[48:49], v[62:63]
	v_cvt_pk_bf16_f32 v48, v52, v53
	v_cvt_pk_bf16_f32 v49, v54, v55
	v_cvt_pk_bf16_f32 v50, v50, v51
	v_cvt_pk_bf16_f32 v51, v56, v57
	global_store_dwordx4 v[64:65], v[48:51], off offset:256
	s_nop 1
	v_lshl_add_u64 v[48:49], v[144:145], 0, s[2:3]
	s_mov_b32 s2, 0x90000
	v_add_co_u32_e32 v54, vcc, s2, v144
	s_mov_b64 s[2:3], 0xa0000
	s_nop 0
	v_addc_co_u32_e32 v55, vcc, 0, v145, vcc
	s_waitcnt vmcnt(15)
	s_nop 1
	v_mov_b32_e32 v50, v202
	v_mov_b32_e32 v51, v203
	v_mov_b32_e32 v52, v204
	v_mov_b32_e32 v53, v205
	s_waitcnt lgkmcnt(0)
	v_lshlrev_b32_e32 v56, 16, v50
	v_and_b32_e32 v57, 0xffff0000, v50
	v_lshlrev_b32_e32 v50, 16, v51
	v_and_b32_e32 v51, 0xffff0000, v51
	v_lshlrev_b32_e32 v58, 16, v52
	v_and_b32_e32 v59, 0xffff0000, v52
	v_lshlrev_b32_e32 v52, 16, v53
	v_and_b32_e32 v53, 0xffff0000, v53
	v_pk_add_f32 v[46:47], v[46:47], v[50:51]
	v_pk_add_f32 v[44:45], v[44:45], v[56:57]
	v_pk_add_f32 v[50:51], v[42:43], v[52:53]
	v_pk_add_f32 v[42:43], v[40:41], v[58:59]
	v_cvt_pk_bf16_f32 v40, v44, v45
	v_cvt_pk_bf16_f32 v41, v46, v47
	v_cvt_pk_bf16_f32 v42, v42, v43
	v_cvt_pk_bf16_f32 v43, v50, v51
	global_store_dwordx4 v[54:55], v[40:43], off
	s_waitcnt vmcnt(15)
	s_nop 1
	v_mov_b32_e32 v40, v206
	v_mov_b32_e32 v41, v207
	v_mov_b32_e32 v42, v208
	v_mov_b32_e32 v43, v209
	s_waitcnt lgkmcnt(0)
; DI unsigned pack2(float a, float b) { f32x2 v = {a, b}; hwbf16x2 r = __builtin_convertvector(v, hwbf16x2); return __builtin_bit_cast(unsigned, r); }
; DI float bflo(unsigned w) { return __uint_as_float(w << 16); }
; DI float bfhi(unsigned w) { return __uint_as_float(w & 0xffff0000u); }
;     DI const char* a(const Unit& u) const { return (const char*)(A + (size_t)u.pm * BM * lda); }
;     DI const char* a(const Unit& u) const { return (const char*)(A + (size_t)u.pm * BM * 2048 + (u.pn >> 1) * 512); }
;     DI void operator()(const f32x4 (&acc)[2][2][4][2], const Unit& u, int wr, int wc, int fr, int fq) const {
;     ...
;         for (int ai = 0; ai < 2; ++ai)
; #pragma unroll
;             for (int m = 0; m < 4; ++m) { const size_t ro = (size_t)(row0 + ai * HALF + m * 16) * D + col0;
; #pragma unroll
;                 for (int bj = 0; bj < 2; ++bj) {
;                     f32x4 x0, x1;
;                     if constexpr (IB) { const u32x4 w = *(const u32x4*)((const bf16_t*)Xin + ro + bj * HALF);
;                         x0 = (f32x4){bflo(w[0]), bfhi(w[0]), bflo(w[1]), bfhi(w[1])}; x1 = (f32x4){bflo(w[2]), bfhi(w[2]), bflo(w[3]), bfhi(w[3])}; }
;                     else { x0 = *(const f32x4*)((const float*)Xin + ro + bj * HALF); x1 = *(const f32x4*)((const float*)Xin + ro + bj * HALF + 4); }
;                     x0 += acc[ai][bj][m][0] * sc[bj][0]; x1 += acc[ai][bj][m][1] * sc[bj][1];
;                     if constexpr (OB) { u32x4 o; o[0] = pack2(x0[0], x0[1]); o[1] = pack2(x0[2], x0[3]); o[2] = pack2(x1[0], x1[1]); o[3] = pack2(x1[2], x1[3]);
;                         *(u32x4*)((bf16_t*)Xout + ro + bj * HALF) = o; }
;                     else { *(f32x4*)((float*)Xout + ro + bj * HALF) = x0; *(f32x4*)((float*)Xout + ro + bj * HALF + 4) = x1; } } }
; template <class Map, class Epi>
; DI void gemm_phase(LAS unsigned char* lds, const Map& MP, const Epi& E, const int nM, const int nN, const int K, const int lda, const int ldb) {
;     ...
;         if (!has_next) break;
; #pragma unroll
;         for (int a = 0; a < 2; ++a)
; #pragma unroll
;             for (int b = 0; b < 2; ++b)
; #pragma unroll
;                 for (int m = 0; m < 4; ++m)
; #pragma unroll
;                     for (int n = 0; n < 2; ++n) acc[a][b][m][n] = (f32x4){0.f, 0.f, 0.f, 0.f};
;         cur = nxt; cA = nA; cB = nB; ++ui;
;     }
;     PG8_WAIT_V(0);
;     if (wr == 0) PG8_BAR;
;     PG8_BAR;
	v_lshlrev_b32_e32 v44, 16, v40
	v_and_b32_e32 v45, 0xffff0000, v40
	v_lshlrev_b32_e32 v40, 16, v41
	v_and_b32_e32 v41, 0xffff0000, v41
	v_lshlrev_b32_e32 v46, 16, v42
	v_and_b32_e32 v47, 0xffff0000, v42
	v_lshlrev_b32_e32 v42, 16, v43
	v_and_b32_e32 v43, 0xffff0000, v43
	v_pk_add_f32 v[38:39], v[38:39], v[40:41]
	v_pk_add_f32 v[36:37], v[36:37], v[44:45]
	v_pk_add_f32 v[40:41], v[34:35], v[42:43]
	v_pk_add_f32 v[34:35], v[32:33], v[46:47]
	v_cvt_pk_bf16_f32 v32, v36, v37
	v_cvt_pk_bf16_f32 v33, v38, v39
	v_cvt_pk_bf16_f32 v34, v34, v35
	v_cvt_pk_bf16_f32 v35, v40, v41
	global_store_dwordx4 v[48:49], v[32:35], off offset:256
	s_nop 1
	v_lshl_add_u64 v[32:33], v[144:145], 0, s[2:3]
	s_mov_b32 s2, 0xa0000
	v_add_co_u32_e32 v38, vcc, s2, v144
	s_mov_b64 s[2:3], 0xb0000
	s_nop 0
	v_addc_co_u32_e32 v39, vcc, 0, v145, vcc
	s_waitcnt vmcnt(15)
	s_nop 1
	v_mov_b32_e32 v34, v210
	v_mov_b32_e32 v35, v211
	v_mov_b32_e32 v36, v212
	v_mov_b32_e32 v37, v213
	s_waitcnt lgkmcnt(0)
	v_lshlrev_b32_e32 v40, 16, v34
	v_and_b32_e32 v41, 0xffff0000, v34
	v_lshlrev_b32_e32 v34, 16, v35
	v_and_b32_e32 v35, 0xffff0000, v35
	v_lshlrev_b32_e32 v42, 16, v36
	v_and_b32_e32 v43, 0xffff0000, v36
	v_lshlrev_b32_e32 v36, 16, v37
	v_and_b32_e32 v37, 0xffff0000, v37
	v_pk_add_f32 v[30:31], v[30:31], v[34:35]
	v_pk_add_f32 v[28:29], v[28:29], v[40:41]
	v_pk_add_f32 v[34:35], v[26:27], v[36:37]
	v_pk_add_f32 v[26:27], v[24:25], v[42:43]
	v_cvt_pk_bf16_f32 v24, v28, v29
	v_cvt_pk_bf16_f32 v25, v30, v31
	v_cvt_pk_bf16_f32 v26, v26, v27
	v_cvt_pk_bf16_f32 v27, v34, v35
	global_store_dwordx4 v[38:39], v[24:27], off
	s_waitcnt vmcnt(15)
	s_nop 1
	v_mov_b32_e32 v24, v214
	v_mov_b32_e32 v25, v215
	v_mov_b32_e32 v26, v216
	v_mov_b32_e32 v27, v217
	s_waitcnt lgkmcnt(0)
	v_lshlrev_b32_e32 v28, 16, v24
	v_and_b32_e32 v29, 0xffff0000, v24
	v_lshlrev_b32_e32 v24, 16, v25
	v_and_b32_e32 v25, 0xffff0000, v25
	v_lshlrev_b32_e32 v30, 16, v26
	v_and_b32_e32 v31, 0xffff0000, v26
	v_lshlrev_b32_e32 v26, 16, v27
	v_and_b32_e32 v27, 0xffff0000, v27
	v_pk_add_f32 v[22:23], v[22:23], v[24:25]
	v_pk_add_f32 v[20:21], v[20:21], v[28:29]
	v_pk_add_f32 v[24:25], v[18:19], v[26:27]
	v_pk_add_f32 v[18:19], v[16:17], v[30:31]
	v_cvt_pk_bf16_f32 v16, v20, v21
	v_cvt_pk_bf16_f32 v17, v22, v23
	v_cvt_pk_bf16_f32 v18, v18, v19
	v_cvt_pk_bf16_f32 v19, v24, v25
	global_store_dwordx4 v[32:33], v[16:19], off offset:256
	s_nop 1
	v_lshl_add_u64 v[16:17], v[144:145], 0, s[2:3]
	s_mov_b32 s2, 0xb0000
	v_add_co_u32_e32 v22, vcc, s2, v144
	s_mov_b32 s2, s55
	s_nop 0
	v_addc_co_u32_e32 v23, vcc, 0, v145, vcc
	s_waitcnt vmcnt(15)
	s_nop 1
	v_mov_b32_e32 v18, v248
	v_mov_b32_e32 v19, v249
	v_mov_b32_e32 v20, v250
	v_mov_b32_e32 v21, v251
	s_and_b64 vcc, exec, s[40:41]
	s_waitcnt lgkmcnt(0)
	v_lshlrev_b32_e32 v24, 16, v18
	v_and_b32_e32 v25, 0xffff0000, v18
	v_lshlrev_b32_e32 v18, 16, v19
	v_and_b32_e32 v19, 0xffff0000, v19
	v_lshlrev_b32_e32 v26, 16, v20
	v_and_b32_e32 v27, 0xffff0000, v20
	v_lshlrev_b32_e32 v20, 16, v21
	v_and_b32_e32 v21, 0xffff0000, v21
	v_pk_add_f32 v[14:15], v[14:15], v[18:19]
	v_pk_add_f32 v[12:13], v[12:13], v[24:25]
	v_pk_add_f32 v[18:19], v[10:11], v[20:21]
	v_pk_add_f32 v[10:11], v[8:9], v[26:27]
	v_cvt_pk_bf16_f32 v8, v12, v13
	v_cvt_pk_bf16_f32 v9, v14, v15
	v_cvt_pk_bf16_f32 v10, v10, v11
	v_cvt_pk_bf16_f32 v11, v18, v19
	global_store_dwordx4 v[22:23], v[8:11], off
	s_waitcnt vmcnt(15)
	s_nop 1
	v_mov_b32_e32 v8, v252
	v_mov_b32_e32 v9, v253
	v_mov_b32_e32 v10, v254
	v_mov_b32_e32 v11, v255
	s_waitcnt lgkmcnt(0)
	v_lshlrev_b32_e32 v12, 16, v8
	v_and_b32_e32 v13, 0xffff0000, v8
	v_lshlrev_b32_e32 v8, 16, v9
	v_and_b32_e32 v9, 0xffff0000, v9
	v_lshlrev_b32_e32 v14, 16, v10
	v_and_b32_e32 v15, 0xffff0000, v10
	v_lshlrev_b32_e32 v10, 16, v11
	v_and_b32_e32 v11, 0xffff0000, v11
	v_pk_add_f32 v[6:7], v[6:7], v[8:9]
	v_pk_add_f32 v[4:5], v[4:5], v[12:13]
	v_pk_add_f32 v[8:9], v[2:3], v[10:11]
	v_pk_add_f32 v[2:3], v[0:1], v[14:15]
	v_cvt_pk_bf16_f32 v0, v4, v5
	v_cvt_pk_bf16_f32 v1, v6, v7
	v_cvt_pk_bf16_f32 v2, v2, v3
	v_cvt_pk_bf16_f32 v3, v8, v9
	global_store_dwordx4 v[16:17], v[0:3], off offset:256
	s_cbranch_vccz .LBB1_543
	s_waitcnt vmcnt(0)
	s_cmpk_gt_u32 s17, 0xff
	s_cbranch_scc1 .LBB1_554
	s_barrier

; #define PG8_STAGE(bufoff, gbase, voff) do { _Pragma("unroll") for (int _i = 0; _i < 2; ++_i) \
;         __builtin_amdgcn_global_load_lds((const unsigned*)((const char*)(gbase) + (voff)[_i]), (LAS unsigned*)(lds + (bufoff) + ldsw + _i * 8192), 16, 0, 0); } while (0)
; #define PG8_LDA(dst, b, h) do { _Pragma("unroll") for (int m = 0; m < 4; ++m) _Pragma("unroll") for (int k = 0; k < 2; ++k) dst[m][k] = *(const LAS bf16x8*)(lds + PG8_SA(b, h) + aoff + m * 2048 + k * 1024); } while (0)
; #define PG8_LDB(dst, b, h) do { _Pragma("unroll") for (int n = 0; n < 2; ++n) _Pragma("unroll") for (int k = 0; k < 2; ++k) dst[n][k] = *(const LAS bf16x8*)(lds + PG8_SB(b, h) + boff + n * 2048 + k * 1024); } while (0)
; #define PG8_MMA(ai, bj, At, Bt) do { __builtin_amdgcn_s_setprio(1); _Pragma("unroll") for (int m = 0; m < 4; ++m) _Pragma("unroll") for (int n = 0; n < 2; ++n) _Pragma("unroll") for (int k = 0; k < 2; ++k) \
;         acc[ai][bj][m][n] = __builtin_amdgcn_mfma_f32_16x16x32_bf16(Bt[n][k], At[m][k], acc[ai][bj][m][n], 0, 0, 0); __builtin_amdgcn_s_setprio(0); } while (0)
; #define PG8_WAIT_V(n) asm volatile("s_waitcnt vmcnt(" #n ")" ::: "memory")
; #define PG8_WAIT_L(n) asm volatile("s_waitcnt lgkmcnt(" #n ")" ::: "memory")
; template <class Map, class Epi>
; DI void gemm_phase(LAS unsigned char* lds, const Map& MP, const Epi& E, const int nM, const int nN, const int K, const int lda, const int ldb) {
;     ...
;         for (int t = 0; t < nt; t += 2) {
;             const bool last = (t == nt - 2);
;             const char* a1 = cA + (size_t)(t + 1) * kstep;
;             const char* a2 = last ? nA : cA + (size_t)(t + 2) * kstep; const char* b2 = last ? nB : cB + (size_t)(t + 2) * kstep;
;             const char* a3 = a2 + kstep; const char* b3 = b2 + kstep;
;             PG8_LDB(B0, 0, 0); PG8_SCHED; PG8_LDA(At, 0, 0); PG8_STAGE(PG8_SA(1, 1), a1 + hstepA, voffA);
;             PG8_WAIT_L(8); PG8_BAR; PG8_WAIT_L(0); PG8_MMA(0, 0, At, B0); PG8_BAR; PG8_SCHED;
;             PG8_LDB(B1, 0, 1); PG8_STAGE(PG8_SB(0, 0), b2, voffB);
;             PG8_BAR; PG8_WAIT_L(0); PG8_MMA(0, 1, At, B1); PG8_BAR;
;             PG8_LDA(At, 0, 1); PG8_STAGE(PG8_SA(0, 0), a2, voffA);
;             PG8_BAR; PG8_WAIT_L(0); PG8_MMA(1, 0, At, B0); PG8_BAR; PG8_SCHED;
;             PG8_STAGE(PG8_SB(0, 1), b2 + hstepB, voffB);
;             PG8_WAIT_V(6); PG8_BAR; PG8_MMA(1, 1, At, B1); PG8_BAR;
.LBB1_693:
	s_add_u32 s3, s20, 0xfff80080
	s_addc_u32 s22, s21, -1
	s_cmp_eq_u32 s54, 28
	s_cselect_b32 s25, s15, s22
	s_cselect_b32 s24, s48, s3
	s_cselect_b32 s23, s13, s53
	s_cselect_b32 s22, s49, s52
	s_add_i32 m0, s31, 0xc000
	ds_read_b128 v[166:169], v148
	ds_read_b128 v[170:173], v148 offset:1024
	ds_read_b128 v[174:177], v148 offset:2048
	ds_read_b128 v[178:181], v148 offset:3072
	ds_read_b128 v[182:185], v148 offset:4096
	ds_read_b128 v[186:189], v148 offset:5120
	ds_read_b128 v[190:193], v148 offset:6144
	ds_read_b128 v[198:201], v148 offset:7168
	global_load_lds_dwordx4 v138, s[20:21]
	s_add_i32 m0, s31, 0xe000
	s_nop 0
	global_load_lds_dwordx4 v136, s[20:21]
	s_waitcnt lgkmcnt(8)
	s_setprio 1
	s_barrier
	s_waitcnt lgkmcnt(7)
	v_mfma_f32_16x16x32_bf16 v[124:127], v[150:153], v[166:169], v[124:127]
	v_mfma_f32_16x16x32_bf16 v[120:123], v[158:161], v[166:169], v[120:123]
	s_waitcnt lgkmcnt(5)
	v_mfma_f32_16x16x32_bf16 v[116:119], v[150:153], v[174:177], v[116:119]
	v_mfma_f32_16x16x32_bf16 v[112:115], v[158:161], v[174:177], v[112:115]
	s_waitcnt lgkmcnt(3)
	v_mfma_f32_16x16x32_bf16 v[100:103], v[150:153], v[182:185], v[100:103]
	v_mfma_f32_16x16x32_bf16 v[96:99], v[158:161], v[182:185], v[96:99]
	s_waitcnt lgkmcnt(1)
	v_mfma_f32_16x16x32_bf16 v[84:87], v[150:153], v[190:193], v[84:87]
	v_mfma_f32_16x16x32_bf16 v[80:83], v[158:161], v[190:193], v[80:83]
	v_mfma_f32_16x16x32_bf16 v[124:127], v[154:157], v[170:173], v[124:127]
	v_mfma_f32_16x16x32_bf16 v[120:123], v[162:165], v[170:173], v[120:123]
	v_mfma_f32_16x16x32_bf16 v[116:119], v[154:157], v[178:181], v[116:119]
	v_mfma_f32_16x16x32_bf16 v[112:115], v[162:165], v[178:181], v[112:115]
	v_mfma_f32_16x16x32_bf16 v[100:103], v[154:157], v[186:189], v[100:103]
	v_mfma_f32_16x16x32_bf16 v[96:99], v[162:165], v[186:189], v[96:99]
	s_waitcnt lgkmcnt(0)
	v_mfma_f32_16x16x32_bf16 v[84:87], v[154:157], v[198:201], v[84:87]
	v_mfma_f32_16x16x32_bf16 v[80:83], v[162:165], v[198:201], v[80:83]
	s_barrier
	s_setprio 0
	s_add_i32 s3, s44, s29
	v_lshl_add_u64 v[194:195], s[22:23], 0, v[132:133]
	s_mov_b32 m0, s3
	ds_read_b128 v[202:205], v149
	ds_read_b128 v[206:209], v149 offset:1024
	ds_read_b128 v[210:213], v149 offset:2048
	ds_read_b128 v[214:217], v149 offset:3072
	global_load_lds_dwordx4 v[194:195], off
	v_lshl_add_u64 v[218:219], s[22:23], 0, v[128:129]
	s_add_i32 m0, s3, 0x2000
	s_nop 0
	global_load_lds_dwordx4 v[218:219], off
	s_setprio 1
	s_barrier
	s_waitcnt lgkmcnt(3)
	v_mfma_f32_16x16x32_bf16 v[108:111], v[202:205], v[166:169], v[108:111]
	s_waitcnt lgkmcnt(1)
	v_mfma_f32_16x16x32_bf16 v[104:107], v[210:213], v[166:169], v[104:107]
	v_mfma_f32_16x16x32_bf16 v[92:95], v[202:205], v[174:177], v[92:95]
	v_mfma_f32_16x16x32_bf16 v[88:91], v[210:213], v[174:177], v[88:91]
	v_mfma_f32_16x16x32_bf16 v[76:79], v[202:205], v[182:185], v[76:79]
	v_mfma_f32_16x16x32_bf16 v[72:75], v[210:213], v[182:185], v[72:75]
	v_mfma_f32_16x16x32_bf16 v[68:71], v[202:205], v[190:193], v[68:71]
	v_mfma_f32_16x16x32_bf16 v[64:67], v[210:213], v[190:193], v[64:67]
	v_mfma_f32_16x16x32_bf16 v[108:111], v[206:209], v[170:173], v[108:111]
	s_mov_b32 m0, s31
	s_waitcnt lgkmcnt(0)
	v_mfma_f32_16x16x32_bf16 v[104:107], v[214:217], v[170:173], v[104:107]
	v_lshl_add_u64 v[220:221], s[24:25], 0, v[134:135]
	v_mfma_f32_16x16x32_bf16 v[92:95], v[206:209], v[178:181], v[92:95]
	v_mfma_f32_16x16x32_bf16 v[88:91], v[214:217], v[178:181], v[88:91]
	v_mfma_f32_16x16x32_bf16 v[76:79], v[206:209], v[186:189], v[76:79]
	v_mfma_f32_16x16x32_bf16 v[72:75], v[214:217], v[186:189], v[72:75]
	v_mfma_f32_16x16x32_bf16 v[68:71], v[206:209], v[198:201], v[68:71]
	v_mfma_f32_16x16x32_bf16 v[64:67], v[214:217], v[198:201], v[64:67]
	s_barrier
	s_setprio 0
	ds_read_b128 v[166:169], v148 offset:16384
	ds_read_b128 v[170:173], v148 offset:17408
	ds_read_b128 v[174:177], v148 offset:18432
	ds_read_b128 v[178:181], v148 offset:19456
	ds_read_b128 v[182:185], v148 offset:20480
	ds_read_b128 v[186:189], v148 offset:21504
	ds_read_b128 v[190:193], v148 offset:22528
	ds_read_b128 v[198:201], v148 offset:23552
	global_load_lds_dwordx4 v[220:221], off
	v_lshl_add_u64 v[222:223], s[24:25], 0, v[130:131]
	s_mov_b32 m0, s11
	s_nop 0
	global_load_lds_dwordx4 v[222:223], off
	s_waitcnt vmcnt(10)
	s_setprio 1
	s_barrier
	s_waitcnt lgkmcnt(7)
	v_mfma_f32_16x16x32_bf16 v[60:63], v[150:153], v[166:169], v[60:63]
	v_mfma_f32_16x16x32_bf16 v[56:59], v[158:161], v[166:169], v[56:59]
	s_waitcnt lgkmcnt(5)
	v_mfma_f32_16x16x32_bf16 v[52:55], v[150:153], v[174:177], v[52:55]
	v_mfma_f32_16x16x32_bf16 v[48:51], v[158:161], v[174:177], v[48:51]
	s_waitcnt lgkmcnt(3)
	v_mfma_f32_16x16x32_bf16 v[36:39], v[150:153], v[182:185], v[36:39]
	v_mfma_f32_16x16x32_bf16 v[32:35], v[158:161], v[182:185], v[32:35]
	s_waitcnt lgkmcnt(1)
	v_mfma_f32_16x16x32_bf16 v[20:23], v[150:153], v[190:193], v[20:23]
	v_mfma_f32_16x16x32_bf16 v[16:19], v[158:161], v[190:193], v[16:19]
	v_mfma_f32_16x16x32_bf16 v[60:63], v[154:157], v[170:173], v[60:63]
	v_mfma_f32_16x16x32_bf16 v[56:59], v[162:165], v[170:173], v[56:59]
	v_mfma_f32_16x16x32_bf16 v[52:55], v[154:157], v[178:181], v[52:55]
	v_mfma_f32_16x16x32_bf16 v[48:51], v[162:165], v[178:181], v[48:51]
	v_mfma_f32_16x16x32_bf16 v[36:39], v[154:157], v[186:189], v[36:39]
	v_mfma_f32_16x16x32_bf16 v[32:35], v[162:165], v[186:189], v[32:35]
	s_waitcnt lgkmcnt(0)
	v_mfma_f32_16x16x32_bf16 v[20:23], v[154:157], v[198:201], v[20:23]
	v_mfma_f32_16x16x32_bf16 v[16:19], v[162:165], v[198:201], v[16:19]
	s_barrier
; #define PG8_STAGE(bufoff, gbase, voff) do { _Pragma("unroll") for (int _i = 0; _i < 2; ++_i) \
;         __builtin_amdgcn_global_load_lds((const unsigned*)((const char*)(gbase) + (voff)[_i]), (LAS unsigned*)(lds + (bufoff) + ldsw + _i * 8192), 16, 0, 0); } while (0)
; #define PG8_LDA(dst, b, h) do { _Pragma("unroll") for (int m = 0; m < 4; ++m) _Pragma("unroll") for (int k = 0; k < 2; ++k) dst[m][k] = *(const LAS bf16x8*)(lds + PG8_SA(b, h) + aoff + m * 2048 + k * 1024); } while (0)
; #define PG8_LDB(dst, b, h) do { _Pragma("unroll") for (int n = 0; n < 2; ++n) _Pragma("unroll") for (int k = 0; k < 2; ++k) dst[n][k] = *(const LAS bf16x8*)(lds + PG8_SB(b, h) + boff + n * 2048 + k * 1024); } while (0)
; #define PG8_MMA(ai, bj, At, Bt) do { __builtin_amdgcn_s_setprio(1); _Pragma("unroll") for (int m = 0; m < 4; ++m) _Pragma("unroll") for (int n = 0; n < 2; ++n) _Pragma("unroll") for (int k = 0; k < 2; ++k) \
;         acc[ai][bj][m][n] = __builtin_amdgcn_mfma_f32_16x16x32_bf16(Bt[n][k], At[m][k], acc[ai][bj][m][n], 0, 0, 0); __builtin_amdgcn_s_setprio(0); } while (0)
; #define PG8_WAIT_V(n) asm volatile("s_waitcnt vmcnt(" #n ")" ::: "memory")
; #define PG8_WAIT_L(n) asm volatile("s_waitcnt lgkmcnt(" #n ")" ::: "memory")
; #define PG8_BAR __builtin_amdgcn_s_barrier()
; #define PG8_SCHED __builtin_amdgcn_sched_barrier(0)
; template <class Map, class Epi>
; DI void gemm_phase(LAS unsigned char* lds, const Map& MP, const Epi& E, const int nM, const int nN, const int K, const int lda, const int ldb) {
;     ...
;             PG8_BAR; PG8_WAIT_L(0); PG8_MMA(1, 0, At, B0); PG8_BAR; PG8_SCHED;
;             PG8_STAGE(PG8_SB(0, 1), b2 + hstepB, voffB);
;             PG8_WAIT_V(6); PG8_BAR; PG8_MMA(1, 1, At, B1); PG8_BAR;
;             PG8_LDB(B0, 1, 0); PG8_SCHED; PG8_LDA(At, 1, 0); PG8_STAGE(PG8_SA(0, 1), a2 + hstepA, voffA);
;             PG8_WAIT_L(8); PG8_BAR; PG8_WAIT_L(0); PG8_MMA(0, 0, At, B0); PG8_BAR; PG8_SCHED;
;             PG8_LDB(B1, 1, 1); PG8_STAGE(PG8_SB(1, 0), b3, voffB);
;             PG8_BAR; PG8_WAIT_L(0); PG8_MMA(0, 1, At, B1); PG8_BAR;
;             PG8_LDA(At, 1, 1); PG8_STAGE(PG8_SA(1, 0), a3, voffA);
;             PG8_BAR; PG8_WAIT_L(0); PG8_MMA(1, 0, At, B0); PG8_BAR; PG8_SCHED;
;             PG8_STAGE(PG8_SB(1, 1), b3 + hstepB, voffB);
	s_setprio 0
	s_add_u32 s56, s22, 0x80000
	s_addc_u32 s57, s23, 0
	s_add_i32 s3, s45, s29
	s_mov_b32 m0, s3
	s_nop 0
	global_load_lds_dwordx4 v132, s[56:57]
	s_add_i32 m0, s3, 0x2000
	s_nop 0
	global_load_lds_dwordx4 v128, s[56:57]
	s_waitcnt vmcnt(6)
	s_setprio 1
	s_barrier
	v_mfma_f32_16x16x32_bf16 v[44:47], v[202:205], v[166:169], v[44:47]
	v_mfma_f32_16x16x32_bf16 v[40:43], v[210:213], v[166:169], v[40:43]
	s_add_i32 s3, 0, 0x18000
	v_add_u32_e32 v162, s3, v146
	ds_read_b128 v[150:153], v162
	v_mfma_f32_16x16x32_bf16 v[28:31], v[202:205], v[174:177], v[28:31]
	v_mfma_f32_16x16x32_bf16 v[24:27], v[210:213], v[174:177], v[24:27]
	ds_read_b128 v[154:157], v162 offset:1024
	v_mfma_f32_16x16x32_bf16 v[12:15], v[202:205], v[182:185], v[12:15]
	v_mfma_f32_16x16x32_bf16 v[8:11], v[210:213], v[182:185], v[8:11]
	ds_read_b128 v[158:161], v162 offset:2048
	v_mfma_f32_16x16x32_bf16 v[4:7], v[202:205], v[190:193], v[4:7]
	v_mfma_f32_16x16x32_bf16 v[0:3], v[210:213], v[190:193], v[0:3]
	ds_read_b128 v[162:165], v162 offset:3072
	v_mfma_f32_16x16x32_bf16 v[44:47], v[206:209], v[170:173], v[44:47]
	v_mfma_f32_16x16x32_bf16 v[40:43], v[214:217], v[170:173], v[40:43]
	v_mfma_f32_16x16x32_bf16 v[28:31], v[206:209], v[178:181], v[28:31]
	v_mfma_f32_16x16x32_bf16 v[24:27], v[214:217], v[178:181], v[24:27]
	v_mfma_f32_16x16x32_bf16 v[12:15], v[206:209], v[186:189], v[12:15]
	v_mfma_f32_16x16x32_bf16 v[8:11], v[214:217], v[186:189], v[8:11]
	v_mfma_f32_16x16x32_bf16 v[4:7], v[206:209], v[198:201], v[4:7]
	v_mfma_f32_16x16x32_bf16 v[0:3], v[214:217], v[198:201], v[0:3]
	s_barrier
	s_setprio 0
	s_add_u32 s24, s24, 0x80000
	s_addc_u32 s25, s25, 0
	s_mov_b32 m0, s34
	ds_read_b128 v[166:169], v148 offset:32768
	ds_read_b128 v[170:173], v148 offset:33792
	ds_read_b128 v[174:177], v148 offset:34816
	ds_read_b128 v[178:181], v148 offset:35840
	ds_read_b128 v[182:185], v148 offset:36864
	ds_read_b128 v[186:189], v148 offset:37888
	ds_read_b128 v[190:193], v148 offset:38912
	ds_read_b128 v[198:201], v148 offset:39936
	global_load_lds_dwordx4 v134, s[24:25]
	s_mov_b32 m0, s35
	s_nop 0
	global_load_lds_dwordx4 v130, s[24:25]
	s_waitcnt lgkmcnt(8)
	s_setprio 1
	s_barrier
	s_waitcnt lgkmcnt(7)
	v_mfma_f32_16x16x32_bf16 v[124:127], v[150:153], v[166:169], v[124:127]
	v_mfma_f32_16x16x32_bf16 v[120:123], v[158:161], v[166:169], v[120:123]
	s_waitcnt lgkmcnt(5)
	v_mfma_f32_16x16x32_bf16 v[116:119], v[150:153], v[174:177], v[116:119]
	v_mfma_f32_16x16x32_bf16 v[112:115], v[158:161], v[174:177], v[112:115]
	s_waitcnt lgkmcnt(3)
	v_mfma_f32_16x16x32_bf16 v[100:103], v[150:153], v[182:185], v[100:103]
	v_mfma_f32_16x16x32_bf16 v[96:99], v[158:161], v[182:185], v[96:99]
	s_waitcnt lgkmcnt(1)
	v_mfma_f32_16x16x32_bf16 v[84:87], v[150:153], v[190:193], v[84:87]
	v_mfma_f32_16x16x32_bf16 v[80:83], v[158:161], v[190:193], v[80:83]
	v_mfma_f32_16x16x32_bf16 v[124:127], v[154:157], v[170:173], v[124:127]
	v_mfma_f32_16x16x32_bf16 v[120:123], v[162:165], v[170:173], v[120:123]
	v_mfma_f32_16x16x32_bf16 v[116:119], v[154:157], v[178:181], v[116:119]
	v_mfma_f32_16x16x32_bf16 v[112:115], v[162:165], v[178:181], v[112:115]
	v_mfma_f32_16x16x32_bf16 v[100:103], v[154:157], v[186:189], v[100:103]
	v_mfma_f32_16x16x32_bf16 v[96:99], v[162:165], v[186:189], v[96:99]
	s_waitcnt lgkmcnt(0)
	v_mfma_f32_16x16x32_bf16 v[84:87], v[154:157], v[198:201], v[84:87]
	v_mfma_f32_16x16x32_bf16 v[80:83], v[162:165], v[198:201], v[80:83]
	s_barrier
	s_setprio 0
	s_add_i32 s24, 0, 0x1c000
	s_add_i32 s3, s3, s29
	v_add_u32_e32 v196, s24, v146
	v_lshl_add_u64 v[194:195], v[194:195], 0, s[8:9]
	s_mov_b32 m0, s3
	ds_read_b128 v[202:205], v196
	ds_read_b128 v[206:209], v196 offset:1024
	ds_read_b128 v[210:213], v196 offset:2048
	ds_read_b128 v[214:217], v196 offset:3072
	global_load_lds_dwordx4 v[194:195], off
	v_lshl_add_u64 v[194:195], v[218:219], 0, s[8:9]
	s_add_i32 m0, s3, 0x2000
	s_nop 0
	global_load_lds_dwordx4 v[194:195], off
	s_setprio 1
	s_barrier
	s_waitcnt lgkmcnt(3)
	v_mfma_f32_16x16x32_bf16 v[108:111], v[202:205], v[166:169], v[108:111]
	s_waitcnt lgkmcnt(1)
	v_mfma_f32_16x16x32_bf16 v[104:107], v[210:213], v[166:169], v[104:107]
	v_mfma_f32_16x16x32_bf16 v[92:95], v[202:205], v[174:177], v[92:95]
	v_mfma_f32_16x16x32_bf16 v[88:91], v[210:213], v[174:177], v[88:91]
	v_mfma_f32_16x16x32_bf16 v[76:79], v[202:205], v[182:185], v[76:79]
	v_mfma_f32_16x16x32_bf16 v[72:75], v[210:213], v[182:185], v[72:75]
	v_mfma_f32_16x16x32_bf16 v[68:71], v[202:205], v[190:193], v[68:71]
	v_mfma_f32_16x16x32_bf16 v[64:67], v[210:213], v[190:193], v[64:67]
	v_mfma_f32_16x16x32_bf16 v[108:111], v[206:209], v[170:173], v[108:111]
	s_mov_b32 m0, s39
	s_waitcnt lgkmcnt(0)
	v_mfma_f32_16x16x32_bf16 v[104:107], v[214:217], v[170:173], v[104:107]
	v_lshl_add_u64 v[194:195], v[220:221], 0, s[8:9]
	v_mfma_f32_16x16x32_bf16 v[92:95], v[206:209], v[178:181], v[92:95]
	v_mfma_f32_16x16x32_bf16 v[88:91], v[214:217], v[178:181], v[88:91]
	v_mfma_f32_16x16x32_bf16 v[76:79], v[206:209], v[186:189], v[76:79]
	v_mfma_f32_16x16x32_bf16 v[72:75], v[214:217], v[186:189], v[72:75]
	v_mfma_f32_16x16x32_bf16 v[68:71], v[206:209], v[198:201], v[68:71]
	v_mfma_f32_16x16x32_bf16 v[64:67], v[214:217], v[198:201], v[64:67]
	s_barrier
	s_setprio 0
	ds_read_b128 v[166:169], v148 offset:49152
	ds_read_b128 v[170:173], v148 offset:50176
	ds_read_b128 v[174:177], v148 offset:51200
	ds_read_b128 v[178:181], v148 offset:52224
	ds_read_b128 v[182:185], v148 offset:53248
	ds_read_b128 v[186:189], v148 offset:54272
	ds_read_b128 v[190:193], v148 offset:55296
	ds_read_b128 v[198:201], v148 offset:56320
	global_load_lds_dwordx4 v[194:195], off
	v_lshl_add_u64 v[194:195], v[222:223], 0, s[8:9]
	s_mov_b32 m0, s42
	s_nop 0
	global_load_lds_dwordx4 v[194:195], off
	s_waitcnt vmcnt(10)
	s_setprio 1
	s_barrier
; #define PG8_STAGE(bufoff, gbase, voff) do { _Pragma("unroll") for (int _i = 0; _i < 2; ++_i) \
;         __builtin_amdgcn_global_load_lds((const unsigned*)((const char*)(gbase) + (voff)[_i]), (LAS unsigned*)(lds + (bufoff) + ldsw + _i * 8192), 16, 0, 0); } while (0)
; #define PG8_LDA(dst, b, h) do { _Pragma("unroll") for (int m = 0; m < 4; ++m) _Pragma("unroll") for (int k = 0; k < 2; ++k) dst[m][k] = *(const LAS bf16x8*)(lds + PG8_SA(b, h) + aoff + m * 2048 + k * 1024); } while (0)
; #define PG8_MMA(ai, bj, At, Bt) do { __builtin_amdgcn_s_setprio(1); _Pragma("unroll") for (int m = 0; m < 4; ++m) _Pragma("unroll") for (int n = 0; n < 2; ++n) _Pragma("unroll") for (int k = 0; k < 2; ++k) \
;         acc[ai][bj][m][n] = __builtin_amdgcn_mfma_f32_16x16x32_bf16(Bt[n][k], At[m][k], acc[ai][bj][m][n], 0, 0, 0); __builtin_amdgcn_s_setprio(0); } while (0)
; #define PG8_WAIT_V(n) asm volatile("s_waitcnt vmcnt(" #n ")" ::: "memory")
; #define PG8_WAIT_L(n) asm volatile("s_waitcnt lgkmcnt(" #n ")" ::: "memory")
; #define PG8_BAR __builtin_amdgcn_s_barrier()
; #define PG8_SCHED __builtin_amdgcn_sched_barrier(0)
; template <class Map, class Epi>
; DI void gemm_phase(LAS unsigned char* lds, const Map& MP, const Epi& E, const int nM, const int nN, const int K, const int lda, const int ldb) {
;     ...
;             PG8_BAR; PG8_WAIT_L(0); PG8_MMA(0, 1, At, B1); PG8_BAR;
;             PG8_LDA(At, 1, 1); PG8_STAGE(PG8_SA(1, 0), a3, voffA);
;             PG8_BAR; PG8_WAIT_L(0); PG8_MMA(1, 0, At, B0); PG8_BAR; PG8_SCHED;
;             PG8_STAGE(PG8_SB(1, 1), b3 + hstepB, voffB);
;             PG8_WAIT_V(6); PG8_BAR; PG8_MMA(1, 1, At, B1); PG8_BAR;
	s_waitcnt lgkmcnt(7)
	v_mfma_f32_16x16x32_bf16 v[60:63], v[150:153], v[166:169], v[60:63]
	v_mfma_f32_16x16x32_bf16 v[56:59], v[158:161], v[166:169], v[56:59]
	s_waitcnt lgkmcnt(5)
	v_mfma_f32_16x16x32_bf16 v[52:55], v[150:153], v[174:177], v[52:55]
	v_mfma_f32_16x16x32_bf16 v[48:51], v[158:161], v[174:177], v[48:51]
	s_waitcnt lgkmcnt(3)
	v_mfma_f32_16x16x32_bf16 v[36:39], v[150:153], v[182:185], v[36:39]
	v_mfma_f32_16x16x32_bf16 v[32:35], v[158:161], v[182:185], v[32:35]
	s_waitcnt lgkmcnt(1)
	v_mfma_f32_16x16x32_bf16 v[20:23], v[150:153], v[190:193], v[20:23]
	v_mfma_f32_16x16x32_bf16 v[16:19], v[158:161], v[190:193], v[16:19]
	v_mfma_f32_16x16x32_bf16 v[60:63], v[154:157], v[170:173], v[60:63]
	v_mfma_f32_16x16x32_bf16 v[56:59], v[162:165], v[170:173], v[56:59]
	v_mfma_f32_16x16x32_bf16 v[52:55], v[154:157], v[178:181], v[52:55]
	v_mfma_f32_16x16x32_bf16 v[48:51], v[162:165], v[178:181], v[48:51]
	v_mfma_f32_16x16x32_bf16 v[36:39], v[154:157], v[186:189], v[36:39]
	v_mfma_f32_16x16x32_bf16 v[32:35], v[162:165], v[186:189], v[32:35]
	s_waitcnt lgkmcnt(0)
	v_mfma_f32_16x16x32_bf16 v[20:23], v[154:157], v[198:201], v[20:23]
	v_mfma_f32_16x16x32_bf16 v[16:19], v[162:165], v[198:201], v[16:19]
	s_barrier
	s_setprio 0
	s_add_u32 s22, s22, 0x80080
	s_addc_u32 s23, s23, 0
	s_add_i32 s3, s24, s29
	s_mov_b32 m0, s3
	s_nop 0
	global_load_lds_dwordx4 v132, s[22:23]
	s_add_i32 m0, s3, 0x2000
	s_nop 0
	global_load_lds_dwordx4 v128, s[22:23]
	s_waitcnt vmcnt(6)
	s_setprio 1
	s_barrier
	v_mfma_f32_16x16x32_bf16 v[44:47], v[202:205], v[166:169], v[44:47]
	v_mfma_f32_16x16x32_bf16 v[40:43], v[210:213], v[166:169], v[40:43]
	ds_read_b128 v[150:153], v147
	v_mfma_f32_16x16x32_bf16 v[28:31], v[202:205], v[174:177], v[28:31]
	v_mfma_f32_16x16x32_bf16 v[24:27], v[210:213], v[174:177], v[24:27]
	ds_read_b128 v[154:157], v147 offset:1024
	v_mfma_f32_16x16x32_bf16 v[12:15], v[202:205], v[182:185], v[12:15]
	v_mfma_f32_16x16x32_bf16 v[8:11], v[210:213], v[182:185], v[8:11]
	ds_read_b128 v[158:161], v147 offset:2048
	v_mfma_f32_16x16x32_bf16 v[4:7], v[202:205], v[190:193], v[4:7]
	v_mfma_f32_16x16x32_bf16 v[0:3], v[210:213], v[190:193], v[0:3]
	ds_read_b128 v[162:165], v147 offset:3072
	v_mfma_f32_16x16x32_bf16 v[44:47], v[206:209], v[170:173], v[44:47]
	s_add_i32 s54, s54, 2
	v_mfma_f32_16x16x32_bf16 v[40:43], v[214:217], v[170:173], v[40:43]
	s_add_u32 s52, s52, 0x100
	s_addc_u32 s53, s53, 0
	v_mfma_f32_16x16x32_bf16 v[28:31], v[206:209], v[178:181], v[28:31]
	s_add_u32 s20, s20, 0x100
	s_addc_u32 s21, s21, 0
	v_mfma_f32_16x16x32_bf16 v[24:27], v[214:217], v[178:181], v[24:27]
	s_cmp_gt_u32 s54, 29
	v_mfma_f32_16x16x32_bf16 v[12:15], v[206:209], v[186:189], v[12:15]
	v_mfma_f32_16x16x32_bf16 v[8:11], v[214:217], v[186:189], v[8:11]
	v_mfma_f32_16x16x32_bf16 v[4:7], v[206:209], v[198:201], v[4:7]
	v_mfma_f32_16x16x32_bf16 v[0:3], v[214:217], v[198:201], v[0:3]
	s_barrier
	s_setprio 0
	s_cbranch_scc0 .LBB1_693
; DI unsigned pack2(float a, float b) { f32x2 v = {a, b}; hwbf16x2 r = __builtin_convertvector(v, hwbf16x2); return __builtin_bit_cast(unsigned, r); }
;     DI const char* a(const Unit& u) const { return (const char*)(A + (size_t)u.pm * BM * lda); }
;     DI const char* a(const Unit& u) const { return (const char*)(A + (size_t)u.pm * BM * 2048 + (u.pn >> 1) * 512); }
;     DI const char* a(const Unit& u) const { return (const char*)((u.pn < 12 ? A1 : A2) + (size_t)u.pm * BM * 512); }
; #define PG8_WAIT_V(n) asm volatile("s_waitcnt vmcnt(" #n ")" ::: "memory")
; #define PG8_BAR __builtin_amdgcn_s_barrier()
;     DI void operator()(const f32x4 (&acc)[2][2][4][2], const Unit& u, int wr, int wc, int fr, int fq) const {
;         bf16_t* O = O1; int ldc = ldc1, pn = u.pn; if (pn >= split) { O = O2; ldc = ldc2; pn -= split; }
;         const int row0 = u.pm * BM + wr * 64 + fr, col0 = pn * BM + wc * 32 + 8 * fq;
; #pragma unroll
;         for (int ai = 0; ai < 2; ++ai)
; #pragma unroll
;             for (int m = 0; m < 4; ++m) { bf16_t* rowp = O + (size_t)(row0 + ai * HALF + m * 16) * ldc + col0;
; #pragma unroll
;                 for (int bj = 0; bj < 2; ++bj) { const f32x4 v0 = acc[ai][bj][m][0], v1 = acc[ai][bj][m][1];
;                     u32x4 o; o[0] = pack2(v0[0], v0[1]); o[1] = pack2(v0[2], v0[3]); o[2] = pack2(v1[0], v1[1]); o[3] = pack2(v1[2], v1[3]);
;                     *(u32x4*)(rowp + bj * HALF) = o; } }
;     }
; template <class Map, class Epi>
; DI void gemm_phase(LAS unsigned char* lds, const Map& MP, const Epi& E, const int nM, const int nN, const int K, const int lda, const int ldb) {
;     ...
;         if (!has_next) break;
; #pragma unroll
;         for (int a = 0; a < 2; ++a)
; #pragma unroll
;             for (int b = 0; b < 2; ++b)
; #pragma unroll
;                 for (int m = 0; m < 4; ++m)
; #pragma unroll
;                     for (int n = 0; n < 2; ++n) acc[a][b][m][n] = (f32x4){0.f, 0.f, 0.f, 0.f};
;         cur = nxt; cA = nA; cB = nB; ++ui;
;     }
;     PG8_WAIT_V(0);
;     if (wr == 0) PG8_BAR;
;     PG8_BAR;
	s_waitcnt lgkmcnt(0)
	s_lshl_b32 s3, s10, 8
	v_mov_b32_e32 v150, v144
	v_mov_b32_e32 v151, v145
	s_add_i32 s3, s3, s37
	v_cvt_pk_bf16_f32 v68, v68, v69
	v_add_u32_e32 v154, s3, v150
	s_lshl_b32 s3, s47, 8
	s_or_b32 s3, s3, s38
	v_lshl_add_u32 v150, v151, 3, s3
	v_ashrrev_i32_e32 v151, 31, v150
	v_lshl_add_u64 v[150:151], v[150:151], 1, s[6:7]
	v_cvt_pk_bf16_f32 v69, v70, v71
	v_cvt_pk_bf16_f32 v70, v64, v65
	v_add_u32_e32 v64, 0x80, v154
	v_mad_i64_i32 v[152:153], s[20:21], v154, s46, v[150:151]
	v_cvt_pk_bf16_f32 v108, v108, v109
	v_cvt_pk_bf16_f32 v109, v110, v111
	v_cvt_pk_bf16_f32 v110, v104, v105
	v_cvt_pk_bf16_f32 v111, v106, v107
	v_add_u32_e32 v104, 16, v154
	v_mad_i64_i32 v[64:65], s[20:21], v64, s46, v[150:151]
	v_cvt_pk_bf16_f32 v44, v44, v45
	v_cvt_pk_bf16_f32 v45, v46, v47
	v_cvt_pk_bf16_f32 v46, v40, v41
	v_cvt_pk_bf16_f32 v47, v42, v43
	v_add_u32_e32 v40, 0x90, v154
	global_store_dwordx4 v[152:153], v[108:111], off offset:256
	v_cvt_pk_bf16_f32 v92, v92, v93
	v_cvt_pk_bf16_f32 v93, v94, v95
	v_mad_i64_i32 v[108:109], s[20:21], v104, s46, v[150:151]
	v_cvt_pk_bf16_f32 v94, v88, v89
	v_cvt_pk_bf16_f32 v95, v90, v91
	v_add_u32_e32 v88, 32, v154
	global_store_dwordx4 v[64:65], v[44:47], off offset:256
	v_cvt_pk_bf16_f32 v28, v28, v29
	v_cvt_pk_bf16_f32 v29, v30, v31
	v_mad_i64_i32 v[44:45], s[20:21], v40, s46, v[150:151]
	v_cvt_pk_bf16_f32 v30, v24, v25
	v_cvt_pk_bf16_f32 v31, v26, v27
	v_add_u32_e32 v24, 0xa0, v154
	global_store_dwordx4 v[108:109], v[92:95], off offset:256
	v_cvt_pk_bf16_f32 v76, v76, v77
	v_cvt_pk_bf16_f32 v77, v78, v79
	v_mad_i64_i32 v[92:93], s[20:21], v88, s46, v[150:151]
	v_cvt_pk_bf16_f32 v78, v72, v73
	v_cvt_pk_bf16_f32 v79, v74, v75
	v_add_u32_e32 v72, 48, v154
	global_store_dwordx4 v[44:45], v[28:31], off offset:256
	v_cvt_pk_bf16_f32 v12, v12, v13
	v_cvt_pk_bf16_f32 v13, v14, v15
	v_mad_i64_i32 v[28:29], s[20:21], v24, s46, v[150:151]
	v_cvt_pk_bf16_f32 v14, v8, v9
	v_cvt_pk_bf16_f32 v15, v10, v11
	v_add_u32_e32 v8, 0xb0, v154
	global_store_dwordx4 v[92:93], v[76:79], off offset:256
	global_store_dwordx4 v[28:29], v[12:15], off offset:256
	v_cvt_pk_bf16_f32 v124, v124, v125
	v_mad_i64_i32 v[76:77], s[20:21], v72, s46, v[150:151]
	v_mad_i64_i32 v[12:13], s[20:21], v8, s46, v[150:151]
	v_cvt_pk_bf16_f32 v125, v126, v127
	v_cvt_pk_bf16_f32 v126, v120, v121
	v_cvt_pk_bf16_f32 v127, v122, v123
	v_cvt_pk_bf16_f32 v104, v116, v117
	v_cvt_pk_bf16_f32 v105, v118, v119
	v_cvt_pk_bf16_f32 v106, v112, v113
	v_cvt_pk_bf16_f32 v107, v114, v115
	v_cvt_pk_bf16_f32 v88, v100, v101
	v_cvt_pk_bf16_f32 v89, v102, v103
	v_cvt_pk_bf16_f32 v90, v96, v97
	v_cvt_pk_bf16_f32 v91, v98, v99
	v_cvt_pk_bf16_f32 v72, v84, v85
	v_cvt_pk_bf16_f32 v73, v86, v87
	v_cvt_pk_bf16_f32 v74, v80, v81
	v_cvt_pk_bf16_f32 v75, v82, v83
	v_cvt_pk_bf16_f32 v71, v66, v67
	v_cvt_pk_bf16_f32 v60, v60, v61
	v_cvt_pk_bf16_f32 v61, v62, v63
	v_cvt_pk_bf16_f32 v62, v56, v57
	v_cvt_pk_bf16_f32 v63, v58, v59
	v_cvt_pk_bf16_f32 v40, v52, v53
	v_cvt_pk_bf16_f32 v41, v54, v55
	v_cvt_pk_bf16_f32 v42, v48, v49
	v_cvt_pk_bf16_f32 v43, v50, v51
	v_cvt_pk_bf16_f32 v24, v36, v37
	v_cvt_pk_bf16_f32 v25, v38, v39
	v_cvt_pk_bf16_f32 v26, v32, v33
	v_cvt_pk_bf16_f32 v27, v34, v35
	v_cvt_pk_bf16_f32 v8, v20, v21
	v_cvt_pk_bf16_f32 v9, v22, v23
	v_cvt_pk_bf16_f32 v10, v16, v17
	v_cvt_pk_bf16_f32 v11, v18, v19
	v_cvt_pk_bf16_f32 v4, v4, v5
	v_cvt_pk_bf16_f32 v5, v6, v7
	v_cvt_pk_bf16_f32 v6, v0, v1
	v_cvt_pk_bf16_f32 v7, v2, v3
	s_and_b64 vcc, exec, s[40:41]
	s_mov_b32 s47, s12
	s_mov_b32 s10, s14
	s_mov_b64 s[20:21], s[18:19]
	s_mov_b64 s[22:23], s[16:17]
	global_store_dwordx4 v[152:153], v[124:127], off
	global_store_dwordx4 v[108:109], v[104:107], off
	global_store_dwordx4 v[92:93], v[88:91], off
	global_store_dwordx4 v[76:77], v[72:75], off
	global_store_dwordx4 v[76:77], v[68:71], off offset:256
	global_store_dwordx4 v[64:65], v[60:63], off
	global_store_dwordx4 v[44:45], v[40:43], off
	global_store_dwordx4 v[28:29], v[24:27], off
	global_store_dwordx4 v[12:13], v[8:11], off
	global_store_dwordx4 v[12:13], v[4:7], off offset:256
	s_cbranch_vccz .LBB1_690
	s_waitcnt vmcnt(0)
	s_cmpk_gt_u32 s4, 0xff
	s_cbranch_scc1 .LBB1_697
	s_barrier

; #define PG8_STAGE(bufoff, gbase, voff) do { _Pragma("unroll") for (int _i = 0; _i < 2; ++_i) \
;         __builtin_amdgcn_global_load_lds((const unsigned*)((const char*)(gbase) + (voff)[_i]), (LAS unsigned*)(lds + (bufoff) + ldsw + _i * 8192), 16, 0, 0); } while (0)
; #define PG8_LDA(dst, b, h) do { _Pragma("unroll") for (int m = 0; m < 4; ++m) _Pragma("unroll") for (int k = 0; k < 2; ++k) dst[m][k] = *(const LAS bf16x8*)(lds + PG8_SA(b, h) + aoff + m * 2048 + k * 1024); } while (0)
; #define PG8_LDB(dst, b, h) do { _Pragma("unroll") for (int n = 0; n < 2; ++n) _Pragma("unroll") for (int k = 0; k < 2; ++k) dst[n][k] = *(const LAS bf16x8*)(lds + PG8_SB(b, h) + boff + n * 2048 + k * 1024); } while (0)
; #define PG8_MMA(ai, bj, At, Bt) do { __builtin_amdgcn_s_setprio(1); _Pragma("unroll") for (int m = 0; m < 4; ++m) _Pragma("unroll") for (int n = 0; n < 2; ++n) _Pragma("unroll") for (int k = 0; k < 2; ++k) \
;         acc[ai][bj][m][n] = __builtin_amdgcn_mfma_f32_16x16x32_bf16(Bt[n][k], At[m][k], acc[ai][bj][m][n], 0, 0, 0); __builtin_amdgcn_s_setprio(0); } while (0)
; #define PG8_WAIT_V(n) asm volatile("s_waitcnt vmcnt(" #n ")" ::: "memory")
; #define PG8_WAIT_L(n) asm volatile("s_waitcnt lgkmcnt(" #n ")" ::: "memory")
; template <class Map, class Epi>
; DI void gemm_phase(LAS unsigned char* lds, const Map& MP, const Epi& E, const int nM, const int nN, const int K, const int lda, const int ldb) {
;     ...
;         for (int t = 0; t < nt; t += 2) {
;             const bool last = (t == nt - 2);
;             const char* a1 = cA + (size_t)(t + 1) * kstep;
;             const char* a2 = last ? nA : cA + (size_t)(t + 2) * kstep; const char* b2 = last ? nB : cB + (size_t)(t + 2) * kstep;
;             const char* a3 = a2 + kstep; const char* b3 = b2 + kstep;
;             PG8_LDB(B0, 0, 0); PG8_SCHED; PG8_LDA(At, 0, 0); PG8_STAGE(PG8_SA(1, 1), a1 + hstepA, voffA);
;             PG8_WAIT_L(8); PG8_BAR; PG8_WAIT_L(0); PG8_MMA(0, 0, At, B0); PG8_BAR; PG8_SCHED;
;             PG8_LDB(B1, 0, 1); PG8_STAGE(PG8_SB(0, 0), b2, voffB);
;             PG8_BAR; PG8_WAIT_L(0); PG8_MMA(0, 1, At, B1); PG8_BAR;
;             PG8_LDA(At, 0, 1); PG8_STAGE(PG8_SA(0, 0), a2, voffA);
;             PG8_BAR; PG8_WAIT_L(0); PG8_MMA(1, 0, At, B0); PG8_BAR; PG8_SCHED;
;             PG8_STAGE(PG8_SB(0, 1), b2 + hstepB, voffB);
;             PG8_WAIT_V(6); PG8_BAR; PG8_MMA(1, 1, At, B1); PG8_BAR;
.LBB1_925:
	s_add_u32 s3, s10, 0xfff80080
	s_addc_u32 s12, s11, -1
	s_cmp_eq_u32 s48, 28
	s_cselect_b32 s15, s4, s12
	s_cselect_b32 s14, s5, s3
	s_cselect_b32 s13, s37, s47
	s_cselect_b32 s12, s38, s39
	s_add_i32 m0, s24, 0xc000
	ds_read_b128 v[168:171], v150
	ds_read_b128 v[172:175], v150 offset:1024
	ds_read_b128 v[176:179], v150 offset:2048
	ds_read_b128 v[180:183], v150 offset:3072
	ds_read_b128 v[184:187], v150 offset:4096
	ds_read_b128 v[188:191], v150 offset:5120
	ds_read_b128 v[192:195], v150 offset:6144
	ds_read_b128 v[198:201], v150 offset:7168
	global_load_lds_dwordx4 v138, s[10:11]
	s_add_i32 m0, s24, 0xe000
	s_nop 0
	global_load_lds_dwordx4 v136, s[10:11]
	s_waitcnt lgkmcnt(8)
	s_setprio 1
	s_barrier
	s_waitcnt lgkmcnt(7)
	v_mfma_f32_16x16x32_bf16 v[124:127], v[152:155], v[168:171], v[124:127]
	v_mfma_f32_16x16x32_bf16 v[120:123], v[160:163], v[168:171], v[120:123]
	s_waitcnt lgkmcnt(5)
	v_mfma_f32_16x16x32_bf16 v[108:111], v[152:155], v[176:179], v[108:111]
	v_mfma_f32_16x16x32_bf16 v[104:107], v[160:163], v[176:179], v[104:107]
	s_waitcnt lgkmcnt(3)
	v_mfma_f32_16x16x32_bf16 v[92:95], v[152:155], v[184:187], v[92:95]
	v_mfma_f32_16x16x32_bf16 v[88:91], v[160:163], v[184:187], v[88:91]
	s_waitcnt lgkmcnt(1)
	v_mfma_f32_16x16x32_bf16 v[76:79], v[152:155], v[192:195], v[76:79]
	v_mfma_f32_16x16x32_bf16 v[72:75], v[160:163], v[192:195], v[72:75]
	v_mfma_f32_16x16x32_bf16 v[124:127], v[156:159], v[172:175], v[124:127]
	v_mfma_f32_16x16x32_bf16 v[120:123], v[164:167], v[172:175], v[120:123]
	v_mfma_f32_16x16x32_bf16 v[108:111], v[156:159], v[180:183], v[108:111]
	v_mfma_f32_16x16x32_bf16 v[104:107], v[164:167], v[180:183], v[104:107]
	v_mfma_f32_16x16x32_bf16 v[92:95], v[156:159], v[188:191], v[92:95]
	v_mfma_f32_16x16x32_bf16 v[88:91], v[164:167], v[188:191], v[88:91]
	s_waitcnt lgkmcnt(0)
	v_mfma_f32_16x16x32_bf16 v[76:79], v[156:159], v[198:201], v[76:79]
	v_mfma_f32_16x16x32_bf16 v[72:75], v[164:167], v[198:201], v[72:75]
	s_barrier
	s_setprio 0
	s_add_i32 s3, s35, s22
	v_lshl_add_u64 v[144:145], s[12:13], 0, v[132:133]
	s_mov_b32 m0, s3
	ds_read_b128 v[202:205], v151
	ds_read_b128 v[206:209], v151 offset:1024
	ds_read_b128 v[210:213], v151 offset:2048
	ds_read_b128 v[214:217], v151 offset:3072
	global_load_lds_dwordx4 v[144:145], off
	v_lshl_add_u64 v[218:219], s[12:13], 0, v[128:129]
	s_add_i32 m0, s3, 0x2000
	s_nop 0
	global_load_lds_dwordx4 v[218:219], off
	s_setprio 1
	s_barrier
	s_waitcnt lgkmcnt(3)
	v_mfma_f32_16x16x32_bf16 v[116:119], v[202:205], v[168:171], v[116:119]
	s_waitcnt lgkmcnt(1)
	v_mfma_f32_16x16x32_bf16 v[112:115], v[210:213], v[168:171], v[112:115]
	v_mfma_f32_16x16x32_bf16 v[100:103], v[202:205], v[176:179], v[100:103]
	v_mfma_f32_16x16x32_bf16 v[96:99], v[210:213], v[176:179], v[96:99]
	v_mfma_f32_16x16x32_bf16 v[84:87], v[202:205], v[184:187], v[84:87]
	v_mfma_f32_16x16x32_bf16 v[80:83], v[210:213], v[184:187], v[80:83]
	v_mfma_f32_16x16x32_bf16 v[68:71], v[202:205], v[192:195], v[68:71]
	v_mfma_f32_16x16x32_bf16 v[64:67], v[210:213], v[192:195], v[64:67]
	v_mfma_f32_16x16x32_bf16 v[116:119], v[206:209], v[172:175], v[116:119]
	s_mov_b32 m0, s24
	s_waitcnt lgkmcnt(0)
	v_mfma_f32_16x16x32_bf16 v[112:115], v[214:217], v[172:175], v[112:115]
	v_lshl_add_u64 v[220:221], s[14:15], 0, v[134:135]
	v_mfma_f32_16x16x32_bf16 v[100:103], v[206:209], v[180:183], v[100:103]
	v_mfma_f32_16x16x32_bf16 v[96:99], v[214:217], v[180:183], v[96:99]
	v_mfma_f32_16x16x32_bf16 v[84:87], v[206:209], v[188:191], v[84:87]
	v_mfma_f32_16x16x32_bf16 v[80:83], v[214:217], v[188:191], v[80:83]
	v_mfma_f32_16x16x32_bf16 v[68:71], v[206:209], v[198:201], v[68:71]
	v_mfma_f32_16x16x32_bf16 v[64:67], v[214:217], v[198:201], v[64:67]
	s_barrier
	s_setprio 0
	ds_read_b128 v[168:171], v150 offset:16384
	ds_read_b128 v[172:175], v150 offset:17408
	ds_read_b128 v[176:179], v150 offset:18432
	ds_read_b128 v[180:183], v150 offset:19456
	ds_read_b128 v[184:187], v150 offset:20480
	ds_read_b128 v[188:191], v150 offset:21504
	ds_read_b128 v[192:195], v150 offset:22528
	ds_read_b128 v[198:201], v150 offset:23552
	global_load_lds_dwordx4 v[220:221], off
	v_lshl_add_u64 v[222:223], s[14:15], 0, v[130:131]
	s_mov_b32 m0, s9
	s_nop 0
	global_load_lds_dwordx4 v[222:223], off
	s_waitcnt vmcnt(10)
	s_setprio 1
	s_barrier
	s_waitcnt lgkmcnt(7)
	v_mfma_f32_16x16x32_bf16 v[60:63], v[152:155], v[168:171], v[60:63]
	v_mfma_f32_16x16x32_bf16 v[56:59], v[160:163], v[168:171], v[56:59]
	s_waitcnt lgkmcnt(5)
	v_mfma_f32_16x16x32_bf16 v[44:47], v[152:155], v[176:179], v[44:47]
	v_mfma_f32_16x16x32_bf16 v[40:43], v[160:163], v[176:179], v[40:43]
	s_waitcnt lgkmcnt(3)
	v_mfma_f32_16x16x32_bf16 v[28:31], v[152:155], v[184:187], v[28:31]
	v_mfma_f32_16x16x32_bf16 v[24:27], v[160:163], v[184:187], v[24:27]
	s_waitcnt lgkmcnt(1)
	v_mfma_f32_16x16x32_bf16 v[12:15], v[152:155], v[192:195], v[12:15]
	v_mfma_f32_16x16x32_bf16 v[8:11], v[160:163], v[192:195], v[8:11]
	v_mfma_f32_16x16x32_bf16 v[60:63], v[156:159], v[172:175], v[60:63]
	v_mfma_f32_16x16x32_bf16 v[56:59], v[164:167], v[172:175], v[56:59]
	v_mfma_f32_16x16x32_bf16 v[44:47], v[156:159], v[180:183], v[44:47]
	v_mfma_f32_16x16x32_bf16 v[40:43], v[164:167], v[180:183], v[40:43]
	v_mfma_f32_16x16x32_bf16 v[28:31], v[156:159], v[188:191], v[28:31]
	v_mfma_f32_16x16x32_bf16 v[24:27], v[164:167], v[188:191], v[24:27]
	s_waitcnt lgkmcnt(0)
	v_mfma_f32_16x16x32_bf16 v[12:15], v[156:159], v[198:201], v[12:15]
	v_mfma_f32_16x16x32_bf16 v[8:11], v[164:167], v[198:201], v[8:11]
	s_barrier
; #define PG8_STAGE(bufoff, gbase, voff) do { _Pragma("unroll") for (int _i = 0; _i < 2; ++_i) \
;         __builtin_amdgcn_global_load_lds((const unsigned*)((const char*)(gbase) + (voff)[_i]), (LAS unsigned*)(lds + (bufoff) + ldsw + _i * 8192), 16, 0, 0); } while (0)
; #define PG8_LDA(dst, b, h) do { _Pragma("unroll") for (int m = 0; m < 4; ++m) _Pragma("unroll") for (int k = 0; k < 2; ++k) dst[m][k] = *(const LAS bf16x8*)(lds + PG8_SA(b, h) + aoff + m * 2048 + k * 1024); } while (0)
; #define PG8_LDB(dst, b, h) do { _Pragma("unroll") for (int n = 0; n < 2; ++n) _Pragma("unroll") for (int k = 0; k < 2; ++k) dst[n][k] = *(const LAS bf16x8*)(lds + PG8_SB(b, h) + boff + n * 2048 + k * 1024); } while (0)
; #define PG8_MMA(ai, bj, At, Bt) do { __builtin_amdgcn_s_setprio(1); _Pragma("unroll") for (int m = 0; m < 4; ++m) _Pragma("unroll") for (int n = 0; n < 2; ++n) _Pragma("unroll") for (int k = 0; k < 2; ++k) \
;         acc[ai][bj][m][n] = __builtin_amdgcn_mfma_f32_16x16x32_bf16(Bt[n][k], At[m][k], acc[ai][bj][m][n], 0, 0, 0); __builtin_amdgcn_s_setprio(0); } while (0)
; #define PG8_WAIT_V(n) asm volatile("s_waitcnt vmcnt(" #n ")" ::: "memory")
; #define PG8_WAIT_L(n) asm volatile("s_waitcnt lgkmcnt(" #n ")" ::: "memory")
; #define PG8_BAR __builtin_amdgcn_s_barrier()
; #define PG8_SCHED __builtin_amdgcn_sched_barrier(0)
; template <class Map, class Epi>
; DI void gemm_phase(LAS unsigned char* lds, const Map& MP, const Epi& E, const int nM, const int nN, const int K, const int lda, const int ldb) {
;     ...
;             PG8_BAR; PG8_WAIT_L(0); PG8_MMA(1, 0, At, B0); PG8_BAR; PG8_SCHED;
;             PG8_STAGE(PG8_SB(0, 1), b2 + hstepB, voffB);
;             PG8_WAIT_V(6); PG8_BAR; PG8_MMA(1, 1, At, B1); PG8_BAR;
;             PG8_LDB(B0, 1, 0); PG8_SCHED; PG8_LDA(At, 1, 0); PG8_STAGE(PG8_SA(0, 1), a2 + hstepA, voffA);
;             PG8_WAIT_L(8); PG8_BAR; PG8_WAIT_L(0); PG8_MMA(0, 0, At, B0); PG8_BAR; PG8_SCHED;
;             PG8_LDB(B1, 1, 1); PG8_STAGE(PG8_SB(1, 0), b3, voffB);
;             PG8_BAR; PG8_WAIT_L(0); PG8_MMA(0, 1, At, B1); PG8_BAR;
;             PG8_LDA(At, 1, 1); PG8_STAGE(PG8_SA(1, 0), a3, voffA);
;             PG8_BAR; PG8_WAIT_L(0); PG8_MMA(1, 0, At, B0); PG8_BAR; PG8_SCHED;
;             PG8_STAGE(PG8_SB(1, 1), b3 + hstepB, voffB);
	s_setprio 0
	s_add_u32 s56, s12, 0x80000
	s_addc_u32 s57, s13, 0
	s_add_i32 s3, s36, s22
	s_mov_b32 m0, s3
	s_nop 0
	global_load_lds_dwordx4 v132, s[56:57]
	s_add_i32 m0, s3, 0x2000
	s_nop 0
	global_load_lds_dwordx4 v128, s[56:57]
	s_waitcnt vmcnt(6)
	s_setprio 1
	s_barrier
	v_mfma_f32_16x16x32_bf16 v[52:55], v[202:205], v[168:171], v[52:55]
	v_mfma_f32_16x16x32_bf16 v[48:51], v[210:213], v[168:171], v[48:51]
	s_add_i32 s3, 0, 0x18000
	v_add_u32_e32 v164, s3, v148
	ds_read_b128 v[152:155], v164
	v_mfma_f32_16x16x32_bf16 v[36:39], v[202:205], v[176:179], v[36:39]
	v_mfma_f32_16x16x32_bf16 v[32:35], v[210:213], v[176:179], v[32:35]
	ds_read_b128 v[156:159], v164 offset:1024
	v_mfma_f32_16x16x32_bf16 v[20:23], v[202:205], v[184:187], v[20:23]
	v_mfma_f32_16x16x32_bf16 v[16:19], v[210:213], v[184:187], v[16:19]
	ds_read_b128 v[160:163], v164 offset:2048
	v_mfma_f32_16x16x32_bf16 v[4:7], v[202:205], v[192:195], v[4:7]
	v_mfma_f32_16x16x32_bf16 v[0:3], v[210:213], v[192:195], v[0:3]
	ds_read_b128 v[164:167], v164 offset:3072
	v_mfma_f32_16x16x32_bf16 v[52:55], v[206:209], v[172:175], v[52:55]
	v_mfma_f32_16x16x32_bf16 v[48:51], v[214:217], v[172:175], v[48:51]
	v_mfma_f32_16x16x32_bf16 v[36:39], v[206:209], v[180:183], v[36:39]
	v_mfma_f32_16x16x32_bf16 v[32:35], v[214:217], v[180:183], v[32:35]
	v_mfma_f32_16x16x32_bf16 v[20:23], v[206:209], v[188:191], v[20:23]
	v_mfma_f32_16x16x32_bf16 v[16:19], v[214:217], v[188:191], v[16:19]
	v_mfma_f32_16x16x32_bf16 v[4:7], v[206:209], v[198:201], v[4:7]
	v_mfma_f32_16x16x32_bf16 v[0:3], v[214:217], v[198:201], v[0:3]
	s_barrier
	s_setprio 0
	s_add_u32 s14, s14, 0x80000
	s_addc_u32 s15, s15, 0
	s_mov_b32 m0, s25
	ds_read_b128 v[168:171], v150 offset:32768
	ds_read_b128 v[172:175], v150 offset:33792
	ds_read_b128 v[176:179], v150 offset:34816
	ds_read_b128 v[180:183], v150 offset:35840
	ds_read_b128 v[184:187], v150 offset:36864
	ds_read_b128 v[188:191], v150 offset:37888
	ds_read_b128 v[192:195], v150 offset:38912
	ds_read_b128 v[198:201], v150 offset:39936
	global_load_lds_dwordx4 v134, s[14:15]
	s_mov_b32 m0, s26
	s_nop 0
	global_load_lds_dwordx4 v130, s[14:15]
	s_waitcnt lgkmcnt(8)
	s_setprio 1
	s_barrier
	s_waitcnt lgkmcnt(7)
	v_mfma_f32_16x16x32_bf16 v[124:127], v[152:155], v[168:171], v[124:127]
	v_mfma_f32_16x16x32_bf16 v[120:123], v[160:163], v[168:171], v[120:123]
	s_waitcnt lgkmcnt(5)
	v_mfma_f32_16x16x32_bf16 v[108:111], v[152:155], v[176:179], v[108:111]
	v_mfma_f32_16x16x32_bf16 v[104:107], v[160:163], v[176:179], v[104:107]
	s_waitcnt lgkmcnt(3)
	v_mfma_f32_16x16x32_bf16 v[92:95], v[152:155], v[184:187], v[92:95]
	v_mfma_f32_16x16x32_bf16 v[88:91], v[160:163], v[184:187], v[88:91]
	s_waitcnt lgkmcnt(1)
	v_mfma_f32_16x16x32_bf16 v[76:79], v[152:155], v[192:195], v[76:79]
	v_mfma_f32_16x16x32_bf16 v[72:75], v[160:163], v[192:195], v[72:75]
	v_mfma_f32_16x16x32_bf16 v[124:127], v[156:159], v[172:175], v[124:127]
	v_mfma_f32_16x16x32_bf16 v[120:123], v[164:167], v[172:175], v[120:123]
	v_mfma_f32_16x16x32_bf16 v[108:111], v[156:159], v[180:183], v[108:111]
	v_mfma_f32_16x16x32_bf16 v[104:107], v[164:167], v[180:183], v[104:107]
	v_mfma_f32_16x16x32_bf16 v[92:95], v[156:159], v[188:191], v[92:95]
	v_mfma_f32_16x16x32_bf16 v[88:91], v[164:167], v[188:191], v[88:91]
	s_waitcnt lgkmcnt(0)
	v_mfma_f32_16x16x32_bf16 v[76:79], v[156:159], v[198:201], v[76:79]
	v_mfma_f32_16x16x32_bf16 v[72:75], v[164:167], v[198:201], v[72:75]
	s_barrier
	s_setprio 0
	s_add_i32 s14, 0, 0x1c000
	s_add_i32 s3, s3, s22
	v_add_u32_e32 v196, s14, v148
	v_lshl_add_u64 v[144:145], v[144:145], 0, s[44:45]
	s_mov_b32 m0, s3
	ds_read_b128 v[202:205], v196
	ds_read_b128 v[206:209], v196 offset:1024
	ds_read_b128 v[210:213], v196 offset:2048
	ds_read_b128 v[214:217], v196 offset:3072
	global_load_lds_dwordx4 v[144:145], off
	v_lshl_add_u64 v[144:145], v[218:219], 0, s[44:45]
	s_add_i32 m0, s3, 0x2000
	s_nop 0
	global_load_lds_dwordx4 v[144:145], off
	s_setprio 1
	s_barrier
	s_waitcnt lgkmcnt(3)
	v_mfma_f32_16x16x32_bf16 v[116:119], v[202:205], v[168:171], v[116:119]
	s_waitcnt lgkmcnt(1)
	v_mfma_f32_16x16x32_bf16 v[112:115], v[210:213], v[168:171], v[112:115]
	v_mfma_f32_16x16x32_bf16 v[100:103], v[202:205], v[176:179], v[100:103]
	v_mfma_f32_16x16x32_bf16 v[96:99], v[210:213], v[176:179], v[96:99]
	v_mfma_f32_16x16x32_bf16 v[84:87], v[202:205], v[184:187], v[84:87]
	v_mfma_f32_16x16x32_bf16 v[80:83], v[210:213], v[184:187], v[80:83]
	v_mfma_f32_16x16x32_bf16 v[68:71], v[202:205], v[192:195], v[68:71]
	v_mfma_f32_16x16x32_bf16 v[64:67], v[210:213], v[192:195], v[64:67]
	v_mfma_f32_16x16x32_bf16 v[116:119], v[206:209], v[172:175], v[116:119]
	s_mov_b32 m0, s30
	s_waitcnt lgkmcnt(0)
	v_mfma_f32_16x16x32_bf16 v[112:115], v[214:217], v[172:175], v[112:115]
	v_lshl_add_u64 v[144:145], v[220:221], 0, s[44:45]
	v_mfma_f32_16x16x32_bf16 v[100:103], v[206:209], v[180:183], v[100:103]
	v_mfma_f32_16x16x32_bf16 v[96:99], v[214:217], v[180:183], v[96:99]
	v_mfma_f32_16x16x32_bf16 v[84:87], v[206:209], v[188:191], v[84:87]
	v_mfma_f32_16x16x32_bf16 v[80:83], v[214:217], v[188:191], v[80:83]
	v_mfma_f32_16x16x32_bf16 v[68:71], v[206:209], v[198:201], v[68:71]
	v_mfma_f32_16x16x32_bf16 v[64:67], v[214:217], v[198:201], v[64:67]
	s_barrier
	s_setprio 0
	ds_read_b128 v[168:171], v150 offset:49152
	ds_read_b128 v[172:175], v150 offset:50176
	ds_read_b128 v[176:179], v150 offset:51200
	ds_read_b128 v[180:183], v150 offset:52224
	ds_read_b128 v[184:187], v150 offset:53248
	ds_read_b128 v[188:191], v150 offset:54272
	ds_read_b128 v[192:195], v150 offset:55296
	ds_read_b128 v[198:201], v150 offset:56320
	global_load_lds_dwordx4 v[144:145], off
	v_lshl_add_u64 v[144:145], v[222:223], 0, s[44:45]
	s_mov_b32 m0, s31
	s_nop 0
	global_load_lds_dwordx4 v[144:145], off
	s_waitcnt vmcnt(10)
	s_setprio 1
	s_barrier
; DI float bflo(unsigned w) { return __uint_as_float(w << 16); }
; DI float bfhi(unsigned w) { return __uint_as_float(w & 0xffff0000u); }
;     DI void operator()(const f32x4 (&acc)[2][2][4][2], const Unit& u, int wr, int wc, int fr, int fq) const {
;     ...
;         for (int ai = 0; ai < 2; ++ai)
; #pragma unroll
;             for (int m = 0; m < 4; ++m) { const size_t ro = (size_t)(row0 + ai * HALF + m * 16) * D + col0;
; #pragma unroll
;                 for (int bj = 0; bj < 2; ++bj) {
;                     f32x4 x0, x1;
;                     if constexpr (IB) { const u32x4 w = *(const u32x4*)((const bf16_t*)Xin + ro + bj * HALF);
;                         x0 = (f32x4){bflo(w[0]), bfhi(w[0]), bflo(w[1]), bfhi(w[1])}; x1 = (f32x4){bflo(w[2]), bfhi(w[2]), bflo(w[3]), bfhi(w[3])}; }
;                     else { x0 = *(const f32x4*)((const float*)Xin + ro + bj * HALF); x1 = *(const f32x4*)((const float*)Xin + ro + bj * HALF + 4); }
;                     x0 += acc[ai][bj][m][0] * sc[bj][0]; x1 += acc[ai][bj][m][1] * sc[bj][1];
;                     if constexpr (OB) { u32x4 o; o[0] = pack2(x0[0], x0[1]); o[1] = pack2(x0[2], x0[3]); o[2] = pack2(x1[0], x1[1]); o[3] = pack2(x1[2], x1[3]);
;                         *(u32x4*)((bf16_t*)Xout + ro + bj * HALF) = o; }
;                     else { *(f32x4*)((float*)Xout + ro + bj * HALF) = x0; *(f32x4*)((float*)Xout + ro + bj * HALF + 4) = x1; } } }
; template <class Map, class Epi>
; DI void gemm_phase(LAS unsigned char* lds, const Map& MP, const Epi& E, const int nM, const int nN, const int K, const int lda, const int ldb) {
;     ...
;             PG8_WAIT_V(6); PG8_BAR; PG8_MMA(1, 1, At, B1); PG8_BAR;
;             PG8_LDB(B0, 1, 0); PG8_SCHED; PG8_LDA(At, 1, 0); PG8_STAGE(PG8_SA(0, 1), a2 + hstepA, voffA);
;             PG8_WAIT_L(8); PG8_BAR; PG8_WAIT_L(0); PG8_MMA(0, 0, At, B0); PG8_BAR; PG8_SCHED;
;             PG8_LDB(B1, 1, 1); PG8_STAGE(PG8_SB(1, 0), b3, voffB);
;             PG8_BAR; PG8_WAIT_L(0); PG8_MMA(0, 1, At, B1); PG8_BAR;
;             PG8_LDA(At, 1, 1); PG8_STAGE(PG8_SA(1, 0), a3, voffA);
;             PG8_BAR; PG8_WAIT_L(0); PG8_MMA(1, 0, At, B0); PG8_BAR; PG8_SCHED;
;             PG8_STAGE(PG8_SB(1, 1), b3 + hstepB, voffB);
;             PG8_WAIT_V(6); PG8_BAR; PG8_MMA(1, 1, At, B1); PG8_BAR;
;         }
;         { int frr = fr, fqq = fq; asm volatile("" : "+v"(frr), "+v"(fqq)); E(acc, cur, wr, wc, frr, fqq); }
	s_waitcnt lgkmcnt(7)
	v_mfma_f32_16x16x32_bf16 v[60:63], v[152:155], v[168:171], v[60:63]
	v_mfma_f32_16x16x32_bf16 v[56:59], v[160:163], v[168:171], v[56:59]
	s_waitcnt lgkmcnt(5)
	v_mfma_f32_16x16x32_bf16 v[44:47], v[152:155], v[176:179], v[44:47]
	v_mfma_f32_16x16x32_bf16 v[40:43], v[160:163], v[176:179], v[40:43]
	s_waitcnt lgkmcnt(3)
	v_mfma_f32_16x16x32_bf16 v[28:31], v[152:155], v[184:187], v[28:31]
	v_mfma_f32_16x16x32_bf16 v[24:27], v[160:163], v[184:187], v[24:27]
	s_waitcnt lgkmcnt(1)
	v_mfma_f32_16x16x32_bf16 v[12:15], v[152:155], v[192:195], v[12:15]
	v_mfma_f32_16x16x32_bf16 v[8:11], v[160:163], v[192:195], v[8:11]
	v_mfma_f32_16x16x32_bf16 v[60:63], v[156:159], v[172:175], v[60:63]
	v_mfma_f32_16x16x32_bf16 v[56:59], v[164:167], v[172:175], v[56:59]
	v_mfma_f32_16x16x32_bf16 v[44:47], v[156:159], v[180:183], v[44:47]
	v_mfma_f32_16x16x32_bf16 v[40:43], v[164:167], v[180:183], v[40:43]
	v_mfma_f32_16x16x32_bf16 v[28:31], v[156:159], v[188:191], v[28:31]
	v_mfma_f32_16x16x32_bf16 v[24:27], v[164:167], v[188:191], v[24:27]
	s_waitcnt lgkmcnt(0)
	v_mfma_f32_16x16x32_bf16 v[12:15], v[156:159], v[198:201], v[12:15]
	v_mfma_f32_16x16x32_bf16 v[8:11], v[164:167], v[198:201], v[8:11]
	s_barrier
	s_setprio 0
	s_add_u32 s12, s12, 0x80080
	s_addc_u32 s13, s13, 0
	s_add_i32 s3, s14, s22
	s_mov_b32 m0, s3
	s_nop 0
	global_load_lds_dwordx4 v132, s[12:13]
	s_add_i32 m0, s3, 0x2000
	s_nop 0
	global_load_lds_dwordx4 v128, s[12:13]
	s_waitcnt vmcnt(6)
	s_setprio 1
	s_barrier
	v_mfma_f32_16x16x32_bf16 v[52:55], v[202:205], v[168:171], v[52:55]
	v_mfma_f32_16x16x32_bf16 v[48:51], v[210:213], v[168:171], v[48:51]
	ds_read_b128 v[152:155], v149
	v_mfma_f32_16x16x32_bf16 v[36:39], v[202:205], v[176:179], v[36:39]
	v_mfma_f32_16x16x32_bf16 v[32:35], v[210:213], v[176:179], v[32:35]
	ds_read_b128 v[156:159], v149 offset:1024
	v_mfma_f32_16x16x32_bf16 v[20:23], v[202:205], v[184:187], v[20:23]
	v_mfma_f32_16x16x32_bf16 v[16:19], v[210:213], v[184:187], v[16:19]
	ds_read_b128 v[160:163], v149 offset:2048
	v_mfma_f32_16x16x32_bf16 v[4:7], v[202:205], v[192:195], v[4:7]
	v_mfma_f32_16x16x32_bf16 v[0:3], v[210:213], v[192:195], v[0:3]
	ds_read_b128 v[164:167], v149 offset:3072
	v_mfma_f32_16x16x32_bf16 v[52:55], v[206:209], v[172:175], v[52:55]
	s_add_i32 s48, s48, 2
	v_mfma_f32_16x16x32_bf16 v[48:51], v[214:217], v[172:175], v[48:51]
	s_add_u32 s39, s39, 0x100
	s_addc_u32 s47, s47, 0
	v_mfma_f32_16x16x32_bf16 v[36:39], v[206:209], v[180:183], v[36:39]
	s_add_u32 s10, s10, 0x100
	s_addc_u32 s11, s11, 0
	v_mfma_f32_16x16x32_bf16 v[32:35], v[214:217], v[180:183], v[32:35]
	s_cmp_gt_u32 s48, 29
	v_mfma_f32_16x16x32_bf16 v[20:23], v[206:209], v[188:191], v[20:23]
	v_mfma_f32_16x16x32_bf16 v[16:19], v[214:217], v[188:191], v[16:19]
	v_mfma_f32_16x16x32_bf16 v[4:7], v[206:209], v[198:201], v[4:7]
	v_mfma_f32_16x16x32_bf16 v[0:3], v[214:217], v[198:201], v[0:3]
	s_barrier
	s_setprio 0
	s_cbranch_scc0 .LBB1_925
	s_waitcnt lgkmcnt(0)
	v_mov_b32_e32 v152, v147
	v_mov_b32_e32 v144, v146
	s_lshl_b32 s2, s2, 8
	s_or_b32 s2, s2, s29
	v_lshl_add_u32 v144, v144, 3, s2
	s_lshl_b32 s2, s8, 8
	s_add_i32 s2, s2, s28
	v_add_u32_e32 v152, s2, v152
	v_ashrrev_i32_e32 v153, 31, v152
	v_lshlrev_b64 v[152:153], 12, v[152:153]
	v_ashrrev_i32_e32 v145, 31, v144
	v_lshl_add_u64 v[152:153], s[42:43], 0, v[152:153]
	v_lshl_add_u64 v[144:145], v[144:145], 1, v[152:153]
	global_load_dwordx4 v[160:163], v[144:145], off
	global_load_dwordx4 v[164:167], v[144:145], off offset:256
	s_mov_b64 s[98:99], 0x10000
	v_lshl_add_u64 v[154:155], v[144:145], 0, s[98:99]
	global_load_dwordx4 v[168:171], v[154:155], off
	global_load_dwordx4 v[172:175], v[154:155], off offset:256
	s_mov_b64 s[98:99], 0x20000
	v_lshl_add_u64 v[154:155], v[144:145], 0, s[98:99]
	global_load_dwordx4 v[176:179], v[154:155], off
	global_load_dwordx4 v[180:183], v[154:155], off offset:256
	s_mov_b64 s[98:99], 0x30000
	v_lshl_add_u64 v[154:155], v[144:145], 0, s[98:99]
	global_load_dwordx4 v[184:187], v[154:155], off
	global_load_dwordx4 v[188:191], v[154:155], off offset:256
	s_mov_b64 s[98:99], 0x80000
	v_lshl_add_u64 v[154:155], v[144:145], 0, s[98:99]
	global_load_dwordx4 v[192:195], v[154:155], off
	global_load_dwordx4 v[198:201], v[154:155], off offset:256
	s_mov_b64 s[98:99], 0x90000
	v_lshl_add_u64 v[154:155], v[144:145], 0, s[98:99]
	global_load_dwordx4 v[202:205], v[154:155], off
	global_load_dwordx4 v[206:209], v[154:155], off offset:256
	s_mov_b64 s[98:99], 0xa0000
	v_lshl_add_u64 v[154:155], v[144:145], 0, s[98:99]
	global_load_dwordx4 v[210:213], v[154:155], off
	global_load_dwordx4 v[214:217], v[154:155], off offset:256
	s_mov_b64 s[98:99], 0xb0000
	v_lshl_add_u64 v[154:155], v[144:145], 0, s[98:99]
	global_load_dwordx4 v[248:251], v[154:155], off
	global_load_dwordx4 v[252:255], v[154:155], off offset:256
	s_waitcnt vmcnt(15)
	s_nop 1
	v_mov_b32_e32 v152, v160
	v_mov_b32_e32 v153, v161
	v_mov_b32_e32 v154, v162
	v_mov_b32_e32 v155, v163
	s_mov_b64 s[2:3], 0x10000
	s_mov_b32 s8, s52
	s_mov_b64 s[10:11], s[6:7]
	s_mov_b64 s[12:13], s[54:55]
	s_waitcnt lgkmcnt(0)
	v_lshlrev_b32_e32 v156, 16, v152
	v_and_b32_e32 v157, 0xffff0000, v152
	v_lshlrev_b32_e32 v152, 16, v153
	v_and_b32_e32 v153, 0xffff0000, v153
	v_lshlrev_b32_e32 v158, 16, v154
	v_and_b32_e32 v159, 0xffff0000, v154
	v_lshlrev_b32_e32 v154, 16, v155
	v_and_b32_e32 v155, 0xffff0000, v155
	v_pk_add_f32 v[126:127], v[126:127], v[152:153]
	v_pk_add_f32 v[124:125], v[124:125], v[156:157]
	v_pk_add_f32 v[152:153], v[122:123], v[154:155]
	v_pk_add_f32 v[122:123], v[120:121], v[158:159]
	v_cvt_pk_bf16_f32 v120, v124, v125
	v_cvt_pk_bf16_f32 v121, v126, v127
	v_cvt_pk_bf16_f32 v122, v122, v123
	v_cvt_pk_bf16_f32 v123, v152, v153
	global_store_dwordx4 v[144:145], v[120:123], off
	s_waitcnt vmcnt(15)
; DI unsigned pack2(float a, float b) { f32x2 v = {a, b}; hwbf16x2 r = __builtin_convertvector(v, hwbf16x2); return __builtin_bit_cast(unsigned, r); }
; DI float bflo(unsigned w) { return __uint_as_float(w << 16); }
; DI float bfhi(unsigned w) { return __uint_as_float(w & 0xffff0000u); }
;     DI void operator()(const f32x4 (&acc)[2][2][4][2], const Unit& u, int wr, int wc, int fr, int fq) const {
;     ...
;         for (int ai = 0; ai < 2; ++ai)
; #pragma unroll
;             for (int m = 0; m < 4; ++m) { const size_t ro = (size_t)(row0 + ai * HALF + m * 16) * D + col0;
; #pragma unroll
;                 for (int bj = 0; bj < 2; ++bj) {
;                     f32x4 x0, x1;
;                     if constexpr (IB) { const u32x4 w = *(const u32x4*)((const bf16_t*)Xin + ro + bj * HALF);
;                         x0 = (f32x4){bflo(w[0]), bfhi(w[0]), bflo(w[1]), bfhi(w[1])}; x1 = (f32x4){bflo(w[2]), bfhi(w[2]), bflo(w[3]), bfhi(w[3])}; }
;                     else { x0 = *(const f32x4*)((const float*)Xin + ro + bj * HALF); x1 = *(const f32x4*)((const float*)Xin + ro + bj * HALF + 4); }
;                     x0 += acc[ai][bj][m][0] * sc[bj][0]; x1 += acc[ai][bj][m][1] * sc[bj][1];
;                     if constexpr (OB) { u32x4 o; o[0] = pack2(x0[0], x0[1]); o[1] = pack2(x0[2], x0[3]); o[2] = pack2(x1[0], x1[1]); o[3] = pack2(x1[2], x1[3]);
;                         *(u32x4*)((bf16_t*)Xout + ro + bj * HALF) = o; }
;                     else { *(f32x4*)((float*)Xout + ro + bj * HALF) = x0; *(f32x4*)((float*)Xout + ro + bj * HALF + 4) = x1; } } }
	s_nop 1
	v_mov_b32_e32 v120, v164
	v_mov_b32_e32 v121, v165
	v_mov_b32_e32 v122, v166
	v_mov_b32_e32 v123, v167
	s_waitcnt lgkmcnt(0)
	v_lshlrev_b32_e32 v124, 16, v120
	v_and_b32_e32 v125, 0xffff0000, v120
	v_lshlrev_b32_e32 v120, 16, v121
	v_and_b32_e32 v121, 0xffff0000, v121
	v_lshlrev_b32_e32 v126, 16, v122
	v_and_b32_e32 v127, 0xffff0000, v122
	v_lshlrev_b32_e32 v122, 16, v123
	v_and_b32_e32 v123, 0xffff0000, v123
	v_pk_add_f32 v[116:117], v[116:117], v[124:125]
	v_pk_add_f32 v[118:119], v[118:119], v[120:121]
	v_pk_add_f32 v[120:121], v[114:115], v[122:123]
	v_pk_add_f32 v[114:115], v[112:113], v[126:127]
	v_cvt_pk_bf16_f32 v112, v116, v117
	v_lshl_add_u64 v[116:117], v[144:145], 0, s[2:3]
	s_mov_b32 s2, 0x10000
	v_cvt_pk_bf16_f32 v113, v118, v119
	v_add_co_u32_e32 v118, vcc, s2, v144
	v_cvt_pk_bf16_f32 v114, v114, v115
	v_cvt_pk_bf16_f32 v115, v120, v121
	v_addc_co_u32_e32 v119, vcc, 0, v145, vcc
	global_store_dwordx4 v[144:145], v[112:115], off offset:256
	s_waitcnt vmcnt(15)
	s_nop 1
	v_mov_b32_e32 v112, v168
	v_mov_b32_e32 v113, v169
	v_mov_b32_e32 v114, v170
	v_mov_b32_e32 v115, v171
	s_mov_b64 s[2:3], 0x20000
	s_waitcnt lgkmcnt(0)
	v_lshlrev_b32_e32 v120, 16, v112
	v_and_b32_e32 v121, 0xffff0000, v112
	v_lshlrev_b32_e32 v112, 16, v113
	v_and_b32_e32 v113, 0xffff0000, v113
	v_lshlrev_b32_e32 v122, 16, v114
	v_and_b32_e32 v123, 0xffff0000, v114
	v_lshlrev_b32_e32 v114, 16, v115
	v_and_b32_e32 v115, 0xffff0000, v115
	v_pk_add_f32 v[110:111], v[110:111], v[112:113]
	v_pk_add_f32 v[108:109], v[108:109], v[120:121]
	v_pk_add_f32 v[112:113], v[106:107], v[114:115]
	v_pk_add_f32 v[106:107], v[104:105], v[122:123]
	v_cvt_pk_bf16_f32 v104, v108, v109
	v_cvt_pk_bf16_f32 v105, v110, v111
	v_cvt_pk_bf16_f32 v106, v106, v107
	v_cvt_pk_bf16_f32 v107, v112, v113
	global_store_dwordx4 v[118:119], v[104:107], off
	s_waitcnt vmcnt(15)
	s_nop 1
	v_mov_b32_e32 v104, v172
	v_mov_b32_e32 v105, v173
	v_mov_b32_e32 v106, v174
	v_mov_b32_e32 v107, v175
	s_waitcnt lgkmcnt(0)
	v_lshlrev_b32_e32 v108, 16, v104
	v_and_b32_e32 v109, 0xffff0000, v104
	v_lshlrev_b32_e32 v104, 16, v105
	v_and_b32_e32 v105, 0xffff0000, v105
	v_lshlrev_b32_e32 v110, 16, v106
	v_and_b32_e32 v111, 0xffff0000, v106
	v_lshlrev_b32_e32 v106, 16, v107
	v_and_b32_e32 v107, 0xffff0000, v107
	v_pk_add_f32 v[100:101], v[100:101], v[108:109]
	v_pk_add_f32 v[102:103], v[102:103], v[104:105]
	v_pk_add_f32 v[104:105], v[98:99], v[106:107]
	v_pk_add_f32 v[98:99], v[96:97], v[110:111]
	v_cvt_pk_bf16_f32 v96, v100, v101
	v_lshl_add_u64 v[100:101], v[144:145], 0, s[2:3]
	s_mov_b32 s2, 0x20000
	v_cvt_pk_bf16_f32 v97, v102, v103
	v_add_co_u32_e32 v102, vcc, s2, v144
	v_cvt_pk_bf16_f32 v98, v98, v99
	v_cvt_pk_bf16_f32 v99, v104, v105
	v_addc_co_u32_e32 v103, vcc, 0, v145, vcc
	global_store_dwordx4 v[116:117], v[96:99], off offset:256
	s_waitcnt vmcnt(15)
	s_nop 1
	v_mov_b32_e32 v96, v176
	v_mov_b32_e32 v97, v177
	v_mov_b32_e32 v98, v178
	v_mov_b32_e32 v99, v179
	s_mov_b64 s[2:3], 0x30000
	s_waitcnt lgkmcnt(0)
	v_lshlrev_b32_e32 v104, 16, v96
	v_and_b32_e32 v105, 0xffff0000, v96
	v_lshlrev_b32_e32 v96, 16, v97
	v_and_b32_e32 v97, 0xffff0000, v97
	v_lshlrev_b32_e32 v106, 16, v98
	v_and_b32_e32 v107, 0xffff0000, v98
	v_lshlrev_b32_e32 v98, 16, v99
	v_and_b32_e32 v99, 0xffff0000, v99
	v_pk_add_f32 v[94:95], v[94:95], v[96:97]
	v_pk_add_f32 v[92:93], v[92:93], v[104:105]
	v_pk_add_f32 v[96:97], v[90:91], v[98:99]
	v_pk_add_f32 v[90:91], v[88:89], v[106:107]
	v_cvt_pk_bf16_f32 v88, v92, v93
	v_cvt_pk_bf16_f32 v89, v94, v95
	v_cvt_pk_bf16_f32 v90, v90, v91
	v_cvt_pk_bf16_f32 v91, v96, v97
	global_store_dwordx4 v[102:103], v[88:91], off
	s_waitcnt vmcnt(15)
	s_nop 1
	v_mov_b32_e32 v88, v180
	v_mov_b32_e32 v89, v181
	v_mov_b32_e32 v90, v182
	v_mov_b32_e32 v91, v183
	s_waitcnt lgkmcnt(0)
	v_lshlrev_b32_e32 v92, 16, v88
	v_and_b32_e32 v93, 0xffff0000, v88
	v_lshlrev_b32_e32 v88, 16, v89
	v_and_b32_e32 v89, 0xffff0000, v89
	v_lshlrev_b32_e32 v94, 16, v90
	v_and_b32_e32 v95, 0xffff0000, v90
	v_lshlrev_b32_e32 v90, 16, v91
	v_and_b32_e32 v91, 0xffff0000, v91
	v_pk_add_f32 v[86:87], v[86:87], v[88:89]
	v_pk_add_f32 v[84:85], v[84:85], v[92:93]
	v_pk_add_f32 v[88:89], v[82:83], v[90:91]
	v_pk_add_f32 v[82:83], v[80:81], v[94:95]
	v_cvt_pk_bf16_f32 v80, v84, v85
	v_cvt_pk_bf16_f32 v81, v86, v87
	v_cvt_pk_bf16_f32 v82, v82, v83
	v_cvt_pk_bf16_f32 v83, v88, v89
	global_store_dwordx4 v[100:101], v[80:83], off offset:256
	s_nop 1
	v_lshl_add_u64 v[80:81], v[144:145], 0, s[2:3]
	s_mov_b32 s2, 0x30000
	v_add_co_u32_e32 v86, vcc, s2, v144
	s_mov_b64 s[2:3], 0x80000
	s_nop 0
	v_addc_co_u32_e32 v87, vcc, 0, v145, vcc
	s_waitcnt vmcnt(15)
	s_nop 1
	v_mov_b32_e32 v82, v184
	v_mov_b32_e32 v83, v185
	v_mov_b32_e32 v84, v186
	v_mov_b32_e32 v85, v187
	s_waitcnt lgkmcnt(0)
	v_lshlrev_b32_e32 v88, 16, v82
	v_and_b32_e32 v89, 0xffff0000, v82
	v_lshlrev_b32_e32 v82, 16, v83
	v_and_b32_e32 v83, 0xffff0000, v83
	v_lshlrev_b32_e32 v90, 16, v84
	v_and_b32_e32 v91, 0xffff0000, v84
	v_lshlrev_b32_e32 v84, 16, v85
	v_and_b32_e32 v85, 0xffff0000, v85
	v_pk_add_f32 v[78:79], v[78:79], v[82:83]
	v_pk_add_f32 v[76:77], v[76:77], v[88:89]
	v_pk_add_f32 v[82:83], v[74:75], v[84:85]
	v_pk_add_f32 v[74:75], v[72:73], v[90:91]
	v_cvt_pk_bf16_f32 v72, v76, v77
	v_cvt_pk_bf16_f32 v73, v78, v79
	v_cvt_pk_bf16_f32 v74, v74, v75
	v_cvt_pk_bf16_f32 v75, v82, v83
	global_store_dwordx4 v[86:87], v[72:75], off
	s_waitcnt vmcnt(15)
	s_nop 1
	v_mov_b32_e32 v72, v188
	v_mov_b32_e32 v73, v189
	v_mov_b32_e32 v74, v190
	v_mov_b32_e32 v75, v191
	s_waitcnt lgkmcnt(0)
; DI unsigned pack2(float a, float b) { f32x2 v = {a, b}; hwbf16x2 r = __builtin_convertvector(v, hwbf16x2); return __builtin_bit_cast(unsigned, r); }
; DI float bflo(unsigned w) { return __uint_as_float(w << 16); }
; DI float bfhi(unsigned w) { return __uint_as_float(w & 0xffff0000u); }
;     DI void operator()(const f32x4 (&acc)[2][2][4][2], const Unit& u, int wr, int wc, int fr, int fq) const {
;     ...
;         for (int ai = 0; ai < 2; ++ai)
; #pragma unroll
;             for (int m = 0; m < 4; ++m) { const size_t ro = (size_t)(row0 + ai * HALF + m * 16) * D + col0;
; #pragma unroll
;                 for (int bj = 0; bj < 2; ++bj) {
;                     f32x4 x0, x1;
;                     if constexpr (IB) { const u32x4 w = *(const u32x4*)((const bf16_t*)Xin + ro + bj * HALF);
;                         x0 = (f32x4){bflo(w[0]), bfhi(w[0]), bflo(w[1]), bfhi(w[1])}; x1 = (f32x4){bflo(w[2]), bfhi(w[2]), bflo(w[3]), bfhi(w[3])}; }
;                     else { x0 = *(const f32x4*)((const float*)Xin + ro + bj * HALF); x1 = *(const f32x4*)((const float*)Xin + ro + bj * HALF + 4); }
;                     x0 += acc[ai][bj][m][0] * sc[bj][0]; x1 += acc[ai][bj][m][1] * sc[bj][1];
;                     if constexpr (OB) { u32x4 o; o[0] = pack2(x0[0], x0[1]); o[1] = pack2(x0[2], x0[3]); o[2] = pack2(x1[0], x1[1]); o[3] = pack2(x1[2], x1[3]);
;                         *(u32x4*)((bf16_t*)Xout + ro + bj * HALF) = o; }
;                     else { *(f32x4*)((float*)Xout + ro + bj * HALF) = x0; *(f32x4*)((float*)Xout + ro + bj * HALF + 4) = x1; } } }
	v_lshlrev_b32_e32 v76, 16, v72
	v_and_b32_e32 v77, 0xffff0000, v72
	v_lshlrev_b32_e32 v72, 16, v73
	v_and_b32_e32 v73, 0xffff0000, v73
	v_lshlrev_b32_e32 v78, 16, v74
	v_and_b32_e32 v79, 0xffff0000, v74
	v_lshlrev_b32_e32 v74, 16, v75
	v_and_b32_e32 v75, 0xffff0000, v75
	v_pk_add_f32 v[70:71], v[70:71], v[72:73]
	v_pk_add_f32 v[68:69], v[68:69], v[76:77]
	v_pk_add_f32 v[72:73], v[66:67], v[74:75]
	v_pk_add_f32 v[66:67], v[64:65], v[78:79]
	v_cvt_pk_bf16_f32 v64, v68, v69
	v_cvt_pk_bf16_f32 v65, v70, v71
	v_cvt_pk_bf16_f32 v66, v66, v67
	v_cvt_pk_bf16_f32 v67, v72, v73
	global_store_dwordx4 v[80:81], v[64:67], off offset:256
	s_nop 1
	v_lshl_add_u64 v[64:65], v[144:145], 0, s[2:3]
	s_mov_b32 s2, 0x80000
	v_add_co_u32_e32 v70, vcc, s2, v144
	s_mov_b64 s[2:3], 0x90000
	s_nop 0
	v_addc_co_u32_e32 v71, vcc, 0, v145, vcc
	s_waitcnt vmcnt(15)
	s_nop 1
	v_mov_b32_e32 v66, v192
	v_mov_b32_e32 v67, v193
	v_mov_b32_e32 v68, v194
	v_mov_b32_e32 v69, v195
	s_waitcnt lgkmcnt(0)
	v_lshlrev_b32_e32 v72, 16, v66
	v_and_b32_e32 v73, 0xffff0000, v66
	v_lshlrev_b32_e32 v66, 16, v67
	v_and_b32_e32 v67, 0xffff0000, v67
	v_lshlrev_b32_e32 v74, 16, v68
	v_and_b32_e32 v75, 0xffff0000, v68
	v_lshlrev_b32_e32 v68, 16, v69
	v_and_b32_e32 v69, 0xffff0000, v69
	v_pk_add_f32 v[62:63], v[62:63], v[66:67]
	v_pk_add_f32 v[60:61], v[60:61], v[72:73]
	v_pk_add_f32 v[66:67], v[58:59], v[68:69]
	v_pk_add_f32 v[58:59], v[56:57], v[74:75]
	v_cvt_pk_bf16_f32 v56, v60, v61
	v_cvt_pk_bf16_f32 v57, v62, v63
	v_cvt_pk_bf16_f32 v58, v58, v59
	v_cvt_pk_bf16_f32 v59, v66, v67
	global_store_dwordx4 v[70:71], v[56:59], off
	s_waitcnt vmcnt(15)
	s_nop 1
	v_mov_b32_e32 v56, v198
	v_mov_b32_e32 v57, v199
	v_mov_b32_e32 v58, v200
	v_mov_b32_e32 v59, v201
	s_waitcnt lgkmcnt(0)
	v_lshlrev_b32_e32 v60, 16, v56
	v_and_b32_e32 v61, 0xffff0000, v56
	v_lshlrev_b32_e32 v56, 16, v57
	v_and_b32_e32 v57, 0xffff0000, v57
	v_lshlrev_b32_e32 v62, 16, v58
	v_and_b32_e32 v63, 0xffff0000, v58
	v_lshlrev_b32_e32 v58, 16, v59
	v_and_b32_e32 v59, 0xffff0000, v59
	v_pk_add_f32 v[54:55], v[54:55], v[56:57]
	v_pk_add_f32 v[52:53], v[52:53], v[60:61]
	v_pk_add_f32 v[56:57], v[50:51], v[58:59]
	v_pk_add_f32 v[50:51], v[48:49], v[62:63]
	v_cvt_pk_bf16_f32 v48, v52, v53
	v_cvt_pk_bf16_f32 v49, v54, v55
	v_cvt_pk_bf16_f32 v50, v50, v51
	v_cvt_pk_bf16_f32 v51, v56, v57
	global_store_dwordx4 v[64:65], v[48:51], off offset:256
	s_nop 1
	v_lshl_add_u64 v[48:49], v[144:145], 0, s[2:3]
	s_mov_b32 s2, 0x90000
	v_add_co_u32_e32 v54, vcc, s2, v144
	s_mov_b64 s[2:3], 0xa0000
	s_nop 0
	v_addc_co_u32_e32 v55, vcc, 0, v145, vcc
	s_waitcnt vmcnt(15)
	s_nop 1
	v_mov_b32_e32 v50, v202
	v_mov_b32_e32 v51, v203
	v_mov_b32_e32 v52, v204
	v_mov_b32_e32 v53, v205
	s_waitcnt lgkmcnt(0)
	v_lshlrev_b32_e32 v56, 16, v50
	v_and_b32_e32 v57, 0xffff0000, v50
	v_lshlrev_b32_e32 v50, 16, v51
	v_and_b32_e32 v51, 0xffff0000, v51
	v_lshlrev_b32_e32 v58, 16, v52
	v_and_b32_e32 v59, 0xffff0000, v52
	v_lshlrev_b32_e32 v52, 16, v53
	v_and_b32_e32 v53, 0xffff0000, v53
	v_pk_add_f32 v[46:47], v[46:47], v[50:51]
	v_pk_add_f32 v[44:45], v[44:45], v[56:57]
	v_pk_add_f32 v[50:51], v[42:43], v[52:53]
	v_pk_add_f32 v[42:43], v[40:41], v[58:59]
	v_cvt_pk_bf16_f32 v40, v44, v45
	v_cvt_pk_bf16_f32 v41, v46, v47
	v_cvt_pk_bf16_f32 v42, v42, v43
	v_cvt_pk_bf16_f32 v43, v50, v51
	global_store_dwordx4 v[54:55], v[40:43], off
	s_waitcnt vmcnt(15)
	s_nop 1
	v_mov_b32_e32 v40, v206
	v_mov_b32_e32 v41, v207
	v_mov_b32_e32 v42, v208
	v_mov_b32_e32 v43, v209
	s_waitcnt lgkmcnt(0)
; DI unsigned pack2(float a, float b) { f32x2 v = {a, b}; hwbf16x2 r = __builtin_convertvector(v, hwbf16x2); return __builtin_bit_cast(unsigned, r); }
; DI float bflo(unsigned w) { return __uint_as_float(w << 16); }
; DI float bfhi(unsigned w) { return __uint_as_float(w & 0xffff0000u); }
;     DI const char* a(const Unit& u) const { return (const char*)(A + (size_t)u.pm * BM * lda); }
;     DI const char* a(const Unit& u) const { return (const char*)(A + (size_t)u.pm * BM * 2048 + (u.pn >> 1) * 512); }
;     DI void operator()(const f32x4 (&acc)[2][2][4][2], const Unit& u, int wr, int wc, int fr, int fq) const {
;     ...
;         for (int ai = 0; ai < 2; ++ai)
; #pragma unroll
;             for (int m = 0; m < 4; ++m) { const size_t ro = (size_t)(row0 + ai * HALF + m * 16) * D + col0;
; #pragma unroll
;                 for (int bj = 0; bj < 2; ++bj) {
;                     f32x4 x0, x1;
;                     if constexpr (IB) { const u32x4 w = *(const u32x4*)((const bf16_t*)Xin + ro + bj * HALF);
;                         x0 = (f32x4){bflo(w[0]), bfhi(w[0]), bflo(w[1]), bfhi(w[1])}; x1 = (f32x4){bflo(w[2]), bfhi(w[2]), bflo(w[3]), bfhi(w[3])}; }
;                     else { x0 = *(const f32x4*)((const float*)Xin + ro + bj * HALF); x1 = *(const f32x4*)((const float*)Xin + ro + bj * HALF + 4); }
;                     x0 += acc[ai][bj][m][0] * sc[bj][0]; x1 += acc[ai][bj][m][1] * sc[bj][1];
;                     if constexpr (OB) { u32x4 o; o[0] = pack2(x0[0], x0[1]); o[1] = pack2(x0[2], x0[3]); o[2] = pack2(x1[0], x1[1]); o[3] = pack2(x1[2], x1[3]);
;                         *(u32x4*)((bf16_t*)Xout + ro + bj * HALF) = o; }
;                     else { *(f32x4*)((float*)Xout + ro + bj * HALF) = x0; *(f32x4*)((float*)Xout + ro + bj * HALF + 4) = x1; } } }
; template <class Map, class Epi>
; DI void gemm_phase(LAS unsigned char* lds, const Map& MP, const Epi& E, const int nM, const int nN, const int K, const int lda, const int ldb) {
;     ...
;         if (!has_next) break;
; #pragma unroll
;         for (int a = 0; a < 2; ++a)
; #pragma unroll
;             for (int b = 0; b < 2; ++b)
; #pragma unroll
;                 for (int m = 0; m < 4; ++m)
; #pragma unroll
;                     for (int n = 0; n < 2; ++n) acc[a][b][m][n] = (f32x4){0.f, 0.f, 0.f, 0.f};
;         cur = nxt; cA = nA; cB = nB; ++ui;
;     }
;     PG8_WAIT_V(0);
;     if (wr == 0) PG8_BAR;
;     PG8_BAR;
	v_lshlrev_b32_e32 v44, 16, v40
	v_and_b32_e32 v45, 0xffff0000, v40
	v_lshlrev_b32_e32 v40, 16, v41
	v_and_b32_e32 v41, 0xffff0000, v41
	v_lshlrev_b32_e32 v46, 16, v42
	v_and_b32_e32 v47, 0xffff0000, v42
	v_lshlrev_b32_e32 v42, 16, v43
	v_and_b32_e32 v43, 0xffff0000, v43
	v_pk_add_f32 v[38:39], v[38:39], v[40:41]
	v_pk_add_f32 v[36:37], v[36:37], v[44:45]
	v_pk_add_f32 v[40:41], v[34:35], v[42:43]
	v_pk_add_f32 v[34:35], v[32:33], v[46:47]
	v_cvt_pk_bf16_f32 v32, v36, v37
	v_cvt_pk_bf16_f32 v33, v38, v39
	v_cvt_pk_bf16_f32 v34, v34, v35
	v_cvt_pk_bf16_f32 v35, v40, v41
	global_store_dwordx4 v[48:49], v[32:35], off offset:256
	s_nop 1
	v_lshl_add_u64 v[32:33], v[144:145], 0, s[2:3]
	s_mov_b32 s2, 0xa0000
	v_add_co_u32_e32 v38, vcc, s2, v144
	s_mov_b64 s[2:3], 0xb0000
	s_nop 0
	v_addc_co_u32_e32 v39, vcc, 0, v145, vcc
	s_waitcnt vmcnt(15)
	s_nop 1
	v_mov_b32_e32 v34, v210
	v_mov_b32_e32 v35, v211
	v_mov_b32_e32 v36, v212
	v_mov_b32_e32 v37, v213
	s_waitcnt lgkmcnt(0)
	v_lshlrev_b32_e32 v40, 16, v34
	v_and_b32_e32 v41, 0xffff0000, v34
	v_lshlrev_b32_e32 v34, 16, v35
	v_and_b32_e32 v35, 0xffff0000, v35
	v_lshlrev_b32_e32 v42, 16, v36
	v_and_b32_e32 v43, 0xffff0000, v36
	v_lshlrev_b32_e32 v36, 16, v37
	v_and_b32_e32 v37, 0xffff0000, v37
	v_pk_add_f32 v[30:31], v[30:31], v[34:35]
	v_pk_add_f32 v[28:29], v[28:29], v[40:41]
	v_pk_add_f32 v[34:35], v[26:27], v[36:37]
	v_pk_add_f32 v[26:27], v[24:25], v[42:43]
	v_cvt_pk_bf16_f32 v24, v28, v29
	v_cvt_pk_bf16_f32 v25, v30, v31
	v_cvt_pk_bf16_f32 v26, v26, v27
	v_cvt_pk_bf16_f32 v27, v34, v35
	global_store_dwordx4 v[38:39], v[24:27], off
	s_waitcnt vmcnt(15)
	s_nop 1
	v_mov_b32_e32 v24, v214
	v_mov_b32_e32 v25, v215
	v_mov_b32_e32 v26, v216
	v_mov_b32_e32 v27, v217
	s_waitcnt lgkmcnt(0)
	v_lshlrev_b32_e32 v28, 16, v24
	v_and_b32_e32 v29, 0xffff0000, v24
	v_lshlrev_b32_e32 v24, 16, v25
	v_and_b32_e32 v25, 0xffff0000, v25
	v_lshlrev_b32_e32 v30, 16, v26
	v_and_b32_e32 v31, 0xffff0000, v26
	v_lshlrev_b32_e32 v26, 16, v27
	v_and_b32_e32 v27, 0xffff0000, v27
	v_pk_add_f32 v[22:23], v[22:23], v[24:25]
	v_pk_add_f32 v[20:21], v[20:21], v[28:29]
	v_pk_add_f32 v[24:25], v[18:19], v[26:27]
	v_pk_add_f32 v[18:19], v[16:17], v[30:31]
	v_cvt_pk_bf16_f32 v16, v20, v21
	v_cvt_pk_bf16_f32 v17, v22, v23
	v_cvt_pk_bf16_f32 v18, v18, v19
	v_cvt_pk_bf16_f32 v19, v24, v25
	global_store_dwordx4 v[32:33], v[16:19], off offset:256
	s_nop 1
	v_lshl_add_u64 v[16:17], v[144:145], 0, s[2:3]
	s_mov_b32 s2, 0xb0000
	v_add_co_u32_e32 v22, vcc, s2, v144
	s_mov_b32 s2, s46
	s_nop 0
	v_addc_co_u32_e32 v23, vcc, 0, v145, vcc
	s_waitcnt vmcnt(15)
	s_nop 1
	v_mov_b32_e32 v18, v248
	v_mov_b32_e32 v19, v249
	v_mov_b32_e32 v20, v250
	v_mov_b32_e32 v21, v251
	s_and_b64 vcc, exec, s[40:41]
	s_waitcnt lgkmcnt(0)
	v_lshlrev_b32_e32 v24, 16, v18
	v_and_b32_e32 v25, 0xffff0000, v18
	v_lshlrev_b32_e32 v18, 16, v19
	v_and_b32_e32 v19, 0xffff0000, v19
	v_lshlrev_b32_e32 v26, 16, v20
	v_and_b32_e32 v27, 0xffff0000, v20
	v_lshlrev_b32_e32 v20, 16, v21
	v_and_b32_e32 v21, 0xffff0000, v21
	v_pk_add_f32 v[14:15], v[14:15], v[18:19]
	v_pk_add_f32 v[12:13], v[12:13], v[24:25]
	v_pk_add_f32 v[18:19], v[10:11], v[20:21]
	v_pk_add_f32 v[10:11], v[8:9], v[26:27]
	v_cvt_pk_bf16_f32 v8, v12, v13
	v_cvt_pk_bf16_f32 v9, v14, v15
	v_cvt_pk_bf16_f32 v10, v10, v11
	v_cvt_pk_bf16_f32 v11, v18, v19
	global_store_dwordx4 v[22:23], v[8:11], off
	s_waitcnt vmcnt(15)
	s_nop 1
	v_mov_b32_e32 v8, v252
	v_mov_b32_e32 v9, v253
	v_mov_b32_e32 v10, v254
	v_mov_b32_e32 v11, v255
	s_waitcnt lgkmcnt(0)
	v_lshlrev_b32_e32 v12, 16, v8
	v_and_b32_e32 v13, 0xffff0000, v8
	v_lshlrev_b32_e32 v8, 16, v9
	v_and_b32_e32 v9, 0xffff0000, v9
	v_lshlrev_b32_e32 v14, 16, v10
	v_and_b32_e32 v15, 0xffff0000, v10
	v_lshlrev_b32_e32 v10, 16, v11
	v_and_b32_e32 v11, 0xffff0000, v11
	v_pk_add_f32 v[6:7], v[6:7], v[8:9]
	v_pk_add_f32 v[4:5], v[4:5], v[12:13]
	v_pk_add_f32 v[8:9], v[2:3], v[10:11]
	v_pk_add_f32 v[2:3], v[0:1], v[14:15]
	v_cvt_pk_bf16_f32 v0, v4, v5
	v_cvt_pk_bf16_f32 v1, v6, v7
	v_cvt_pk_bf16_f32 v2, v2, v3
	v_cvt_pk_bf16_f32 v3, v8, v9
	global_store_dwordx4 v[16:17], v[0:3], off offset:256
	s_cbranch_vccz .LBB1_922
	s_waitcnt vmcnt(0)
	s_cmpk_gt_u32 s17, 0xff
	s_cbranch_scc1 .LBB1_929
	s_barrier

; #define PG8_STAGE(bufoff, gbase, voff) do { _Pragma("unroll") for (int _i = 0; _i < 2; ++_i) \
;         __builtin_amdgcn_global_load_lds((const unsigned*)((const char*)(gbase) + (voff)[_i]), (LAS unsigned*)(lds + (bufoff) + ldsw + _i * 8192), 16, 0, 0); } while (0)
; #define PG8_LDA(dst, b, h) do { _Pragma("unroll") for (int m = 0; m < 4; ++m) _Pragma("unroll") for (int k = 0; k < 2; ++k) dst[m][k] = *(const LAS bf16x8*)(lds + PG8_SA(b, h) + aoff + m * 2048 + k * 1024); } while (0)
; #define PG8_LDB(dst, b, h) do { _Pragma("unroll") for (int n = 0; n < 2; ++n) _Pragma("unroll") for (int k = 0; k < 2; ++k) dst[n][k] = *(const LAS bf16x8*)(lds + PG8_SB(b, h) + boff + n * 2048 + k * 1024); } while (0)
; #define PG8_MMA(ai, bj, At, Bt) do { __builtin_amdgcn_s_setprio(1); _Pragma("unroll") for (int m = 0; m < 4; ++m) _Pragma("unroll") for (int n = 0; n < 2; ++n) _Pragma("unroll") for (int k = 0; k < 2; ++k) \
;         acc[ai][bj][m][n] = __builtin_amdgcn_mfma_f32_16x16x32_bf16(Bt[n][k], At[m][k], acc[ai][bj][m][n], 0, 0, 0); __builtin_amdgcn_s_setprio(0); } while (0)
; #define PG8_WAIT_V(n) asm volatile("s_waitcnt vmcnt(" #n ")" ::: "memory")
; #define PG8_WAIT_L(n) asm volatile("s_waitcnt lgkmcnt(" #n ")" ::: "memory")
; template <class Map, class Epi>
; DI void gemm_phase(LAS unsigned char* lds, const Map& MP, const Epi& E, const int nM, const int nN, const int K, const int lda, const int ldb) {
;     ...
;         for (int t = 0; t < nt; t += 2) {
;             const bool last = (t == nt - 2);
;             const char* a1 = cA + (size_t)(t + 1) * kstep;
;             const char* a2 = last ? nA : cA + (size_t)(t + 2) * kstep; const char* b2 = last ? nB : cB + (size_t)(t + 2) * kstep;
;             const char* a3 = a2 + kstep; const char* b3 = b2 + kstep;
;             PG8_LDB(B0, 0, 0); PG8_SCHED; PG8_LDA(At, 0, 0); PG8_STAGE(PG8_SA(1, 1), a1 + hstepA, voffA);
;             PG8_WAIT_L(8); PG8_BAR; PG8_WAIT_L(0); PG8_MMA(0, 0, At, B0); PG8_BAR; PG8_SCHED;
;             PG8_LDB(B1, 0, 1); PG8_STAGE(PG8_SB(0, 0), b2, voffB);
;             PG8_BAR; PG8_WAIT_L(0); PG8_MMA(0, 1, At, B1); PG8_BAR;
;             PG8_LDA(At, 0, 1); PG8_STAGE(PG8_SA(0, 0), a2, voffA);
;             PG8_BAR; PG8_WAIT_L(0); PG8_MMA(1, 0, At, B0); PG8_BAR; PG8_SCHED;
;             PG8_STAGE(PG8_SB(0, 1), b2 + hstepB, voffB);
;             PG8_WAIT_V(6); PG8_BAR; PG8_MMA(1, 1, At, B1); PG8_BAR;
.LBB1_1069:
	s_add_u32 s24, s42, 0xfff80080
	s_addc_u32 s25, s43, -1
	s_cmp_eq_u32 s3, 28
	s_cselect_b32 s47, s23, s25
	s_cselect_b32 s46, s58, s24
	s_cselect_b32 s25, s21, vcc_hi
	s_cselect_b32 s24, s59, vcc_lo
	s_add_i32 m0, s38, 0xc000
	ds_read_b128 v[96:99], v190
	ds_read_b128 v[100:103], v190 offset:1024
	ds_read_b128 v[108:111], v190 offset:2048
	ds_read_b128 v[112:115], v190 offset:3072
	ds_read_b128 v[160:163], v190 offset:4096
	ds_read_b128 v[164:167], v190 offset:5120
	ds_read_b128 v[198:201], v190 offset:6144
	ds_read_b128 v[202:205], v190 offset:7168
	global_load_lds_dwordx4 v178, s[42:43]
	s_add_i32 m0, s38, 0xe000
	s_nop 0
	global_load_lds_dwordx4 v176, s[42:43]
	s_waitcnt lgkmcnt(8)
	s_setprio 1
	s_barrier
	s_waitcnt lgkmcnt(7)
	v_mfma_f32_16x16x32_bf16 v[148:151], v[80:83], v[96:99], v[148:151]
	v_mfma_f32_16x16x32_bf16 v[144:147], v[88:91], v[96:99], v[144:147]
	s_waitcnt lgkmcnt(5)
	v_mfma_f32_16x16x32_bf16 v[136:139], v[80:83], v[108:111], v[136:139]
	v_mfma_f32_16x16x32_bf16 v[128:131], v[88:91], v[108:111], v[128:131]
	s_waitcnt lgkmcnt(3)
	v_mfma_f32_16x16x32_bf16 v[120:123], v[80:83], v[160:163], v[120:123]
	v_mfma_f32_16x16x32_bf16 v[104:107], v[88:91], v[160:163], v[104:107]
	s_waitcnt lgkmcnt(1)
	v_mfma_f32_16x16x32_bf16 v[76:79], v[80:83], v[198:201], v[76:79]
	v_mfma_f32_16x16x32_bf16 v[72:75], v[88:91], v[198:201], v[72:75]
	v_mfma_f32_16x16x32_bf16 v[148:151], v[84:87], v[100:103], v[148:151]
	v_mfma_f32_16x16x32_bf16 v[144:147], v[92:95], v[100:103], v[144:147]
	v_mfma_f32_16x16x32_bf16 v[136:139], v[84:87], v[112:115], v[136:139]
	v_mfma_f32_16x16x32_bf16 v[128:131], v[92:95], v[112:115], v[128:131]
	v_mfma_f32_16x16x32_bf16 v[120:123], v[84:87], v[164:167], v[120:123]
	v_mfma_f32_16x16x32_bf16 v[104:107], v[92:95], v[164:167], v[104:107]
	s_waitcnt lgkmcnt(0)
	v_mfma_f32_16x16x32_bf16 v[76:79], v[84:87], v[202:205], v[76:79]
	v_mfma_f32_16x16x32_bf16 v[72:75], v[92:95], v[202:205], v[72:75]
	s_barrier
	s_setprio 0
	s_add_i32 s68, s31, s66
	v_lshl_add_u64 v[184:185], s[24:25], 0, v[172:173]
	s_mov_b32 m0, s68
	ds_read_b128 v[206:209], v191
	ds_read_b128 v[210:213], v191 offset:1024
	ds_read_b128 v[214:217], v191 offset:2048
	ds_read_b128 v[218:221], v191 offset:3072
	global_load_lds_dwordx4 v[184:185], off
	v_lshl_add_u64 v[194:195], s[24:25], 0, v[168:169]
	s_add_i32 m0, s68, 0x2000
	s_nop 0
	global_load_lds_dwordx4 v[194:195], off
	s_setprio 1
	s_barrier
	s_waitcnt lgkmcnt(3)
	v_mfma_f32_16x16x32_bf16 v[156:159], v[206:209], v[96:99], v[156:159]
	s_waitcnt lgkmcnt(1)
	v_mfma_f32_16x16x32_bf16 v[96:99], v[214:217], v[96:99], v[152:155]
	v_mfma_f32_16x16x32_bf16 v[156:159], v[210:213], v[100:103], v[156:159]
	s_waitcnt lgkmcnt(0)
	v_mfma_f32_16x16x32_bf16 v[96:99], v[218:221], v[100:103], v[96:99]
	v_mfma_f32_16x16x32_bf16 v[100:103], v[206:209], v[108:111], v[140:143]
	v_mfma_f32_16x16x32_bf16 v[108:111], v[214:217], v[108:111], v[132:135]
	v_mfma_f32_16x16x32_bf16 v[116:119], v[214:217], v[160:163], v[116:119]
	v_mfma_f32_16x16x32_bf16 v[68:71], v[206:209], v[198:201], v[68:71]
	v_mfma_f32_16x16x32_bf16 v[64:67], v[214:217], v[198:201], v[64:67]
	s_mov_b32 m0, s38
	v_mfma_f32_16x16x32_bf16 v[100:103], v[210:213], v[112:115], v[100:103]
	v_lshl_add_u64 v[226:227], s[46:47], 0, v[174:175]
	v_mfma_f32_16x16x32_bf16 v[108:111], v[218:221], v[112:115], v[108:111]
	v_mfma_f32_16x16x32_bf16 v[112:115], v[206:209], v[160:163], v[124:127]
	v_mfma_f32_16x16x32_bf16 v[116:119], v[218:221], v[164:167], v[116:119]
	v_mfma_f32_16x16x32_bf16 v[68:71], v[210:213], v[202:205], v[68:71]
	v_mfma_f32_16x16x32_bf16 v[64:67], v[218:221], v[202:205], v[64:67]
	v_mfma_f32_16x16x32_bf16 v[112:115], v[210:213], v[164:167], v[112:115]
	s_barrier
	s_setprio 0
	ds_read_b128 v[124:127], v190 offset:16384
	ds_read_b128 v[132:135], v190 offset:17408
	ds_read_b128 v[140:143], v190 offset:18432
	ds_read_b128 v[152:155], v190 offset:19456
	ds_read_b128 v[160:163], v190 offset:20480
	ds_read_b128 v[164:167], v190 offset:21504
	ds_read_b128 v[198:201], v190 offset:22528
	ds_read_b128 v[202:205], v190 offset:23552
	global_load_lds_dwordx4 v[226:227], off
	v_lshl_add_u64 v[234:235], s[46:47], 0, v[170:171]
	s_mov_b32 m0, s39
	s_nop 0
	global_load_lds_dwordx4 v[234:235], off
	s_waitcnt vmcnt(10)
	s_setprio 1
	s_barrier
	s_waitcnt lgkmcnt(7)
	v_mfma_f32_16x16x32_bf16 v[60:63], v[80:83], v[124:127], v[60:63]
	v_mfma_f32_16x16x32_bf16 v[48:51], v[88:91], v[124:127], v[48:51]
	s_waitcnt lgkmcnt(5)
	v_mfma_f32_16x16x32_bf16 v[40:43], v[80:83], v[140:143], v[40:43]
	v_mfma_f32_16x16x32_bf16 v[32:35], v[88:91], v[140:143], v[32:35]
	s_waitcnt lgkmcnt(3)
	v_mfma_f32_16x16x32_bf16 v[24:27], v[80:83], v[160:163], v[24:27]
	v_mfma_f32_16x16x32_bf16 v[16:19], v[88:91], v[160:163], v[16:19]
	s_waitcnt lgkmcnt(1)
	v_mfma_f32_16x16x32_bf16 v[12:15], v[80:83], v[198:201], v[12:15]
	v_mfma_f32_16x16x32_bf16 v[8:11], v[88:91], v[198:201], v[8:11]
	v_mfma_f32_16x16x32_bf16 v[60:63], v[84:87], v[132:135], v[60:63]
	v_mfma_f32_16x16x32_bf16 v[48:51], v[92:95], v[132:135], v[48:51]
	v_mfma_f32_16x16x32_bf16 v[40:43], v[84:87], v[152:155], v[40:43]
	v_mfma_f32_16x16x32_bf16 v[32:35], v[92:95], v[152:155], v[32:35]
	v_mfma_f32_16x16x32_bf16 v[24:27], v[84:87], v[164:167], v[24:27]
	v_mfma_f32_16x16x32_bf16 v[16:19], v[92:95], v[164:167], v[16:19]
	s_waitcnt lgkmcnt(0)
	v_mfma_f32_16x16x32_bf16 v[12:15], v[84:87], v[202:205], v[12:15]
	v_mfma_f32_16x16x32_bf16 v[8:11], v[92:95], v[202:205], v[8:11]
	s_barrier
	s_setprio 0
	s_add_u32 s68, s24, 0x80000
	s_addc_u32 s69, s25, 0
	s_add_i32 s70, s2, s66
	s_mov_b32 m0, s70
	s_nop 0
	global_load_lds_dwordx4 v172, s[68:69]
	s_add_i32 m0, s70, 0x2000
	s_nop 0
	global_load_lds_dwordx4 v168, s[68:69]
	s_waitcnt vmcnt(6)
	s_setprio 1
	s_barrier
; #define PG8_STAGE(bufoff, gbase, voff) do { _Pragma("unroll") for (int _i = 0; _i < 2; ++_i) \
;         __builtin_amdgcn_global_load_lds((const unsigned*)((const char*)(gbase) + (voff)[_i]), (LAS unsigned*)(lds + (bufoff) + ldsw + _i * 8192), 16, 0, 0); } while (0)
; #define PG8_LDA(dst, b, h) do { _Pragma("unroll") for (int m = 0; m < 4; ++m) _Pragma("unroll") for (int k = 0; k < 2; ++k) dst[m][k] = *(const LAS bf16x8*)(lds + PG8_SA(b, h) + aoff + m * 2048 + k * 1024); } while (0)
; #define PG8_LDB(dst, b, h) do { _Pragma("unroll") for (int n = 0; n < 2; ++n) _Pragma("unroll") for (int k = 0; k < 2; ++k) dst[n][k] = *(const LAS bf16x8*)(lds + PG8_SB(b, h) + boff + n * 2048 + k * 1024); } while (0)
; #define PG8_MMA(ai, bj, At, Bt) do { __builtin_amdgcn_s_setprio(1); _Pragma("unroll") for (int m = 0; m < 4; ++m) _Pragma("unroll") for (int n = 0; n < 2; ++n) _Pragma("unroll") for (int k = 0; k < 2; ++k) \
;         acc[ai][bj][m][n] = __builtin_amdgcn_mfma_f32_16x16x32_bf16(Bt[n][k], At[m][k], acc[ai][bj][m][n], 0, 0, 0); __builtin_amdgcn_s_setprio(0); } while (0)
; #define PG8_WAIT_V(n) asm volatile("s_waitcnt vmcnt(" #n ")" ::: "memory")
; #define PG8_WAIT_L(n) asm volatile("s_waitcnt lgkmcnt(" #n ")" ::: "memory")
; #define PG8_BAR __builtin_amdgcn_s_barrier()
; #define PG8_SCHED __builtin_amdgcn_sched_barrier(0)
; template <class Map, class Epi>
; DI void gemm_phase(LAS unsigned char* lds, const Map& MP, const Epi& E, const int nM, const int nN, const int K, const int lda, const int ldb) {
;     ...
;             PG8_BAR; PG8_WAIT_L(0); PG8_MMA(1, 0, At, B0); PG8_BAR; PG8_SCHED;
;             PG8_STAGE(PG8_SB(0, 1), b2 + hstepB, voffB);
;             PG8_WAIT_V(6); PG8_BAR; PG8_MMA(1, 1, At, B1); PG8_BAR;
;             PG8_LDB(B0, 1, 0); PG8_SCHED; PG8_LDA(At, 1, 0); PG8_STAGE(PG8_SA(0, 1), a2 + hstepA, voffA);
;             PG8_WAIT_L(8); PG8_BAR; PG8_WAIT_L(0); PG8_MMA(0, 0, At, B0); PG8_BAR; PG8_SCHED;
;             PG8_LDB(B1, 1, 1); PG8_STAGE(PG8_SB(1, 0), b3, voffB);
;             PG8_BAR; PG8_WAIT_L(0); PG8_MMA(0, 1, At, B1); PG8_BAR;
;             PG8_LDA(At, 1, 1); PG8_STAGE(PG8_SA(1, 0), a3, voffA);
;             PG8_BAR; PG8_WAIT_L(0); PG8_MMA(1, 0, At, B0); PG8_BAR; PG8_SCHED;
;             PG8_STAGE(PG8_SB(1, 1), b3 + hstepB, voffB);
	v_mfma_f32_16x16x32_bf16 v[56:59], v[206:209], v[124:127], v[56:59]
	v_mfma_f32_16x16x32_bf16 v[52:55], v[214:217], v[124:127], v[52:55]
	s_add_i32 s68, 0, 0x18000
	v_add_u32_e32 v92, s68, v188
	ds_read_b128 v[80:83], v92
	v_mfma_f32_16x16x32_bf16 v[44:47], v[206:209], v[140:143], v[44:47]
	v_mfma_f32_16x16x32_bf16 v[36:39], v[214:217], v[140:143], v[36:39]
	ds_read_b128 v[84:87], v92 offset:1024
	v_mfma_f32_16x16x32_bf16 v[28:31], v[206:209], v[160:163], v[28:31]
	v_mfma_f32_16x16x32_bf16 v[20:23], v[214:217], v[160:163], v[20:23]
	ds_read_b128 v[88:91], v92 offset:2048
	v_mfma_f32_16x16x32_bf16 v[4:7], v[206:209], v[198:201], v[4:7]
	v_mfma_f32_16x16x32_bf16 v[0:3], v[214:217], v[198:201], v[0:3]
	ds_read_b128 v[92:95], v92 offset:3072
	v_mfma_f32_16x16x32_bf16 v[56:59], v[210:213], v[132:135], v[56:59]
	v_mfma_f32_16x16x32_bf16 v[52:55], v[218:221], v[132:135], v[52:55]
	v_mfma_f32_16x16x32_bf16 v[44:47], v[210:213], v[152:155], v[44:47]
	v_mfma_f32_16x16x32_bf16 v[36:39], v[218:221], v[152:155], v[36:39]
	v_mfma_f32_16x16x32_bf16 v[28:31], v[210:213], v[164:167], v[28:31]
	v_mfma_f32_16x16x32_bf16 v[20:23], v[218:221], v[164:167], v[20:23]
	v_mfma_f32_16x16x32_bf16 v[4:7], v[210:213], v[202:205], v[4:7]
	v_mfma_f32_16x16x32_bf16 v[0:3], v[218:221], v[202:205], v[0:3]
	s_barrier
	s_setprio 0
	s_add_u32 s46, s46, 0x80000
	s_addc_u32 s47, s47, 0
	s_mov_b32 m0, s56
	ds_read_b128 v[124:127], v190 offset:32768
	ds_read_b128 v[132:135], v190 offset:33792
	ds_read_b128 v[160:163], v190 offset:34816
	ds_read_b128 v[164:167], v190 offset:35840
	ds_read_b128 v[198:201], v190 offset:36864
	ds_read_b128 v[202:205], v190 offset:37888
	ds_read_b128 v[206:209], v190 offset:38912
	ds_read_b128 v[210:213], v190 offset:39936
	global_load_lds_dwordx4 v174, s[46:47]
	s_mov_b32 m0, s57
	s_nop 0
	global_load_lds_dwordx4 v170, s[46:47]
	s_waitcnt lgkmcnt(8)
	s_setprio 1
	s_barrier
	s_waitcnt lgkmcnt(7)
	v_mfma_f32_16x16x32_bf16 v[140:143], v[80:83], v[124:127], v[148:151]
	s_waitcnt lgkmcnt(6)
	v_mfma_f32_16x16x32_bf16 v[148:151], v[84:87], v[132:135], v[140:143]
	v_mfma_f32_16x16x32_bf16 v[140:143], v[88:91], v[124:127], v[144:147]
	s_waitcnt lgkmcnt(5)
	v_mfma_f32_16x16x32_bf16 v[136:139], v[80:83], v[160:163], v[136:139]
	v_mfma_f32_16x16x32_bf16 v[128:131], v[88:91], v[160:163], v[128:131]
	s_waitcnt lgkmcnt(3)
	v_mfma_f32_16x16x32_bf16 v[120:123], v[80:83], v[198:201], v[120:123]
	v_mfma_f32_16x16x32_bf16 v[104:107], v[88:91], v[198:201], v[104:107]
	s_waitcnt lgkmcnt(1)
	v_mfma_f32_16x16x32_bf16 v[76:79], v[80:83], v[206:209], v[76:79]
	v_mfma_f32_16x16x32_bf16 v[72:75], v[88:91], v[206:209], v[72:75]
	v_mfma_f32_16x16x32_bf16 v[144:147], v[92:95], v[132:135], v[140:143]
	v_mfma_f32_16x16x32_bf16 v[136:139], v[84:87], v[164:167], v[136:139]
	v_mfma_f32_16x16x32_bf16 v[128:131], v[92:95], v[164:167], v[128:131]
	v_mfma_f32_16x16x32_bf16 v[120:123], v[84:87], v[202:205], v[120:123]
	v_mfma_f32_16x16x32_bf16 v[104:107], v[92:95], v[202:205], v[104:107]
	s_waitcnt lgkmcnt(0)
	v_mfma_f32_16x16x32_bf16 v[76:79], v[84:87], v[210:213], v[76:79]
	v_mfma_f32_16x16x32_bf16 v[72:75], v[92:95], v[210:213], v[72:75]
	s_barrier
	s_setprio 0
	s_add_i32 s46, 0, 0x1c000
	v_add_u32_e32 v140, s46, v188
	s_add_i32 s47, s68, s66
	ds_read_b128 v[214:217], v140
	ds_read_b128 v[218:221], v140 offset:1024
	ds_read_b128 v[222:225], v140 offset:2048
	ds_read_b128 v[230:233], v140 offset:3072
	v_lshl_add_u64 v[140:141], v[184:185], 0, s[14:15]
	s_mov_b32 m0, s47
	s_nop 0
	global_load_lds_dwordx4 v[140:141], off
	v_lshl_add_u64 v[140:141], v[194:195], 0, s[14:15]
	s_add_i32 m0, s47, 0x2000
	s_nop 0
	global_load_lds_dwordx4 v[140:141], off
	s_setprio 1
	s_barrier
	s_waitcnt lgkmcnt(1)
	v_mfma_f32_16x16x32_bf16 v[96:99], v[222:225], v[124:127], v[96:99]
	v_mfma_f32_16x16x32_bf16 v[140:143], v[214:217], v[124:127], v[156:159]
	s_waitcnt lgkmcnt(0)
	v_mfma_f32_16x16x32_bf16 v[152:155], v[230:233], v[132:135], v[96:99]
	v_mfma_f32_16x16x32_bf16 v[96:99], v[214:217], v[160:163], v[100:103]
	v_mfma_f32_16x16x32_bf16 v[156:159], v[218:221], v[132:135], v[140:143]
	v_mfma_f32_16x16x32_bf16 v[140:143], v[218:221], v[164:167], v[96:99]
	v_mfma_f32_16x16x32_bf16 v[96:99], v[222:225], v[160:163], v[108:111]
	v_mfma_f32_16x16x32_bf16 v[132:135], v[230:233], v[164:167], v[96:99]
	v_mfma_f32_16x16x32_bf16 v[96:99], v[214:217], v[198:201], v[112:115]
	s_mov_b32 m0, s63
	v_mfma_f32_16x16x32_bf16 v[124:127], v[218:221], v[202:205], v[96:99]
	v_lshl_add_u64 v[184:185], v[226:227], 0, s[14:15]
	v_mfma_f32_16x16x32_bf16 v[96:99], v[222:225], v[198:201], v[116:119]
	v_mfma_f32_16x16x32_bf16 v[68:71], v[214:217], v[206:209], v[68:71]
	v_mfma_f32_16x16x32_bf16 v[64:67], v[222:225], v[206:209], v[64:67]
	v_mfma_f32_16x16x32_bf16 v[116:119], v[230:233], v[202:205], v[96:99]
	v_mfma_f32_16x16x32_bf16 v[68:71], v[218:221], v[210:213], v[68:71]
	v_mfma_f32_16x16x32_bf16 v[64:67], v[230:233], v[210:213], v[64:67]
	s_barrier
	s_setprio 0
	ds_read_b128 v[96:99], v190 offset:49152
	ds_read_b128 v[100:103], v190 offset:50176
	ds_read_b128 v[108:111], v190 offset:51200
	ds_read_b128 v[112:115], v190 offset:52224
	ds_read_b128 v[160:163], v190 offset:53248
	ds_read_b128 v[164:167], v190 offset:54272
	ds_read_b128 v[198:201], v190 offset:55296
	ds_read_b128 v[202:205], v190 offset:56320
	global_load_lds_dwordx4 v[184:185], off
	v_lshl_add_u64 v[184:185], v[234:235], 0, s[14:15]
	s_mov_b32 m0, s4
	s_nop 0
	global_load_lds_dwordx4 v[184:185], off
	s_waitcnt vmcnt(10)
	s_setprio 1
	s_barrier
; #define PG8_STAGE(bufoff, gbase, voff) do { _Pragma("unroll") for (int _i = 0; _i < 2; ++_i) \
;         __builtin_amdgcn_global_load_lds((const unsigned*)((const char*)(gbase) + (voff)[_i]), (LAS unsigned*)(lds + (bufoff) + ldsw + _i * 8192), 16, 0, 0); } while (0)
; #define PG8_LDA(dst, b, h) do { _Pragma("unroll") for (int m = 0; m < 4; ++m) _Pragma("unroll") for (int k = 0; k < 2; ++k) dst[m][k] = *(const LAS bf16x8*)(lds + PG8_SA(b, h) + aoff + m * 2048 + k * 1024); } while (0)
; #define PG8_MMA(ai, bj, At, Bt) do { __builtin_amdgcn_s_setprio(1); _Pragma("unroll") for (int m = 0; m < 4; ++m) _Pragma("unroll") for (int n = 0; n < 2; ++n) _Pragma("unroll") for (int k = 0; k < 2; ++k) \
;         acc[ai][bj][m][n] = __builtin_amdgcn_mfma_f32_16x16x32_bf16(Bt[n][k], At[m][k], acc[ai][bj][m][n], 0, 0, 0); __builtin_amdgcn_s_setprio(0); } while (0)
; #define PG8_WAIT_V(n) asm volatile("s_waitcnt vmcnt(" #n ")" ::: "memory")
; #define PG8_WAIT_L(n) asm volatile("s_waitcnt lgkmcnt(" #n ")" ::: "memory")
; #define PG8_BAR __builtin_amdgcn_s_barrier()
; #define PG8_SCHED __builtin_amdgcn_sched_barrier(0)
; template <class Map, class Epi>
; DI void gemm_phase(LAS unsigned char* lds, const Map& MP, const Epi& E, const int nM, const int nN, const int K, const int lda, const int ldb) {
;     ...
;             PG8_BAR; PG8_WAIT_L(0); PG8_MMA(0, 1, At, B1); PG8_BAR;
;             PG8_LDA(At, 1, 1); PG8_STAGE(PG8_SA(1, 0), a3, voffA);
;             PG8_BAR; PG8_WAIT_L(0); PG8_MMA(1, 0, At, B0); PG8_BAR; PG8_SCHED;
;             PG8_STAGE(PG8_SB(1, 1), b3 + hstepB, voffB);
;             PG8_WAIT_V(6); PG8_BAR; PG8_MMA(1, 1, At, B1); PG8_BAR;
	s_waitcnt lgkmcnt(7)
	v_mfma_f32_16x16x32_bf16 v[60:63], v[80:83], v[96:99], v[60:63]
	v_mfma_f32_16x16x32_bf16 v[48:51], v[88:91], v[96:99], v[48:51]
	s_waitcnt lgkmcnt(5)
	v_mfma_f32_16x16x32_bf16 v[40:43], v[80:83], v[108:111], v[40:43]
	v_mfma_f32_16x16x32_bf16 v[32:35], v[88:91], v[108:111], v[32:35]
	s_waitcnt lgkmcnt(3)
	v_mfma_f32_16x16x32_bf16 v[24:27], v[80:83], v[160:163], v[24:27]
	v_mfma_f32_16x16x32_bf16 v[16:19], v[88:91], v[160:163], v[16:19]
	s_waitcnt lgkmcnt(1)
	v_mfma_f32_16x16x32_bf16 v[12:15], v[80:83], v[198:201], v[12:15]
	v_mfma_f32_16x16x32_bf16 v[8:11], v[88:91], v[198:201], v[8:11]
	v_mfma_f32_16x16x32_bf16 v[60:63], v[84:87], v[100:103], v[60:63]
	v_mfma_f32_16x16x32_bf16 v[48:51], v[92:95], v[100:103], v[48:51]
	v_mfma_f32_16x16x32_bf16 v[40:43], v[84:87], v[112:115], v[40:43]
	v_mfma_f32_16x16x32_bf16 v[32:35], v[92:95], v[112:115], v[32:35]
	v_mfma_f32_16x16x32_bf16 v[24:27], v[84:87], v[164:167], v[24:27]
	v_mfma_f32_16x16x32_bf16 v[16:19], v[92:95], v[164:167], v[16:19]
	s_waitcnt lgkmcnt(0)
	v_mfma_f32_16x16x32_bf16 v[12:15], v[84:87], v[202:205], v[12:15]
	v_mfma_f32_16x16x32_bf16 v[8:11], v[92:95], v[202:205], v[8:11]
	s_barrier
	s_setprio 0
	s_add_u32 s24, s24, 0x80080
	s_addc_u32 s25, s25, 0
	s_add_i32 s46, s46, s66
	s_mov_b32 m0, s46
	s_nop 0
	global_load_lds_dwordx4 v172, s[24:25]
	s_add_i32 m0, s46, 0x2000
	s_nop 0
	global_load_lds_dwordx4 v168, s[24:25]
	s_waitcnt vmcnt(6)
	s_setprio 1
	s_barrier
	v_mfma_f32_16x16x32_bf16 v[56:59], v[214:217], v[96:99], v[56:59]
	v_mfma_f32_16x16x32_bf16 v[52:55], v[222:225], v[96:99], v[52:55]
	ds_read_b128 v[80:83], v189
	v_mfma_f32_16x16x32_bf16 v[44:47], v[214:217], v[108:111], v[44:47]
	v_mfma_f32_16x16x32_bf16 v[36:39], v[222:225], v[108:111], v[36:39]
	ds_read_b128 v[84:87], v189 offset:1024
	v_mfma_f32_16x16x32_bf16 v[28:31], v[214:217], v[160:163], v[28:31]
	v_mfma_f32_16x16x32_bf16 v[20:23], v[222:225], v[160:163], v[20:23]
	ds_read_b128 v[88:91], v189 offset:2048
	v_mfma_f32_16x16x32_bf16 v[4:7], v[214:217], v[198:201], v[4:7]
	v_mfma_f32_16x16x32_bf16 v[0:3], v[222:225], v[198:201], v[0:3]
	ds_read_b128 v[92:95], v189 offset:3072
	v_mfma_f32_16x16x32_bf16 v[56:59], v[218:221], v[100:103], v[56:59]
	s_add_i32 s3, s3, 2
	v_mfma_f32_16x16x32_bf16 v[52:55], v[230:233], v[100:103], v[52:55]
	s_add_u32 vcc_lo, vcc_lo, 0x100
	s_addc_u32 vcc_hi, vcc_hi, 0
	v_mfma_f32_16x16x32_bf16 v[44:47], v[218:221], v[112:115], v[44:47]
	s_add_u32 s42, s42, 0x100
	s_addc_u32 s43, s43, 0
	v_mfma_f32_16x16x32_bf16 v[36:39], v[230:233], v[112:115], v[36:39]
	s_cmp_gt_u32 s3, 29
	v_mfma_f32_16x16x32_bf16 v[28:31], v[218:221], v[164:167], v[28:31]
	v_mfma_f32_16x16x32_bf16 v[20:23], v[230:233], v[164:167], v[20:23]
	v_mfma_f32_16x16x32_bf16 v[4:7], v[218:221], v[202:205], v[4:7]
	v_mfma_f32_16x16x32_bf16 v[0:3], v[230:233], v[202:205], v[0:3]
	s_barrier
	s_setprio 0
	s_cbranch_scc0 .LBB1_1069
; DI float silu_mul(float g, float v) { return g * v * __builtin_amdgcn_rcpf(1.0f + __builtin_amdgcn_exp2f(-LOG2E * g)); }
;     DI void operator()(const f32x4 (&acc)[2][2][4][2], const Unit& u, int wr, int wc, int fr, int fq) const {
;         const int row0 = u.pm * BM + wr * 64 + fr, ch0 = u.pn * 128 + wc * 32 + 8 * fq;
;         f32x4 w0[2], w1[2], w2[2], bb[2];
; #pragma unroll
;         for (int n = 0; n < 2; ++n) { w0[n] = *(const f32x4*)(cw + ch0 + 4 * n); w1[n] = *(const f32x4*)(cw + DFF + ch0 + 4 * n); w2[n] = *(const f32x4*)(cw + 2 * DFF + ch0 + 4 * n); bb[n] = *(const f32x4*)(cb + ch0 + 4 * n); }
; #pragma unroll
;         for (int ai = 0; ai < 2; ++ai)
; #pragma unroll
;             for (int m = 0; m < 4; ++m) {
;                 const bool efirst = (m == 0) && (fr == 0), elast = (m == 3) && (fr == 15);
;                 const int row = row0 + ai * HALF + m * 16;
;                 f32x4 gc[2];
; #pragma unroll
;                 for (int n = 0; n < 2; ++n) {
;                     const f32x4 g = acc[ai][0][m][n];
;                     const f32x4 gprev = acc[ai][0][m > 0 ? m - 1 : 0][n], gnext = acc[ai][0][m < 3 ? m + 1 : 3][n];
;                     f32x4 up, dn;
; #pragma unroll
;                     for (int e = 0; e < 4; ++e) {
;                         const float pu = (m > 0 && fr == 15) ? gprev[e] : g[e];
;                         const float pd = (m < 3 && fr == 0) ? gnext[e] : g[e];
;                         up[e] = dpp_ror1(pu); dn[e] = dpp_ror15(pd);
;                     }
;                     if (efirst) up = (f32x4){0.f, 0.f, 0.f, 0.f};
;                     if (elast) dn = (f32x4){0.f, 0.f, 0.f, 0.f};
;                     gc[n] = w0[n] * up + w1[n] * g + w2[n] * dn + bb[n];
;                 }
;                 if (efirst || elast) {
;                     const size_t eo = (size_t)((row >> 6) * 2 + (elast ? 1 : 0)) * DFF + ch0;
; #pragma unroll
;                     for (int n = 0; n < 2; ++n) { *(f32x4*)(EP + eo + 4 * n) = gc[n]; *(f32x4*)(ER + eo + 4 * n) = acc[ai][0][m][n]; *(f32x4*)(EV + eo + 4 * n) = acc[ai][1][m][n]; }
;                 } else {
;                     const f32x4 v0 = acc[ai][1][m][0], v1 = acc[ai][1][m][1];
;                     u32x4 o;
;                     o[0] = pack2(silu_mul(gc[0][0], v0[0]), silu_mul(gc[0][1], v0[1])); o[1] = pack2(silu_mul(gc[0][2], v0[2]), silu_mul(gc[0][3], v0[3]));
	s_waitcnt lgkmcnt(0)
	s_lshl_b32 s21, s45, 7
	v_mov_b32_e32 v194, v186
	v_mov_b32_e32 v80, v187
	s_or_b32 s21, s21, s62
	v_mov_b32_e32 v160, 0
	v_lshl_add_u32 v184, v80, 3, s21
	v_ashrrev_i32_e32 v185, 31, v184
	v_lshlrev_b64 v[80:81], 2, v[184:185]
	v_lshl_add_u64 v[84:85], s[6:7], 0, v[80:81]
	v_lshl_add_u64 v[88:89], s[16:17], 0, v[80:81]
	v_lshl_add_u64 v[92:93], s[18:19], 0, v[80:81]
	v_lshl_add_u64 v[112:113], s[52:53], 0, v[80:81]
	global_load_dwordx4 v[80:83], v[84:85], off offset:16
	global_load_dwordx4 v[96:99], v[84:85], off
	s_nop 0
	global_load_dwordx4 v[84:87], v[88:89], off offset:16
	global_load_dwordx4 v[100:103], v[88:89], off
	s_nop 0
	global_load_dwordx4 v[88:91], v[92:93], off offset:16
	global_load_dwordx4 v[108:111], v[92:93], off
	s_nop 0
	global_load_dwordx4 v[92:95], v[112:113], off offset:16
	s_nop 0
	global_load_dwordx4 v[112:115], v[112:113], off
	v_cmp_eq_u32_e32 vcc, 0, v194
	v_mov_b32_e32 v164, 0
	v_mov_b32_e32 v195, 0
	v_cndmask_b32_e32 v161, v148, v136, vcc
	v_cndmask_b32_e32 v162, v149, v137, vcc
	v_cndmask_b32_e32 v163, v150, v138, vcc
	v_mov_b32_dpp v160, v161 row_ror:15 row_mask:0xf bank_mask:0xf
	v_mov_b32_e32 v161, 0
	v_mov_b32_e32 v166, 0
	v_mov_b32_e32 v167, 0
	v_mov_b32_dpp v161, v162 row_ror:15 row_mask:0xf bank_mask:0xf
	v_mov_b32_e32 v162, 0
	v_mov_b32_dpp v164, v150 row_ror:1 row_mask:0xf bank_mask:0xf
	v_cndmask_b32_e32 v165, v151, v139, vcc
	v_mov_b32_dpp v162, v163 row_ror:15 row_mask:0xf bank_mask:0xf
	v_mov_b32_dpp v195, v151 row_ror:1 row_mask:0xf bank_mask:0xf
	v_mov_b32_e32 v163, 0
	v_mov_b32_dpp v166, v148 row_ror:1 row_mask:0xf bank_mask:0xf
	v_mov_b32_dpp v167, v149 row_ror:1 row_mask:0xf bank_mask:0xf
	v_mov_b32_dpp v163, v165 row_ror:15 row_mask:0xf bank_mask:0xf
	v_cndmask_b32_e64 v165, v195, 0, vcc
	v_cndmask_b32_e64 v164, v164, 0, vcc
	v_cndmask_b32_e64 v167, v167, 0, vcc
	v_cndmask_b32_e64 v166, v166, 0, vcc
	v_mov_b32_e32 v195, 0
	v_mov_b32_e32 v196, 0
	v_mov_b32_e32 v198, 0
	v_mov_b32_e32 v200, 0
	v_mov_b32_dpp v195, v144 row_ror:1 row_mask:0xf bank_mask:0xf
	v_mov_b32_dpp v196, v145 row_ror:1 row_mask:0xf bank_mask:0xf
	v_mov_b32_dpp v198, v146 row_ror:1 row_mask:0xf bank_mask:0xf
	v_cndmask_b32_e32 v199, v147, v131, vcc
	v_mov_b32_dpp v200, v147 row_ror:1 row_mask:0xf bank_mask:0xf
	v_cndmask_b32_e64 v198, v198, 0, vcc
	v_cndmask_b32_e64 v201, v196, 0, vcc
	s_lshl_b32 s3, s44, 8
	s_add_i32 s3, s3, s49
	v_add_u32_e32 v193, s3, v194
	v_cmp_ne_u32_e64 s[46:47], 0, v194
	s_waitcnt vmcnt(0)
	v_pk_mul_f32 v[164:165], v[98:99], v[164:165]
	v_pk_mul_f32 v[166:167], v[96:97], v[166:167]
	v_pk_fma_f32 v[164:165], v[150:151], v[102:103], v[164:165]
	v_pk_fma_f32 v[166:167], v[148:149], v[100:101], v[166:167]
	v_pk_fma_f32 v[162:163], v[110:111], v[162:163], v[164:165]
	v_cndmask_b32_e32 v165, v144, v128, vcc
	v_mov_b32_e32 v164, 0
	v_pk_fma_f32 v[160:161], v[108:109], v[160:161], v[166:167]
	v_cndmask_b32_e32 v166, v145, v129, vcc
	v_mov_b32_dpp v164, v165 row_ror:15 row_mask:0xf bank_mask:0xf
	v_mov_b32_e32 v165, 0
	v_cndmask_b32_e32 v167, v146, v130, vcc
	v_pk_add_f32 v[162:163], v[114:115], v[162:163]
	v_mov_b32_dpp v165, v166 row_ror:15 row_mask:0xf bank_mask:0xf
	v_mov_b32_e32 v166, 0
	v_pk_add_f32 v[160:161], v[112:113], v[160:161]
	s_nop 0
	v_mov_b32_dpp v166, v167 row_ror:15 row_mask:0xf bank_mask:0xf
	v_mov_b32_e32 v167, 0
	s_nop 1
	v_mov_b32_dpp v167, v199 row_ror:15 row_mask:0xf bank_mask:0xf
	v_cndmask_b32_e64 v199, v200, 0, vcc
	v_cndmask_b32_e64 v200, v195, 0, vcc
	v_pk_mul_f32 v[200:201], v[80:81], v[200:201]
	v_pk_mul_f32 v[198:199], v[82:83], v[198:199]
	v_pk_fma_f32 v[200:201], v[144:145], v[84:85], v[200:201]
	v_pk_fma_f32 v[198:199], v[146:147], v[86:87], v[198:199]
	v_pk_fma_f32 v[164:165], v[88:89], v[164:165], v[200:201]
	v_pk_fma_f32 v[166:167], v[90:91], v[166:167], v[198:199]
	v_pk_add_f32 v[164:165], v[92:93], v[164:165]
	v_pk_add_f32 v[166:167], v[94:95], v[166:167]
	s_and_saveexec_b64 s[24:25], s[46:47]
	s_xor_b64 s[24:25], exec, s[24:25]
	s_cbranch_execz .LBB1_1072
	v_mul_f32_e32 v195, 0xbfb8aa3b, v160
	v_exp_f32_e32 v195, v195
	v_mul_f32_e32 v196, 0xbfb8aa3b, v161
	v_exp_f32_e32 v196, v196
	v_pk_mul_f32 v[160:161], v[156:157], v[160:161]
	v_add_f32_e32 v195, 1.0, v195
	v_rcp_f32_e32 v198, v195
	v_add_f32_e32 v196, 1.0, v196
	v_mul_f32_e32 v195, 0xbfb8aa3b, v162
	v_rcp_f32_e32 v199, v196
	v_exp_f32_e32 v195, v195
	v_mul_f32_e32 v196, 0xbfb8aa3b, v163
	v_exp_f32_e32 v196, v196
	v_pk_mul_f32 v[160:161], v[160:161], v[198:199]
	v_add_f32_e32 v195, 1.0, v195
	v_rcp_f32_e32 v200, v195
	v_add_f32_e32 v195, 1.0, v196
	v_rcp_f32_e32 v201, v195
	v_cvt_pk_bf16_f32 v160, v160, v161
	v_mul_f32_e32 v161, 0xbfb8aa3b, v164
	v_exp_f32_e32 v195, v161
	v_mul_f32_e32 v161, 0xbfb8aa3b, v165
	v_exp_f32_e32 v196, v161
	v_pk_mul_f32 v[162:163], v[158:159], v[162:163]
	v_pk_mul_f32 v[164:165], v[152:153], v[164:165]
	v_pk_mul_f32 v[162:163], v[162:163], v[200:201]
	s_nop 0
	v_cvt_pk_bf16_f32 v161, v162, v163
	v_add_f32_e32 v162, 1.0, v195
	v_mul_f32_e32 v195, 0xbfb8aa3b, v166
	v_add_f32_e32 v163, 1.0, v196
	v_exp_f32_e32 v195, v195
	v_mul_f32_e32 v196, 0xbfb8aa3b, v167
	v_exp_f32_e32 v196, v196
	v_rcp_f32_e32 v162, v162
	v_add_f32_e32 v195, 1.0, v195
	v_rcp_f32_e32 v198, v195
	v_add_f32_e32 v195, 1.0, v196
	v_rcp_f32_e32 v163, v163
	v_rcp_f32_e32 v199, v195
	v_pk_mul_f32 v[166:167], v[154:155], v[166:167]
	v_pk_mul_f32 v[162:163], v[164:165], v[162:163]
	v_pk_mul_f32 v[164:165], v[166:167], v[198:199]
	v_cvt_pk_bf16_f32 v162, v162, v163
	v_cvt_pk_bf16_f32 v163, v164, v165
	v_mov_b64_e32 v[164:165], s[54:55]
	v_mad_i64_i32 v[164:165], s[42:43], v193, s60, v[164:165]
	v_lshl_add_u64 v[164:165], v[184:185], 1, v[164:165]
	global_store_dwordx4 v[164:165], v[160:163], off

; #define PG8_STAGE(bufoff, gbase, voff) do { _Pragma("unroll") for (int _i = 0; _i < 2; ++_i) \
;         __builtin_amdgcn_global_load_lds((const unsigned*)((const char*)(gbase) + (voff)[_i]), (LAS unsigned*)(lds + (bufoff) + ldsw + _i * 8192), 16, 0, 0); } while (0)
; #define PG8_LDA(dst, b, h) do { _Pragma("unroll") for (int m = 0; m < 4; ++m) _Pragma("unroll") for (int k = 0; k < 2; ++k) dst[m][k] = *(const LAS bf16x8*)(lds + PG8_SA(b, h) + aoff + m * 2048 + k * 1024); } while (0)
; #define PG8_LDB(dst, b, h) do { _Pragma("unroll") for (int n = 0; n < 2; ++n) _Pragma("unroll") for (int k = 0; k < 2; ++k) dst[n][k] = *(const LAS bf16x8*)(lds + PG8_SB(b, h) + boff + n * 2048 + k * 1024); } while (0)
; #define PG8_MMA(ai, bj, At, Bt) do { __builtin_amdgcn_s_setprio(1); _Pragma("unroll") for (int m = 0; m < 4; ++m) _Pragma("unroll") for (int n = 0; n < 2; ++n) _Pragma("unroll") for (int k = 0; k < 2; ++k) \
;         acc[ai][bj][m][n] = __builtin_amdgcn_mfma_f32_16x16x32_bf16(Bt[n][k], At[m][k], acc[ai][bj][m][n], 0, 0, 0); __builtin_amdgcn_s_setprio(0); } while (0)
; #define PG8_WAIT_V(n) asm volatile("s_waitcnt vmcnt(" #n ")" ::: "memory")
; #define PG8_WAIT_L(n) asm volatile("s_waitcnt lgkmcnt(" #n ")" ::: "memory")
; template <class Map, class Epi>
; DI void gemm_phase(LAS unsigned char* lds, const Map& MP, const Epi& E, const int nM, const int nN, const int K, const int lda, const int ldb) {
;     ...
;         for (int t = 0; t < nt; t += 2) {
;             const bool last = (t == nt - 2);
;             const char* a1 = cA + (size_t)(t + 1) * kstep;
;             const char* a2 = last ? nA : cA + (size_t)(t + 2) * kstep; const char* b2 = last ? nB : cB + (size_t)(t + 2) * kstep;
;             const char* a3 = a2 + kstep; const char* b3 = b2 + kstep;
;             PG8_LDB(B0, 0, 0); PG8_SCHED; PG8_LDA(At, 0, 0); PG8_STAGE(PG8_SA(1, 1), a1 + hstepA, voffA);
;             PG8_WAIT_L(8); PG8_BAR; PG8_WAIT_L(0); PG8_MMA(0, 0, At, B0); PG8_BAR; PG8_SCHED;
;             PG8_LDB(B1, 0, 1); PG8_STAGE(PG8_SB(0, 0), b2, voffB);
;             PG8_BAR; PG8_WAIT_L(0); PG8_MMA(0, 1, At, B1); PG8_BAR;
;             PG8_LDA(At, 0, 1); PG8_STAGE(PG8_SA(0, 0), a2, voffA);
;             PG8_BAR; PG8_WAIT_L(0); PG8_MMA(1, 0, At, B0); PG8_BAR; PG8_SCHED;
;             PG8_STAGE(PG8_SB(0, 1), b2 + hstepB, voffB);
;             PG8_WAIT_V(6); PG8_BAR; PG8_MMA(1, 1, At, B1); PG8_BAR;
.LBB1_1239:
	s_add_u32 s10, s8, 0x100
	s_addc_u32 s11, s9, 0
	s_cmpk_eq_i32 s3, 0x54
	s_cselect_b32 s15, s43, s11
	s_cselect_b32 s14, s42, s10
	s_cselect_b32 s13, s7, s38
	s_cselect_b32 s12, s6, s5
	s_add_i32 m0, s24, 0xc000
	ds_read_b128 v[168:171], v150
	ds_read_b128 v[172:175], v150 offset:1024
	ds_read_b128 v[176:179], v150 offset:2048
	ds_read_b128 v[180:183], v150 offset:3072
	ds_read_b128 v[184:187], v150 offset:4096
	ds_read_b128 v[188:191], v150 offset:5120
	ds_read_b128 v[192:195], v150 offset:6144
	ds_read_b128 v[198:201], v150 offset:7168
	global_load_lds_dwordx4 v138, s[8:9]
	s_add_i32 m0, s24, 0xe000
	s_nop 0
	global_load_lds_dwordx4 v136, s[8:9]
	s_waitcnt lgkmcnt(8)
	s_setprio 1
	s_barrier
	s_waitcnt lgkmcnt(7)
	v_mfma_f32_16x16x32_bf16 v[124:127], v[152:155], v[168:171], v[124:127]
	v_mfma_f32_16x16x32_bf16 v[120:123], v[160:163], v[168:171], v[120:123]
	s_waitcnt lgkmcnt(5)
	v_mfma_f32_16x16x32_bf16 v[108:111], v[152:155], v[176:179], v[108:111]
	v_mfma_f32_16x16x32_bf16 v[104:107], v[160:163], v[176:179], v[104:107]
	s_waitcnt lgkmcnt(3)
	v_mfma_f32_16x16x32_bf16 v[92:95], v[152:155], v[184:187], v[92:95]
	v_mfma_f32_16x16x32_bf16 v[88:91], v[160:163], v[184:187], v[88:91]
	s_waitcnt lgkmcnt(1)
	v_mfma_f32_16x16x32_bf16 v[76:79], v[152:155], v[192:195], v[76:79]
	v_mfma_f32_16x16x32_bf16 v[72:75], v[160:163], v[192:195], v[72:75]
	v_mfma_f32_16x16x32_bf16 v[124:127], v[156:159], v[172:175], v[124:127]
	v_mfma_f32_16x16x32_bf16 v[120:123], v[164:167], v[172:175], v[120:123]
	v_mfma_f32_16x16x32_bf16 v[108:111], v[156:159], v[180:183], v[108:111]
	v_mfma_f32_16x16x32_bf16 v[104:107], v[164:167], v[180:183], v[104:107]
	v_mfma_f32_16x16x32_bf16 v[92:95], v[156:159], v[188:191], v[92:95]
	v_mfma_f32_16x16x32_bf16 v[88:91], v[164:167], v[188:191], v[88:91]
	s_waitcnt lgkmcnt(0)
	v_mfma_f32_16x16x32_bf16 v[76:79], v[156:159], v[198:201], v[76:79]
	v_mfma_f32_16x16x32_bf16 v[72:75], v[164:167], v[198:201], v[72:75]
	s_barrier
	s_setprio 0
	s_add_i32 s8, s35, s22
	v_lshl_add_u64 v[144:145], s[12:13], 0, v[132:133]
	s_mov_b32 m0, s8
	ds_read_b128 v[202:205], v151
	ds_read_b128 v[206:209], v151 offset:1024
	ds_read_b128 v[210:213], v151 offset:2048
	ds_read_b128 v[214:217], v151 offset:3072
	global_load_lds_dwordx4 v[144:145], off
	v_lshl_add_u64 v[218:219], s[12:13], 0, v[128:129]
	s_add_i32 m0, s8, 0x2000
	s_nop 0
	global_load_lds_dwordx4 v[218:219], off
	s_setprio 1
	s_barrier
	s_waitcnt lgkmcnt(3)
	v_mfma_f32_16x16x32_bf16 v[116:119], v[202:205], v[168:171], v[116:119]
	s_waitcnt lgkmcnt(1)
	v_mfma_f32_16x16x32_bf16 v[112:115], v[210:213], v[168:171], v[112:115]
	v_mfma_f32_16x16x32_bf16 v[100:103], v[202:205], v[176:179], v[100:103]
	v_mfma_f32_16x16x32_bf16 v[96:99], v[210:213], v[176:179], v[96:99]
	v_mfma_f32_16x16x32_bf16 v[84:87], v[202:205], v[184:187], v[84:87]
	v_mfma_f32_16x16x32_bf16 v[80:83], v[210:213], v[184:187], v[80:83]
	v_mfma_f32_16x16x32_bf16 v[68:71], v[202:205], v[192:195], v[68:71]
	v_mfma_f32_16x16x32_bf16 v[64:67], v[210:213], v[192:195], v[64:67]
	v_mfma_f32_16x16x32_bf16 v[116:119], v[206:209], v[172:175], v[116:119]
	s_mov_b32 m0, s24
	s_waitcnt lgkmcnt(0)
	v_mfma_f32_16x16x32_bf16 v[112:115], v[214:217], v[172:175], v[112:115]
	v_lshl_add_u64 v[220:221], s[14:15], 0, v[134:135]
	v_mfma_f32_16x16x32_bf16 v[100:103], v[206:209], v[180:183], v[100:103]
	v_mfma_f32_16x16x32_bf16 v[96:99], v[214:217], v[180:183], v[96:99]
	v_mfma_f32_16x16x32_bf16 v[84:87], v[206:209], v[188:191], v[84:87]
	v_mfma_f32_16x16x32_bf16 v[80:83], v[214:217], v[188:191], v[80:83]
	v_mfma_f32_16x16x32_bf16 v[68:71], v[206:209], v[198:201], v[68:71]
	v_mfma_f32_16x16x32_bf16 v[64:67], v[214:217], v[198:201], v[64:67]
	s_barrier
	s_setprio 0
	ds_read_b128 v[168:171], v150 offset:16384
	ds_read_b128 v[172:175], v150 offset:17408
	ds_read_b128 v[176:179], v150 offset:18432
	ds_read_b128 v[180:183], v150 offset:19456
	ds_read_b128 v[184:187], v150 offset:20480
	ds_read_b128 v[188:191], v150 offset:21504
	ds_read_b128 v[192:195], v150 offset:22528
	ds_read_b128 v[198:201], v150 offset:23552
	global_load_lds_dwordx4 v[220:221], off
	v_lshl_add_u64 v[222:223], s[14:15], 0, v[130:131]
	s_mov_b32 m0, s25
	s_nop 0
	global_load_lds_dwordx4 v[222:223], off
	s_waitcnt vmcnt(10)
	s_setprio 1
	s_barrier
	s_waitcnt lgkmcnt(7)
	v_mfma_f32_16x16x32_bf16 v[60:63], v[152:155], v[168:171], v[60:63]
	v_mfma_f32_16x16x32_bf16 v[56:59], v[160:163], v[168:171], v[56:59]
	s_waitcnt lgkmcnt(5)
	v_mfma_f32_16x16x32_bf16 v[44:47], v[152:155], v[176:179], v[44:47]
	v_mfma_f32_16x16x32_bf16 v[40:43], v[160:163], v[176:179], v[40:43]
	s_waitcnt lgkmcnt(3)
	v_mfma_f32_16x16x32_bf16 v[28:31], v[152:155], v[184:187], v[28:31]
	v_mfma_f32_16x16x32_bf16 v[24:27], v[160:163], v[184:187], v[24:27]
	s_waitcnt lgkmcnt(1)
	v_mfma_f32_16x16x32_bf16 v[12:15], v[152:155], v[192:195], v[12:15]
	v_mfma_f32_16x16x32_bf16 v[8:11], v[160:163], v[192:195], v[8:11]
	v_mfma_f32_16x16x32_bf16 v[60:63], v[156:159], v[172:175], v[60:63]
	v_mfma_f32_16x16x32_bf16 v[56:59], v[164:167], v[172:175], v[56:59]
	v_mfma_f32_16x16x32_bf16 v[44:47], v[156:159], v[180:183], v[44:47]
	v_mfma_f32_16x16x32_bf16 v[40:43], v[164:167], v[180:183], v[40:43]
	v_mfma_f32_16x16x32_bf16 v[28:31], v[156:159], v[188:191], v[28:31]
	v_mfma_f32_16x16x32_bf16 v[24:27], v[164:167], v[188:191], v[24:27]
	s_waitcnt lgkmcnt(0)
	v_mfma_f32_16x16x32_bf16 v[12:15], v[156:159], v[198:201], v[12:15]
	v_mfma_f32_16x16x32_bf16 v[8:11], v[164:167], v[198:201], v[8:11]
	s_barrier
	s_setprio 0
	s_add_u32 s8, s12, 0x160000
	s_addc_u32 s9, s13, 0
	s_add_i32 s39, s36, s22
	s_mov_b32 m0, s39
	s_nop 0
	global_load_lds_dwordx4 v132, s[8:9]
	s_add_i32 m0, s39, 0x2000
	s_nop 0
	global_load_lds_dwordx4 v128, s[8:9]
	s_waitcnt vmcnt(6)
	s_setprio 1
	s_barrier
; #define PG8_STAGE(bufoff, gbase, voff) do { _Pragma("unroll") for (int _i = 0; _i < 2; ++_i) \
;         __builtin_amdgcn_global_load_lds((const unsigned*)((const char*)(gbase) + (voff)[_i]), (LAS unsigned*)(lds + (bufoff) + ldsw + _i * 8192), 16, 0, 0); } while (0)
; #define PG8_LDA(dst, b, h) do { _Pragma("unroll") for (int m = 0; m < 4; ++m) _Pragma("unroll") for (int k = 0; k < 2; ++k) dst[m][k] = *(const LAS bf16x8*)(lds + PG8_SA(b, h) + aoff + m * 2048 + k * 1024); } while (0)
; #define PG8_LDB(dst, b, h) do { _Pragma("unroll") for (int n = 0; n < 2; ++n) _Pragma("unroll") for (int k = 0; k < 2; ++k) dst[n][k] = *(const LAS bf16x8*)(lds + PG8_SB(b, h) + boff + n * 2048 + k * 1024); } while (0)
; #define PG8_MMA(ai, bj, At, Bt) do { __builtin_amdgcn_s_setprio(1); _Pragma("unroll") for (int m = 0; m < 4; ++m) _Pragma("unroll") for (int n = 0; n < 2; ++n) _Pragma("unroll") for (int k = 0; k < 2; ++k) \
;         acc[ai][bj][m][n] = __builtin_amdgcn_mfma_f32_16x16x32_bf16(Bt[n][k], At[m][k], acc[ai][bj][m][n], 0, 0, 0); __builtin_amdgcn_s_setprio(0); } while (0)
; #define PG8_WAIT_V(n) asm volatile("s_waitcnt vmcnt(" #n ")" ::: "memory")
; #define PG8_WAIT_L(n) asm volatile("s_waitcnt lgkmcnt(" #n ")" ::: "memory")
; #define PG8_BAR __builtin_amdgcn_s_barrier()
; #define PG8_SCHED __builtin_amdgcn_sched_barrier(0)
; template <class Map, class Epi>
; DI void gemm_phase(LAS unsigned char* lds, const Map& MP, const Epi& E, const int nM, const int nN, const int K, const int lda, const int ldb) {
;     ...
;             PG8_BAR; PG8_WAIT_L(0); PG8_MMA(1, 0, At, B0); PG8_BAR; PG8_SCHED;
;             PG8_STAGE(PG8_SB(0, 1), b2 + hstepB, voffB);
;             PG8_WAIT_V(6); PG8_BAR; PG8_MMA(1, 1, At, B1); PG8_BAR;
;             PG8_LDB(B0, 1, 0); PG8_SCHED; PG8_LDA(At, 1, 0); PG8_STAGE(PG8_SA(0, 1), a2 + hstepA, voffA);
;             PG8_WAIT_L(8); PG8_BAR; PG8_WAIT_L(0); PG8_MMA(0, 0, At, B0); PG8_BAR; PG8_SCHED;
;             PG8_LDB(B1, 1, 1); PG8_STAGE(PG8_SB(1, 0), b3, voffB);
;             PG8_BAR; PG8_WAIT_L(0); PG8_MMA(0, 1, At, B1); PG8_BAR;
;             PG8_LDA(At, 1, 1); PG8_STAGE(PG8_SA(1, 0), a3, voffA);
;             PG8_BAR; PG8_WAIT_L(0); PG8_MMA(1, 0, At, B0); PG8_BAR; PG8_SCHED;
;             PG8_STAGE(PG8_SB(1, 1), b3 + hstepB, voffB);
	v_mfma_f32_16x16x32_bf16 v[52:55], v[202:205], v[168:171], v[52:55]
	v_mfma_f32_16x16x32_bf16 v[48:51], v[210:213], v[168:171], v[48:51]
	s_add_i32 s39, 0, 0x18000
	v_add_u32_e32 v164, s39, v148
	ds_read_b128 v[152:155], v164
	v_mfma_f32_16x16x32_bf16 v[36:39], v[202:205], v[176:179], v[36:39]
	v_mfma_f32_16x16x32_bf16 v[32:35], v[210:213], v[176:179], v[32:35]
	ds_read_b128 v[156:159], v164 offset:1024
	v_mfma_f32_16x16x32_bf16 v[20:23], v[202:205], v[184:187], v[20:23]
	v_mfma_f32_16x16x32_bf16 v[16:19], v[210:213], v[184:187], v[16:19]
	ds_read_b128 v[160:163], v164 offset:2048
	v_mfma_f32_16x16x32_bf16 v[4:7], v[202:205], v[192:195], v[4:7]
	v_mfma_f32_16x16x32_bf16 v[0:3], v[210:213], v[192:195], v[0:3]
	ds_read_b128 v[164:167], v164 offset:3072
	v_mfma_f32_16x16x32_bf16 v[52:55], v[206:209], v[172:175], v[52:55]
	v_mfma_f32_16x16x32_bf16 v[48:51], v[214:217], v[172:175], v[48:51]
	v_mfma_f32_16x16x32_bf16 v[36:39], v[206:209], v[180:183], v[36:39]
	v_mfma_f32_16x16x32_bf16 v[32:35], v[214:217], v[180:183], v[32:35]
	v_mfma_f32_16x16x32_bf16 v[20:23], v[206:209], v[188:191], v[20:23]
	v_mfma_f32_16x16x32_bf16 v[16:19], v[214:217], v[188:191], v[16:19]
	v_mfma_f32_16x16x32_bf16 v[4:7], v[206:209], v[198:201], v[4:7]
	v_mfma_f32_16x16x32_bf16 v[0:3], v[214:217], v[198:201], v[0:3]
	s_barrier
	s_setprio 0
	s_add_u32 s8, s14, 0x160000
	s_addc_u32 s9, s15, 0
	s_mov_b32 m0, s26
	ds_read_b128 v[168:171], v150 offset:32768
	ds_read_b128 v[172:175], v150 offset:33792
	ds_read_b128 v[176:179], v150 offset:34816
	ds_read_b128 v[180:183], v150 offset:35840
	ds_read_b128 v[184:187], v150 offset:36864
	ds_read_b128 v[188:191], v150 offset:37888
	ds_read_b128 v[192:195], v150 offset:38912
	ds_read_b128 v[198:201], v150 offset:39936
	global_load_lds_dwordx4 v134, s[8:9]
	s_mov_b32 m0, s27
	s_nop 0
	global_load_lds_dwordx4 v130, s[8:9]
	s_waitcnt lgkmcnt(8)
	s_setprio 1
	s_barrier
	s_waitcnt lgkmcnt(7)
	v_mfma_f32_16x16x32_bf16 v[124:127], v[152:155], v[168:171], v[124:127]
	v_mfma_f32_16x16x32_bf16 v[120:123], v[160:163], v[168:171], v[120:123]
	s_waitcnt lgkmcnt(5)
	v_mfma_f32_16x16x32_bf16 v[108:111], v[152:155], v[176:179], v[108:111]
	v_mfma_f32_16x16x32_bf16 v[104:107], v[160:163], v[176:179], v[104:107]
	s_waitcnt lgkmcnt(3)
	v_mfma_f32_16x16x32_bf16 v[92:95], v[152:155], v[184:187], v[92:95]
	v_mfma_f32_16x16x32_bf16 v[88:91], v[160:163], v[184:187], v[88:91]
	s_waitcnt lgkmcnt(1)
	v_mfma_f32_16x16x32_bf16 v[76:79], v[152:155], v[192:195], v[76:79]
	v_mfma_f32_16x16x32_bf16 v[72:75], v[160:163], v[192:195], v[72:75]
	v_mfma_f32_16x16x32_bf16 v[124:127], v[156:159], v[172:175], v[124:127]
	v_mfma_f32_16x16x32_bf16 v[120:123], v[164:167], v[172:175], v[120:123]
	v_mfma_f32_16x16x32_bf16 v[108:111], v[156:159], v[180:183], v[108:111]
	v_mfma_f32_16x16x32_bf16 v[104:107], v[164:167], v[180:183], v[104:107]
	v_mfma_f32_16x16x32_bf16 v[92:95], v[156:159], v[188:191], v[92:95]
	v_mfma_f32_16x16x32_bf16 v[88:91], v[164:167], v[188:191], v[88:91]
	s_waitcnt lgkmcnt(0)
	v_mfma_f32_16x16x32_bf16 v[76:79], v[156:159], v[198:201], v[76:79]
	v_mfma_f32_16x16x32_bf16 v[72:75], v[164:167], v[198:201], v[72:75]
	s_barrier
	s_setprio 0
	s_add_i32 s14, 0, 0x1c000
	s_add_i32 s8, s39, s22
	v_add_u32_e32 v196, s14, v148
	v_lshl_add_u64 v[144:145], v[144:145], 0, s[52:53]
	s_mov_b32 m0, s8
	ds_read_b128 v[202:205], v196
	ds_read_b128 v[206:209], v196 offset:1024
	ds_read_b128 v[210:213], v196 offset:2048
	ds_read_b128 v[214:217], v196 offset:3072
	global_load_lds_dwordx4 v[144:145], off
	v_lshl_add_u64 v[144:145], v[218:219], 0, s[52:53]
	s_add_i32 m0, s8, 0x2000
	s_nop 0
	global_load_lds_dwordx4 v[144:145], off
	s_setprio 1
	s_barrier
	s_waitcnt lgkmcnt(3)
	v_mfma_f32_16x16x32_bf16 v[116:119], v[202:205], v[168:171], v[116:119]
	s_waitcnt lgkmcnt(1)
	v_mfma_f32_16x16x32_bf16 v[112:115], v[210:213], v[168:171], v[112:115]
	v_mfma_f32_16x16x32_bf16 v[100:103], v[202:205], v[176:179], v[100:103]
	v_mfma_f32_16x16x32_bf16 v[96:99], v[210:213], v[176:179], v[96:99]
	v_mfma_f32_16x16x32_bf16 v[84:87], v[202:205], v[184:187], v[84:87]
	v_mfma_f32_16x16x32_bf16 v[80:83], v[210:213], v[184:187], v[80:83]
	v_mfma_f32_16x16x32_bf16 v[68:71], v[202:205], v[192:195], v[68:71]
	v_mfma_f32_16x16x32_bf16 v[64:67], v[210:213], v[192:195], v[64:67]
	v_mfma_f32_16x16x32_bf16 v[116:119], v[206:209], v[172:175], v[116:119]
	s_mov_b32 m0, s30
	s_waitcnt lgkmcnt(0)
	v_mfma_f32_16x16x32_bf16 v[112:115], v[214:217], v[172:175], v[112:115]
	v_lshl_add_u64 v[144:145], v[220:221], 0, s[52:53]
	v_mfma_f32_16x16x32_bf16 v[100:103], v[206:209], v[180:183], v[100:103]
	v_mfma_f32_16x16x32_bf16 v[96:99], v[214:217], v[180:183], v[96:99]
	v_mfma_f32_16x16x32_bf16 v[84:87], v[206:209], v[188:191], v[84:87]
	v_mfma_f32_16x16x32_bf16 v[80:83], v[214:217], v[188:191], v[80:83]
	v_mfma_f32_16x16x32_bf16 v[68:71], v[206:209], v[198:201], v[68:71]
	v_mfma_f32_16x16x32_bf16 v[64:67], v[214:217], v[198:201], v[64:67]
	s_barrier
	s_setprio 0
	ds_read_b128 v[168:171], v150 offset:49152
	ds_read_b128 v[172:175], v150 offset:50176
	ds_read_b128 v[176:179], v150 offset:51200
	ds_read_b128 v[180:183], v150 offset:52224
	ds_read_b128 v[184:187], v150 offset:53248
	ds_read_b128 v[188:191], v150 offset:54272
	ds_read_b128 v[192:195], v150 offset:55296
	ds_read_b128 v[198:201], v150 offset:56320
	global_load_lds_dwordx4 v[144:145], off
	v_lshl_add_u64 v[144:145], v[222:223], 0, s[52:53]
	s_mov_b32 m0, s31
	s_nop 0
	global_load_lds_dwordx4 v[144:145], off
	s_waitcnt vmcnt(10)
	s_setprio 1
	s_barrier
; DI float bflo(unsigned w) { return __uint_as_float(w << 16); }
; DI float bfhi(unsigned w) { return __uint_as_float(w & 0xffff0000u); }
;     DI void operator()(const f32x4 (&acc)[2][2][4][2], const Unit& u, int wr, int wc, int fr, int fq) const {
;     ...
;         for (int ai = 0; ai < 2; ++ai)
; #pragma unroll
;             for (int m = 0; m < 4; ++m) { const size_t ro = (size_t)(row0 + ai * HALF + m * 16) * D + col0;
; #pragma unroll
;                 for (int bj = 0; bj < 2; ++bj) {
;                     f32x4 x0, x1;
;                     if constexpr (IB) { const u32x4 w = *(const u32x4*)((const bf16_t*)Xin + ro + bj * HALF);
;                         x0 = (f32x4){bflo(w[0]), bfhi(w[0]), bflo(w[1]), bfhi(w[1])}; x1 = (f32x4){bflo(w[2]), bfhi(w[2]), bflo(w[3]), bfhi(w[3])}; }
;                     else { x0 = *(const f32x4*)((const float*)Xin + ro + bj * HALF); x1 = *(const f32x4*)((const float*)Xin + ro + bj * HALF + 4); }
;                     x0 += acc[ai][bj][m][0] * sc[bj][0]; x1 += acc[ai][bj][m][1] * sc[bj][1];
;                     if constexpr (OB) { u32x4 o; o[0] = pack2(x0[0], x0[1]); o[1] = pack2(x0[2], x0[3]); o[2] = pack2(x1[0], x1[1]); o[3] = pack2(x1[2], x1[3]);
;                         *(u32x4*)((bf16_t*)Xout + ro + bj * HALF) = o; }
;                     else { *(f32x4*)((float*)Xout + ro + bj * HALF) = x0; *(f32x4*)((float*)Xout + ro + bj * HALF + 4) = x1; } } }
; template <class Map, class Epi>
; DI void gemm_phase(LAS unsigned char* lds, const Map& MP, const Epi& E, const int nM, const int nN, const int K, const int lda, const int ldb) {
;     ...
;             PG8_WAIT_V(6); PG8_BAR; PG8_MMA(1, 1, At, B1); PG8_BAR;
;             PG8_LDB(B0, 1, 0); PG8_SCHED; PG8_LDA(At, 1, 0); PG8_STAGE(PG8_SA(0, 1), a2 + hstepA, voffA);
;             PG8_WAIT_L(8); PG8_BAR; PG8_WAIT_L(0); PG8_MMA(0, 0, At, B0); PG8_BAR; PG8_SCHED;
;             PG8_LDB(B1, 1, 1); PG8_STAGE(PG8_SB(1, 0), b3, voffB);
;             PG8_BAR; PG8_WAIT_L(0); PG8_MMA(0, 1, At, B1); PG8_BAR;
;             PG8_LDA(At, 1, 1); PG8_STAGE(PG8_SA(1, 0), a3, voffA);
;             PG8_BAR; PG8_WAIT_L(0); PG8_MMA(1, 0, At, B0); PG8_BAR; PG8_SCHED;
;             PG8_STAGE(PG8_SB(1, 1), b3 + hstepB, voffB);
;             PG8_WAIT_V(6); PG8_BAR; PG8_MMA(1, 1, At, B1); PG8_BAR;
;         }
;         { int frr = fr, fqq = fq; asm volatile("" : "+v"(frr), "+v"(fqq)); E(acc, cur, wr, wc, frr, fqq); }
	s_waitcnt lgkmcnt(7)
	v_mfma_f32_16x16x32_bf16 v[60:63], v[152:155], v[168:171], v[60:63]
	v_mfma_f32_16x16x32_bf16 v[56:59], v[160:163], v[168:171], v[56:59]
	s_waitcnt lgkmcnt(5)
	v_mfma_f32_16x16x32_bf16 v[44:47], v[152:155], v[176:179], v[44:47]
	v_mfma_f32_16x16x32_bf16 v[40:43], v[160:163], v[176:179], v[40:43]
	s_waitcnt lgkmcnt(3)
	v_mfma_f32_16x16x32_bf16 v[28:31], v[152:155], v[184:187], v[28:31]
	v_mfma_f32_16x16x32_bf16 v[24:27], v[160:163], v[184:187], v[24:27]
	s_waitcnt lgkmcnt(1)
	v_mfma_f32_16x16x32_bf16 v[12:15], v[152:155], v[192:195], v[12:15]
	v_mfma_f32_16x16x32_bf16 v[8:11], v[160:163], v[192:195], v[8:11]
	v_mfma_f32_16x16x32_bf16 v[60:63], v[156:159], v[172:175], v[60:63]
	v_mfma_f32_16x16x32_bf16 v[56:59], v[164:167], v[172:175], v[56:59]
	v_mfma_f32_16x16x32_bf16 v[44:47], v[156:159], v[180:183], v[44:47]
	v_mfma_f32_16x16x32_bf16 v[40:43], v[164:167], v[180:183], v[40:43]
	v_mfma_f32_16x16x32_bf16 v[28:31], v[156:159], v[188:191], v[28:31]
	v_mfma_f32_16x16x32_bf16 v[24:27], v[164:167], v[188:191], v[24:27]
	s_waitcnt lgkmcnt(0)
	v_mfma_f32_16x16x32_bf16 v[12:15], v[156:159], v[198:201], v[12:15]
	v_mfma_f32_16x16x32_bf16 v[8:11], v[164:167], v[198:201], v[8:11]
	s_barrier
	s_setprio 0
	s_add_u32 s8, s12, 0x160080
	s_addc_u32 s9, s13, 0
	s_add_i32 s12, s14, s22
	s_mov_b32 m0, s12
	s_nop 0
	global_load_lds_dwordx4 v132, s[8:9]
	s_add_i32 m0, s12, 0x2000
	s_nop 0
	global_load_lds_dwordx4 v128, s[8:9]
	s_waitcnt vmcnt(6)
	s_setprio 1
	s_barrier
	v_mfma_f32_16x16x32_bf16 v[52:55], v[202:205], v[168:171], v[52:55]
	v_mfma_f32_16x16x32_bf16 v[48:51], v[210:213], v[168:171], v[48:51]
	ds_read_b128 v[152:155], v149
	v_mfma_f32_16x16x32_bf16 v[36:39], v[202:205], v[176:179], v[36:39]
	v_mfma_f32_16x16x32_bf16 v[32:35], v[210:213], v[176:179], v[32:35]
	ds_read_b128 v[156:159], v149 offset:1024
	v_mfma_f32_16x16x32_bf16 v[20:23], v[202:205], v[184:187], v[20:23]
	v_mfma_f32_16x16x32_bf16 v[16:19], v[210:213], v[184:187], v[16:19]
	ds_read_b128 v[160:163], v149 offset:2048
	v_mfma_f32_16x16x32_bf16 v[4:7], v[202:205], v[192:195], v[4:7]
	v_mfma_f32_16x16x32_bf16 v[0:3], v[210:213], v[192:195], v[0:3]
	ds_read_b128 v[164:167], v149 offset:3072
	v_mfma_f32_16x16x32_bf16 v[52:55], v[206:209], v[172:175], v[52:55]
	s_add_i32 s3, s3, 2
	v_mfma_f32_16x16x32_bf16 v[48:51], v[214:217], v[172:175], v[48:51]
	s_add_u32 s5, s5, 0x100
	s_addc_u32 s38, s38, 0
	v_mfma_f32_16x16x32_bf16 v[36:39], v[206:209], v[180:183], v[36:39]
	s_cmpk_gt_u32 s3, 0x55
	v_mfma_f32_16x16x32_bf16 v[32:35], v[214:217], v[180:183], v[32:35]
	s_mov_b64 s[8:9], s[10:11]
	v_mfma_f32_16x16x32_bf16 v[20:23], v[206:209], v[188:191], v[20:23]
	v_mfma_f32_16x16x32_bf16 v[16:19], v[214:217], v[188:191], v[16:19]
	v_mfma_f32_16x16x32_bf16 v[4:7], v[206:209], v[198:201], v[4:7]
	v_mfma_f32_16x16x32_bf16 v[0:3], v[214:217], v[198:201], v[0:3]
	s_barrier
	s_setprio 0
	s_cbranch_scc0 .LBB1_1239
	s_waitcnt lgkmcnt(0)
	v_mov_b32_e32 v152, v147
	v_mov_b32_e32 v144, v146
	s_lshl_b32 s2, s2, 8
	s_add_i32 s2, s2, s29
	s_lshl_b32 s3, s4, 8
	v_add_u32_e32 v152, s2, v152
	s_or_b32 s3, s3, s54
	v_ashrrev_i32_e32 v153, 31, v152
	v_lshl_add_u32 v144, v144, 3, s3
	v_lshlrev_b64 v[152:153], 12, v[152:153]
	v_ashrrev_i32_e32 v145, 31, v144
	v_lshl_add_u64 v[152:153], s[46:47], 0, v[152:153]
	v_lshl_add_u64 v[144:145], v[144:145], 1, v[152:153]
	global_load_dwordx4 v[160:163], v[144:145], off
	global_load_dwordx4 v[164:167], v[144:145], off offset:256
	s_mov_b64 s[98:99], 0x10000
	v_lshl_add_u64 v[154:155], v[144:145], 0, s[98:99]
	global_load_dwordx4 v[168:171], v[154:155], off
	global_load_dwordx4 v[172:175], v[154:155], off offset:256
	s_mov_b64 s[98:99], 0x20000
	v_lshl_add_u64 v[154:155], v[144:145], 0, s[98:99]
	global_load_dwordx4 v[176:179], v[154:155], off
	global_load_dwordx4 v[180:183], v[154:155], off offset:256
	s_mov_b64 s[98:99], 0x30000
	v_lshl_add_u64 v[154:155], v[144:145], 0, s[98:99]
	global_load_dwordx4 v[184:187], v[154:155], off
	global_load_dwordx4 v[188:191], v[154:155], off offset:256
	s_mov_b64 s[98:99], 0x80000
	v_lshl_add_u64 v[154:155], v[144:145], 0, s[98:99]
	global_load_dwordx4 v[192:195], v[154:155], off
	global_load_dwordx4 v[198:201], v[154:155], off offset:256
	s_mov_b64 s[98:99], 0x90000
	v_lshl_add_u64 v[154:155], v[144:145], 0, s[98:99]
	global_load_dwordx4 v[202:205], v[154:155], off
	global_load_dwordx4 v[206:209], v[154:155], off offset:256
	s_mov_b64 s[98:99], 0xa0000
	v_lshl_add_u64 v[154:155], v[144:145], 0, s[98:99]
	global_load_dwordx4 v[210:213], v[154:155], off
	global_load_dwordx4 v[214:217], v[154:155], off offset:256
	s_mov_b64 s[98:99], 0xb0000
	v_lshl_add_u64 v[154:155], v[144:145], 0, s[98:99]
	global_load_dwordx4 v[248:251], v[154:155], off
	global_load_dwordx4 v[252:255], v[154:155], off offset:256
	s_waitcnt vmcnt(15)
	s_nop 1
	v_mov_b32_e32 v152, v160
	v_mov_b32_e32 v153, v161
	v_mov_b32_e32 v154, v162
	v_mov_b32_e32 v155, v163
	s_mov_b64 s[2:3], 0x10000
	s_mov_b32 s4, s37
	s_mov_b64 s[10:11], s[6:7]
	s_mov_b64 s[8:9], s[42:43]
	s_waitcnt lgkmcnt(0)
	v_lshlrev_b32_e32 v156, 16, v152
	v_and_b32_e32 v157, 0xffff0000, v152
	v_lshlrev_b32_e32 v152, 16, v153
	v_and_b32_e32 v153, 0xffff0000, v153
	v_lshlrev_b32_e32 v158, 16, v154
	v_and_b32_e32 v159, 0xffff0000, v154
	v_lshlrev_b32_e32 v154, 16, v155
	v_and_b32_e32 v155, 0xffff0000, v155
	v_pk_add_f32 v[126:127], v[126:127], v[152:153]
	v_pk_add_f32 v[124:125], v[124:125], v[156:157]
	v_pk_add_f32 v[152:153], v[122:123], v[154:155]
	v_pk_add_f32 v[122:123], v[120:121], v[158:159]
	v_cvt_pk_bf16_f32 v120, v124, v125
	v_cvt_pk_bf16_f32 v121, v126, v127
	v_cvt_pk_bf16_f32 v122, v122, v123
	v_cvt_pk_bf16_f32 v123, v152, v153
	global_store_dwordx4 v[144:145], v[120:123], off
	s_waitcnt vmcnt(15)
; DI unsigned pack2(float a, float b) { f32x2 v = {a, b}; hwbf16x2 r = __builtin_convertvector(v, hwbf16x2); return __builtin_bit_cast(unsigned, r); }
; DI float bflo(unsigned w) { return __uint_as_float(w << 16); }
; DI float bfhi(unsigned w) { return __uint_as_float(w & 0xffff0000u); }
;     DI void operator()(const f32x4 (&acc)[2][2][4][2], const Unit& u, int wr, int wc, int fr, int fq) const {
;     ...
;             for (int m = 0; m < 4; ++m) { const size_t ro = (size_t)(row0 + ai * HALF + m * 16) * D + col0;
; #pragma unroll
;                 for (int bj = 0; bj < 2; ++bj) {
;                     f32x4 x0, x1;
;                     if constexpr (IB) { const u32x4 w = *(const u32x4*)((const bf16_t*)Xin + ro + bj * HALF);
;                         x0 = (f32x4){bflo(w[0]), bfhi(w[0]), bflo(w[1]), bfhi(w[1])}; x1 = (f32x4){bflo(w[2]), bfhi(w[2]), bflo(w[3]), bfhi(w[3])}; }
;                     else { x0 = *(const f32x4*)((const float*)Xin + ro + bj * HALF); x1 = *(const f32x4*)((const float*)Xin + ro + bj * HALF + 4); }
;                     x0 += acc[ai][bj][m][0] * sc[bj][0]; x1 += acc[ai][bj][m][1] * sc[bj][1];
;                     if constexpr (OB) { u32x4 o; o[0] = pack2(x0[0], x0[1]); o[1] = pack2(x0[2], x0[3]); o[2] = pack2(x1[0], x1[1]); o[3] = pack2(x1[2], x1[3]);
;                         *(u32x4*)((bf16_t*)Xout + ro + bj * HALF) = o; }
;                     else { *(f32x4*)((float*)Xout + ro + bj * HALF) = x0; *(f32x4*)((float*)Xout + ro + bj * HALF + 4) = x1; } } }
	s_nop 1
	v_mov_b32_e32 v120, v164
	v_mov_b32_e32 v121, v165
	v_mov_b32_e32 v122, v166
	v_mov_b32_e32 v123, v167
	s_waitcnt lgkmcnt(0)
	v_lshlrev_b32_e32 v124, 16, v120
	v_and_b32_e32 v125, 0xffff0000, v120
	v_lshlrev_b32_e32 v120, 16, v121
	v_and_b32_e32 v121, 0xffff0000, v121
	v_lshlrev_b32_e32 v126, 16, v122
	v_and_b32_e32 v127, 0xffff0000, v122
	v_lshlrev_b32_e32 v122, 16, v123
	v_and_b32_e32 v123, 0xffff0000, v123
	v_pk_add_f32 v[116:117], v[116:117], v[124:125]
	v_pk_add_f32 v[118:119], v[118:119], v[120:121]
	v_pk_add_f32 v[120:121], v[114:115], v[122:123]
	v_pk_add_f32 v[114:115], v[112:113], v[126:127]
	v_cvt_pk_bf16_f32 v112, v116, v117
	v_lshl_add_u64 v[116:117], v[144:145], 0, s[2:3]
	s_mov_b32 s2, 0x10000
	v_cvt_pk_bf16_f32 v113, v118, v119
	v_add_co_u32_e32 v118, vcc, s2, v144
	v_cvt_pk_bf16_f32 v114, v114, v115
	v_cvt_pk_bf16_f32 v115, v120, v121
	v_addc_co_u32_e32 v119, vcc, 0, v145, vcc
	global_store_dwordx4 v[144:145], v[112:115], off offset:256
	s_waitcnt vmcnt(15)
	s_nop 1
	v_mov_b32_e32 v112, v168
	v_mov_b32_e32 v113, v169
	v_mov_b32_e32 v114, v170
	v_mov_b32_e32 v115, v171
	s_mov_b64 s[2:3], 0x20000
	s_waitcnt lgkmcnt(0)
	v_lshlrev_b32_e32 v120, 16, v112
	v_and_b32_e32 v121, 0xffff0000, v112
	v_lshlrev_b32_e32 v112, 16, v113
	v_and_b32_e32 v113, 0xffff0000, v113
	v_lshlrev_b32_e32 v122, 16, v114
	v_and_b32_e32 v123, 0xffff0000, v114
	v_lshlrev_b32_e32 v114, 16, v115
	v_and_b32_e32 v115, 0xffff0000, v115
	v_pk_add_f32 v[110:111], v[110:111], v[112:113]
	v_pk_add_f32 v[108:109], v[108:109], v[120:121]
	v_pk_add_f32 v[112:113], v[106:107], v[114:115]
	v_pk_add_f32 v[106:107], v[104:105], v[122:123]
	v_cvt_pk_bf16_f32 v104, v108, v109
	v_cvt_pk_bf16_f32 v105, v110, v111
	v_cvt_pk_bf16_f32 v106, v106, v107
	v_cvt_pk_bf16_f32 v107, v112, v113
	global_store_dwordx4 v[118:119], v[104:107], off
	s_waitcnt vmcnt(15)
	s_nop 1
	v_mov_b32_e32 v104, v172
	v_mov_b32_e32 v105, v173
	v_mov_b32_e32 v106, v174
	v_mov_b32_e32 v107, v175
	s_waitcnt lgkmcnt(0)
	v_lshlrev_b32_e32 v108, 16, v104
	v_and_b32_e32 v109, 0xffff0000, v104
	v_lshlrev_b32_e32 v104, 16, v105
	v_and_b32_e32 v105, 0xffff0000, v105
	v_lshlrev_b32_e32 v110, 16, v106
	v_and_b32_e32 v111, 0xffff0000, v106
	v_lshlrev_b32_e32 v106, 16, v107
	v_and_b32_e32 v107, 0xffff0000, v107
	v_pk_add_f32 v[100:101], v[100:101], v[108:109]
	v_pk_add_f32 v[102:103], v[102:103], v[104:105]
	v_pk_add_f32 v[104:105], v[98:99], v[106:107]
	v_pk_add_f32 v[98:99], v[96:97], v[110:111]
	v_cvt_pk_bf16_f32 v96, v100, v101
	v_lshl_add_u64 v[100:101], v[144:145], 0, s[2:3]
	s_mov_b32 s2, 0x20000
	v_cvt_pk_bf16_f32 v97, v102, v103
	v_add_co_u32_e32 v102, vcc, s2, v144
	v_cvt_pk_bf16_f32 v98, v98, v99
	v_cvt_pk_bf16_f32 v99, v104, v105
	v_addc_co_u32_e32 v103, vcc, 0, v145, vcc
	global_store_dwordx4 v[116:117], v[96:99], off offset:256
	s_waitcnt vmcnt(15)
	s_nop 1
	v_mov_b32_e32 v96, v176
	v_mov_b32_e32 v97, v177
	v_mov_b32_e32 v98, v178
	v_mov_b32_e32 v99, v179
	s_mov_b64 s[2:3], 0x30000
	s_waitcnt lgkmcnt(0)
	v_lshlrev_b32_e32 v104, 16, v96
	v_and_b32_e32 v105, 0xffff0000, v96
	v_lshlrev_b32_e32 v96, 16, v97
	v_and_b32_e32 v97, 0xffff0000, v97
	v_lshlrev_b32_e32 v106, 16, v98
	v_and_b32_e32 v107, 0xffff0000, v98
	v_lshlrev_b32_e32 v98, 16, v99
	v_and_b32_e32 v99, 0xffff0000, v99
	v_pk_add_f32 v[94:95], v[94:95], v[96:97]
	v_pk_add_f32 v[92:93], v[92:93], v[104:105]
	v_pk_add_f32 v[96:97], v[90:91], v[98:99]
	v_pk_add_f32 v[90:91], v[88:89], v[106:107]
	v_cvt_pk_bf16_f32 v88, v92, v93
	v_cvt_pk_bf16_f32 v89, v94, v95
	v_cvt_pk_bf16_f32 v90, v90, v91
	v_cvt_pk_bf16_f32 v91, v96, v97
	global_store_dwordx4 v[102:103], v[88:91], off
	s_waitcnt vmcnt(15)
	s_nop 1
	v_mov_b32_e32 v88, v180
	v_mov_b32_e32 v89, v181
	v_mov_b32_e32 v90, v182
	v_mov_b32_e32 v91, v183
	s_waitcnt lgkmcnt(0)
	v_lshlrev_b32_e32 v92, 16, v88
	v_and_b32_e32 v93, 0xffff0000, v88
	v_lshlrev_b32_e32 v88, 16, v89
	v_and_b32_e32 v89, 0xffff0000, v89
	v_lshlrev_b32_e32 v94, 16, v90
	v_and_b32_e32 v95, 0xffff0000, v90
	v_lshlrev_b32_e32 v90, 16, v91
	v_and_b32_e32 v91, 0xffff0000, v91
	v_pk_add_f32 v[86:87], v[86:87], v[88:89]
	v_pk_add_f32 v[84:85], v[84:85], v[92:93]
	v_pk_add_f32 v[88:89], v[82:83], v[90:91]
	v_pk_add_f32 v[82:83], v[80:81], v[94:95]
	v_cvt_pk_bf16_f32 v80, v84, v85
	v_cvt_pk_bf16_f32 v81, v86, v87
	v_cvt_pk_bf16_f32 v82, v82, v83
	v_cvt_pk_bf16_f32 v83, v88, v89
	global_store_dwordx4 v[100:101], v[80:83], off offset:256
	s_nop 1
	v_lshl_add_u64 v[80:81], v[144:145], 0, s[2:3]
	s_mov_b32 s2, 0x30000
	v_add_co_u32_e32 v86, vcc, s2, v144
	s_mov_b64 s[2:3], 0x80000
	s_nop 0
	v_addc_co_u32_e32 v87, vcc, 0, v145, vcc
	s_waitcnt vmcnt(15)
	s_nop 1
	v_mov_b32_e32 v82, v184
	v_mov_b32_e32 v83, v185
	v_mov_b32_e32 v84, v186
	v_mov_b32_e32 v85, v187
	s_waitcnt lgkmcnt(0)
	v_lshlrev_b32_e32 v88, 16, v82
	v_and_b32_e32 v89, 0xffff0000, v82
	v_lshlrev_b32_e32 v82, 16, v83
	v_and_b32_e32 v83, 0xffff0000, v83
	v_lshlrev_b32_e32 v90, 16, v84
	v_and_b32_e32 v91, 0xffff0000, v84
	v_lshlrev_b32_e32 v84, 16, v85
	v_and_b32_e32 v85, 0xffff0000, v85
	v_pk_add_f32 v[78:79], v[78:79], v[82:83]
	v_pk_add_f32 v[76:77], v[76:77], v[88:89]
	v_pk_add_f32 v[82:83], v[74:75], v[84:85]
	v_pk_add_f32 v[74:75], v[72:73], v[90:91]
	v_cvt_pk_bf16_f32 v72, v76, v77
	v_cvt_pk_bf16_f32 v73, v78, v79
	v_cvt_pk_bf16_f32 v74, v74, v75
	v_cvt_pk_bf16_f32 v75, v82, v83
	global_store_dwordx4 v[86:87], v[72:75], off
	s_waitcnt vmcnt(15)
	s_nop 1
	v_mov_b32_e32 v72, v188
	v_mov_b32_e32 v73, v189
	v_mov_b32_e32 v74, v190
	v_mov_b32_e32 v75, v191
	s_waitcnt lgkmcnt(0)
; DI unsigned pack2(float a, float b) { f32x2 v = {a, b}; hwbf16x2 r = __builtin_convertvector(v, hwbf16x2); return __builtin_bit_cast(unsigned, r); }
; DI float bflo(unsigned w) { return __uint_as_float(w << 16); }
; DI float bfhi(unsigned w) { return __uint_as_float(w & 0xffff0000u); }
;     DI void operator()(const f32x4 (&acc)[2][2][4][2], const Unit& u, int wr, int wc, int fr, int fq) const {
;     ...
;             for (int m = 0; m < 4; ++m) { const size_t ro = (size_t)(row0 + ai * HALF + m * 16) * D + col0;
; #pragma unroll
;                 for (int bj = 0; bj < 2; ++bj) {
;                     f32x4 x0, x1;
;                     if constexpr (IB) { const u32x4 w = *(const u32x4*)((const bf16_t*)Xin + ro + bj * HALF);
;                         x0 = (f32x4){bflo(w[0]), bfhi(w[0]), bflo(w[1]), bfhi(w[1])}; x1 = (f32x4){bflo(w[2]), bfhi(w[2]), bflo(w[3]), bfhi(w[3])}; }
;                     else { x0 = *(const f32x4*)((const float*)Xin + ro + bj * HALF); x1 = *(const f32x4*)((const float*)Xin + ro + bj * HALF + 4); }
;                     x0 += acc[ai][bj][m][0] * sc[bj][0]; x1 += acc[ai][bj][m][1] * sc[bj][1];
;                     if constexpr (OB) { u32x4 o; o[0] = pack2(x0[0], x0[1]); o[1] = pack2(x0[2], x0[3]); o[2] = pack2(x1[0], x1[1]); o[3] = pack2(x1[2], x1[3]);
;                         *(u32x4*)((bf16_t*)Xout + ro + bj * HALF) = o; }
;                     else { *(f32x4*)((float*)Xout + ro + bj * HALF) = x0; *(f32x4*)((float*)Xout + ro + bj * HALF + 4) = x1; } } }
	v_lshlrev_b32_e32 v76, 16, v72
	v_and_b32_e32 v77, 0xffff0000, v72
	v_lshlrev_b32_e32 v72, 16, v73
	v_and_b32_e32 v73, 0xffff0000, v73
	v_lshlrev_b32_e32 v78, 16, v74
	v_and_b32_e32 v79, 0xffff0000, v74
	v_lshlrev_b32_e32 v74, 16, v75
	v_and_b32_e32 v75, 0xffff0000, v75
	v_pk_add_f32 v[70:71], v[70:71], v[72:73]
	v_pk_add_f32 v[68:69], v[68:69], v[76:77]
	v_pk_add_f32 v[72:73], v[66:67], v[74:75]
	v_pk_add_f32 v[66:67], v[64:65], v[78:79]
	v_cvt_pk_bf16_f32 v64, v68, v69
	v_cvt_pk_bf16_f32 v65, v70, v71
	v_cvt_pk_bf16_f32 v66, v66, v67
	v_cvt_pk_bf16_f32 v67, v72, v73
	global_store_dwordx4 v[80:81], v[64:67], off offset:256
	s_nop 1
	v_lshl_add_u64 v[64:65], v[144:145], 0, s[2:3]
	s_mov_b32 s2, 0x80000
	v_add_co_u32_e32 v70, vcc, s2, v144
	s_mov_b64 s[2:3], 0x90000
	s_nop 0
	v_addc_co_u32_e32 v71, vcc, 0, v145, vcc
	s_waitcnt vmcnt(15)
	s_nop 1
	v_mov_b32_e32 v66, v192
	v_mov_b32_e32 v67, v193
	v_mov_b32_e32 v68, v194
	v_mov_b32_e32 v69, v195
	s_waitcnt lgkmcnt(0)
	v_lshlrev_b32_e32 v72, 16, v66
	v_and_b32_e32 v73, 0xffff0000, v66
	v_lshlrev_b32_e32 v66, 16, v67
	v_and_b32_e32 v67, 0xffff0000, v67
	v_lshlrev_b32_e32 v74, 16, v68
	v_and_b32_e32 v75, 0xffff0000, v68
	v_lshlrev_b32_e32 v68, 16, v69
	v_and_b32_e32 v69, 0xffff0000, v69
	v_pk_add_f32 v[62:63], v[62:63], v[66:67]
	v_pk_add_f32 v[60:61], v[60:61], v[72:73]
	v_pk_add_f32 v[66:67], v[58:59], v[68:69]
	v_pk_add_f32 v[58:59], v[56:57], v[74:75]
	v_cvt_pk_bf16_f32 v56, v60, v61
	v_cvt_pk_bf16_f32 v57, v62, v63
	v_cvt_pk_bf16_f32 v58, v58, v59
	v_cvt_pk_bf16_f32 v59, v66, v67
	global_store_dwordx4 v[70:71], v[56:59], off
	s_waitcnt vmcnt(15)
	s_nop 1
	v_mov_b32_e32 v56, v198
	v_mov_b32_e32 v57, v199
	v_mov_b32_e32 v58, v200
	v_mov_b32_e32 v59, v201
	s_waitcnt lgkmcnt(0)
	v_lshlrev_b32_e32 v60, 16, v56
	v_and_b32_e32 v61, 0xffff0000, v56
	v_lshlrev_b32_e32 v56, 16, v57
	v_and_b32_e32 v57, 0xffff0000, v57
	v_lshlrev_b32_e32 v62, 16, v58
	v_and_b32_e32 v63, 0xffff0000, v58
	v_lshlrev_b32_e32 v58, 16, v59
	v_and_b32_e32 v59, 0xffff0000, v59
	v_pk_add_f32 v[54:55], v[54:55], v[56:57]
	v_pk_add_f32 v[52:53], v[52:53], v[60:61]
	v_pk_add_f32 v[56:57], v[50:51], v[58:59]
	v_pk_add_f32 v[50:51], v[48:49], v[62:63]
	v_cvt_pk_bf16_f32 v48, v52, v53
	v_cvt_pk_bf16_f32 v49, v54, v55
	v_cvt_pk_bf16_f32 v50, v50, v51
	v_cvt_pk_bf16_f32 v51, v56, v57
	global_store_dwordx4 v[64:65], v[48:51], off offset:256
	s_nop 1
	v_lshl_add_u64 v[48:49], v[144:145], 0, s[2:3]
	s_mov_b32 s2, 0x90000
	v_add_co_u32_e32 v54, vcc, s2, v144
	s_mov_b64 s[2:3], 0xa0000
	s_nop 0
	v_addc_co_u32_e32 v55, vcc, 0, v145, vcc
	s_waitcnt vmcnt(15)
	s_nop 1
	v_mov_b32_e32 v50, v202
	v_mov_b32_e32 v51, v203
	v_mov_b32_e32 v52, v204
	v_mov_b32_e32 v53, v205
	s_waitcnt lgkmcnt(0)
	v_lshlrev_b32_e32 v56, 16, v50
	v_and_b32_e32 v57, 0xffff0000, v50
	v_lshlrev_b32_e32 v50, 16, v51
	v_and_b32_e32 v51, 0xffff0000, v51
	v_lshlrev_b32_e32 v58, 16, v52
	v_and_b32_e32 v59, 0xffff0000, v52
	v_lshlrev_b32_e32 v52, 16, v53
	v_and_b32_e32 v53, 0xffff0000, v53
	v_pk_add_f32 v[46:47], v[46:47], v[50:51]
	v_pk_add_f32 v[44:45], v[44:45], v[56:57]
	v_pk_add_f32 v[50:51], v[42:43], v[52:53]
	v_pk_add_f32 v[42:43], v[40:41], v[58:59]
	v_cvt_pk_bf16_f32 v40, v44, v45
	v_cvt_pk_bf16_f32 v41, v46, v47
	v_cvt_pk_bf16_f32 v42, v42, v43
	v_cvt_pk_bf16_f32 v43, v50, v51
	global_store_dwordx4 v[54:55], v[40:43], off
	s_waitcnt vmcnt(15)
	s_nop 1
	v_mov_b32_e32 v40, v206
	v_mov_b32_e32 v41, v207
	v_mov_b32_e32 v42, v208
	v_mov_b32_e32 v43, v209
	s_waitcnt lgkmcnt(0)
; DI unsigned pack2(float a, float b) { f32x2 v = {a, b}; hwbf16x2 r = __builtin_convertvector(v, hwbf16x2); return __builtin_bit_cast(unsigned, r); }
; DI float bflo(unsigned w) { return __uint_as_float(w << 16); }
; DI float bfhi(unsigned w) { return __uint_as_float(w & 0xffff0000u); }
;     DI const char* a(const Unit& u) const { return (const char*)(A + (size_t)u.pm * BM * lda); }
;     DI const char* a(const Unit& u) const { return (const char*)(A + (size_t)u.pm * BM * 2048 + (u.pn >> 1) * 512); }
; #define PG8_BAR __builtin_amdgcn_s_barrier()
;     DI void operator()(const f32x4 (&acc)[2][2][4][2], const Unit& u, int wr, int wc, int fr, int fq) const {
;     ...
;             for (int m = 0; m < 4; ++m) { const size_t ro = (size_t)(row0 + ai * HALF + m * 16) * D + col0;
; #pragma unroll
;                 for (int bj = 0; bj < 2; ++bj) {
;                     f32x4 x0, x1;
;                     if constexpr (IB) { const u32x4 w = *(const u32x4*)((const bf16_t*)Xin + ro + bj * HALF);
;                         x0 = (f32x4){bflo(w[0]), bfhi(w[0]), bflo(w[1]), bfhi(w[1])}; x1 = (f32x4){bflo(w[2]), bfhi(w[2]), bflo(w[3]), bfhi(w[3])}; }
;                     else { x0 = *(const f32x4*)((const float*)Xin + ro + bj * HALF); x1 = *(const f32x4*)((const float*)Xin + ro + bj * HALF + 4); }
;                     x0 += acc[ai][bj][m][0] * sc[bj][0]; x1 += acc[ai][bj][m][1] * sc[bj][1];
;                     if constexpr (OB) { u32x4 o; o[0] = pack2(x0[0], x0[1]); o[1] = pack2(x0[2], x0[3]); o[2] = pack2(x1[0], x1[1]); o[3] = pack2(x1[2], x1[3]);
;                         *(u32x4*)((bf16_t*)Xout + ro + bj * HALF) = o; }
;                     else { *(f32x4*)((float*)Xout + ro + bj * HALF) = x0; *(f32x4*)((float*)Xout + ro + bj * HALF + 4) = x1; } } }
; template <class Map, class Epi>
; DI void gemm_phase(LAS unsigned char* lds, const Map& MP, const Epi& E, const int nM, const int nN, const int K, const int lda, const int ldb) {
;     ...
;         if (!has_next) break;
; #pragma unroll
;         for (int a = 0; a < 2; ++a)
; #pragma unroll
;             for (int b = 0; b < 2; ++b)
; #pragma unroll
;                 for (int m = 0; m < 4; ++m)
; #pragma unroll
;                     for (int n = 0; n < 2; ++n) acc[a][b][m][n] = (f32x4){0.f, 0.f, 0.f, 0.f};
;         cur = nxt; cA = nA; cB = nB; ++ui;
;     }
;     PG8_WAIT_V(0);
;     if (wr == 0) PG8_BAR;
;     PG8_BAR;
	v_lshlrev_b32_e32 v44, 16, v40
	v_and_b32_e32 v45, 0xffff0000, v40
	v_lshlrev_b32_e32 v40, 16, v41
	v_and_b32_e32 v41, 0xffff0000, v41
	v_lshlrev_b32_e32 v46, 16, v42
	v_and_b32_e32 v47, 0xffff0000, v42
	v_lshlrev_b32_e32 v42, 16, v43
	v_and_b32_e32 v43, 0xffff0000, v43
	v_pk_add_f32 v[38:39], v[38:39], v[40:41]
	v_pk_add_f32 v[36:37], v[36:37], v[44:45]
	v_pk_add_f32 v[40:41], v[34:35], v[42:43]
	v_pk_add_f32 v[34:35], v[32:33], v[46:47]
	v_cvt_pk_bf16_f32 v32, v36, v37
	v_cvt_pk_bf16_f32 v33, v38, v39
	v_cvt_pk_bf16_f32 v34, v34, v35
	v_cvt_pk_bf16_f32 v35, v40, v41
	global_store_dwordx4 v[48:49], v[32:35], off offset:256
	s_nop 1
	v_lshl_add_u64 v[32:33], v[144:145], 0, s[2:3]
	s_mov_b32 s2, 0xa0000
	v_add_co_u32_e32 v38, vcc, s2, v144
	s_mov_b64 s[2:3], 0xb0000
	s_nop 0
	v_addc_co_u32_e32 v39, vcc, 0, v145, vcc
	s_waitcnt vmcnt(15)
	s_nop 1
	v_mov_b32_e32 v34, v210
	v_mov_b32_e32 v35, v211
	v_mov_b32_e32 v36, v212
	v_mov_b32_e32 v37, v213
	s_waitcnt lgkmcnt(0)
	v_lshlrev_b32_e32 v40, 16, v34
	v_and_b32_e32 v41, 0xffff0000, v34
	v_lshlrev_b32_e32 v34, 16, v35
	v_and_b32_e32 v35, 0xffff0000, v35
	v_lshlrev_b32_e32 v42, 16, v36
	v_and_b32_e32 v43, 0xffff0000, v36
	v_lshlrev_b32_e32 v36, 16, v37
	v_and_b32_e32 v37, 0xffff0000, v37
	v_pk_add_f32 v[30:31], v[30:31], v[34:35]
	v_pk_add_f32 v[28:29], v[28:29], v[40:41]
	v_pk_add_f32 v[34:35], v[26:27], v[36:37]
	v_pk_add_f32 v[26:27], v[24:25], v[42:43]
	v_cvt_pk_bf16_f32 v24, v28, v29
	v_cvt_pk_bf16_f32 v25, v30, v31
	v_cvt_pk_bf16_f32 v26, v26, v27
	v_cvt_pk_bf16_f32 v27, v34, v35
	global_store_dwordx4 v[38:39], v[24:27], off
	s_waitcnt vmcnt(15)
	s_nop 1
	v_mov_b32_e32 v24, v214
	v_mov_b32_e32 v25, v215
	v_mov_b32_e32 v26, v216
	v_mov_b32_e32 v27, v217
	s_waitcnt lgkmcnt(0)
	v_lshlrev_b32_e32 v28, 16, v24
	v_and_b32_e32 v29, 0xffff0000, v24
	v_lshlrev_b32_e32 v24, 16, v25
	v_and_b32_e32 v25, 0xffff0000, v25
	v_lshlrev_b32_e32 v30, 16, v26
	v_and_b32_e32 v31, 0xffff0000, v26
	v_lshlrev_b32_e32 v26, 16, v27
	v_and_b32_e32 v27, 0xffff0000, v27
	v_pk_add_f32 v[22:23], v[22:23], v[24:25]
	v_pk_add_f32 v[20:21], v[20:21], v[28:29]
	v_pk_add_f32 v[24:25], v[18:19], v[26:27]
	v_pk_add_f32 v[18:19], v[16:17], v[30:31]
	v_cvt_pk_bf16_f32 v16, v20, v21
	v_cvt_pk_bf16_f32 v17, v22, v23
	v_cvt_pk_bf16_f32 v18, v18, v19
	v_cvt_pk_bf16_f32 v19, v24, v25
	global_store_dwordx4 v[32:33], v[16:19], off offset:256
	s_nop 1
	v_lshl_add_u64 v[16:17], v[144:145], 0, s[2:3]
	s_mov_b32 s2, 0xb0000
	v_add_co_u32_e32 v22, vcc, s2, v144
	s_mov_b32 s2, s55
	s_nop 0
	v_addc_co_u32_e32 v23, vcc, 0, v145, vcc
	s_waitcnt vmcnt(15)
	s_nop 1
	v_mov_b32_e32 v18, v248
	v_mov_b32_e32 v19, v249
	v_mov_b32_e32 v20, v250
	v_mov_b32_e32 v21, v251
	s_and_b64 vcc, exec, s[40:41]
	s_waitcnt lgkmcnt(0)
	v_lshlrev_b32_e32 v24, 16, v18
	v_and_b32_e32 v25, 0xffff0000, v18
	v_lshlrev_b32_e32 v18, 16, v19
	v_and_b32_e32 v19, 0xffff0000, v19
	v_lshlrev_b32_e32 v26, 16, v20
	v_and_b32_e32 v27, 0xffff0000, v20
	v_lshlrev_b32_e32 v20, 16, v21
	v_and_b32_e32 v21, 0xffff0000, v21
	v_pk_add_f32 v[14:15], v[14:15], v[18:19]
	v_pk_add_f32 v[12:13], v[12:13], v[24:25]
	v_pk_add_f32 v[18:19], v[10:11], v[20:21]
	v_pk_add_f32 v[10:11], v[8:9], v[26:27]
	v_cvt_pk_bf16_f32 v8, v12, v13
	v_cvt_pk_bf16_f32 v9, v14, v15
	v_cvt_pk_bf16_f32 v10, v10, v11
	v_cvt_pk_bf16_f32 v11, v18, v19
	global_store_dwordx4 v[22:23], v[8:11], off
	s_waitcnt vmcnt(15)
	s_nop 1
	v_mov_b32_e32 v8, v252
	v_mov_b32_e32 v9, v253
	v_mov_b32_e32 v10, v254
	v_mov_b32_e32 v11, v255
	s_waitcnt lgkmcnt(0)
	v_lshlrev_b32_e32 v12, 16, v8
	v_and_b32_e32 v13, 0xffff0000, v8
	v_lshlrev_b32_e32 v8, 16, v9
	v_and_b32_e32 v9, 0xffff0000, v9
	v_lshlrev_b32_e32 v14, 16, v10
	v_and_b32_e32 v15, 0xffff0000, v10
	v_lshlrev_b32_e32 v10, 16, v11
	v_and_b32_e32 v11, 0xffff0000, v11
	v_pk_add_f32 v[6:7], v[6:7], v[8:9]
	v_pk_add_f32 v[4:5], v[4:5], v[12:13]
	v_pk_add_f32 v[8:9], v[2:3], v[10:11]
	v_pk_add_f32 v[2:3], v[0:1], v[14:15]
	v_cvt_pk_bf16_f32 v0, v4, v5
	v_cvt_pk_bf16_f32 v1, v6, v7
	v_cvt_pk_bf16_f32 v2, v2, v3
	v_cvt_pk_bf16_f32 v3, v8, v9
	global_store_dwordx4 v[16:17], v[0:3], off offset:256
	s_cbranch_vccz .LBB1_1232
	s_waitcnt vmcnt(0)
	s_cmpk_gt_u32 s17, 0xff
	s_cbranch_scc1 .LBB1_1243
	s_barrier

; #define PG8_STAGE(bufoff, gbase, voff) do { _Pragma("unroll") for (int _i = 0; _i < 2; ++_i) \
;         __builtin_amdgcn_global_load_lds((const unsigned*)((const char*)(gbase) + (voff)[_i]), (LAS unsigned*)(lds + (bufoff) + ldsw + _i * 8192), 16, 0, 0); } while (0)
; #define PG8_LDA(dst, b, h) do { _Pragma("unroll") for (int m = 0; m < 4; ++m) _Pragma("unroll") for (int k = 0; k < 2; ++k) dst[m][k] = *(const LAS bf16x8*)(lds + PG8_SA(b, h) + aoff + m * 2048 + k * 1024); } while (0)
; #define PG8_LDB(dst, b, h) do { _Pragma("unroll") for (int n = 0; n < 2; ++n) _Pragma("unroll") for (int k = 0; k < 2; ++k) dst[n][k] = *(const LAS bf16x8*)(lds + PG8_SB(b, h) + boff + n * 2048 + k * 1024); } while (0)
; #define PG8_MMA(ai, bj, At, Bt) do { __builtin_amdgcn_s_setprio(1); _Pragma("unroll") for (int m = 0; m < 4; ++m) _Pragma("unroll") for (int n = 0; n < 2; ++n) _Pragma("unroll") for (int k = 0; k < 2; ++k) \
;         acc[ai][bj][m][n] = __builtin_amdgcn_mfma_f32_16x16x32_bf16(Bt[n][k], At[m][k], acc[ai][bj][m][n], 0, 0, 0); __builtin_amdgcn_s_setprio(0); } while (0)
; #define PG8_WAIT_V(n) asm volatile("s_waitcnt vmcnt(" #n ")" ::: "memory")
; #define PG8_WAIT_L(n) asm volatile("s_waitcnt lgkmcnt(" #n ")" ::: "memory")
; template <class Map, class Epi>
; DI void gemm_phase(LAS unsigned char* lds, const Map& MP, const Epi& E, const int nM, const int nN, const int K, const int lda, const int ldb) {
;     ...
;         for (int t = 0; t < nt; t += 2) {
;             const bool last = (t == nt - 2);
;             const char* a1 = cA + (size_t)(t + 1) * kstep;
;             const char* a2 = last ? nA : cA + (size_t)(t + 2) * kstep; const char* b2 = last ? nB : cB + (size_t)(t + 2) * kstep;
;             const char* a3 = a2 + kstep; const char* b3 = b2 + kstep;
;             PG8_LDB(B0, 0, 0); PG8_SCHED; PG8_LDA(At, 0, 0); PG8_STAGE(PG8_SA(1, 1), a1 + hstepA, voffA);
;             PG8_WAIT_L(8); PG8_BAR; PG8_WAIT_L(0); PG8_MMA(0, 0, At, B0); PG8_BAR; PG8_SCHED;
;             PG8_LDB(B1, 0, 1); PG8_STAGE(PG8_SB(0, 0), b2, voffB);
;             PG8_BAR; PG8_WAIT_L(0); PG8_MMA(0, 1, At, B1); PG8_BAR;
;             PG8_LDA(At, 0, 1); PG8_STAGE(PG8_SA(0, 0), a2, voffA);
;             PG8_BAR; PG8_WAIT_L(0); PG8_MMA(1, 0, At, B0); PG8_BAR; PG8_SCHED;
;             PG8_STAGE(PG8_SB(0, 1), b2 + hstepB, voffB);
;             PG8_WAIT_V(6); PG8_BAR; PG8_MMA(1, 1, At, B1); PG8_BAR;
.LBB1_1382:
	s_add_u32 s22, s20, 0xfff80080
	s_addc_u32 s23, s21, -1
	s_cmp_eq_u32 s3, 28
	s_cselect_b32 s25, s15, s23
	s_cselect_b32 s24, s48, s22
	s_cselect_b32 s23, s13, s53
	s_cselect_b32 s22, s49, s52
	s_add_i32 m0, s31, 0xc000
	ds_read_b128 v[166:169], v148
	ds_read_b128 v[170:173], v148 offset:1024
	ds_read_b128 v[174:177], v148 offset:2048
	ds_read_b128 v[178:181], v148 offset:3072
	ds_read_b128 v[182:185], v148 offset:4096
	ds_read_b128 v[186:189], v148 offset:5120
	ds_read_b128 v[190:193], v148 offset:6144
	ds_read_b128 v[198:201], v148 offset:7168
	global_load_lds_dwordx4 v138, s[20:21]
	s_add_i32 m0, s31, 0xe000
	s_nop 0
	global_load_lds_dwordx4 v136, s[20:21]
	s_waitcnt lgkmcnt(8)
	s_setprio 1
	s_barrier
	s_waitcnt lgkmcnt(7)
	v_mfma_f32_16x16x32_bf16 v[124:127], v[150:153], v[166:169], v[124:127]
	v_mfma_f32_16x16x32_bf16 v[120:123], v[158:161], v[166:169], v[120:123]
	s_waitcnt lgkmcnt(5)
	v_mfma_f32_16x16x32_bf16 v[116:119], v[150:153], v[174:177], v[116:119]
	v_mfma_f32_16x16x32_bf16 v[112:115], v[158:161], v[174:177], v[112:115]
	s_waitcnt lgkmcnt(3)
	v_mfma_f32_16x16x32_bf16 v[100:103], v[150:153], v[182:185], v[100:103]
	v_mfma_f32_16x16x32_bf16 v[96:99], v[158:161], v[182:185], v[96:99]
	s_waitcnt lgkmcnt(1)
	v_mfma_f32_16x16x32_bf16 v[84:87], v[150:153], v[190:193], v[84:87]
	v_mfma_f32_16x16x32_bf16 v[80:83], v[158:161], v[190:193], v[80:83]
	v_mfma_f32_16x16x32_bf16 v[124:127], v[154:157], v[170:173], v[124:127]
	v_mfma_f32_16x16x32_bf16 v[120:123], v[162:165], v[170:173], v[120:123]
	v_mfma_f32_16x16x32_bf16 v[116:119], v[154:157], v[178:181], v[116:119]
	v_mfma_f32_16x16x32_bf16 v[112:115], v[162:165], v[178:181], v[112:115]
	v_mfma_f32_16x16x32_bf16 v[100:103], v[154:157], v[186:189], v[100:103]
	v_mfma_f32_16x16x32_bf16 v[96:99], v[162:165], v[186:189], v[96:99]
	s_waitcnt lgkmcnt(0)
	v_mfma_f32_16x16x32_bf16 v[84:87], v[154:157], v[198:201], v[84:87]
	v_mfma_f32_16x16x32_bf16 v[80:83], v[162:165], v[198:201], v[80:83]
	s_barrier
	s_setprio 0
	s_add_i32 s54, s44, s29
	v_lshl_add_u64 v[194:195], s[22:23], 0, v[132:133]
	s_mov_b32 m0, s54
	ds_read_b128 v[202:205], v149
	ds_read_b128 v[206:209], v149 offset:1024
	ds_read_b128 v[210:213], v149 offset:2048
	ds_read_b128 v[214:217], v149 offset:3072
	global_load_lds_dwordx4 v[194:195], off
	v_lshl_add_u64 v[218:219], s[22:23], 0, v[128:129]
	s_add_i32 m0, s54, 0x2000
	s_nop 0
	global_load_lds_dwordx4 v[218:219], off
	s_setprio 1
	s_barrier
	s_waitcnt lgkmcnt(3)
	v_mfma_f32_16x16x32_bf16 v[108:111], v[202:205], v[166:169], v[108:111]
	s_waitcnt lgkmcnt(1)
	v_mfma_f32_16x16x32_bf16 v[104:107], v[210:213], v[166:169], v[104:107]
	v_mfma_f32_16x16x32_bf16 v[92:95], v[202:205], v[174:177], v[92:95]
	v_mfma_f32_16x16x32_bf16 v[88:91], v[210:213], v[174:177], v[88:91]
	v_mfma_f32_16x16x32_bf16 v[76:79], v[202:205], v[182:185], v[76:79]
	v_mfma_f32_16x16x32_bf16 v[72:75], v[210:213], v[182:185], v[72:75]
	v_mfma_f32_16x16x32_bf16 v[68:71], v[202:205], v[190:193], v[68:71]
	v_mfma_f32_16x16x32_bf16 v[64:67], v[210:213], v[190:193], v[64:67]
	v_mfma_f32_16x16x32_bf16 v[108:111], v[206:209], v[170:173], v[108:111]
	s_mov_b32 m0, s31
	s_waitcnt lgkmcnt(0)
	v_mfma_f32_16x16x32_bf16 v[104:107], v[214:217], v[170:173], v[104:107]
	v_lshl_add_u64 v[220:221], s[24:25], 0, v[134:135]
	v_mfma_f32_16x16x32_bf16 v[92:95], v[206:209], v[178:181], v[92:95]
	v_mfma_f32_16x16x32_bf16 v[88:91], v[214:217], v[178:181], v[88:91]
	v_mfma_f32_16x16x32_bf16 v[76:79], v[206:209], v[186:189], v[76:79]
	v_mfma_f32_16x16x32_bf16 v[72:75], v[214:217], v[186:189], v[72:75]
	v_mfma_f32_16x16x32_bf16 v[68:71], v[206:209], v[198:201], v[68:71]
	v_mfma_f32_16x16x32_bf16 v[64:67], v[214:217], v[198:201], v[64:67]
	s_barrier
	s_setprio 0
	ds_read_b128 v[166:169], v148 offset:16384
	ds_read_b128 v[170:173], v148 offset:17408
	ds_read_b128 v[174:177], v148 offset:18432
	ds_read_b128 v[178:181], v148 offset:19456
	ds_read_b128 v[182:185], v148 offset:20480
	ds_read_b128 v[186:189], v148 offset:21504
	ds_read_b128 v[190:193], v148 offset:22528
	ds_read_b128 v[198:201], v148 offset:23552
	global_load_lds_dwordx4 v[220:221], off
	v_lshl_add_u64 v[222:223], s[24:25], 0, v[130:131]
	s_mov_b32 m0, s11
	s_nop 0
	global_load_lds_dwordx4 v[222:223], off
	s_waitcnt vmcnt(10)
	s_setprio 1
	s_barrier
	s_waitcnt lgkmcnt(7)
	v_mfma_f32_16x16x32_bf16 v[60:63], v[150:153], v[166:169], v[60:63]
	v_mfma_f32_16x16x32_bf16 v[56:59], v[158:161], v[166:169], v[56:59]
	s_waitcnt lgkmcnt(5)
	v_mfma_f32_16x16x32_bf16 v[52:55], v[150:153], v[174:177], v[52:55]
	v_mfma_f32_16x16x32_bf16 v[48:51], v[158:161], v[174:177], v[48:51]
	s_waitcnt lgkmcnt(3)
	v_mfma_f32_16x16x32_bf16 v[36:39], v[150:153], v[182:185], v[36:39]
	v_mfma_f32_16x16x32_bf16 v[32:35], v[158:161], v[182:185], v[32:35]
	s_waitcnt lgkmcnt(1)
	v_mfma_f32_16x16x32_bf16 v[20:23], v[150:153], v[190:193], v[20:23]
	v_mfma_f32_16x16x32_bf16 v[16:19], v[158:161], v[190:193], v[16:19]
	v_mfma_f32_16x16x32_bf16 v[60:63], v[154:157], v[170:173], v[60:63]
	v_mfma_f32_16x16x32_bf16 v[56:59], v[162:165], v[170:173], v[56:59]
	v_mfma_f32_16x16x32_bf16 v[52:55], v[154:157], v[178:181], v[52:55]
	v_mfma_f32_16x16x32_bf16 v[48:51], v[162:165], v[178:181], v[48:51]
	v_mfma_f32_16x16x32_bf16 v[36:39], v[154:157], v[186:189], v[36:39]
	v_mfma_f32_16x16x32_bf16 v[32:35], v[162:165], v[186:189], v[32:35]
	s_waitcnt lgkmcnt(0)
	v_mfma_f32_16x16x32_bf16 v[20:23], v[154:157], v[198:201], v[20:23]
	v_mfma_f32_16x16x32_bf16 v[16:19], v[162:165], v[198:201], v[16:19]
	s_barrier
; #define PG8_STAGE(bufoff, gbase, voff) do { _Pragma("unroll") for (int _i = 0; _i < 2; ++_i) \
;         __builtin_amdgcn_global_load_lds((const unsigned*)((const char*)(gbase) + (voff)[_i]), (LAS unsigned*)(lds + (bufoff) + ldsw + _i * 8192), 16, 0, 0); } while (0)
; #define PG8_LDA(dst, b, h) do { _Pragma("unroll") for (int m = 0; m < 4; ++m) _Pragma("unroll") for (int k = 0; k < 2; ++k) dst[m][k] = *(const LAS bf16x8*)(lds + PG8_SA(b, h) + aoff + m * 2048 + k * 1024); } while (0)
; #define PG8_LDB(dst, b, h) do { _Pragma("unroll") for (int n = 0; n < 2; ++n) _Pragma("unroll") for (int k = 0; k < 2; ++k) dst[n][k] = *(const LAS bf16x8*)(lds + PG8_SB(b, h) + boff + n * 2048 + k * 1024); } while (0)
; #define PG8_MMA(ai, bj, At, Bt) do { __builtin_amdgcn_s_setprio(1); _Pragma("unroll") for (int m = 0; m < 4; ++m) _Pragma("unroll") for (int n = 0; n < 2; ++n) _Pragma("unroll") for (int k = 0; k < 2; ++k) \
;         acc[ai][bj][m][n] = __builtin_amdgcn_mfma_f32_16x16x32_bf16(Bt[n][k], At[m][k], acc[ai][bj][m][n], 0, 0, 0); __builtin_amdgcn_s_setprio(0); } while (0)
; #define PG8_WAIT_V(n) asm volatile("s_waitcnt vmcnt(" #n ")" ::: "memory")
; #define PG8_WAIT_L(n) asm volatile("s_waitcnt lgkmcnt(" #n ")" ::: "memory")
; #define PG8_BAR __builtin_amdgcn_s_barrier()
; #define PG8_SCHED __builtin_amdgcn_sched_barrier(0)
; template <class Map, class Epi>
; DI void gemm_phase(LAS unsigned char* lds, const Map& MP, const Epi& E, const int nM, const int nN, const int K, const int lda, const int ldb) {
;     ...
;             PG8_BAR; PG8_WAIT_L(0); PG8_MMA(1, 0, At, B0); PG8_BAR; PG8_SCHED;
;             PG8_STAGE(PG8_SB(0, 1), b2 + hstepB, voffB);
;             PG8_WAIT_V(6); PG8_BAR; PG8_MMA(1, 1, At, B1); PG8_BAR;
;             PG8_LDB(B0, 1, 0); PG8_SCHED; PG8_LDA(At, 1, 0); PG8_STAGE(PG8_SA(0, 1), a2 + hstepA, voffA);
;             PG8_WAIT_L(8); PG8_BAR; PG8_WAIT_L(0); PG8_MMA(0, 0, At, B0); PG8_BAR; PG8_SCHED;
;             PG8_LDB(B1, 1, 1); PG8_STAGE(PG8_SB(1, 0), b3, voffB);
;             PG8_BAR; PG8_WAIT_L(0); PG8_MMA(0, 1, At, B1); PG8_BAR;
;             PG8_LDA(At, 1, 1); PG8_STAGE(PG8_SA(1, 0), a3, voffA);
	s_setprio 0
	s_add_u32 s54, s22, 0x80000
	s_addc_u32 s55, s23, 0
	s_add_i32 s56, s45, s29
	s_mov_b32 m0, s56
	s_nop 0
	global_load_lds_dwordx4 v132, s[54:55]
	s_add_i32 m0, s56, 0x2000
	s_nop 0
	global_load_lds_dwordx4 v128, s[54:55]
	s_waitcnt vmcnt(6)
	s_setprio 1
	s_barrier
	v_mfma_f32_16x16x32_bf16 v[44:47], v[202:205], v[166:169], v[44:47]
	v_mfma_f32_16x16x32_bf16 v[40:43], v[210:213], v[166:169], v[40:43]
	s_add_i32 s54, 0, 0x18000
	v_add_u32_e32 v162, s54, v146
	ds_read_b128 v[150:153], v162
	v_mfma_f32_16x16x32_bf16 v[28:31], v[202:205], v[174:177], v[28:31]
	v_mfma_f32_16x16x32_bf16 v[24:27], v[210:213], v[174:177], v[24:27]
	ds_read_b128 v[154:157], v162 offset:1024
	v_mfma_f32_16x16x32_bf16 v[12:15], v[202:205], v[182:185], v[12:15]
	v_mfma_f32_16x16x32_bf16 v[8:11], v[210:213], v[182:185], v[8:11]
	ds_read_b128 v[158:161], v162 offset:2048
	v_mfma_f32_16x16x32_bf16 v[4:7], v[202:205], v[190:193], v[4:7]
	v_mfma_f32_16x16x32_bf16 v[0:3], v[210:213], v[190:193], v[0:3]
	ds_read_b128 v[162:165], v162 offset:3072
	v_mfma_f32_16x16x32_bf16 v[44:47], v[206:209], v[170:173], v[44:47]
	v_mfma_f32_16x16x32_bf16 v[40:43], v[214:217], v[170:173], v[40:43]
	v_mfma_f32_16x16x32_bf16 v[28:31], v[206:209], v[178:181], v[28:31]
	v_mfma_f32_16x16x32_bf16 v[24:27], v[214:217], v[178:181], v[24:27]
	v_mfma_f32_16x16x32_bf16 v[12:15], v[206:209], v[186:189], v[12:15]
	v_mfma_f32_16x16x32_bf16 v[8:11], v[214:217], v[186:189], v[8:11]
	v_mfma_f32_16x16x32_bf16 v[4:7], v[206:209], v[198:201], v[4:7]
	v_mfma_f32_16x16x32_bf16 v[0:3], v[214:217], v[198:201], v[0:3]
	s_barrier
	s_setprio 0
	s_add_u32 s24, s24, 0x80000
	s_addc_u32 s25, s25, 0
	s_mov_b32 m0, s34
	ds_read_b128 v[166:169], v148 offset:32768
	ds_read_b128 v[170:173], v148 offset:33792
	ds_read_b128 v[174:177], v148 offset:34816
	ds_read_b128 v[178:181], v148 offset:35840
	ds_read_b128 v[182:185], v148 offset:36864
	ds_read_b128 v[186:189], v148 offset:37888
	ds_read_b128 v[190:193], v148 offset:38912
	ds_read_b128 v[198:201], v148 offset:39936
	global_load_lds_dwordx4 v134, s[24:25]
	s_mov_b32 m0, s35
	s_nop 0
	global_load_lds_dwordx4 v130, s[24:25]
	s_waitcnt lgkmcnt(8)
	s_setprio 1
	s_barrier
	s_waitcnt lgkmcnt(7)
	v_mfma_f32_16x16x32_bf16 v[124:127], v[150:153], v[166:169], v[124:127]
	v_mfma_f32_16x16x32_bf16 v[120:123], v[158:161], v[166:169], v[120:123]
	s_waitcnt lgkmcnt(5)
	v_mfma_f32_16x16x32_bf16 v[116:119], v[150:153], v[174:177], v[116:119]
	v_mfma_f32_16x16x32_bf16 v[112:115], v[158:161], v[174:177], v[112:115]
	s_waitcnt lgkmcnt(3)
	v_mfma_f32_16x16x32_bf16 v[100:103], v[150:153], v[182:185], v[100:103]
	v_mfma_f32_16x16x32_bf16 v[96:99], v[158:161], v[182:185], v[96:99]
	s_waitcnt lgkmcnt(1)
	v_mfma_f32_16x16x32_bf16 v[84:87], v[150:153], v[190:193], v[84:87]
	v_mfma_f32_16x16x32_bf16 v[80:83], v[158:161], v[190:193], v[80:83]
	v_mfma_f32_16x16x32_bf16 v[124:127], v[154:157], v[170:173], v[124:127]
	v_mfma_f32_16x16x32_bf16 v[120:123], v[162:165], v[170:173], v[120:123]
	v_mfma_f32_16x16x32_bf16 v[116:119], v[154:157], v[178:181], v[116:119]
	v_mfma_f32_16x16x32_bf16 v[112:115], v[162:165], v[178:181], v[112:115]
	v_mfma_f32_16x16x32_bf16 v[100:103], v[154:157], v[186:189], v[100:103]
	v_mfma_f32_16x16x32_bf16 v[96:99], v[162:165], v[186:189], v[96:99]
	s_waitcnt lgkmcnt(0)
	v_mfma_f32_16x16x32_bf16 v[84:87], v[154:157], v[198:201], v[84:87]
	v_mfma_f32_16x16x32_bf16 v[80:83], v[162:165], v[198:201], v[80:83]
	s_barrier
	s_setprio 0
	s_add_i32 s24, 0, 0x1c000
	s_add_i32 s25, s54, s29
	v_add_u32_e32 v196, s24, v146
	v_lshl_add_u64 v[194:195], v[194:195], 0, s[8:9]
	s_mov_b32 m0, s25
	ds_read_b128 v[202:205], v196
	ds_read_b128 v[206:209], v196 offset:1024
	ds_read_b128 v[210:213], v196 offset:2048
	ds_read_b128 v[214:217], v196 offset:3072
	global_load_lds_dwordx4 v[194:195], off
	v_lshl_add_u64 v[194:195], v[218:219], 0, s[8:9]
	s_add_i32 m0, s25, 0x2000
	s_nop 0
	global_load_lds_dwordx4 v[194:195], off
	s_setprio 1
	s_barrier
	s_waitcnt lgkmcnt(3)
	v_mfma_f32_16x16x32_bf16 v[108:111], v[202:205], v[166:169], v[108:111]
	s_waitcnt lgkmcnt(1)
	v_mfma_f32_16x16x32_bf16 v[104:107], v[210:213], v[166:169], v[104:107]
	v_mfma_f32_16x16x32_bf16 v[92:95], v[202:205], v[174:177], v[92:95]
	v_mfma_f32_16x16x32_bf16 v[88:91], v[210:213], v[174:177], v[88:91]
	v_mfma_f32_16x16x32_bf16 v[76:79], v[202:205], v[182:185], v[76:79]
	v_mfma_f32_16x16x32_bf16 v[72:75], v[210:213], v[182:185], v[72:75]
	v_mfma_f32_16x16x32_bf16 v[68:71], v[202:205], v[190:193], v[68:71]
	v_mfma_f32_16x16x32_bf16 v[64:67], v[210:213], v[190:193], v[64:67]
	v_mfma_f32_16x16x32_bf16 v[108:111], v[206:209], v[170:173], v[108:111]
	s_mov_b32 m0, s39
	s_waitcnt lgkmcnt(0)
	v_mfma_f32_16x16x32_bf16 v[104:107], v[214:217], v[170:173], v[104:107]
	v_lshl_add_u64 v[194:195], v[220:221], 0, s[8:9]
	v_mfma_f32_16x16x32_bf16 v[92:95], v[206:209], v[178:181], v[92:95]
	v_mfma_f32_16x16x32_bf16 v[88:91], v[214:217], v[178:181], v[88:91]
	v_mfma_f32_16x16x32_bf16 v[76:79], v[206:209], v[186:189], v[76:79]
	v_mfma_f32_16x16x32_bf16 v[72:75], v[214:217], v[186:189], v[72:75]
	v_mfma_f32_16x16x32_bf16 v[68:71], v[206:209], v[198:201], v[68:71]
	v_mfma_f32_16x16x32_bf16 v[64:67], v[214:217], v[198:201], v[64:67]
	s_barrier
	s_setprio 0
	ds_read_b128 v[166:169], v148 offset:49152
	ds_read_b128 v[170:173], v148 offset:50176
	ds_read_b128 v[174:177], v148 offset:51200
	ds_read_b128 v[178:181], v148 offset:52224
	ds_read_b128 v[182:185], v148 offset:53248
	ds_read_b128 v[186:189], v148 offset:54272
	ds_read_b128 v[190:193], v148 offset:55296
	ds_read_b128 v[198:201], v148 offset:56320
	global_load_lds_dwordx4 v[194:195], off
	v_lshl_add_u64 v[194:195], v[222:223], 0, s[8:9]
	s_mov_b32 m0, s42
	s_nop 0
	global_load_lds_dwordx4 v[194:195], off
	s_waitcnt vmcnt(10)
	s_setprio 1
	s_barrier
; #define PG8_STAGE(bufoff, gbase, voff) do { _Pragma("unroll") for (int _i = 0; _i < 2; ++_i) \
;         __builtin_amdgcn_global_load_lds((const unsigned*)((const char*)(gbase) + (voff)[_i]), (LAS unsigned*)(lds + (bufoff) + ldsw + _i * 8192), 16, 0, 0); } while (0)
; #define PG8_LDA(dst, b, h) do { _Pragma("unroll") for (int m = 0; m < 4; ++m) _Pragma("unroll") for (int k = 0; k < 2; ++k) dst[m][k] = *(const LAS bf16x8*)(lds + PG8_SA(b, h) + aoff + m * 2048 + k * 1024); } while (0)
; #define PG8_MMA(ai, bj, At, Bt) do { __builtin_amdgcn_s_setprio(1); _Pragma("unroll") for (int m = 0; m < 4; ++m) _Pragma("unroll") for (int n = 0; n < 2; ++n) _Pragma("unroll") for (int k = 0; k < 2; ++k) \
;         acc[ai][bj][m][n] = __builtin_amdgcn_mfma_f32_16x16x32_bf16(Bt[n][k], At[m][k], acc[ai][bj][m][n], 0, 0, 0); __builtin_amdgcn_s_setprio(0); } while (0)
; #define PG8_WAIT_V(n) asm volatile("s_waitcnt vmcnt(" #n ")" ::: "memory")
; #define PG8_WAIT_L(n) asm volatile("s_waitcnt lgkmcnt(" #n ")" ::: "memory")
; #define PG8_BAR __builtin_amdgcn_s_barrier()
; #define PG8_SCHED __builtin_amdgcn_sched_barrier(0)
; template <class Map, class Epi>
; DI void gemm_phase(LAS unsigned char* lds, const Map& MP, const Epi& E, const int nM, const int nN, const int K, const int lda, const int ldb) {
;     ...
;             PG8_LDA(At, 1, 1); PG8_STAGE(PG8_SA(1, 0), a3, voffA);
;             PG8_BAR; PG8_WAIT_L(0); PG8_MMA(1, 0, At, B0); PG8_BAR; PG8_SCHED;
;             PG8_STAGE(PG8_SB(1, 1), b3 + hstepB, voffB);
;             PG8_WAIT_V(6); PG8_BAR; PG8_MMA(1, 1, At, B1); PG8_BAR;
	s_waitcnt lgkmcnt(7)
	v_mfma_f32_16x16x32_bf16 v[60:63], v[150:153], v[166:169], v[60:63]
	v_mfma_f32_16x16x32_bf16 v[56:59], v[158:161], v[166:169], v[56:59]
	s_waitcnt lgkmcnt(5)
	v_mfma_f32_16x16x32_bf16 v[52:55], v[150:153], v[174:177], v[52:55]
	v_mfma_f32_16x16x32_bf16 v[48:51], v[158:161], v[174:177], v[48:51]
	s_waitcnt lgkmcnt(3)
	v_mfma_f32_16x16x32_bf16 v[36:39], v[150:153], v[182:185], v[36:39]
	v_mfma_f32_16x16x32_bf16 v[32:35], v[158:161], v[182:185], v[32:35]
	s_waitcnt lgkmcnt(1)
	v_mfma_f32_16x16x32_bf16 v[20:23], v[150:153], v[190:193], v[20:23]
	v_mfma_f32_16x16x32_bf16 v[16:19], v[158:161], v[190:193], v[16:19]
	v_mfma_f32_16x16x32_bf16 v[60:63], v[154:157], v[170:173], v[60:63]
	v_mfma_f32_16x16x32_bf16 v[56:59], v[162:165], v[170:173], v[56:59]
	v_mfma_f32_16x16x32_bf16 v[52:55], v[154:157], v[178:181], v[52:55]
	v_mfma_f32_16x16x32_bf16 v[48:51], v[162:165], v[178:181], v[48:51]
	v_mfma_f32_16x16x32_bf16 v[36:39], v[154:157], v[186:189], v[36:39]
	v_mfma_f32_16x16x32_bf16 v[32:35], v[162:165], v[186:189], v[32:35]
	s_waitcnt lgkmcnt(0)
	v_mfma_f32_16x16x32_bf16 v[20:23], v[154:157], v[198:201], v[20:23]
	v_mfma_f32_16x16x32_bf16 v[16:19], v[162:165], v[198:201], v[16:19]
	s_barrier
	s_setprio 0
	s_add_u32 s22, s22, 0x80080
	s_addc_u32 s23, s23, 0
	s_add_i32 s24, s24, s29
	s_mov_b32 m0, s24
	s_nop 0
	global_load_lds_dwordx4 v132, s[22:23]
	s_add_i32 m0, s24, 0x2000
	s_nop 0
	global_load_lds_dwordx4 v128, s[22:23]
	s_waitcnt vmcnt(6)
	s_setprio 1
	s_barrier
	v_mfma_f32_16x16x32_bf16 v[44:47], v[202:205], v[166:169], v[44:47]
	v_mfma_f32_16x16x32_bf16 v[40:43], v[210:213], v[166:169], v[40:43]
	ds_read_b128 v[150:153], v147
	v_mfma_f32_16x16x32_bf16 v[28:31], v[202:205], v[174:177], v[28:31]
	v_mfma_f32_16x16x32_bf16 v[24:27], v[210:213], v[174:177], v[24:27]
	ds_read_b128 v[154:157], v147 offset:1024
	v_mfma_f32_16x16x32_bf16 v[12:15], v[202:205], v[182:185], v[12:15]
	v_mfma_f32_16x16x32_bf16 v[8:11], v[210:213], v[182:185], v[8:11]
	ds_read_b128 v[158:161], v147 offset:2048
	v_mfma_f32_16x16x32_bf16 v[4:7], v[202:205], v[190:193], v[4:7]
	v_mfma_f32_16x16x32_bf16 v[0:3], v[210:213], v[190:193], v[0:3]
	ds_read_b128 v[162:165], v147 offset:3072
	v_mfma_f32_16x16x32_bf16 v[44:47], v[206:209], v[170:173], v[44:47]
	s_add_i32 s3, s3, 2
	v_mfma_f32_16x16x32_bf16 v[40:43], v[214:217], v[170:173], v[40:43]
	s_add_u32 s52, s52, 0x100
	s_addc_u32 s53, s53, 0
	v_mfma_f32_16x16x32_bf16 v[28:31], v[206:209], v[178:181], v[28:31]
	s_add_u32 s20, s20, 0x100
	s_addc_u32 s21, s21, 0
	v_mfma_f32_16x16x32_bf16 v[24:27], v[214:217], v[178:181], v[24:27]
	s_cmp_gt_u32 s3, 29
	v_mfma_f32_16x16x32_bf16 v[12:15], v[206:209], v[186:189], v[12:15]
	v_mfma_f32_16x16x32_bf16 v[8:11], v[214:217], v[186:189], v[8:11]
	v_mfma_f32_16x16x32_bf16 v[4:7], v[206:209], v[198:201], v[4:7]
	v_mfma_f32_16x16x32_bf16 v[0:3], v[214:217], v[198:201], v[0:3]
	s_barrier
	s_setprio 0
	s_cbranch_scc0 .LBB1_1382
; DI unsigned pack2(float a, float b) { f32x2 v = {a, b}; hwbf16x2 r = __builtin_convertvector(v, hwbf16x2); return __builtin_bit_cast(unsigned, r); }
;     DI const char* a(const Unit& u) const { return (const char*)(A + (size_t)u.pm * BM * lda); }
;     DI const char* a(const Unit& u) const { return (const char*)(A + (size_t)u.pm * BM * 2048 + (u.pn >> 1) * 512); }
;     DI const char* a(const Unit& u) const { return (const char*)((u.pn < 12 ? A1 : A2) + (size_t)u.pm * BM * 512); }
; #define PG8_WAIT_V(n) asm volatile("s_waitcnt vmcnt(" #n ")" ::: "memory")
; #define PG8_BAR __builtin_amdgcn_s_barrier()
;     DI void operator()(const f32x4 (&acc)[2][2][4][2], const Unit& u, int wr, int wc, int fr, int fq) const {
;         bf16_t* O = O1; int ldc = ldc1, pn = u.pn; if (pn >= split) { O = O2; ldc = ldc2; pn -= split; }
;         const int row0 = u.pm * BM + wr * 64 + fr, col0 = pn * BM + wc * 32 + 8 * fq;
; #pragma unroll
;         for (int ai = 0; ai < 2; ++ai)
; #pragma unroll
;             for (int m = 0; m < 4; ++m) { bf16_t* rowp = O + (size_t)(row0 + ai * HALF + m * 16) * ldc + col0;
; #pragma unroll
;                 for (int bj = 0; bj < 2; ++bj) { const f32x4 v0 = acc[ai][bj][m][0], v1 = acc[ai][bj][m][1];
;                     u32x4 o; o[0] = pack2(v0[0], v0[1]); o[1] = pack2(v0[2], v0[3]); o[2] = pack2(v1[0], v1[1]); o[3] = pack2(v1[2], v1[3]);
;                     *(u32x4*)(rowp + bj * HALF) = o; } }
;     }
; template <class Map, class Epi>
; DI void gemm_phase(LAS unsigned char* lds, const Map& MP, const Epi& E, const int nM, const int nN, const int K, const int lda, const int ldb) {
;     ...
;         if (!has_next) break;
; #pragma unroll
;         for (int a = 0; a < 2; ++a)
; #pragma unroll
;             for (int b = 0; b < 2; ++b)
; #pragma unroll
;                 for (int m = 0; m < 4; ++m)
; #pragma unroll
;                     for (int n = 0; n < 2; ++n) acc[a][b][m][n] = (f32x4){0.f, 0.f, 0.f, 0.f};
;         cur = nxt; cA = nA; cB = nB; ++ui;
;     }
;     PG8_WAIT_V(0);
;     if (wr == 0) PG8_BAR;
;     PG8_BAR;
	s_waitcnt lgkmcnt(0)
	s_lshl_b32 s3, s10, 8
	v_mov_b32_e32 v150, v144
	v_mov_b32_e32 v151, v145
	s_add_i32 s3, s3, s37
	v_cvt_pk_bf16_f32 v68, v68, v69
	v_add_u32_e32 v154, s3, v150
	s_lshl_b32 s3, s47, 8
	s_or_b32 s3, s3, s38
	v_lshl_add_u32 v150, v151, 3, s3
	v_ashrrev_i32_e32 v151, 31, v150
	v_lshl_add_u64 v[150:151], v[150:151], 1, s[6:7]
	v_cvt_pk_bf16_f32 v69, v70, v71
	v_cvt_pk_bf16_f32 v70, v64, v65
	v_add_u32_e32 v64, 0x80, v154
	v_mad_i64_i32 v[152:153], s[20:21], v154, s46, v[150:151]
	v_cvt_pk_bf16_f32 v108, v108, v109
	v_cvt_pk_bf16_f32 v109, v110, v111
	v_cvt_pk_bf16_f32 v110, v104, v105
	v_cvt_pk_bf16_f32 v111, v106, v107
	v_add_u32_e32 v104, 16, v154
	v_mad_i64_i32 v[64:65], s[20:21], v64, s46, v[150:151]
	v_cvt_pk_bf16_f32 v44, v44, v45
	v_cvt_pk_bf16_f32 v45, v46, v47
	v_cvt_pk_bf16_f32 v46, v40, v41
	v_cvt_pk_bf16_f32 v47, v42, v43
	v_add_u32_e32 v40, 0x90, v154
	global_store_dwordx4 v[152:153], v[108:111], off offset:256
	v_cvt_pk_bf16_f32 v92, v92, v93
	v_cvt_pk_bf16_f32 v93, v94, v95
	v_mad_i64_i32 v[108:109], s[20:21], v104, s46, v[150:151]
	v_cvt_pk_bf16_f32 v94, v88, v89
	v_cvt_pk_bf16_f32 v95, v90, v91
	v_add_u32_e32 v88, 32, v154
	global_store_dwordx4 v[64:65], v[44:47], off offset:256
	v_cvt_pk_bf16_f32 v28, v28, v29
	v_cvt_pk_bf16_f32 v29, v30, v31
	v_mad_i64_i32 v[44:45], s[20:21], v40, s46, v[150:151]
	v_cvt_pk_bf16_f32 v30, v24, v25
	v_cvt_pk_bf16_f32 v31, v26, v27
	v_add_u32_e32 v24, 0xa0, v154
	global_store_dwordx4 v[108:109], v[92:95], off offset:256
	v_cvt_pk_bf16_f32 v76, v76, v77
	v_cvt_pk_bf16_f32 v77, v78, v79
	v_mad_i64_i32 v[92:93], s[20:21], v88, s46, v[150:151]
	v_cvt_pk_bf16_f32 v78, v72, v73
	v_cvt_pk_bf16_f32 v79, v74, v75
	v_add_u32_e32 v72, 48, v154
	global_store_dwordx4 v[44:45], v[28:31], off offset:256
	v_cvt_pk_bf16_f32 v12, v12, v13
	v_cvt_pk_bf16_f32 v13, v14, v15
	v_mad_i64_i32 v[28:29], s[20:21], v24, s46, v[150:151]
	v_cvt_pk_bf16_f32 v14, v8, v9
	v_cvt_pk_bf16_f32 v15, v10, v11
	v_add_u32_e32 v8, 0xb0, v154
	global_store_dwordx4 v[92:93], v[76:79], off offset:256
	global_store_dwordx4 v[28:29], v[12:15], off offset:256
	v_cvt_pk_bf16_f32 v124, v124, v125
	v_mad_i64_i32 v[76:77], s[20:21], v72, s46, v[150:151]
	v_mad_i64_i32 v[12:13], s[20:21], v8, s46, v[150:151]
	v_cvt_pk_bf16_f32 v125, v126, v127
	v_cvt_pk_bf16_f32 v126, v120, v121
	v_cvt_pk_bf16_f32 v127, v122, v123
	v_cvt_pk_bf16_f32 v104, v116, v117
	v_cvt_pk_bf16_f32 v105, v118, v119
	v_cvt_pk_bf16_f32 v106, v112, v113
	v_cvt_pk_bf16_f32 v107, v114, v115
	v_cvt_pk_bf16_f32 v88, v100, v101
	v_cvt_pk_bf16_f32 v89, v102, v103
	v_cvt_pk_bf16_f32 v90, v96, v97
	v_cvt_pk_bf16_f32 v91, v98, v99
	v_cvt_pk_bf16_f32 v72, v84, v85
	v_cvt_pk_bf16_f32 v73, v86, v87
	v_cvt_pk_bf16_f32 v74, v80, v81
	v_cvt_pk_bf16_f32 v75, v82, v83
	v_cvt_pk_bf16_f32 v71, v66, v67
	v_cvt_pk_bf16_f32 v60, v60, v61
	v_cvt_pk_bf16_f32 v61, v62, v63
	v_cvt_pk_bf16_f32 v62, v56, v57
	v_cvt_pk_bf16_f32 v63, v58, v59
	v_cvt_pk_bf16_f32 v40, v52, v53
	v_cvt_pk_bf16_f32 v41, v54, v55
	v_cvt_pk_bf16_f32 v42, v48, v49
	v_cvt_pk_bf16_f32 v43, v50, v51
	v_cvt_pk_bf16_f32 v24, v36, v37
	v_cvt_pk_bf16_f32 v25, v38, v39
	v_cvt_pk_bf16_f32 v26, v32, v33
	v_cvt_pk_bf16_f32 v27, v34, v35
	v_cvt_pk_bf16_f32 v8, v20, v21
	v_cvt_pk_bf16_f32 v9, v22, v23
	v_cvt_pk_bf16_f32 v10, v16, v17
	v_cvt_pk_bf16_f32 v11, v18, v19
	v_cvt_pk_bf16_f32 v4, v4, v5
	v_cvt_pk_bf16_f32 v5, v6, v7
	v_cvt_pk_bf16_f32 v6, v0, v1
	v_cvt_pk_bf16_f32 v7, v2, v3
	s_and_b64 vcc, exec, s[40:41]
	s_mov_b32 s47, s12
	s_mov_b32 s10, s14
	s_mov_b64 s[20:21], s[18:19]
	s_mov_b64 s[22:23], s[16:17]
	global_store_dwordx4 v[152:153], v[124:127], off
	global_store_dwordx4 v[108:109], v[104:107], off
	global_store_dwordx4 v[92:93], v[88:91], off
	global_store_dwordx4 v[76:77], v[72:75], off
	global_store_dwordx4 v[76:77], v[68:71], off offset:256
	global_store_dwordx4 v[64:65], v[60:63], off
	global_store_dwordx4 v[44:45], v[40:43], off
	global_store_dwordx4 v[28:29], v[24:27], off
	global_store_dwordx4 v[12:13], v[8:11], off
	global_store_dwordx4 v[12:13], v[4:7], off offset:256
	s_cbranch_vccz .LBB1_1379
	s_waitcnt vmcnt(0)
	s_cmpk_gt_u32 s4, 0xff
	s_cbranch_scc1 .LBB1_1386
	s_barrier

; #define PG8_STAGE(bufoff, gbase, voff) do { _Pragma("unroll") for (int _i = 0; _i < 2; ++_i) \
;         __builtin_amdgcn_global_load_lds((const unsigned*)((const char*)(gbase) + (voff)[_i]), (LAS unsigned*)(lds + (bufoff) + ldsw + _i * 8192), 16, 0, 0); } while (0)
; #define PG8_LDA(dst, b, h) do { _Pragma("unroll") for (int m = 0; m < 4; ++m) _Pragma("unroll") for (int k = 0; k < 2; ++k) dst[m][k] = *(const LAS bf16x8*)(lds + PG8_SA(b, h) + aoff + m * 2048 + k * 1024); } while (0)
; #define PG8_LDB(dst, b, h) do { _Pragma("unroll") for (int n = 0; n < 2; ++n) _Pragma("unroll") for (int k = 0; k < 2; ++k) dst[n][k] = *(const LAS bf16x8*)(lds + PG8_SB(b, h) + boff + n * 2048 + k * 1024); } while (0)
; #define PG8_MMA(ai, bj, At, Bt) do { __builtin_amdgcn_s_setprio(1); _Pragma("unroll") for (int m = 0; m < 4; ++m) _Pragma("unroll") for (int n = 0; n < 2; ++n) _Pragma("unroll") for (int k = 0; k < 2; ++k) \
;         acc[ai][bj][m][n] = __builtin_amdgcn_mfma_f32_16x16x32_bf16(Bt[n][k], At[m][k], acc[ai][bj][m][n], 0, 0, 0); __builtin_amdgcn_s_setprio(0); } while (0)
; #define PG8_WAIT_V(n) asm volatile("s_waitcnt vmcnt(" #n ")" ::: "memory")
; #define PG8_WAIT_L(n) asm volatile("s_waitcnt lgkmcnt(" #n ")" ::: "memory")
; template <class Map, class Epi>
; DI void gemm_phase(LAS unsigned char* lds, const Map& MP, const Epi& E, const int nM, const int nN, const int K, const int lda, const int ldb) {
;     ...
;         for (int t = 0; t < nt; t += 2) {
;             const bool last = (t == nt - 2);
;             const char* a1 = cA + (size_t)(t + 1) * kstep;
;             const char* a2 = last ? nA : cA + (size_t)(t + 2) * kstep; const char* b2 = last ? nB : cB + (size_t)(t + 2) * kstep;
;             const char* a3 = a2 + kstep; const char* b3 = b2 + kstep;
;             PG8_LDB(B0, 0, 0); PG8_SCHED; PG8_LDA(At, 0, 0); PG8_STAGE(PG8_SA(1, 1), a1 + hstepA, voffA);
;             PG8_WAIT_L(8); PG8_BAR; PG8_WAIT_L(0); PG8_MMA(0, 0, At, B0); PG8_BAR; PG8_SCHED;
;             PG8_LDB(B1, 0, 1); PG8_STAGE(PG8_SB(0, 0), b2, voffB);
;             PG8_BAR; PG8_WAIT_L(0); PG8_MMA(0, 1, At, B1); PG8_BAR;
;             PG8_LDA(At, 0, 1); PG8_STAGE(PG8_SA(0, 0), a2, voffA);
;             PG8_BAR; PG8_WAIT_L(0); PG8_MMA(1, 0, At, B0); PG8_BAR; PG8_SCHED;
;             PG8_STAGE(PG8_SB(0, 1), b2 + hstepB, voffB);
;             PG8_WAIT_V(6); PG8_BAR; PG8_MMA(1, 1, At, B1); PG8_BAR;
.LBB1_1529:
	s_add_u32 s20, s18, 0xfffe0080
	s_addc_u32 s21, s19, -1
	s_cmp_eq_u32 s3, 4
	s_cselect_b32 s23, s13, s21
	s_cselect_b32 s22, s52, s20
	s_cselect_b32 s21, s53, s56
	s_cselect_b32 s20, s54, s55
	s_add_i32 m0, s11, 0xc000
	ds_read_b128 v[166:169], v148
	ds_read_b128 v[170:173], v148 offset:1024
	ds_read_b128 v[174:177], v148 offset:2048
	ds_read_b128 v[178:181], v148 offset:3072
	ds_read_b128 v[182:185], v148 offset:4096
	ds_read_b128 v[186:189], v148 offset:5120
	ds_read_b128 v[190:193], v148 offset:6144
	ds_read_b128 v[198:201], v148 offset:7168
	global_load_lds_dwordx4 v138, s[18:19]
	s_add_i32 m0, s11, 0xe000
	s_nop 0
	global_load_lds_dwordx4 v136, s[18:19]
	s_waitcnt lgkmcnt(8)
	s_setprio 1
	s_barrier
	s_waitcnt lgkmcnt(7)
	v_mfma_f32_16x16x32_bf16 v[124:127], v[150:153], v[166:169], v[124:127]
	v_mfma_f32_16x16x32_bf16 v[120:123], v[158:161], v[166:169], v[120:123]
	s_waitcnt lgkmcnt(5)
	v_mfma_f32_16x16x32_bf16 v[116:119], v[150:153], v[174:177], v[116:119]
	v_mfma_f32_16x16x32_bf16 v[112:115], v[158:161], v[174:177], v[112:115]
	s_waitcnt lgkmcnt(3)
	v_mfma_f32_16x16x32_bf16 v[100:103], v[150:153], v[182:185], v[100:103]
	v_mfma_f32_16x16x32_bf16 v[96:99], v[158:161], v[182:185], v[96:99]
	s_waitcnt lgkmcnt(1)
	v_mfma_f32_16x16x32_bf16 v[84:87], v[150:153], v[190:193], v[84:87]
	v_mfma_f32_16x16x32_bf16 v[80:83], v[158:161], v[190:193], v[80:83]
	v_mfma_f32_16x16x32_bf16 v[124:127], v[154:157], v[170:173], v[124:127]
	v_mfma_f32_16x16x32_bf16 v[120:123], v[162:165], v[170:173], v[120:123]
	v_mfma_f32_16x16x32_bf16 v[116:119], v[154:157], v[178:181], v[116:119]
	v_mfma_f32_16x16x32_bf16 v[112:115], v[162:165], v[178:181], v[112:115]
	v_mfma_f32_16x16x32_bf16 v[100:103], v[154:157], v[186:189], v[100:103]
	v_mfma_f32_16x16x32_bf16 v[96:99], v[162:165], v[186:189], v[96:99]
	s_waitcnt lgkmcnt(0)
	v_mfma_f32_16x16x32_bf16 v[84:87], v[154:157], v[198:201], v[84:87]
	v_mfma_f32_16x16x32_bf16 v[80:83], v[162:165], v[198:201], v[80:83]
	s_barrier
	s_setprio 0
	s_add_i32 s57, s47, s31
	v_lshl_add_u64 v[194:195], s[20:21], 0, v[132:133]
	s_mov_b32 m0, s57
	ds_read_b128 v[202:205], v149
	ds_read_b128 v[206:209], v149 offset:1024
	ds_read_b128 v[210:213], v149 offset:2048
	ds_read_b128 v[214:217], v149 offset:3072
	global_load_lds_dwordx4 v[194:195], off
	v_lshl_add_u64 v[218:219], s[20:21], 0, v[128:129]
	s_add_i32 m0, s57, 0x2000
	s_nop 0
	global_load_lds_dwordx4 v[218:219], off
	s_setprio 1
	s_barrier
	s_waitcnt lgkmcnt(3)
	v_mfma_f32_16x16x32_bf16 v[108:111], v[202:205], v[166:169], v[108:111]
	s_waitcnt lgkmcnt(1)
	v_mfma_f32_16x16x32_bf16 v[104:107], v[210:213], v[166:169], v[104:107]
	v_mfma_f32_16x16x32_bf16 v[92:95], v[202:205], v[174:177], v[92:95]
	v_mfma_f32_16x16x32_bf16 v[88:91], v[210:213], v[174:177], v[88:91]
	v_mfma_f32_16x16x32_bf16 v[76:79], v[202:205], v[182:185], v[76:79]
	v_mfma_f32_16x16x32_bf16 v[72:75], v[210:213], v[182:185], v[72:75]
	v_mfma_f32_16x16x32_bf16 v[68:71], v[202:205], v[190:193], v[68:71]
	v_mfma_f32_16x16x32_bf16 v[64:67], v[210:213], v[190:193], v[64:67]
	v_mfma_f32_16x16x32_bf16 v[108:111], v[206:209], v[170:173], v[108:111]
	s_mov_b32 m0, s11
	s_waitcnt lgkmcnt(0)
	v_mfma_f32_16x16x32_bf16 v[104:107], v[214:217], v[170:173], v[104:107]
	v_lshl_add_u64 v[220:221], s[22:23], 0, v[134:135]
	v_mfma_f32_16x16x32_bf16 v[92:95], v[206:209], v[178:181], v[92:95]
	v_mfma_f32_16x16x32_bf16 v[88:91], v[214:217], v[178:181], v[88:91]
	v_mfma_f32_16x16x32_bf16 v[76:79], v[206:209], v[186:189], v[76:79]
	v_mfma_f32_16x16x32_bf16 v[72:75], v[214:217], v[186:189], v[72:75]
	v_mfma_f32_16x16x32_bf16 v[68:71], v[206:209], v[198:201], v[68:71]
	v_mfma_f32_16x16x32_bf16 v[64:67], v[214:217], v[198:201], v[64:67]
	s_barrier
	s_setprio 0
	ds_read_b128 v[166:169], v148 offset:16384
	ds_read_b128 v[170:173], v148 offset:17408
	ds_read_b128 v[174:177], v148 offset:18432
	ds_read_b128 v[178:181], v148 offset:19456
	ds_read_b128 v[182:185], v148 offset:20480
	ds_read_b128 v[186:189], v148 offset:21504
	ds_read_b128 v[190:193], v148 offset:22528
	ds_read_b128 v[198:201], v148 offset:23552
	global_load_lds_dwordx4 v[220:221], off
	v_lshl_add_u64 v[222:223], s[22:23], 0, v[130:131]
	s_mov_b32 m0, s35
	s_nop 0
	global_load_lds_dwordx4 v[222:223], off
	s_waitcnt vmcnt(10)
	s_setprio 1
	s_barrier
	s_waitcnt lgkmcnt(7)
	v_mfma_f32_16x16x32_bf16 v[60:63], v[150:153], v[166:169], v[60:63]
	v_mfma_f32_16x16x32_bf16 v[56:59], v[158:161], v[166:169], v[56:59]
	s_waitcnt lgkmcnt(5)
	v_mfma_f32_16x16x32_bf16 v[52:55], v[150:153], v[174:177], v[52:55]
	v_mfma_f32_16x16x32_bf16 v[48:51], v[158:161], v[174:177], v[48:51]
	s_waitcnt lgkmcnt(3)
	v_mfma_f32_16x16x32_bf16 v[36:39], v[150:153], v[182:185], v[36:39]
	v_mfma_f32_16x16x32_bf16 v[32:35], v[158:161], v[182:185], v[32:35]
	s_waitcnt lgkmcnt(1)
	v_mfma_f32_16x16x32_bf16 v[20:23], v[150:153], v[190:193], v[20:23]
	v_mfma_f32_16x16x32_bf16 v[16:19], v[158:161], v[190:193], v[16:19]
	v_mfma_f32_16x16x32_bf16 v[60:63], v[154:157], v[170:173], v[60:63]
	v_mfma_f32_16x16x32_bf16 v[56:59], v[162:165], v[170:173], v[56:59]
	v_mfma_f32_16x16x32_bf16 v[52:55], v[154:157], v[178:181], v[52:55]
	v_mfma_f32_16x16x32_bf16 v[48:51], v[162:165], v[178:181], v[48:51]
	v_mfma_f32_16x16x32_bf16 v[36:39], v[154:157], v[186:189], v[36:39]
	v_mfma_f32_16x16x32_bf16 v[32:35], v[162:165], v[186:189], v[32:35]
	s_waitcnt lgkmcnt(0)
	v_mfma_f32_16x16x32_bf16 v[20:23], v[154:157], v[198:201], v[20:23]
	v_mfma_f32_16x16x32_bf16 v[16:19], v[162:165], v[198:201], v[16:19]
	s_barrier
; #define PG8_STAGE(bufoff, gbase, voff) do { _Pragma("unroll") for (int _i = 0; _i < 2; ++_i) \
;         __builtin_amdgcn_global_load_lds((const unsigned*)((const char*)(gbase) + (voff)[_i]), (LAS unsigned*)(lds + (bufoff) + ldsw + _i * 8192), 16, 0, 0); } while (0)
; #define PG8_LDA(dst, b, h) do { _Pragma("unroll") for (int m = 0; m < 4; ++m) _Pragma("unroll") for (int k = 0; k < 2; ++k) dst[m][k] = *(const LAS bf16x8*)(lds + PG8_SA(b, h) + aoff + m * 2048 + k * 1024); } while (0)
; #define PG8_LDB(dst, b, h) do { _Pragma("unroll") for (int n = 0; n < 2; ++n) _Pragma("unroll") for (int k = 0; k < 2; ++k) dst[n][k] = *(const LAS bf16x8*)(lds + PG8_SB(b, h) + boff + n * 2048 + k * 1024); } while (0)
; #define PG8_MMA(ai, bj, At, Bt) do { __builtin_amdgcn_s_setprio(1); _Pragma("unroll") for (int m = 0; m < 4; ++m) _Pragma("unroll") for (int n = 0; n < 2; ++n) _Pragma("unroll") for (int k = 0; k < 2; ++k) \
;         acc[ai][bj][m][n] = __builtin_amdgcn_mfma_f32_16x16x32_bf16(Bt[n][k], At[m][k], acc[ai][bj][m][n], 0, 0, 0); __builtin_amdgcn_s_setprio(0); } while (0)
; #define PG8_WAIT_V(n) asm volatile("s_waitcnt vmcnt(" #n ")" ::: "memory")
; #define PG8_WAIT_L(n) asm volatile("s_waitcnt lgkmcnt(" #n ")" ::: "memory")
; #define PG8_BAR __builtin_amdgcn_s_barrier()
; #define PG8_SCHED __builtin_amdgcn_sched_barrier(0)
; template <class Map, class Epi>
; DI void gemm_phase(LAS unsigned char* lds, const Map& MP, const Epi& E, const int nM, const int nN, const int K, const int lda, const int ldb) {
;     ...
;             PG8_BAR; PG8_WAIT_L(0); PG8_MMA(1, 0, At, B0); PG8_BAR; PG8_SCHED;
;             PG8_STAGE(PG8_SB(0, 1), b2 + hstepB, voffB);
;             PG8_WAIT_V(6); PG8_BAR; PG8_MMA(1, 1, At, B1); PG8_BAR;
;             PG8_LDB(B0, 1, 0); PG8_SCHED; PG8_LDA(At, 1, 0); PG8_STAGE(PG8_SA(0, 1), a2 + hstepA, voffA);
;             PG8_WAIT_L(8); PG8_BAR; PG8_WAIT_L(0); PG8_MMA(0, 0, At, B0); PG8_BAR; PG8_SCHED;
;             PG8_LDB(B1, 1, 1); PG8_STAGE(PG8_SB(1, 0), b3, voffB);
;             PG8_BAR; PG8_WAIT_L(0); PG8_MMA(0, 1, At, B1); PG8_BAR;
;             PG8_LDA(At, 1, 1); PG8_STAGE(PG8_SA(1, 0), a3, voffA);
	s_setprio 0
	s_add_u32 s58, s20, 0x20000
	s_addc_u32 s59, s21, 0
	s_add_i32 s57, s48, s31
	s_mov_b32 m0, s57
	s_nop 0
	global_load_lds_dwordx4 v132, s[58:59]
	s_add_i32 m0, s57, 0x2000
	s_nop 0
	global_load_lds_dwordx4 v128, s[58:59]
	s_waitcnt vmcnt(6)
	s_setprio 1
	s_barrier
	v_mfma_f32_16x16x32_bf16 v[44:47], v[202:205], v[166:169], v[44:47]
	v_mfma_f32_16x16x32_bf16 v[40:43], v[210:213], v[166:169], v[40:43]
	s_add_i32 s57, 0, 0x18000
	v_add_u32_e32 v162, s57, v146
	ds_read_b128 v[150:153], v162
	v_mfma_f32_16x16x32_bf16 v[28:31], v[202:205], v[174:177], v[28:31]
	v_mfma_f32_16x16x32_bf16 v[24:27], v[210:213], v[174:177], v[24:27]
	ds_read_b128 v[154:157], v162 offset:1024
	v_mfma_f32_16x16x32_bf16 v[12:15], v[202:205], v[182:185], v[12:15]
	v_mfma_f32_16x16x32_bf16 v[8:11], v[210:213], v[182:185], v[8:11]
	ds_read_b128 v[158:161], v162 offset:2048
	v_mfma_f32_16x16x32_bf16 v[4:7], v[202:205], v[190:193], v[4:7]
	v_mfma_f32_16x16x32_bf16 v[0:3], v[210:213], v[190:193], v[0:3]
	ds_read_b128 v[162:165], v162 offset:3072
	v_mfma_f32_16x16x32_bf16 v[44:47], v[206:209], v[170:173], v[44:47]
	v_mfma_f32_16x16x32_bf16 v[40:43], v[214:217], v[170:173], v[40:43]
	v_mfma_f32_16x16x32_bf16 v[28:31], v[206:209], v[178:181], v[28:31]
	v_mfma_f32_16x16x32_bf16 v[24:27], v[214:217], v[178:181], v[24:27]
	v_mfma_f32_16x16x32_bf16 v[12:15], v[206:209], v[186:189], v[12:15]
	v_mfma_f32_16x16x32_bf16 v[8:11], v[214:217], v[186:189], v[8:11]
	v_mfma_f32_16x16x32_bf16 v[4:7], v[206:209], v[198:201], v[4:7]
	v_mfma_f32_16x16x32_bf16 v[0:3], v[214:217], v[198:201], v[0:3]
	s_barrier
	s_setprio 0
	s_add_u32 s22, s22, 0x20000
	s_addc_u32 s23, s23, 0
	s_mov_b32 m0, s36
	ds_read_b128 v[166:169], v148 offset:32768
	ds_read_b128 v[170:173], v148 offset:33792
	ds_read_b128 v[174:177], v148 offset:34816
	ds_read_b128 v[178:181], v148 offset:35840
	ds_read_b128 v[182:185], v148 offset:36864
	ds_read_b128 v[186:189], v148 offset:37888
	ds_read_b128 v[190:193], v148 offset:38912
	ds_read_b128 v[198:201], v148 offset:39936
	global_load_lds_dwordx4 v134, s[22:23]
	s_mov_b32 m0, s37
	s_nop 0
	global_load_lds_dwordx4 v130, s[22:23]
	s_waitcnt lgkmcnt(8)
	s_setprio 1
	s_barrier
	s_waitcnt lgkmcnt(7)
	v_mfma_f32_16x16x32_bf16 v[124:127], v[150:153], v[166:169], v[124:127]
	v_mfma_f32_16x16x32_bf16 v[120:123], v[158:161], v[166:169], v[120:123]
	s_waitcnt lgkmcnt(5)
	v_mfma_f32_16x16x32_bf16 v[116:119], v[150:153], v[174:177], v[116:119]
	v_mfma_f32_16x16x32_bf16 v[112:115], v[158:161], v[174:177], v[112:115]
	s_waitcnt lgkmcnt(3)
	v_mfma_f32_16x16x32_bf16 v[100:103], v[150:153], v[182:185], v[100:103]
	v_mfma_f32_16x16x32_bf16 v[96:99], v[158:161], v[182:185], v[96:99]
	s_waitcnt lgkmcnt(1)
	v_mfma_f32_16x16x32_bf16 v[84:87], v[150:153], v[190:193], v[84:87]
	v_mfma_f32_16x16x32_bf16 v[80:83], v[158:161], v[190:193], v[80:83]
	v_mfma_f32_16x16x32_bf16 v[124:127], v[154:157], v[170:173], v[124:127]
	v_mfma_f32_16x16x32_bf16 v[120:123], v[162:165], v[170:173], v[120:123]
	v_mfma_f32_16x16x32_bf16 v[116:119], v[154:157], v[178:181], v[116:119]
	v_mfma_f32_16x16x32_bf16 v[112:115], v[162:165], v[178:181], v[112:115]
	v_mfma_f32_16x16x32_bf16 v[100:103], v[154:157], v[186:189], v[100:103]
	v_mfma_f32_16x16x32_bf16 v[96:99], v[162:165], v[186:189], v[96:99]
	s_waitcnt lgkmcnt(0)
	v_mfma_f32_16x16x32_bf16 v[84:87], v[154:157], v[198:201], v[84:87]
	v_mfma_f32_16x16x32_bf16 v[80:83], v[162:165], v[198:201], v[80:83]
	s_barrier
	s_setprio 0
	s_add_i32 s22, 0, 0x1c000
	s_add_i32 s23, s57, s31
	v_add_u32_e32 v196, s22, v146
	v_lshl_add_u64 v[194:195], v[194:195], 0, s[8:9]
	s_mov_b32 m0, s23
	ds_read_b128 v[202:205], v196
	ds_read_b128 v[206:209], v196 offset:1024
	ds_read_b128 v[210:213], v196 offset:2048
	ds_read_b128 v[214:217], v196 offset:3072
	global_load_lds_dwordx4 v[194:195], off
	v_lshl_add_u64 v[194:195], v[218:219], 0, s[8:9]
	s_add_i32 m0, s23, 0x2000
	s_nop 0
	global_load_lds_dwordx4 v[194:195], off
	s_setprio 1
	s_barrier
	s_waitcnt lgkmcnt(3)
	v_mfma_f32_16x16x32_bf16 v[108:111], v[202:205], v[166:169], v[108:111]
	s_waitcnt lgkmcnt(1)
	v_mfma_f32_16x16x32_bf16 v[104:107], v[210:213], v[166:169], v[104:107]
	v_mfma_f32_16x16x32_bf16 v[92:95], v[202:205], v[174:177], v[92:95]
	v_mfma_f32_16x16x32_bf16 v[88:91], v[210:213], v[174:177], v[88:91]
	v_mfma_f32_16x16x32_bf16 v[76:79], v[202:205], v[182:185], v[76:79]
	v_mfma_f32_16x16x32_bf16 v[72:75], v[210:213], v[182:185], v[72:75]
	v_mfma_f32_16x16x32_bf16 v[68:71], v[202:205], v[190:193], v[68:71]
	v_mfma_f32_16x16x32_bf16 v[64:67], v[210:213], v[190:193], v[64:67]
	v_mfma_f32_16x16x32_bf16 v[108:111], v[206:209], v[170:173], v[108:111]
	s_mov_b32 m0, s43
	s_waitcnt lgkmcnt(0)
	v_mfma_f32_16x16x32_bf16 v[104:107], v[214:217], v[170:173], v[104:107]
	v_lshl_add_u64 v[194:195], v[220:221], 0, s[8:9]
	v_mfma_f32_16x16x32_bf16 v[92:95], v[206:209], v[178:181], v[92:95]
	v_mfma_f32_16x16x32_bf16 v[88:91], v[214:217], v[178:181], v[88:91]
	v_mfma_f32_16x16x32_bf16 v[76:79], v[206:209], v[186:189], v[76:79]
	v_mfma_f32_16x16x32_bf16 v[72:75], v[214:217], v[186:189], v[72:75]
	v_mfma_f32_16x16x32_bf16 v[68:71], v[206:209], v[198:201], v[68:71]
	v_mfma_f32_16x16x32_bf16 v[64:67], v[214:217], v[198:201], v[64:67]
	s_barrier
	s_setprio 0
	ds_read_b128 v[166:169], v148 offset:49152
	ds_read_b128 v[170:173], v148 offset:50176
	ds_read_b128 v[174:177], v148 offset:51200
	ds_read_b128 v[178:181], v148 offset:52224
	ds_read_b128 v[182:185], v148 offset:53248
	ds_read_b128 v[186:189], v148 offset:54272
	ds_read_b128 v[190:193], v148 offset:55296
	ds_read_b128 v[198:201], v148 offset:56320
	global_load_lds_dwordx4 v[194:195], off
	v_lshl_add_u64 v[194:195], v[222:223], 0, s[8:9]
	s_mov_b32 m0, s44
	s_nop 0
	global_load_lds_dwordx4 v[194:195], off
	s_waitcnt vmcnt(10)
	s_setprio 1
	s_barrier
; #define PG8_STAGE(bufoff, gbase, voff) do { _Pragma("unroll") for (int _i = 0; _i < 2; ++_i) \
;         __builtin_amdgcn_global_load_lds((const unsigned*)((const char*)(gbase) + (voff)[_i]), (LAS unsigned*)(lds + (bufoff) + ldsw + _i * 8192), 16, 0, 0); } while (0)
; #define PG8_LDA(dst, b, h) do { _Pragma("unroll") for (int m = 0; m < 4; ++m) _Pragma("unroll") for (int k = 0; k < 2; ++k) dst[m][k] = *(const LAS bf16x8*)(lds + PG8_SA(b, h) + aoff + m * 2048 + k * 1024); } while (0)
; #define PG8_MMA(ai, bj, At, Bt) do { __builtin_amdgcn_s_setprio(1); _Pragma("unroll") for (int m = 0; m < 4; ++m) _Pragma("unroll") for (int n = 0; n < 2; ++n) _Pragma("unroll") for (int k = 0; k < 2; ++k) \
;         acc[ai][bj][m][n] = __builtin_amdgcn_mfma_f32_16x16x32_bf16(Bt[n][k], At[m][k], acc[ai][bj][m][n], 0, 0, 0); __builtin_amdgcn_s_setprio(0); } while (0)
; #define PG8_WAIT_V(n) asm volatile("s_waitcnt vmcnt(" #n ")" ::: "memory")
; #define PG8_WAIT_L(n) asm volatile("s_waitcnt lgkmcnt(" #n ")" ::: "memory")
; #define PG8_BAR __builtin_amdgcn_s_barrier()
; #define PG8_SCHED __builtin_amdgcn_sched_barrier(0)
; template <class Map, class Epi>
; DI void gemm_phase(LAS unsigned char* lds, const Map& MP, const Epi& E, const int nM, const int nN, const int K, const int lda, const int ldb) {
;     ...
;             PG8_LDA(At, 1, 1); PG8_STAGE(PG8_SA(1, 0), a3, voffA);
;             PG8_BAR; PG8_WAIT_L(0); PG8_MMA(1, 0, At, B0); PG8_BAR; PG8_SCHED;
;             PG8_STAGE(PG8_SB(1, 1), b3 + hstepB, voffB);
;             PG8_WAIT_V(6); PG8_BAR; PG8_MMA(1, 1, At, B1); PG8_BAR;
	s_waitcnt lgkmcnt(7)
	v_mfma_f32_16x16x32_bf16 v[60:63], v[150:153], v[166:169], v[60:63]
	v_mfma_f32_16x16x32_bf16 v[56:59], v[158:161], v[166:169], v[56:59]
	s_waitcnt lgkmcnt(5)
	v_mfma_f32_16x16x32_bf16 v[52:55], v[150:153], v[174:177], v[52:55]
	v_mfma_f32_16x16x32_bf16 v[48:51], v[158:161], v[174:177], v[48:51]
	s_waitcnt lgkmcnt(3)
	v_mfma_f32_16x16x32_bf16 v[36:39], v[150:153], v[182:185], v[36:39]
	v_mfma_f32_16x16x32_bf16 v[32:35], v[158:161], v[182:185], v[32:35]
	s_waitcnt lgkmcnt(1)
	v_mfma_f32_16x16x32_bf16 v[20:23], v[150:153], v[190:193], v[20:23]
	v_mfma_f32_16x16x32_bf16 v[16:19], v[158:161], v[190:193], v[16:19]
	v_mfma_f32_16x16x32_bf16 v[60:63], v[154:157], v[170:173], v[60:63]
	v_mfma_f32_16x16x32_bf16 v[56:59], v[162:165], v[170:173], v[56:59]
	v_mfma_f32_16x16x32_bf16 v[52:55], v[154:157], v[178:181], v[52:55]
	v_mfma_f32_16x16x32_bf16 v[48:51], v[162:165], v[178:181], v[48:51]
	v_mfma_f32_16x16x32_bf16 v[36:39], v[154:157], v[186:189], v[36:39]
	v_mfma_f32_16x16x32_bf16 v[32:35], v[162:165], v[186:189], v[32:35]
	s_waitcnt lgkmcnt(0)
	v_mfma_f32_16x16x32_bf16 v[20:23], v[154:157], v[198:201], v[20:23]
	v_mfma_f32_16x16x32_bf16 v[16:19], v[162:165], v[198:201], v[16:19]
	s_barrier
	s_setprio 0
	s_add_u32 s20, s20, 0x20080
	s_addc_u32 s21, s21, 0
	s_add_i32 s22, s22, s31
	s_mov_b32 m0, s22
	s_nop 0
	global_load_lds_dwordx4 v132, s[20:21]
	s_add_i32 m0, s22, 0x2000
	s_nop 0
	global_load_lds_dwordx4 v128, s[20:21]
	s_waitcnt vmcnt(6)
	s_setprio 1
	s_barrier
	v_mfma_f32_16x16x32_bf16 v[44:47], v[202:205], v[166:169], v[44:47]
	v_mfma_f32_16x16x32_bf16 v[40:43], v[210:213], v[166:169], v[40:43]
	ds_read_b128 v[150:153], v147
	v_mfma_f32_16x16x32_bf16 v[28:31], v[202:205], v[174:177], v[28:31]
	v_mfma_f32_16x16x32_bf16 v[24:27], v[210:213], v[174:177], v[24:27]
	ds_read_b128 v[154:157], v147 offset:1024
	v_mfma_f32_16x16x32_bf16 v[12:15], v[202:205], v[182:185], v[12:15]
	v_mfma_f32_16x16x32_bf16 v[8:11], v[210:213], v[182:185], v[8:11]
	ds_read_b128 v[158:161], v147 offset:2048
	v_mfma_f32_16x16x32_bf16 v[4:7], v[202:205], v[190:193], v[4:7]
	v_mfma_f32_16x16x32_bf16 v[0:3], v[210:213], v[190:193], v[0:3]
	ds_read_b128 v[162:165], v147 offset:3072
	v_mfma_f32_16x16x32_bf16 v[44:47], v[206:209], v[170:173], v[44:47]
	s_add_i32 s3, s3, 2
	v_mfma_f32_16x16x32_bf16 v[40:43], v[214:217], v[170:173], v[40:43]
	s_add_u32 s55, s55, 0x100
	s_addc_u32 s56, s56, 0
	v_mfma_f32_16x16x32_bf16 v[28:31], v[206:209], v[178:181], v[28:31]
	s_add_u32 s18, s18, 0x100
	s_addc_u32 s19, s19, 0
	v_mfma_f32_16x16x32_bf16 v[24:27], v[214:217], v[178:181], v[24:27]
	s_cmp_gt_u32 s3, 5
	v_mfma_f32_16x16x32_bf16 v[12:15], v[206:209], v[186:189], v[12:15]
	v_mfma_f32_16x16x32_bf16 v[8:11], v[214:217], v[186:189], v[8:11]
	v_mfma_f32_16x16x32_bf16 v[4:7], v[206:209], v[198:201], v[4:7]
	v_mfma_f32_16x16x32_bf16 v[0:3], v[214:217], v[198:201], v[0:3]
	s_barrier
	s_setprio 0
	s_cbranch_scc0 .LBB1_1529
; DI unsigned pack2(float a, float b) { f32x2 v = {a, b}; hwbf16x2 r = __builtin_convertvector(v, hwbf16x2); return __builtin_bit_cast(unsigned, r); }
;     DI void operator()(const f32x4 (&acc)[2][2][4][2], const Unit& u, int wr, int wc, int fr, int fq) const {
;         bf16_t* O = O1; int ldc = ldc1, pn = u.pn; if (pn >= split) { O = O2; ldc = ldc2; pn -= split; }
;         const int row0 = u.pm * BM + wr * 64 + fr, col0 = pn * BM + wc * 32 + 8 * fq;
; #pragma unroll
;         for (int ai = 0; ai < 2; ++ai)
; #pragma unroll
;             for (int m = 0; m < 4; ++m) { bf16_t* rowp = O + (size_t)(row0 + ai * HALF + m * 16) * ldc + col0;
; #pragma unroll
;                 for (int bj = 0; bj < 2; ++bj) { const f32x4 v0 = acc[ai][bj][m][0], v1 = acc[ai][bj][m][1];
;                     u32x4 o; o[0] = pack2(v0[0], v0[1]); o[1] = pack2(v0[2], v0[3]); o[2] = pack2(v1[0], v1[1]); o[3] = pack2(v1[2], v1[3]);
;                     *(u32x4*)(rowp + bj * HALF) = o; } }
;     }
	s_waitcnt lgkmcnt(0)
	s_cmp_lt_i32 s45, 12
	s_cselect_b32 s3, 0, -12
	s_mov_b32 s13, 0x1e510000
	s_movk_i32 s18, 0xc00
	s_cselect_b32 s13, s13, 0x2a510000
	s_cselect_b32 s20, s18, 0x1000
	s_add_i32 s3, s3, s45
	s_add_u32 s18, s6, s13
	v_mov_b32_e32 v150, v144
	v_mov_b32_e32 v151, v145
	s_addc_u32 s19, s7, 0
	s_lshl_b32 s10, s10, 8
	s_lshl_b32 s3, s3, 8
	s_add_i32 s10, s10, s39
	s_or_b32 s3, s3, s42
	v_add_u32_e32 v154, s10, v150
	v_lshl_add_u32 v150, v151, 3, s3
	v_ashrrev_i32_e32 v151, 31, v150
	v_lshl_add_u64 v[150:151], v[150:151], 1, s[18:19]
	v_mad_i64_i32 v[152:153], s[18:19], s20, v154, 0
	v_cvt_pk_bf16_f32 v108, v108, v109
	v_cvt_pk_bf16_f32 v109, v110, v111
	v_cvt_pk_bf16_f32 v110, v104, v105
	v_add_u32_e32 v104, 16, v154
	v_lshl_add_u64 v[152:153], v[152:153], 1, v[150:151]
	v_cvt_pk_bf16_f32 v111, v106, v107
	v_mad_i64_i32 v[104:105], s[18:19], s20, v104, 0
	v_cvt_pk_bf16_f32 v92, v92, v93
	v_cvt_pk_bf16_f32 v93, v94, v95
	v_cvt_pk_bf16_f32 v94, v88, v89
	v_add_u32_e32 v88, 32, v154
	v_cvt_pk_bf16_f32 v124, v124, v125
	v_cvt_pk_bf16_f32 v125, v126, v127
	v_cvt_pk_bf16_f32 v126, v120, v121
	v_cvt_pk_bf16_f32 v127, v122, v123
	global_store_dwordx4 v[152:153], v[108:111], off offset:256
	v_cvt_pk_bf16_f32 v95, v90, v91
	v_mad_i64_i32 v[88:89], s[18:19], s20, v88, 0
	v_lshl_add_u64 v[108:109], v[104:105], 1, v[150:151]
	v_cvt_pk_bf16_f32 v76, v76, v77
	v_cvt_pk_bf16_f32 v77, v78, v79
	v_cvt_pk_bf16_f32 v78, v72, v73
	v_add_u32_e32 v72, 48, v154
	v_cvt_pk_bf16_f32 v68, v68, v69
	v_cvt_pk_bf16_f32 v69, v70, v71
	v_cvt_pk_bf16_f32 v70, v64, v65
	v_add_u32_e32 v64, 0x80, v154
	global_store_dwordx4 v[152:153], v[124:127], off
	v_cvt_pk_bf16_f32 v104, v116, v117
	v_cvt_pk_bf16_f32 v105, v118, v119
	v_cvt_pk_bf16_f32 v106, v112, v113
	v_cvt_pk_bf16_f32 v107, v114, v115
	global_store_dwordx4 v[108:109], v[92:95], off offset:256
	v_cvt_pk_bf16_f32 v79, v74, v75
	v_mad_i64_i32 v[72:73], s[18:19], s20, v72, 0
	v_lshl_add_u64 v[92:93], v[88:89], 1, v[150:151]
	v_mad_i64_i32 v[64:65], s[18:19], s20, v64, 0
	v_cvt_pk_bf16_f32 v44, v44, v45
	v_cvt_pk_bf16_f32 v45, v46, v47
	v_cvt_pk_bf16_f32 v46, v40, v41
	v_add_u32_e32 v40, 0x90, v154
	global_store_dwordx4 v[108:109], v[104:107], off
	v_cvt_pk_bf16_f32 v88, v100, v101
	v_cvt_pk_bf16_f32 v89, v102, v103
	v_cvt_pk_bf16_f32 v90, v96, v97
	v_cvt_pk_bf16_f32 v91, v98, v99
	global_store_dwordx4 v[92:93], v[76:79], off offset:256
	v_cvt_pk_bf16_f32 v74, v80, v81
	v_cvt_pk_bf16_f32 v75, v82, v83
	v_lshl_add_u64 v[76:77], v[72:73], 1, v[150:151]
	v_cvt_pk_bf16_f32 v72, v84, v85
	v_cvt_pk_bf16_f32 v73, v86, v87
	v_cvt_pk_bf16_f32 v71, v66, v67
	v_lshl_add_u64 v[64:65], v[64:65], 1, v[150:151]
	v_cvt_pk_bf16_f32 v47, v42, v43
	v_mad_i64_i32 v[40:41], s[18:19], s20, v40, 0
	v_cvt_pk_bf16_f32 v28, v28, v29
	v_cvt_pk_bf16_f32 v29, v30, v31
	v_cvt_pk_bf16_f32 v30, v24, v25
	v_add_u32_e32 v24, 0xa0, v154
	global_store_dwordx4 v[92:93], v[88:91], off
	global_store_dwordx4 v[76:77], v[72:75], off
	global_store_dwordx4 v[76:77], v[68:71], off offset:256
	v_cvt_pk_bf16_f32 v60, v60, v61
	v_cvt_pk_bf16_f32 v61, v62, v63
	v_cvt_pk_bf16_f32 v62, v56, v57
	v_cvt_pk_bf16_f32 v63, v58, v59
	global_store_dwordx4 v[64:65], v[44:47], off offset:256
	v_cvt_pk_bf16_f32 v31, v26, v27
	v_mad_i64_i32 v[24:25], s[18:19], s20, v24, 0
	v_lshl_add_u64 v[44:45], v[40:41], 1, v[150:151]
	v_cvt_pk_bf16_f32 v12, v12, v13
	v_cvt_pk_bf16_f32 v13, v14, v15
	v_cvt_pk_bf16_f32 v14, v8, v9
	v_add_u32_e32 v8, 0xb0, v154
	global_store_dwordx4 v[64:65], v[60:63], off
	v_cvt_pk_bf16_f32 v40, v52, v53
	v_cvt_pk_bf16_f32 v41, v54, v55
	v_cvt_pk_bf16_f32 v42, v48, v49
	v_cvt_pk_bf16_f32 v43, v50, v51
	global_store_dwordx4 v[44:45], v[28:31], off offset:256
	v_cvt_pk_bf16_f32 v15, v10, v11
	v_mad_i64_i32 v[8:9], s[18:19], s20, v8, 0
	v_lshl_add_u64 v[28:29], v[24:25], 1, v[150:151]
	global_store_dwordx4 v[44:45], v[40:43], off
	v_cvt_pk_bf16_f32 v24, v36, v37
	v_cvt_pk_bf16_f32 v25, v38, v39
	v_cvt_pk_bf16_f32 v26, v32, v33
	v_cvt_pk_bf16_f32 v27, v34, v35
	global_store_dwordx4 v[28:29], v[12:15], off offset:256
	v_cvt_pk_bf16_f32 v10, v16, v17
	v_cvt_pk_bf16_f32 v11, v18, v19
	v_lshl_add_u64 v[12:13], v[8:9], 1, v[150:151]
	v_cvt_pk_bf16_f32 v8, v20, v21
	v_cvt_pk_bf16_f32 v9, v22, v23
	v_cvt_pk_bf16_f32 v4, v4, v5
	v_cvt_pk_bf16_f32 v5, v6, v7
	v_cvt_pk_bf16_f32 v6, v0, v1
	v_cvt_pk_bf16_f32 v7, v2, v3
	s_and_b64 vcc, exec, s[40:41]
	s_mov_b32 s45, s49
	s_mov_b32 s10, s12
	s_mov_b64 s[18:19], s[16:17]
	s_mov_b64 s[20:21], s[14:15]
	global_store_dwordx4 v[28:29], v[24:27], off
	global_store_dwordx4 v[12:13], v[8:11], off
	global_store_dwordx4 v[12:13], v[4:7], off offset:256
	s_cbranch_vccz .LBB1_1526
	s_waitcnt vmcnt(0)
	s_cmpk_gt_u32 s4, 0xff
	s_cbranch_scc1 .LBB1_1533
	s_barrier

; #define PG8_STAGE(bufoff, gbase, voff) do { _Pragma("unroll") for (int _i = 0; _i < 2; ++_i) \
;         __builtin_amdgcn_global_load_lds((const unsigned*)((const char*)(gbase) + (voff)[_i]), (LAS unsigned*)(lds + (bufoff) + ldsw + _i * 8192), 16, 0, 0); } while (0)
; #define PG8_LDA(dst, b, h) do { _Pragma("unroll") for (int m = 0; m < 4; ++m) _Pragma("unroll") for (int k = 0; k < 2; ++k) dst[m][k] = *(const LAS bf16x8*)(lds + PG8_SA(b, h) + aoff + m * 2048 + k * 1024); } while (0)
; #define PG8_LDB(dst, b, h) do { _Pragma("unroll") for (int n = 0; n < 2; ++n) _Pragma("unroll") for (int k = 0; k < 2; ++k) dst[n][k] = *(const LAS bf16x8*)(lds + PG8_SB(b, h) + boff + n * 2048 + k * 1024); } while (0)
; #define PG8_MMA(ai, bj, At, Bt) do { __builtin_amdgcn_s_setprio(1); _Pragma("unroll") for (int m = 0; m < 4; ++m) _Pragma("unroll") for (int n = 0; n < 2; ++n) _Pragma("unroll") for (int k = 0; k < 2; ++k) \
;         acc[ai][bj][m][n] = __builtin_amdgcn_mfma_f32_16x16x32_bf16(Bt[n][k], At[m][k], acc[ai][bj][m][n], 0, 0, 0); __builtin_amdgcn_s_setprio(0); } while (0)
; #define PG8_WAIT_V(n) asm volatile("s_waitcnt vmcnt(" #n ")" ::: "memory")
; #define PG8_WAIT_L(n) asm volatile("s_waitcnt lgkmcnt(" #n ")" ::: "memory")
; template <class Map, class Epi>
; DI void gemm_phase(LAS unsigned char* lds, const Map& MP, const Epi& E, const int nM, const int nN, const int K, const int lda, const int ldb) {
;     ...
;         for (int t = 0; t < nt; t += 2) {
;             const bool last = (t == nt - 2);
;             const char* a1 = cA + (size_t)(t + 1) * kstep;
;             const char* a2 = last ? nA : cA + (size_t)(t + 2) * kstep; const char* b2 = last ? nB : cB + (size_t)(t + 2) * kstep;
;             const char* a3 = a2 + kstep; const char* b3 = b2 + kstep;
;             PG8_LDB(B0, 0, 0); PG8_SCHED; PG8_LDA(At, 0, 0); PG8_STAGE(PG8_SA(1, 1), a1 + hstepA, voffA);
;             PG8_WAIT_L(8); PG8_BAR; PG8_WAIT_L(0); PG8_MMA(0, 0, At, B0); PG8_BAR; PG8_SCHED;
;             PG8_LDB(B1, 0, 1); PG8_STAGE(PG8_SB(0, 0), b2, voffB);
;             PG8_BAR; PG8_WAIT_L(0); PG8_MMA(0, 1, At, B1); PG8_BAR;
;             PG8_LDA(At, 0, 1); PG8_STAGE(PG8_SA(0, 0), a2, voffA);
;             PG8_BAR; PG8_WAIT_L(0); PG8_MMA(1, 0, At, B0); PG8_BAR; PG8_SCHED;
;             PG8_STAGE(PG8_SB(0, 1), b2 + hstepB, voffB);
;             PG8_WAIT_V(6); PG8_BAR; PG8_MMA(1, 1, At, B1); PG8_BAR;
.LBB1_1764:
	s_add_u32 s12, s10, 0xfff80080
	s_addc_u32 s13, s11, -1
	s_cmp_eq_u32 s3, 28
	s_cselect_b32 s15, s37, s13
	s_cselect_b32 s14, s38, s12
	s_cselect_b32 s13, s39, s48
	s_cselect_b32 s12, s45, s47
	s_add_i32 m0, s24, 0xc000
	ds_read_b128 v[168:171], v150
	ds_read_b128 v[172:175], v150 offset:1024
	ds_read_b128 v[176:179], v150 offset:2048
	ds_read_b128 v[180:183], v150 offset:3072
	ds_read_b128 v[184:187], v150 offset:4096
	ds_read_b128 v[188:191], v150 offset:5120
	ds_read_b128 v[192:195], v150 offset:6144
	ds_read_b128 v[198:201], v150 offset:7168
	global_load_lds_dwordx4 v138, s[10:11]
	s_add_i32 m0, s24, 0xe000
	s_nop 0
	global_load_lds_dwordx4 v136, s[10:11]
	s_waitcnt lgkmcnt(8)
	s_setprio 1
	s_barrier
	s_waitcnt lgkmcnt(7)
	v_mfma_f32_16x16x32_bf16 v[124:127], v[152:155], v[168:171], v[124:127]
	v_mfma_f32_16x16x32_bf16 v[120:123], v[160:163], v[168:171], v[120:123]
	s_waitcnt lgkmcnt(5)
	v_mfma_f32_16x16x32_bf16 v[108:111], v[152:155], v[176:179], v[108:111]
	v_mfma_f32_16x16x32_bf16 v[104:107], v[160:163], v[176:179], v[104:107]
	s_waitcnt lgkmcnt(3)
	v_mfma_f32_16x16x32_bf16 v[92:95], v[152:155], v[184:187], v[92:95]
	v_mfma_f32_16x16x32_bf16 v[88:91], v[160:163], v[184:187], v[88:91]
	s_waitcnt lgkmcnt(1)
	v_mfma_f32_16x16x32_bf16 v[76:79], v[152:155], v[192:195], v[76:79]
	v_mfma_f32_16x16x32_bf16 v[72:75], v[160:163], v[192:195], v[72:75]
	v_mfma_f32_16x16x32_bf16 v[124:127], v[156:159], v[172:175], v[124:127]
	v_mfma_f32_16x16x32_bf16 v[120:123], v[164:167], v[172:175], v[120:123]
	v_mfma_f32_16x16x32_bf16 v[108:111], v[156:159], v[180:183], v[108:111]
	v_mfma_f32_16x16x32_bf16 v[104:107], v[164:167], v[180:183], v[104:107]
	v_mfma_f32_16x16x32_bf16 v[92:95], v[156:159], v[188:191], v[92:95]
	v_mfma_f32_16x16x32_bf16 v[88:91], v[164:167], v[188:191], v[88:91]
	s_waitcnt lgkmcnt(0)
	v_mfma_f32_16x16x32_bf16 v[76:79], v[156:159], v[198:201], v[76:79]
	v_mfma_f32_16x16x32_bf16 v[72:75], v[164:167], v[198:201], v[72:75]
	s_barrier
	s_setprio 0
	s_add_i32 s49, s35, s22
	v_lshl_add_u64 v[144:145], s[12:13], 0, v[132:133]
	s_mov_b32 m0, s49
	ds_read_b128 v[202:205], v151
	ds_read_b128 v[206:209], v151 offset:1024
	ds_read_b128 v[210:213], v151 offset:2048
	ds_read_b128 v[214:217], v151 offset:3072
	global_load_lds_dwordx4 v[144:145], off
	v_lshl_add_u64 v[218:219], s[12:13], 0, v[128:129]
	s_add_i32 m0, s49, 0x2000
	s_nop 0
	global_load_lds_dwordx4 v[218:219], off
	s_setprio 1
	s_barrier
	s_waitcnt lgkmcnt(3)
	v_mfma_f32_16x16x32_bf16 v[116:119], v[202:205], v[168:171], v[116:119]
	s_waitcnt lgkmcnt(1)
	v_mfma_f32_16x16x32_bf16 v[112:115], v[210:213], v[168:171], v[112:115]
	v_mfma_f32_16x16x32_bf16 v[100:103], v[202:205], v[176:179], v[100:103]
	v_mfma_f32_16x16x32_bf16 v[96:99], v[210:213], v[176:179], v[96:99]
	v_mfma_f32_16x16x32_bf16 v[84:87], v[202:205], v[184:187], v[84:87]
	v_mfma_f32_16x16x32_bf16 v[80:83], v[210:213], v[184:187], v[80:83]
	v_mfma_f32_16x16x32_bf16 v[68:71], v[202:205], v[192:195], v[68:71]
	v_mfma_f32_16x16x32_bf16 v[64:67], v[210:213], v[192:195], v[64:67]
	v_mfma_f32_16x16x32_bf16 v[116:119], v[206:209], v[172:175], v[116:119]
	s_mov_b32 m0, s24
	s_waitcnt lgkmcnt(0)
	v_mfma_f32_16x16x32_bf16 v[112:115], v[214:217], v[172:175], v[112:115]
	v_lshl_add_u64 v[220:221], s[14:15], 0, v[134:135]
	v_mfma_f32_16x16x32_bf16 v[100:103], v[206:209], v[180:183], v[100:103]
	v_mfma_f32_16x16x32_bf16 v[96:99], v[214:217], v[180:183], v[96:99]
	v_mfma_f32_16x16x32_bf16 v[84:87], v[206:209], v[188:191], v[84:87]
	v_mfma_f32_16x16x32_bf16 v[80:83], v[214:217], v[188:191], v[80:83]
	v_mfma_f32_16x16x32_bf16 v[68:71], v[206:209], v[198:201], v[68:71]
	v_mfma_f32_16x16x32_bf16 v[64:67], v[214:217], v[198:201], v[64:67]
	s_barrier
	s_setprio 0
	ds_read_b128 v[168:171], v150 offset:16384
	ds_read_b128 v[172:175], v150 offset:17408
	ds_read_b128 v[176:179], v150 offset:18432
	ds_read_b128 v[180:183], v150 offset:19456
	ds_read_b128 v[184:187], v150 offset:20480
	ds_read_b128 v[188:191], v150 offset:21504
	ds_read_b128 v[192:195], v150 offset:22528
	ds_read_b128 v[198:201], v150 offset:23552
	global_load_lds_dwordx4 v[220:221], off
	v_lshl_add_u64 v[222:223], s[14:15], 0, v[130:131]
	s_mov_b32 m0, s9
	s_nop 0
	global_load_lds_dwordx4 v[222:223], off
	s_waitcnt vmcnt(10)
	s_setprio 1
	s_barrier
	s_waitcnt lgkmcnt(7)
	v_mfma_f32_16x16x32_bf16 v[60:63], v[152:155], v[168:171], v[60:63]
	v_mfma_f32_16x16x32_bf16 v[56:59], v[160:163], v[168:171], v[56:59]
	s_waitcnt lgkmcnt(5)
	v_mfma_f32_16x16x32_bf16 v[44:47], v[152:155], v[176:179], v[44:47]
	v_mfma_f32_16x16x32_bf16 v[40:43], v[160:163], v[176:179], v[40:43]
	s_waitcnt lgkmcnt(3)
	v_mfma_f32_16x16x32_bf16 v[28:31], v[152:155], v[184:187], v[28:31]
	v_mfma_f32_16x16x32_bf16 v[24:27], v[160:163], v[184:187], v[24:27]
	s_waitcnt lgkmcnt(1)
	v_mfma_f32_16x16x32_bf16 v[12:15], v[152:155], v[192:195], v[12:15]
	v_mfma_f32_16x16x32_bf16 v[8:11], v[160:163], v[192:195], v[8:11]
	v_mfma_f32_16x16x32_bf16 v[60:63], v[156:159], v[172:175], v[60:63]
	v_mfma_f32_16x16x32_bf16 v[56:59], v[164:167], v[172:175], v[56:59]
	v_mfma_f32_16x16x32_bf16 v[44:47], v[156:159], v[180:183], v[44:47]
	v_mfma_f32_16x16x32_bf16 v[40:43], v[164:167], v[180:183], v[40:43]
	v_mfma_f32_16x16x32_bf16 v[28:31], v[156:159], v[188:191], v[28:31]
	v_mfma_f32_16x16x32_bf16 v[24:27], v[164:167], v[188:191], v[24:27]
	s_waitcnt lgkmcnt(0)
	v_mfma_f32_16x16x32_bf16 v[12:15], v[156:159], v[198:201], v[12:15]
	v_mfma_f32_16x16x32_bf16 v[8:11], v[164:167], v[198:201], v[8:11]
	s_barrier
; #define PG8_STAGE(bufoff, gbase, voff) do { _Pragma("unroll") for (int _i = 0; _i < 2; ++_i) \
;         __builtin_amdgcn_global_load_lds((const unsigned*)((const char*)(gbase) + (voff)[_i]), (LAS unsigned*)(lds + (bufoff) + ldsw + _i * 8192), 16, 0, 0); } while (0)
; #define PG8_LDA(dst, b, h) do { _Pragma("unroll") for (int m = 0; m < 4; ++m) _Pragma("unroll") for (int k = 0; k < 2; ++k) dst[m][k] = *(const LAS bf16x8*)(lds + PG8_SA(b, h) + aoff + m * 2048 + k * 1024); } while (0)
; #define PG8_LDB(dst, b, h) do { _Pragma("unroll") for (int n = 0; n < 2; ++n) _Pragma("unroll") for (int k = 0; k < 2; ++k) dst[n][k] = *(const LAS bf16x8*)(lds + PG8_SB(b, h) + boff + n * 2048 + k * 1024); } while (0)
; #define PG8_MMA(ai, bj, At, Bt) do { __builtin_amdgcn_s_setprio(1); _Pragma("unroll") for (int m = 0; m < 4; ++m) _Pragma("unroll") for (int n = 0; n < 2; ++n) _Pragma("unroll") for (int k = 0; k < 2; ++k) \
;         acc[ai][bj][m][n] = __builtin_amdgcn_mfma_f32_16x16x32_bf16(Bt[n][k], At[m][k], acc[ai][bj][m][n], 0, 0, 0); __builtin_amdgcn_s_setprio(0); } while (0)
; #define PG8_WAIT_V(n) asm volatile("s_waitcnt vmcnt(" #n ")" ::: "memory")
; #define PG8_WAIT_L(n) asm volatile("s_waitcnt lgkmcnt(" #n ")" ::: "memory")
; #define PG8_BAR __builtin_amdgcn_s_barrier()
; #define PG8_SCHED __builtin_amdgcn_sched_barrier(0)
; template <class Map, class Epi>
; DI void gemm_phase(LAS unsigned char* lds, const Map& MP, const Epi& E, const int nM, const int nN, const int K, const int lda, const int ldb) {
;     ...
;             PG8_BAR; PG8_WAIT_L(0); PG8_MMA(1, 0, At, B0); PG8_BAR; PG8_SCHED;
;             PG8_STAGE(PG8_SB(0, 1), b2 + hstepB, voffB);
;             PG8_WAIT_V(6); PG8_BAR; PG8_MMA(1, 1, At, B1); PG8_BAR;
;             PG8_LDB(B0, 1, 0); PG8_SCHED; PG8_LDA(At, 1, 0); PG8_STAGE(PG8_SA(0, 1), a2 + hstepA, voffA);
;             PG8_WAIT_L(8); PG8_BAR; PG8_WAIT_L(0); PG8_MMA(0, 0, At, B0); PG8_BAR; PG8_SCHED;
;             PG8_LDB(B1, 1, 1); PG8_STAGE(PG8_SB(1, 0), b3, voffB);
;             PG8_BAR; PG8_WAIT_L(0); PG8_MMA(0, 1, At, B1); PG8_BAR;
;             PG8_LDA(At, 1, 1); PG8_STAGE(PG8_SA(1, 0), a3, voffA);
	s_setprio 0
	s_add_u32 s54, s12, 0x80000
	s_addc_u32 s55, s13, 0
	s_add_i32 s49, s36, s22
	s_mov_b32 m0, s49
	s_nop 0
	global_load_lds_dwordx4 v132, s[54:55]
	s_add_i32 m0, s49, 0x2000
	s_nop 0
	global_load_lds_dwordx4 v128, s[54:55]
	s_waitcnt vmcnt(6)
	s_setprio 1
	s_barrier
	v_mfma_f32_16x16x32_bf16 v[52:55], v[202:205], v[168:171], v[52:55]
	v_mfma_f32_16x16x32_bf16 v[48:51], v[210:213], v[168:171], v[48:51]
	s_add_i32 s49, 0, 0x18000
	v_add_u32_e32 v164, s49, v148
	ds_read_b128 v[152:155], v164
	v_mfma_f32_16x16x32_bf16 v[36:39], v[202:205], v[176:179], v[36:39]
	v_mfma_f32_16x16x32_bf16 v[32:35], v[210:213], v[176:179], v[32:35]
	ds_read_b128 v[156:159], v164 offset:1024
	v_mfma_f32_16x16x32_bf16 v[20:23], v[202:205], v[184:187], v[20:23]
	v_mfma_f32_16x16x32_bf16 v[16:19], v[210:213], v[184:187], v[16:19]
	ds_read_b128 v[160:163], v164 offset:2048
	v_mfma_f32_16x16x32_bf16 v[4:7], v[202:205], v[192:195], v[4:7]
	v_mfma_f32_16x16x32_bf16 v[0:3], v[210:213], v[192:195], v[0:3]
	ds_read_b128 v[164:167], v164 offset:3072
	v_mfma_f32_16x16x32_bf16 v[52:55], v[206:209], v[172:175], v[52:55]
	v_mfma_f32_16x16x32_bf16 v[48:51], v[214:217], v[172:175], v[48:51]
	v_mfma_f32_16x16x32_bf16 v[36:39], v[206:209], v[180:183], v[36:39]
	v_mfma_f32_16x16x32_bf16 v[32:35], v[214:217], v[180:183], v[32:35]
	v_mfma_f32_16x16x32_bf16 v[20:23], v[206:209], v[188:191], v[20:23]
	v_mfma_f32_16x16x32_bf16 v[16:19], v[214:217], v[188:191], v[16:19]
	v_mfma_f32_16x16x32_bf16 v[4:7], v[206:209], v[198:201], v[4:7]
	v_mfma_f32_16x16x32_bf16 v[0:3], v[214:217], v[198:201], v[0:3]
	s_barrier
	s_setprio 0
	s_add_u32 s14, s14, 0x80000
	s_addc_u32 s15, s15, 0
	s_mov_b32 m0, s25
	ds_read_b128 v[168:171], v150 offset:32768
	ds_read_b128 v[172:175], v150 offset:33792
	ds_read_b128 v[176:179], v150 offset:34816
	ds_read_b128 v[180:183], v150 offset:35840
	ds_read_b128 v[184:187], v150 offset:36864
	ds_read_b128 v[188:191], v150 offset:37888
	ds_read_b128 v[192:195], v150 offset:38912
	ds_read_b128 v[198:201], v150 offset:39936
	global_load_lds_dwordx4 v134, s[14:15]
	s_mov_b32 m0, s26
	s_nop 0
	global_load_lds_dwordx4 v130, s[14:15]
	s_waitcnt lgkmcnt(8)
	s_setprio 1
	s_barrier
	s_waitcnt lgkmcnt(7)
	v_mfma_f32_16x16x32_bf16 v[124:127], v[152:155], v[168:171], v[124:127]
	v_mfma_f32_16x16x32_bf16 v[120:123], v[160:163], v[168:171], v[120:123]
	s_waitcnt lgkmcnt(5)
	v_mfma_f32_16x16x32_bf16 v[108:111], v[152:155], v[176:179], v[108:111]
	v_mfma_f32_16x16x32_bf16 v[104:107], v[160:163], v[176:179], v[104:107]
	s_waitcnt lgkmcnt(3)
	v_mfma_f32_16x16x32_bf16 v[92:95], v[152:155], v[184:187], v[92:95]
	v_mfma_f32_16x16x32_bf16 v[88:91], v[160:163], v[184:187], v[88:91]
	s_waitcnt lgkmcnt(1)
	v_mfma_f32_16x16x32_bf16 v[76:79], v[152:155], v[192:195], v[76:79]
	v_mfma_f32_16x16x32_bf16 v[72:75], v[160:163], v[192:195], v[72:75]
	v_mfma_f32_16x16x32_bf16 v[124:127], v[156:159], v[172:175], v[124:127]
	v_mfma_f32_16x16x32_bf16 v[120:123], v[164:167], v[172:175], v[120:123]
	v_mfma_f32_16x16x32_bf16 v[108:111], v[156:159], v[180:183], v[108:111]
	v_mfma_f32_16x16x32_bf16 v[104:107], v[164:167], v[180:183], v[104:107]
	v_mfma_f32_16x16x32_bf16 v[92:95], v[156:159], v[188:191], v[92:95]
	v_mfma_f32_16x16x32_bf16 v[88:91], v[164:167], v[188:191], v[88:91]
	s_waitcnt lgkmcnt(0)
	v_mfma_f32_16x16x32_bf16 v[76:79], v[156:159], v[198:201], v[76:79]
	v_mfma_f32_16x16x32_bf16 v[72:75], v[164:167], v[198:201], v[72:75]
	s_barrier
	s_setprio 0
	s_add_i32 s14, 0, 0x1c000
	s_add_i32 s15, s49, s22
	v_add_u32_e32 v196, s14, v148
	v_lshl_add_u64 v[144:145], v[144:145], 0, s[42:43]
	s_mov_b32 m0, s15
	ds_read_b128 v[202:205], v196
	ds_read_b128 v[206:209], v196 offset:1024
	ds_read_b128 v[210:213], v196 offset:2048
	ds_read_b128 v[214:217], v196 offset:3072
	global_load_lds_dwordx4 v[144:145], off
	v_lshl_add_u64 v[144:145], v[218:219], 0, s[42:43]
	s_add_i32 m0, s15, 0x2000
	s_nop 0
	global_load_lds_dwordx4 v[144:145], off
	s_setprio 1
	s_barrier
	s_waitcnt lgkmcnt(3)
	v_mfma_f32_16x16x32_bf16 v[116:119], v[202:205], v[168:171], v[116:119]
	s_waitcnt lgkmcnt(1)
	v_mfma_f32_16x16x32_bf16 v[112:115], v[210:213], v[168:171], v[112:115]
	v_mfma_f32_16x16x32_bf16 v[100:103], v[202:205], v[176:179], v[100:103]
	v_mfma_f32_16x16x32_bf16 v[96:99], v[210:213], v[176:179], v[96:99]
	v_mfma_f32_16x16x32_bf16 v[84:87], v[202:205], v[184:187], v[84:87]
	v_mfma_f32_16x16x32_bf16 v[80:83], v[210:213], v[184:187], v[80:83]
	v_mfma_f32_16x16x32_bf16 v[68:71], v[202:205], v[192:195], v[68:71]
	v_mfma_f32_16x16x32_bf16 v[64:67], v[210:213], v[192:195], v[64:67]
	v_mfma_f32_16x16x32_bf16 v[116:119], v[206:209], v[172:175], v[116:119]
	s_mov_b32 m0, s30
	s_waitcnt lgkmcnt(0)
	v_mfma_f32_16x16x32_bf16 v[112:115], v[214:217], v[172:175], v[112:115]
	v_lshl_add_u64 v[144:145], v[220:221], 0, s[42:43]
	v_mfma_f32_16x16x32_bf16 v[100:103], v[206:209], v[180:183], v[100:103]
	v_mfma_f32_16x16x32_bf16 v[96:99], v[214:217], v[180:183], v[96:99]
	v_mfma_f32_16x16x32_bf16 v[84:87], v[206:209], v[188:191], v[84:87]
	v_mfma_f32_16x16x32_bf16 v[80:83], v[214:217], v[188:191], v[80:83]
	v_mfma_f32_16x16x32_bf16 v[68:71], v[206:209], v[198:201], v[68:71]
	v_mfma_f32_16x16x32_bf16 v[64:67], v[214:217], v[198:201], v[64:67]
	s_barrier
	s_setprio 0
	ds_read_b128 v[168:171], v150 offset:49152
	ds_read_b128 v[172:175], v150 offset:50176
	ds_read_b128 v[176:179], v150 offset:51200
	ds_read_b128 v[180:183], v150 offset:52224
	ds_read_b128 v[184:187], v150 offset:53248
	ds_read_b128 v[188:191], v150 offset:54272
	ds_read_b128 v[192:195], v150 offset:55296
	ds_read_b128 v[198:201], v150 offset:56320
	global_load_lds_dwordx4 v[144:145], off
	v_lshl_add_u64 v[144:145], v[222:223], 0, s[42:43]
	s_mov_b32 m0, s31
	s_nop 0
	global_load_lds_dwordx4 v[144:145], off
	s_waitcnt vmcnt(10)
	s_setprio 1
	s_barrier
; DI unsigned pack2(float a, float b) { f32x2 v = {a, b}; hwbf16x2 r = __builtin_convertvector(v, hwbf16x2); return __builtin_bit_cast(unsigned, r); }
; DI float bflo(unsigned w) { return __uint_as_float(w << 16); }
; DI float bfhi(unsigned w) { return __uint_as_float(w & 0xffff0000u); }
; #define PG8_WAIT_V(n) asm volatile("s_waitcnt vmcnt(" #n ")" ::: "memory")
; #define PG8_WAIT_L(n) asm volatile("s_waitcnt lgkmcnt(" #n ")" ::: "memory")
;     DI void operator()(const f32x4 (&acc)[2][2][4][2], const Unit& u, int wr, int wc, int fr, int fq) const {
;         const int row0 = u.pm * BM + wr * 64 + fr, col0 = u.pn * BM + wc * 32 + 8 * fq;
;         f32x4 sc[2][2];
; #pragma unroll
;         for (int bj = 0; bj < 2; ++bj)
; #pragma unroll
;             for (int n = 0; n < 2; ++n) sc[bj][n] = scale ? *(const f32x4*)(scale + col0 + bj * HALF + 4 * n) : (f32x4){1.f, 1.f, 1.f, 1.f};
; #pragma unroll
;         for (int ai = 0; ai < 2; ++ai)
; #pragma unroll
;             for (int m = 0; m < 4; ++m) { const size_t ro = (size_t)(row0 + ai * HALF + m * 16) * D + col0;
; #pragma unroll
;                 for (int bj = 0; bj < 2; ++bj) {
;                     f32x4 x0, x1;
;                     if constexpr (IB) { const u32x4 w = *(const u32x4*)((const bf16_t*)Xin + ro + bj * HALF);
;                         x0 = (f32x4){bflo(w[0]), bfhi(w[0]), bflo(w[1]), bfhi(w[1])}; x1 = (f32x4){bflo(w[2]), bfhi(w[2]), bflo(w[3]), bfhi(w[3])}; }
;                     else { x0 = *(const f32x4*)((const float*)Xin + ro + bj * HALF); x1 = *(const f32x4*)((const float*)Xin + ro + bj * HALF + 4); }
;                     x0 += acc[ai][bj][m][0] * sc[bj][0]; x1 += acc[ai][bj][m][1] * sc[bj][1];
;                     if constexpr (OB) { u32x4 o; o[0] = pack2(x0[0], x0[1]); o[1] = pack2(x0[2], x0[3]); o[2] = pack2(x1[0], x1[1]); o[3] = pack2(x1[2], x1[3]);
;                         *(u32x4*)((bf16_t*)Xout + ro + bj * HALF) = o; }
; template <class Map, class Epi>
; DI void gemm_phase(LAS unsigned char* lds, const Map& MP, const Epi& E, const int nM, const int nN, const int K, const int lda, const int ldb) {
;     ...
;             PG8_LDA(At, 1, 1); PG8_STAGE(PG8_SA(1, 0), a3, voffA);
;             PG8_BAR; PG8_WAIT_L(0); PG8_MMA(1, 0, At, B0); PG8_BAR; PG8_SCHED;
;             PG8_STAGE(PG8_SB(1, 1), b3 + hstepB, voffB);
;             PG8_WAIT_V(6); PG8_BAR; PG8_MMA(1, 1, At, B1); PG8_BAR;
	s_waitcnt lgkmcnt(7)
	v_mfma_f32_16x16x32_bf16 v[60:63], v[152:155], v[168:171], v[60:63]
	v_mfma_f32_16x16x32_bf16 v[56:59], v[160:163], v[168:171], v[56:59]
	s_waitcnt lgkmcnt(5)
	v_mfma_f32_16x16x32_bf16 v[44:47], v[152:155], v[176:179], v[44:47]
	v_mfma_f32_16x16x32_bf16 v[40:43], v[160:163], v[176:179], v[40:43]
	s_waitcnt lgkmcnt(3)
	v_mfma_f32_16x16x32_bf16 v[28:31], v[152:155], v[184:187], v[28:31]
	v_mfma_f32_16x16x32_bf16 v[24:27], v[160:163], v[184:187], v[24:27]
	s_waitcnt lgkmcnt(1)
	v_mfma_f32_16x16x32_bf16 v[12:15], v[152:155], v[192:195], v[12:15]
	v_mfma_f32_16x16x32_bf16 v[8:11], v[160:163], v[192:195], v[8:11]
	v_mfma_f32_16x16x32_bf16 v[60:63], v[156:159], v[172:175], v[60:63]
	v_mfma_f32_16x16x32_bf16 v[56:59], v[164:167], v[172:175], v[56:59]
	v_mfma_f32_16x16x32_bf16 v[44:47], v[156:159], v[180:183], v[44:47]
	v_mfma_f32_16x16x32_bf16 v[40:43], v[164:167], v[180:183], v[40:43]
	v_mfma_f32_16x16x32_bf16 v[28:31], v[156:159], v[188:191], v[28:31]
	v_mfma_f32_16x16x32_bf16 v[24:27], v[164:167], v[188:191], v[24:27]
	s_waitcnt lgkmcnt(0)
	v_mfma_f32_16x16x32_bf16 v[12:15], v[156:159], v[198:201], v[12:15]
	v_mfma_f32_16x16x32_bf16 v[8:11], v[164:167], v[198:201], v[8:11]
	s_barrier
	s_setprio 0
	s_add_u32 s12, s12, 0x80080
	s_addc_u32 s13, s13, 0
	s_add_i32 s14, s14, s22
	s_mov_b32 m0, s14
	s_nop 0
	global_load_lds_dwordx4 v132, s[12:13]
	s_add_i32 m0, s14, 0x2000
	s_nop 0
	global_load_lds_dwordx4 v128, s[12:13]
	s_waitcnt vmcnt(6)
	s_setprio 1
	s_barrier
	v_mfma_f32_16x16x32_bf16 v[52:55], v[202:205], v[168:171], v[52:55]
	v_mfma_f32_16x16x32_bf16 v[48:51], v[210:213], v[168:171], v[48:51]
	ds_read_b128 v[152:155], v149
	v_mfma_f32_16x16x32_bf16 v[36:39], v[202:205], v[176:179], v[36:39]
	v_mfma_f32_16x16x32_bf16 v[32:35], v[210:213], v[176:179], v[32:35]
	ds_read_b128 v[156:159], v149 offset:1024
	v_mfma_f32_16x16x32_bf16 v[20:23], v[202:205], v[184:187], v[20:23]
	v_mfma_f32_16x16x32_bf16 v[16:19], v[210:213], v[184:187], v[16:19]
	ds_read_b128 v[160:163], v149 offset:2048
	v_mfma_f32_16x16x32_bf16 v[4:7], v[202:205], v[192:195], v[4:7]
	v_mfma_f32_16x16x32_bf16 v[0:3], v[210:213], v[192:195], v[0:3]
	ds_read_b128 v[164:167], v149 offset:3072
	v_mfma_f32_16x16x32_bf16 v[52:55], v[206:209], v[172:175], v[52:55]
	s_add_i32 s3, s3, 2
	v_mfma_f32_16x16x32_bf16 v[48:51], v[214:217], v[172:175], v[48:51]
	s_add_u32 s47, s47, 0x100
	s_addc_u32 s48, s48, 0
	v_mfma_f32_16x16x32_bf16 v[36:39], v[206:209], v[180:183], v[36:39]
	s_add_u32 s10, s10, 0x100
	s_addc_u32 s11, s11, 0
	v_mfma_f32_16x16x32_bf16 v[32:35], v[214:217], v[180:183], v[32:35]
	s_cmp_gt_u32 s3, 29
	v_mfma_f32_16x16x32_bf16 v[20:23], v[206:209], v[188:191], v[20:23]
	v_mfma_f32_16x16x32_bf16 v[16:19], v[214:217], v[188:191], v[16:19]
	v_mfma_f32_16x16x32_bf16 v[4:7], v[206:209], v[198:201], v[4:7]
	v_mfma_f32_16x16x32_bf16 v[0:3], v[214:217], v[198:201], v[0:3]
	s_barrier
	s_setprio 0
	s_cbranch_scc0 .LBB1_1764
	s_waitcnt lgkmcnt(0)
	v_mov_b32_e32 v152, v147
	v_mov_b32_e32 v144, v146
	s_lshl_b32 s2, s2, 8
	s_or_b32 s2, s2, s29
	v_lshl_add_u32 v144, v144, 3, s2
	s_lshl_b32 s2, s8, 8
	s_add_i32 s2, s2, s28
	v_add_u32_e32 v152, s2, v152
	v_ashrrev_i32_e32 v153, 31, v152
	v_lshlrev_b64 v[152:153], 12, v[152:153]
	v_ashrrev_i32_e32 v145, 31, v144
	v_lshl_add_u64 v[152:153], s[4:5], 0, v[152:153]
	v_lshl_add_u64 v[144:145], v[144:145], 1, v[152:153]
	global_load_dwordx4 v[160:163], v[144:145], off
	global_load_dwordx4 v[164:167], v[144:145], off offset:256
	s_mov_b64 s[98:99], 0x10000
	v_lshl_add_u64 v[154:155], v[144:145], 0, s[98:99]
	global_load_dwordx4 v[168:171], v[154:155], off
	global_load_dwordx4 v[172:175], v[154:155], off offset:256
	s_mov_b64 s[98:99], 0x20000
	v_lshl_add_u64 v[154:155], v[144:145], 0, s[98:99]
	global_load_dwordx4 v[176:179], v[154:155], off
	global_load_dwordx4 v[180:183], v[154:155], off offset:256
	s_mov_b64 s[98:99], 0x30000
	v_lshl_add_u64 v[154:155], v[144:145], 0, s[98:99]
	global_load_dwordx4 v[184:187], v[154:155], off
	global_load_dwordx4 v[188:191], v[154:155], off offset:256
	s_mov_b64 s[98:99], 0x80000
	v_lshl_add_u64 v[154:155], v[144:145], 0, s[98:99]
	global_load_dwordx4 v[192:195], v[154:155], off
	global_load_dwordx4 v[198:201], v[154:155], off offset:256
	s_mov_b64 s[98:99], 0x90000
	v_lshl_add_u64 v[154:155], v[144:145], 0, s[98:99]
	global_load_dwordx4 v[202:205], v[154:155], off
	global_load_dwordx4 v[206:209], v[154:155], off offset:256
	s_mov_b64 s[98:99], 0xa0000
	v_lshl_add_u64 v[154:155], v[144:145], 0, s[98:99]
	global_load_dwordx4 v[210:213], v[154:155], off
	global_load_dwordx4 v[214:217], v[154:155], off offset:256
	s_mov_b64 s[98:99], 0xb0000
	v_lshl_add_u64 v[154:155], v[144:145], 0, s[98:99]
	global_load_dwordx4 v[248:251], v[154:155], off
	global_load_dwordx4 v[252:255], v[154:155], off offset:256
	s_waitcnt vmcnt(15)
	s_nop 1
	v_mov_b32_e32 v152, v160
	v_mov_b32_e32 v153, v161
	v_mov_b32_e32 v154, v162
	v_mov_b32_e32 v155, v163
	s_mov_b64 s[2:3], 0x10000
	s_mov_b32 s8, s46
	s_mov_b64 s[10:11], s[6:7]
	s_mov_b64 s[12:13], s[52:53]
	s_waitcnt lgkmcnt(0)
	v_lshlrev_b32_e32 v156, 16, v152
	v_and_b32_e32 v157, 0xffff0000, v152
	v_lshlrev_b32_e32 v152, 16, v153
	v_and_b32_e32 v153, 0xffff0000, v153
	v_lshlrev_b32_e32 v158, 16, v154
	v_and_b32_e32 v159, 0xffff0000, v154
	v_lshlrev_b32_e32 v154, 16, v155
	v_and_b32_e32 v155, 0xffff0000, v155
	v_pk_add_f32 v[126:127], v[126:127], v[152:153]
	v_pk_add_f32 v[124:125], v[124:125], v[156:157]
	v_pk_add_f32 v[152:153], v[122:123], v[154:155]
	v_pk_add_f32 v[122:123], v[120:121], v[158:159]
	v_cvt_pk_bf16_f32 v120, v124, v125
	v_cvt_pk_bf16_f32 v121, v126, v127
	v_cvt_pk_bf16_f32 v122, v122, v123
	v_cvt_pk_bf16_f32 v123, v152, v153
	global_store_dwordx4 v[144:145], v[120:123], off
	s_waitcnt vmcnt(15)
; DI unsigned pack2(float a, float b) { f32x2 v = {a, b}; hwbf16x2 r = __builtin_convertvector(v, hwbf16x2); return __builtin_bit_cast(unsigned, r); }
; DI float bflo(unsigned w) { return __uint_as_float(w << 16); }
; DI float bfhi(unsigned w) { return __uint_as_float(w & 0xffff0000u); }
;     DI void operator()(const f32x4 (&acc)[2][2][4][2], const Unit& u, int wr, int wc, int fr, int fq) const {
;     ...
;             for (int m = 0; m < 4; ++m) { const size_t ro = (size_t)(row0 + ai * HALF + m * 16) * D + col0;
; #pragma unroll
;                 for (int bj = 0; bj < 2; ++bj) {
;                     f32x4 x0, x1;
;                     if constexpr (IB) { const u32x4 w = *(const u32x4*)((const bf16_t*)Xin + ro + bj * HALF);
;                         x0 = (f32x4){bflo(w[0]), bfhi(w[0]), bflo(w[1]), bfhi(w[1])}; x1 = (f32x4){bflo(w[2]), bfhi(w[2]), bflo(w[3]), bfhi(w[3])}; }
;                     else { x0 = *(const f32x4*)((const float*)Xin + ro + bj * HALF); x1 = *(const f32x4*)((const float*)Xin + ro + bj * HALF + 4); }
;                     x0 += acc[ai][bj][m][0] * sc[bj][0]; x1 += acc[ai][bj][m][1] * sc[bj][1];
;                     if constexpr (OB) { u32x4 o; o[0] = pack2(x0[0], x0[1]); o[1] = pack2(x0[2], x0[3]); o[2] = pack2(x1[0], x1[1]); o[3] = pack2(x1[2], x1[3]);
;                         *(u32x4*)((bf16_t*)Xout + ro + bj * HALF) = o; }
;                     else { *(f32x4*)((float*)Xout + ro + bj * HALF) = x0; *(f32x4*)((float*)Xout + ro + bj * HALF + 4) = x1; } } }
	s_nop 1
	v_mov_b32_e32 v120, v164
	v_mov_b32_e32 v121, v165
	v_mov_b32_e32 v122, v166
	v_mov_b32_e32 v123, v167
	s_waitcnt lgkmcnt(0)
	v_lshlrev_b32_e32 v124, 16, v120
	v_and_b32_e32 v125, 0xffff0000, v120
	v_lshlrev_b32_e32 v120, 16, v121
	v_and_b32_e32 v121, 0xffff0000, v121
	v_lshlrev_b32_e32 v126, 16, v122
	v_and_b32_e32 v127, 0xffff0000, v122
	v_lshlrev_b32_e32 v122, 16, v123
	v_and_b32_e32 v123, 0xffff0000, v123
	v_pk_add_f32 v[116:117], v[116:117], v[124:125]
	v_pk_add_f32 v[118:119], v[118:119], v[120:121]
	v_pk_add_f32 v[120:121], v[114:115], v[122:123]
	v_pk_add_f32 v[114:115], v[112:113], v[126:127]
	v_cvt_pk_bf16_f32 v112, v116, v117
	v_lshl_add_u64 v[116:117], v[144:145], 0, s[2:3]
	s_mov_b32 s2, 0x10000
	v_cvt_pk_bf16_f32 v113, v118, v119
	v_add_co_u32_e32 v118, vcc, s2, v144
	v_cvt_pk_bf16_f32 v114, v114, v115
	v_cvt_pk_bf16_f32 v115, v120, v121
	v_addc_co_u32_e32 v119, vcc, 0, v145, vcc
	global_store_dwordx4 v[144:145], v[112:115], off offset:256
	s_waitcnt vmcnt(15)
	s_nop 1
	v_mov_b32_e32 v112, v168
	v_mov_b32_e32 v113, v169
	v_mov_b32_e32 v114, v170
	v_mov_b32_e32 v115, v171
	s_mov_b64 s[2:3], 0x20000
	s_waitcnt lgkmcnt(0)
	v_lshlrev_b32_e32 v120, 16, v112
	v_and_b32_e32 v121, 0xffff0000, v112
	v_lshlrev_b32_e32 v112, 16, v113
	v_and_b32_e32 v113, 0xffff0000, v113
	v_lshlrev_b32_e32 v122, 16, v114
	v_and_b32_e32 v123, 0xffff0000, v114
	v_lshlrev_b32_e32 v114, 16, v115
	v_and_b32_e32 v115, 0xffff0000, v115
	v_pk_add_f32 v[110:111], v[110:111], v[112:113]
	v_pk_add_f32 v[108:109], v[108:109], v[120:121]
	v_pk_add_f32 v[112:113], v[106:107], v[114:115]
	v_pk_add_f32 v[106:107], v[104:105], v[122:123]
	v_cvt_pk_bf16_f32 v104, v108, v109
	v_cvt_pk_bf16_f32 v105, v110, v111
	v_cvt_pk_bf16_f32 v106, v106, v107
	v_cvt_pk_bf16_f32 v107, v112, v113
	global_store_dwordx4 v[118:119], v[104:107], off
	s_waitcnt vmcnt(15)
	s_nop 1
	v_mov_b32_e32 v104, v172
	v_mov_b32_e32 v105, v173
	v_mov_b32_e32 v106, v174
	v_mov_b32_e32 v107, v175
	s_waitcnt lgkmcnt(0)
	v_lshlrev_b32_e32 v108, 16, v104
	v_and_b32_e32 v109, 0xffff0000, v104
	v_lshlrev_b32_e32 v104, 16, v105
	v_and_b32_e32 v105, 0xffff0000, v105
	v_lshlrev_b32_e32 v110, 16, v106
	v_and_b32_e32 v111, 0xffff0000, v106
	v_lshlrev_b32_e32 v106, 16, v107
	v_and_b32_e32 v107, 0xffff0000, v107
	v_pk_add_f32 v[100:101], v[100:101], v[108:109]
	v_pk_add_f32 v[102:103], v[102:103], v[104:105]
	v_pk_add_f32 v[104:105], v[98:99], v[106:107]
	v_pk_add_f32 v[98:99], v[96:97], v[110:111]
	v_cvt_pk_bf16_f32 v96, v100, v101
	v_lshl_add_u64 v[100:101], v[144:145], 0, s[2:3]
	s_mov_b32 s2, 0x20000
	v_cvt_pk_bf16_f32 v97, v102, v103
	v_add_co_u32_e32 v102, vcc, s2, v144
	v_cvt_pk_bf16_f32 v98, v98, v99
	v_cvt_pk_bf16_f32 v99, v104, v105
	v_addc_co_u32_e32 v103, vcc, 0, v145, vcc
	global_store_dwordx4 v[116:117], v[96:99], off offset:256
	s_waitcnt vmcnt(15)
	s_nop 1
	v_mov_b32_e32 v96, v176
	v_mov_b32_e32 v97, v177
	v_mov_b32_e32 v98, v178
	v_mov_b32_e32 v99, v179
	s_mov_b64 s[2:3], 0x30000
	s_waitcnt lgkmcnt(0)
	v_lshlrev_b32_e32 v104, 16, v96
	v_and_b32_e32 v105, 0xffff0000, v96
	v_lshlrev_b32_e32 v96, 16, v97
	v_and_b32_e32 v97, 0xffff0000, v97
	v_lshlrev_b32_e32 v106, 16, v98
	v_and_b32_e32 v107, 0xffff0000, v98
	v_lshlrev_b32_e32 v98, 16, v99
	v_and_b32_e32 v99, 0xffff0000, v99
	v_pk_add_f32 v[94:95], v[94:95], v[96:97]
	v_pk_add_f32 v[92:93], v[92:93], v[104:105]
	v_pk_add_f32 v[96:97], v[90:91], v[98:99]
	v_pk_add_f32 v[90:91], v[88:89], v[106:107]
	v_cvt_pk_bf16_f32 v88, v92, v93
	v_cvt_pk_bf16_f32 v89, v94, v95
	v_cvt_pk_bf16_f32 v90, v90, v91
	v_cvt_pk_bf16_f32 v91, v96, v97
	global_store_dwordx4 v[102:103], v[88:91], off
	s_waitcnt vmcnt(15)
	s_nop 1
	v_mov_b32_e32 v88, v180
	v_mov_b32_e32 v89, v181
	v_mov_b32_e32 v90, v182
	v_mov_b32_e32 v91, v183
	s_waitcnt lgkmcnt(0)
	v_lshlrev_b32_e32 v92, 16, v88
	v_and_b32_e32 v93, 0xffff0000, v88
	v_lshlrev_b32_e32 v88, 16, v89
	v_and_b32_e32 v89, 0xffff0000, v89
	v_lshlrev_b32_e32 v94, 16, v90
	v_and_b32_e32 v95, 0xffff0000, v90
	v_lshlrev_b32_e32 v90, 16, v91
	v_and_b32_e32 v91, 0xffff0000, v91
	v_pk_add_f32 v[86:87], v[86:87], v[88:89]
	v_pk_add_f32 v[84:85], v[84:85], v[92:93]
	v_pk_add_f32 v[88:89], v[82:83], v[90:91]
	v_pk_add_f32 v[82:83], v[80:81], v[94:95]
	v_cvt_pk_bf16_f32 v80, v84, v85
	v_cvt_pk_bf16_f32 v81, v86, v87
	v_cvt_pk_bf16_f32 v82, v82, v83
	v_cvt_pk_bf16_f32 v83, v88, v89
	global_store_dwordx4 v[100:101], v[80:83], off offset:256
	s_nop 1
	v_lshl_add_u64 v[80:81], v[144:145], 0, s[2:3]
	s_mov_b32 s2, 0x30000
	v_add_co_u32_e32 v86, vcc, s2, v144
	s_mov_b64 s[2:3], 0x80000
	s_nop 0
	v_addc_co_u32_e32 v87, vcc, 0, v145, vcc
	s_waitcnt vmcnt(15)
	s_nop 1
	v_mov_b32_e32 v82, v184
	v_mov_b32_e32 v83, v185
	v_mov_b32_e32 v84, v186
	v_mov_b32_e32 v85, v187
	s_waitcnt lgkmcnt(0)
	v_lshlrev_b32_e32 v88, 16, v82
	v_and_b32_e32 v89, 0xffff0000, v82
	v_lshlrev_b32_e32 v82, 16, v83
	v_and_b32_e32 v83, 0xffff0000, v83
	v_lshlrev_b32_e32 v90, 16, v84
	v_and_b32_e32 v91, 0xffff0000, v84
	v_lshlrev_b32_e32 v84, 16, v85
	v_and_b32_e32 v85, 0xffff0000, v85
	v_pk_add_f32 v[78:79], v[78:79], v[82:83]
	v_pk_add_f32 v[76:77], v[76:77], v[88:89]
	v_pk_add_f32 v[82:83], v[74:75], v[84:85]
	v_pk_add_f32 v[74:75], v[72:73], v[90:91]
	v_cvt_pk_bf16_f32 v72, v76, v77
	v_cvt_pk_bf16_f32 v73, v78, v79
	v_cvt_pk_bf16_f32 v74, v74, v75
	v_cvt_pk_bf16_f32 v75, v82, v83
	global_store_dwordx4 v[86:87], v[72:75], off
	s_waitcnt vmcnt(15)
	s_nop 1
	v_mov_b32_e32 v72, v188
	v_mov_b32_e32 v73, v189
	v_mov_b32_e32 v74, v190
	v_mov_b32_e32 v75, v191
	s_waitcnt lgkmcnt(0)
; DI unsigned pack2(float a, float b) { f32x2 v = {a, b}; hwbf16x2 r = __builtin_convertvector(v, hwbf16x2); return __builtin_bit_cast(unsigned, r); }
; DI float bflo(unsigned w) { return __uint_as_float(w << 16); }
; DI float bfhi(unsigned w) { return __uint_as_float(w & 0xffff0000u); }
;     DI void operator()(const f32x4 (&acc)[2][2][4][2], const Unit& u, int wr, int wc, int fr, int fq) const {
;     ...
;             for (int m = 0; m < 4; ++m) { const size_t ro = (size_t)(row0 + ai * HALF + m * 16) * D + col0;
; #pragma unroll
;                 for (int bj = 0; bj < 2; ++bj) {
;                     f32x4 x0, x1;
;                     if constexpr (IB) { const u32x4 w = *(const u32x4*)((const bf16_t*)Xin + ro + bj * HALF);
;                         x0 = (f32x4){bflo(w[0]), bfhi(w[0]), bflo(w[1]), bfhi(w[1])}; x1 = (f32x4){bflo(w[2]), bfhi(w[2]), bflo(w[3]), bfhi(w[3])}; }
;                     else { x0 = *(const f32x4*)((const float*)Xin + ro + bj * HALF); x1 = *(const f32x4*)((const float*)Xin + ro + bj * HALF + 4); }
;                     x0 += acc[ai][bj][m][0] * sc[bj][0]; x1 += acc[ai][bj][m][1] * sc[bj][1];
;                     if constexpr (OB) { u32x4 o; o[0] = pack2(x0[0], x0[1]); o[1] = pack2(x0[2], x0[3]); o[2] = pack2(x1[0], x1[1]); o[3] = pack2(x1[2], x1[3]);
;                         *(u32x4*)((bf16_t*)Xout + ro + bj * HALF) = o; }
;                     else { *(f32x4*)((float*)Xout + ro + bj * HALF) = x0; *(f32x4*)((float*)Xout + ro + bj * HALF + 4) = x1; } } }
	v_lshlrev_b32_e32 v76, 16, v72
	v_and_b32_e32 v77, 0xffff0000, v72
	v_lshlrev_b32_e32 v72, 16, v73
	v_and_b32_e32 v73, 0xffff0000, v73
	v_lshlrev_b32_e32 v78, 16, v74
	v_and_b32_e32 v79, 0xffff0000, v74
	v_lshlrev_b32_e32 v74, 16, v75
	v_and_b32_e32 v75, 0xffff0000, v75
	v_pk_add_f32 v[70:71], v[70:71], v[72:73]
	v_pk_add_f32 v[68:69], v[68:69], v[76:77]
	v_pk_add_f32 v[72:73], v[66:67], v[74:75]
	v_pk_add_f32 v[66:67], v[64:65], v[78:79]
	v_cvt_pk_bf16_f32 v64, v68, v69
	v_cvt_pk_bf16_f32 v65, v70, v71
	v_cvt_pk_bf16_f32 v66, v66, v67
	v_cvt_pk_bf16_f32 v67, v72, v73
	global_store_dwordx4 v[80:81], v[64:67], off offset:256
	s_nop 1
	v_lshl_add_u64 v[64:65], v[144:145], 0, s[2:3]
	s_mov_b32 s2, 0x80000
	v_add_co_u32_e32 v70, vcc, s2, v144
	s_mov_b64 s[2:3], 0x90000
	s_nop 0
	v_addc_co_u32_e32 v71, vcc, 0, v145, vcc
	s_waitcnt vmcnt(15)
	s_nop 1
	v_mov_b32_e32 v66, v192
	v_mov_b32_e32 v67, v193
	v_mov_b32_e32 v68, v194
	v_mov_b32_e32 v69, v195
	s_waitcnt lgkmcnt(0)
	v_lshlrev_b32_e32 v72, 16, v66
	v_and_b32_e32 v73, 0xffff0000, v66
	v_lshlrev_b32_e32 v66, 16, v67
	v_and_b32_e32 v67, 0xffff0000, v67
	v_lshlrev_b32_e32 v74, 16, v68
	v_and_b32_e32 v75, 0xffff0000, v68
	v_lshlrev_b32_e32 v68, 16, v69
	v_and_b32_e32 v69, 0xffff0000, v69
	v_pk_add_f32 v[62:63], v[62:63], v[66:67]
	v_pk_add_f32 v[60:61], v[60:61], v[72:73]
	v_pk_add_f32 v[66:67], v[58:59], v[68:69]
	v_pk_add_f32 v[58:59], v[56:57], v[74:75]
	v_cvt_pk_bf16_f32 v56, v60, v61
	v_cvt_pk_bf16_f32 v57, v62, v63
	v_cvt_pk_bf16_f32 v58, v58, v59
	v_cvt_pk_bf16_f32 v59, v66, v67
	global_store_dwordx4 v[70:71], v[56:59], off
	s_waitcnt vmcnt(15)
	s_nop 1
	v_mov_b32_e32 v56, v198
	v_mov_b32_e32 v57, v199
	v_mov_b32_e32 v58, v200
	v_mov_b32_e32 v59, v201
	s_waitcnt lgkmcnt(0)
	v_lshlrev_b32_e32 v60, 16, v56
	v_and_b32_e32 v61, 0xffff0000, v56
	v_lshlrev_b32_e32 v56, 16, v57
	v_and_b32_e32 v57, 0xffff0000, v57
	v_lshlrev_b32_e32 v62, 16, v58
	v_and_b32_e32 v63, 0xffff0000, v58
	v_lshlrev_b32_e32 v58, 16, v59
	v_and_b32_e32 v59, 0xffff0000, v59
	v_pk_add_f32 v[54:55], v[54:55], v[56:57]
	v_pk_add_f32 v[52:53], v[52:53], v[60:61]
	v_pk_add_f32 v[56:57], v[50:51], v[58:59]
	v_pk_add_f32 v[50:51], v[48:49], v[62:63]
	v_cvt_pk_bf16_f32 v48, v52, v53
	v_cvt_pk_bf16_f32 v49, v54, v55
	v_cvt_pk_bf16_f32 v50, v50, v51
	v_cvt_pk_bf16_f32 v51, v56, v57
	global_store_dwordx4 v[64:65], v[48:51], off offset:256
	s_nop 1
	v_lshl_add_u64 v[48:49], v[144:145], 0, s[2:3]
	s_mov_b32 s2, 0x90000
	v_add_co_u32_e32 v54, vcc, s2, v144
	s_mov_b64 s[2:3], 0xa0000
	s_nop 0
	v_addc_co_u32_e32 v55, vcc, 0, v145, vcc
	s_waitcnt vmcnt(15)
	s_nop 1
	v_mov_b32_e32 v50, v202
	v_mov_b32_e32 v51, v203
	v_mov_b32_e32 v52, v204
	v_mov_b32_e32 v53, v205
	s_waitcnt lgkmcnt(0)
	v_lshlrev_b32_e32 v56, 16, v50
	v_and_b32_e32 v57, 0xffff0000, v50
	v_lshlrev_b32_e32 v50, 16, v51
	v_and_b32_e32 v51, 0xffff0000, v51
	v_lshlrev_b32_e32 v58, 16, v52
	v_and_b32_e32 v59, 0xffff0000, v52
	v_lshlrev_b32_e32 v52, 16, v53
	v_and_b32_e32 v53, 0xffff0000, v53
	v_pk_add_f32 v[46:47], v[46:47], v[50:51]
	v_pk_add_f32 v[44:45], v[44:45], v[56:57]
	v_pk_add_f32 v[50:51], v[42:43], v[52:53]
	v_pk_add_f32 v[42:43], v[40:41], v[58:59]
	v_cvt_pk_bf16_f32 v40, v44, v45
	v_cvt_pk_bf16_f32 v41, v46, v47
	v_cvt_pk_bf16_f32 v42, v42, v43
	v_cvt_pk_bf16_f32 v43, v50, v51
	global_store_dwordx4 v[54:55], v[40:43], off
	s_waitcnt vmcnt(15)
	s_nop 1
	v_mov_b32_e32 v40, v206
	v_mov_b32_e32 v41, v207
	v_mov_b32_e32 v42, v208
	v_mov_b32_e32 v43, v209
	s_waitcnt lgkmcnt(0)
; DI unsigned pack2(float a, float b) { f32x2 v = {a, b}; hwbf16x2 r = __builtin_convertvector(v, hwbf16x2); return __builtin_bit_cast(unsigned, r); }
; DI float bflo(unsigned w) { return __uint_as_float(w << 16); }
; DI float bfhi(unsigned w) { return __uint_as_float(w & 0xffff0000u); }
;     DI const char* a(const Unit& u) const { return (const char*)(A + (size_t)u.pm * BM * lda); }
;     DI const char* a(const Unit& u) const { return (const char*)(A + (size_t)u.pm * BM * 2048 + (u.pn >> 1) * 512); }
; #define PG8_BAR __builtin_amdgcn_s_barrier()
;     DI void operator()(const f32x4 (&acc)[2][2][4][2], const Unit& u, int wr, int wc, int fr, int fq) const {
;     ...
;             for (int m = 0; m < 4; ++m) { const size_t ro = (size_t)(row0 + ai * HALF + m * 16) * D + col0;
; #pragma unroll
;                 for (int bj = 0; bj < 2; ++bj) {
;                     f32x4 x0, x1;
;                     if constexpr (IB) { const u32x4 w = *(const u32x4*)((const bf16_t*)Xin + ro + bj * HALF);
;                         x0 = (f32x4){bflo(w[0]), bfhi(w[0]), bflo(w[1]), bfhi(w[1])}; x1 = (f32x4){bflo(w[2]), bfhi(w[2]), bflo(w[3]), bfhi(w[3])}; }
;                     else { x0 = *(const f32x4*)((const float*)Xin + ro + bj * HALF); x1 = *(const f32x4*)((const float*)Xin + ro + bj * HALF + 4); }
;                     x0 += acc[ai][bj][m][0] * sc[bj][0]; x1 += acc[ai][bj][m][1] * sc[bj][1];
;                     if constexpr (OB) { u32x4 o; o[0] = pack2(x0[0], x0[1]); o[1] = pack2(x0[2], x0[3]); o[2] = pack2(x1[0], x1[1]); o[3] = pack2(x1[2], x1[3]);
;                         *(u32x4*)((bf16_t*)Xout + ro + bj * HALF) = o; }
;                     else { *(f32x4*)((float*)Xout + ro + bj * HALF) = x0; *(f32x4*)((float*)Xout + ro + bj * HALF + 4) = x1; } } }
; template <class Map, class Epi>
; DI void gemm_phase(LAS unsigned char* lds, const Map& MP, const Epi& E, const int nM, const int nN, const int K, const int lda, const int ldb) {
;     ...
;         if (!has_next) break;
; #pragma unroll
;         for (int a = 0; a < 2; ++a)
; #pragma unroll
;             for (int b = 0; b < 2; ++b)
; #pragma unroll
;                 for (int m = 0; m < 4; ++m)
; #pragma unroll
;                     for (int n = 0; n < 2; ++n) acc[a][b][m][n] = (f32x4){0.f, 0.f, 0.f, 0.f};
;         cur = nxt; cA = nA; cB = nB; ++ui;
;     }
;     PG8_WAIT_V(0);
;     if (wr == 0) PG8_BAR;
;     PG8_BAR;
	v_lshlrev_b32_e32 v44, 16, v40
	v_and_b32_e32 v45, 0xffff0000, v40
	v_lshlrev_b32_e32 v40, 16, v41
	v_and_b32_e32 v41, 0xffff0000, v41
	v_lshlrev_b32_e32 v46, 16, v42
	v_and_b32_e32 v47, 0xffff0000, v42
	v_lshlrev_b32_e32 v42, 16, v43
	v_and_b32_e32 v43, 0xffff0000, v43
	v_pk_add_f32 v[38:39], v[38:39], v[40:41]
	v_pk_add_f32 v[36:37], v[36:37], v[44:45]
	v_pk_add_f32 v[40:41], v[34:35], v[42:43]
	v_pk_add_f32 v[34:35], v[32:33], v[46:47]
	v_cvt_pk_bf16_f32 v32, v36, v37
	v_cvt_pk_bf16_f32 v33, v38, v39
	v_cvt_pk_bf16_f32 v34, v34, v35
	v_cvt_pk_bf16_f32 v35, v40, v41
	global_store_dwordx4 v[48:49], v[32:35], off offset:256
	s_nop 1
	v_lshl_add_u64 v[32:33], v[144:145], 0, s[2:3]
	s_mov_b32 s2, 0xa0000
	v_add_co_u32_e32 v38, vcc, s2, v144
	s_mov_b64 s[2:3], 0xb0000
	s_nop 0
	v_addc_co_u32_e32 v39, vcc, 0, v145, vcc
	s_waitcnt vmcnt(15)
	s_nop 1
	v_mov_b32_e32 v34, v210
	v_mov_b32_e32 v35, v211
	v_mov_b32_e32 v36, v212
	v_mov_b32_e32 v37, v213
	s_waitcnt lgkmcnt(0)
	v_lshlrev_b32_e32 v40, 16, v34
	v_and_b32_e32 v41, 0xffff0000, v34
	v_lshlrev_b32_e32 v34, 16, v35
	v_and_b32_e32 v35, 0xffff0000, v35
	v_lshlrev_b32_e32 v42, 16, v36
	v_and_b32_e32 v43, 0xffff0000, v36
	v_lshlrev_b32_e32 v36, 16, v37
	v_and_b32_e32 v37, 0xffff0000, v37
	v_pk_add_f32 v[30:31], v[30:31], v[34:35]
	v_pk_add_f32 v[28:29], v[28:29], v[40:41]
	v_pk_add_f32 v[34:35], v[26:27], v[36:37]
	v_pk_add_f32 v[26:27], v[24:25], v[42:43]
	v_cvt_pk_bf16_f32 v24, v28, v29
	v_cvt_pk_bf16_f32 v25, v30, v31
	v_cvt_pk_bf16_f32 v26, v26, v27
	v_cvt_pk_bf16_f32 v27, v34, v35
	global_store_dwordx4 v[38:39], v[24:27], off
	s_waitcnt vmcnt(15)
	s_nop 1
	v_mov_b32_e32 v24, v214
	v_mov_b32_e32 v25, v215
	v_mov_b32_e32 v26, v216
	v_mov_b32_e32 v27, v217
	s_waitcnt lgkmcnt(0)
	v_lshlrev_b32_e32 v28, 16, v24
	v_and_b32_e32 v29, 0xffff0000, v24
	v_lshlrev_b32_e32 v24, 16, v25
	v_and_b32_e32 v25, 0xffff0000, v25
	v_lshlrev_b32_e32 v30, 16, v26
	v_and_b32_e32 v31, 0xffff0000, v26
	v_lshlrev_b32_e32 v26, 16, v27
	v_and_b32_e32 v27, 0xffff0000, v27
	v_pk_add_f32 v[22:23], v[22:23], v[24:25]
	v_pk_add_f32 v[20:21], v[20:21], v[28:29]
	v_pk_add_f32 v[24:25], v[18:19], v[26:27]
	v_pk_add_f32 v[18:19], v[16:17], v[30:31]
	v_cvt_pk_bf16_f32 v16, v20, v21
	v_cvt_pk_bf16_f32 v17, v22, v23
	v_cvt_pk_bf16_f32 v18, v18, v19
	v_cvt_pk_bf16_f32 v19, v24, v25
	global_store_dwordx4 v[32:33], v[16:19], off offset:256
	s_nop 1
	v_lshl_add_u64 v[16:17], v[144:145], 0, s[2:3]
	s_mov_b32 s2, 0xb0000
	v_add_co_u32_e32 v22, vcc, s2, v144
	s_mov_b32 s2, s44
	s_nop 0
	v_addc_co_u32_e32 v23, vcc, 0, v145, vcc
	s_waitcnt vmcnt(15)
	s_nop 1
	v_mov_b32_e32 v18, v248
	v_mov_b32_e32 v19, v249
	v_mov_b32_e32 v20, v250
	v_mov_b32_e32 v21, v251
	s_and_b64 vcc, exec, s[40:41]
	s_waitcnt lgkmcnt(0)
	v_lshlrev_b32_e32 v24, 16, v18
	v_and_b32_e32 v25, 0xffff0000, v18
	v_lshlrev_b32_e32 v18, 16, v19
	v_and_b32_e32 v19, 0xffff0000, v19
	v_lshlrev_b32_e32 v26, 16, v20
	v_and_b32_e32 v27, 0xffff0000, v20
	v_lshlrev_b32_e32 v20, 16, v21
	v_and_b32_e32 v21, 0xffff0000, v21
	v_pk_add_f32 v[14:15], v[14:15], v[18:19]
	v_pk_add_f32 v[12:13], v[12:13], v[24:25]
	v_pk_add_f32 v[18:19], v[10:11], v[20:21]
	v_pk_add_f32 v[10:11], v[8:9], v[26:27]
	v_cvt_pk_bf16_f32 v8, v12, v13
	v_cvt_pk_bf16_f32 v9, v14, v15
	v_cvt_pk_bf16_f32 v10, v10, v11
	v_cvt_pk_bf16_f32 v11, v18, v19
	global_store_dwordx4 v[22:23], v[8:11], off
	s_waitcnt vmcnt(15)
	s_nop 1
	v_mov_b32_e32 v8, v252
	v_mov_b32_e32 v9, v253
	v_mov_b32_e32 v10, v254
	v_mov_b32_e32 v11, v255
	s_waitcnt lgkmcnt(0)
	v_lshlrev_b32_e32 v12, 16, v8
	v_and_b32_e32 v13, 0xffff0000, v8
	v_lshlrev_b32_e32 v8, 16, v9
	v_and_b32_e32 v9, 0xffff0000, v9
	v_lshlrev_b32_e32 v14, 16, v10
	v_and_b32_e32 v15, 0xffff0000, v10
	v_lshlrev_b32_e32 v10, 16, v11
	v_and_b32_e32 v11, 0xffff0000, v11
	v_pk_add_f32 v[6:7], v[6:7], v[8:9]
	v_pk_add_f32 v[4:5], v[4:5], v[12:13]
	v_pk_add_f32 v[8:9], v[2:3], v[10:11]
	v_pk_add_f32 v[2:3], v[0:1], v[14:15]
	v_cvt_pk_bf16_f32 v0, v4, v5
	v_cvt_pk_bf16_f32 v1, v6, v7
	v_cvt_pk_bf16_f32 v2, v2, v3
	v_cvt_pk_bf16_f32 v3, v8, v9
	global_store_dwordx4 v[16:17], v[0:3], off offset:256
	s_cbranch_vccz .LBB1_1761
	s_waitcnt vmcnt(0)
	s_cmpk_gt_u32 s17, 0xff
	s_cbranch_scc1 .LBB1_1768
	s_barrier

; #define PG8_STAGE(bufoff, gbase, voff) do { _Pragma("unroll") for (int _i = 0; _i < 2; ++_i) \
;         __builtin_amdgcn_global_load_lds((const unsigned*)((const char*)(gbase) + (voff)[_i]), (LAS unsigned*)(lds + (bufoff) + ldsw + _i * 8192), 16, 0, 0); } while (0)
; #define PG8_LDA(dst, b, h) do { _Pragma("unroll") for (int m = 0; m < 4; ++m) _Pragma("unroll") for (int k = 0; k < 2; ++k) dst[m][k] = *(const LAS bf16x8*)(lds + PG8_SA(b, h) + aoff + m * 2048 + k * 1024); } while (0)
; #define PG8_LDB(dst, b, h) do { _Pragma("unroll") for (int n = 0; n < 2; ++n) _Pragma("unroll") for (int k = 0; k < 2; ++k) dst[n][k] = *(const LAS bf16x8*)(lds + PG8_SB(b, h) + boff + n * 2048 + k * 1024); } while (0)
; #define PG8_MMA(ai, bj, At, Bt) do { __builtin_amdgcn_s_setprio(1); _Pragma("unroll") for (int m = 0; m < 4; ++m) _Pragma("unroll") for (int n = 0; n < 2; ++n) _Pragma("unroll") for (int k = 0; k < 2; ++k) \
;         acc[ai][bj][m][n] = __builtin_amdgcn_mfma_f32_16x16x32_bf16(Bt[n][k], At[m][k], acc[ai][bj][m][n], 0, 0, 0); __builtin_amdgcn_s_setprio(0); } while (0)
; #define PG8_WAIT_V(n) asm volatile("s_waitcnt vmcnt(" #n ")" ::: "memory")
; #define PG8_WAIT_L(n) asm volatile("s_waitcnt lgkmcnt(" #n ")" ::: "memory")
; template <class Map, class Epi>
; DI void gemm_phase(LAS unsigned char* lds, const Map& MP, const Epi& E, const int nM, const int nN, const int K, const int lda, const int ldb) {
;     ...
;         for (int t = 0; t < nt; t += 2) {
;             const bool last = (t == nt - 2);
;             const char* a1 = cA + (size_t)(t + 1) * kstep;
;             const char* a2 = last ? nA : cA + (size_t)(t + 2) * kstep; const char* b2 = last ? nB : cB + (size_t)(t + 2) * kstep;
;             const char* a3 = a2 + kstep; const char* b3 = b2 + kstep;
;             PG8_LDB(B0, 0, 0); PG8_SCHED; PG8_LDA(At, 0, 0); PG8_STAGE(PG8_SA(1, 1), a1 + hstepA, voffA);
;             PG8_WAIT_L(8); PG8_BAR; PG8_WAIT_L(0); PG8_MMA(0, 0, At, B0); PG8_BAR; PG8_SCHED;
;             PG8_LDB(B1, 0, 1); PG8_STAGE(PG8_SB(0, 0), b2, voffB);
;             PG8_BAR; PG8_WAIT_L(0); PG8_MMA(0, 1, At, B1); PG8_BAR;
;             PG8_LDA(At, 0, 1); PG8_STAGE(PG8_SA(0, 0), a2, voffA);
;             PG8_BAR; PG8_WAIT_L(0); PG8_MMA(1, 0, At, B0); PG8_BAR; PG8_SCHED;
;             PG8_STAGE(PG8_SB(0, 1), b2 + hstepB, voffB);
;             PG8_WAIT_V(6); PG8_BAR; PG8_MMA(1, 1, At, B1); PG8_BAR;
.LBB1_1908:
	s_add_u32 s28, s42, 0xfff80080
	s_addc_u32 s29, s43, -1
	s_cmp_eq_u32 s3, 28
	s_cselect_b32 s47, s23, s29
	s_cselect_b32 s46, s58, s28
	s_cselect_b32 s29, s21, vcc_hi
	s_cselect_b32 s28, s59, vcc_lo
	s_add_i32 m0, s38, 0xc000
	ds_read_b128 v[96:99], v190
	ds_read_b128 v[100:103], v190 offset:1024
	ds_read_b128 v[108:111], v190 offset:2048
	ds_read_b128 v[112:115], v190 offset:3072
	ds_read_b128 v[160:163], v190 offset:4096
	ds_read_b128 v[164:167], v190 offset:5120
	ds_read_b128 v[198:201], v190 offset:6144
	ds_read_b128 v[202:205], v190 offset:7168
	global_load_lds_dwordx4 v178, s[42:43]
	s_add_i32 m0, s38, 0xe000
	s_nop 0
	global_load_lds_dwordx4 v176, s[42:43]
	s_waitcnt lgkmcnt(8)
	s_setprio 1
	s_barrier
	s_waitcnt lgkmcnt(7)
	v_mfma_f32_16x16x32_bf16 v[148:151], v[80:83], v[96:99], v[148:151]
	v_mfma_f32_16x16x32_bf16 v[144:147], v[88:91], v[96:99], v[144:147]
	s_waitcnt lgkmcnt(5)
	v_mfma_f32_16x16x32_bf16 v[136:139], v[80:83], v[108:111], v[136:139]
	v_mfma_f32_16x16x32_bf16 v[128:131], v[88:91], v[108:111], v[128:131]
	s_waitcnt lgkmcnt(3)
	v_mfma_f32_16x16x32_bf16 v[120:123], v[80:83], v[160:163], v[120:123]
	v_mfma_f32_16x16x32_bf16 v[104:107], v[88:91], v[160:163], v[104:107]
	s_waitcnt lgkmcnt(1)
	v_mfma_f32_16x16x32_bf16 v[76:79], v[80:83], v[198:201], v[76:79]
	v_mfma_f32_16x16x32_bf16 v[72:75], v[88:91], v[198:201], v[72:75]
	v_mfma_f32_16x16x32_bf16 v[148:151], v[84:87], v[100:103], v[148:151]
	v_mfma_f32_16x16x32_bf16 v[144:147], v[92:95], v[100:103], v[144:147]
	v_mfma_f32_16x16x32_bf16 v[136:139], v[84:87], v[112:115], v[136:139]
	v_mfma_f32_16x16x32_bf16 v[128:131], v[92:95], v[112:115], v[128:131]
	v_mfma_f32_16x16x32_bf16 v[120:123], v[84:87], v[164:167], v[120:123]
	v_mfma_f32_16x16x32_bf16 v[104:107], v[92:95], v[164:167], v[104:107]
	s_waitcnt lgkmcnt(0)
	v_mfma_f32_16x16x32_bf16 v[76:79], v[84:87], v[202:205], v[76:79]
	v_mfma_f32_16x16x32_bf16 v[72:75], v[92:95], v[202:205], v[72:75]
	s_barrier
	s_setprio 0
	s_add_i32 s68, s2, s54
	v_lshl_add_u64 v[184:185], s[28:29], 0, v[172:173]
	s_mov_b32 m0, s68
	ds_read_b128 v[206:209], v191
	ds_read_b128 v[210:213], v191 offset:1024
	ds_read_b128 v[214:217], v191 offset:2048
	ds_read_b128 v[218:221], v191 offset:3072
	global_load_lds_dwordx4 v[184:185], off
	v_lshl_add_u64 v[194:195], s[28:29], 0, v[168:169]
	s_add_i32 m0, s68, 0x2000
	s_nop 0
	global_load_lds_dwordx4 v[194:195], off
	s_setprio 1
	s_barrier
	s_waitcnt lgkmcnt(3)
	v_mfma_f32_16x16x32_bf16 v[156:159], v[206:209], v[96:99], v[156:159]
	s_waitcnt lgkmcnt(1)
	v_mfma_f32_16x16x32_bf16 v[96:99], v[214:217], v[96:99], v[152:155]
	v_mfma_f32_16x16x32_bf16 v[156:159], v[210:213], v[100:103], v[156:159]
	s_waitcnt lgkmcnt(0)
	v_mfma_f32_16x16x32_bf16 v[96:99], v[218:221], v[100:103], v[96:99]
	v_mfma_f32_16x16x32_bf16 v[100:103], v[206:209], v[108:111], v[140:143]
	v_mfma_f32_16x16x32_bf16 v[108:111], v[214:217], v[108:111], v[132:135]
	v_mfma_f32_16x16x32_bf16 v[116:119], v[214:217], v[160:163], v[116:119]
	v_mfma_f32_16x16x32_bf16 v[68:71], v[206:209], v[198:201], v[68:71]
	v_mfma_f32_16x16x32_bf16 v[64:67], v[214:217], v[198:201], v[64:67]
	s_mov_b32 m0, s38
	v_mfma_f32_16x16x32_bf16 v[100:103], v[210:213], v[112:115], v[100:103]
	v_lshl_add_u64 v[226:227], s[46:47], 0, v[174:175]
	v_mfma_f32_16x16x32_bf16 v[108:111], v[218:221], v[112:115], v[108:111]
	v_mfma_f32_16x16x32_bf16 v[112:115], v[206:209], v[160:163], v[124:127]
	v_mfma_f32_16x16x32_bf16 v[116:119], v[218:221], v[164:167], v[116:119]
	v_mfma_f32_16x16x32_bf16 v[68:71], v[210:213], v[202:205], v[68:71]
	v_mfma_f32_16x16x32_bf16 v[64:67], v[218:221], v[202:205], v[64:67]
	v_mfma_f32_16x16x32_bf16 v[112:115], v[210:213], v[164:167], v[112:115]
	s_barrier
	s_setprio 0
	ds_read_b128 v[124:127], v190 offset:16384
	ds_read_b128 v[132:135], v190 offset:17408
	ds_read_b128 v[140:143], v190 offset:18432
	ds_read_b128 v[152:155], v190 offset:19456
	ds_read_b128 v[160:163], v190 offset:20480
	ds_read_b128 v[164:167], v190 offset:21504
	ds_read_b128 v[198:201], v190 offset:22528
	ds_read_b128 v[202:205], v190 offset:23552
	global_load_lds_dwordx4 v[226:227], off
	v_lshl_add_u64 v[234:235], s[46:47], 0, v[170:171]
	s_mov_b32 m0, s39
	s_nop 0
	global_load_lds_dwordx4 v[234:235], off
	s_waitcnt vmcnt(10)
	s_setprio 1
	s_barrier
	s_waitcnt lgkmcnt(7)
	v_mfma_f32_16x16x32_bf16 v[60:63], v[80:83], v[124:127], v[60:63]
	v_mfma_f32_16x16x32_bf16 v[48:51], v[88:91], v[124:127], v[48:51]
	s_waitcnt lgkmcnt(5)
	v_mfma_f32_16x16x32_bf16 v[40:43], v[80:83], v[140:143], v[40:43]
	v_mfma_f32_16x16x32_bf16 v[32:35], v[88:91], v[140:143], v[32:35]
	s_waitcnt lgkmcnt(3)
	v_mfma_f32_16x16x32_bf16 v[24:27], v[80:83], v[160:163], v[24:27]
	v_mfma_f32_16x16x32_bf16 v[16:19], v[88:91], v[160:163], v[16:19]
	s_waitcnt lgkmcnt(1)
	v_mfma_f32_16x16x32_bf16 v[12:15], v[80:83], v[198:201], v[12:15]
	v_mfma_f32_16x16x32_bf16 v[8:11], v[88:91], v[198:201], v[8:11]
	v_mfma_f32_16x16x32_bf16 v[60:63], v[84:87], v[132:135], v[60:63]
	v_mfma_f32_16x16x32_bf16 v[48:51], v[92:95], v[132:135], v[48:51]
	v_mfma_f32_16x16x32_bf16 v[40:43], v[84:87], v[152:155], v[40:43]
	v_mfma_f32_16x16x32_bf16 v[32:35], v[92:95], v[152:155], v[32:35]
	v_mfma_f32_16x16x32_bf16 v[24:27], v[84:87], v[164:167], v[24:27]
	v_mfma_f32_16x16x32_bf16 v[16:19], v[92:95], v[164:167], v[16:19]
	s_waitcnt lgkmcnt(0)
	v_mfma_f32_16x16x32_bf16 v[12:15], v[84:87], v[202:205], v[12:15]
	v_mfma_f32_16x16x32_bf16 v[8:11], v[92:95], v[202:205], v[8:11]
	s_barrier
	s_setprio 0
	s_add_u32 s68, s28, 0x80000
	s_addc_u32 s69, s29, 0
	s_add_i32 s70, s31, s54
	s_mov_b32 m0, s70
	s_nop 0
	global_load_lds_dwordx4 v172, s[68:69]
	s_add_i32 m0, s70, 0x2000
	s_nop 0
	global_load_lds_dwordx4 v168, s[68:69]
	s_waitcnt vmcnt(6)
	s_setprio 1
	s_barrier
; #define PG8_STAGE(bufoff, gbase, voff) do { _Pragma("unroll") for (int _i = 0; _i < 2; ++_i) \
;         __builtin_amdgcn_global_load_lds((const unsigned*)((const char*)(gbase) + (voff)[_i]), (LAS unsigned*)(lds + (bufoff) + ldsw + _i * 8192), 16, 0, 0); } while (0)
; #define PG8_LDA(dst, b, h) do { _Pragma("unroll") for (int m = 0; m < 4; ++m) _Pragma("unroll") for (int k = 0; k < 2; ++k) dst[m][k] = *(const LAS bf16x8*)(lds + PG8_SA(b, h) + aoff + m * 2048 + k * 1024); } while (0)
; #define PG8_LDB(dst, b, h) do { _Pragma("unroll") for (int n = 0; n < 2; ++n) _Pragma("unroll") for (int k = 0; k < 2; ++k) dst[n][k] = *(const LAS bf16x8*)(lds + PG8_SB(b, h) + boff + n * 2048 + k * 1024); } while (0)
; #define PG8_MMA(ai, bj, At, Bt) do { __builtin_amdgcn_s_setprio(1); _Pragma("unroll") for (int m = 0; m < 4; ++m) _Pragma("unroll") for (int n = 0; n < 2; ++n) _Pragma("unroll") for (int k = 0; k < 2; ++k) \
;         acc[ai][bj][m][n] = __builtin_amdgcn_mfma_f32_16x16x32_bf16(Bt[n][k], At[m][k], acc[ai][bj][m][n], 0, 0, 0); __builtin_amdgcn_s_setprio(0); } while (0)
; #define PG8_WAIT_V(n) asm volatile("s_waitcnt vmcnt(" #n ")" ::: "memory")
; #define PG8_WAIT_L(n) asm volatile("s_waitcnt lgkmcnt(" #n ")" ::: "memory")
; #define PG8_BAR __builtin_amdgcn_s_barrier()
; #define PG8_SCHED __builtin_amdgcn_sched_barrier(0)
; template <class Map, class Epi>
; DI void gemm_phase(LAS unsigned char* lds, const Map& MP, const Epi& E, const int nM, const int nN, const int K, const int lda, const int ldb) {
;     ...
;             PG8_BAR; PG8_WAIT_L(0); PG8_MMA(1, 0, At, B0); PG8_BAR; PG8_SCHED;
;             PG8_STAGE(PG8_SB(0, 1), b2 + hstepB, voffB);
;             PG8_WAIT_V(6); PG8_BAR; PG8_MMA(1, 1, At, B1); PG8_BAR;
;             PG8_LDB(B0, 1, 0); PG8_SCHED; PG8_LDA(At, 1, 0); PG8_STAGE(PG8_SA(0, 1), a2 + hstepA, voffA);
;             PG8_WAIT_L(8); PG8_BAR; PG8_WAIT_L(0); PG8_MMA(0, 0, At, B0); PG8_BAR; PG8_SCHED;
;             PG8_LDB(B1, 1, 1); PG8_STAGE(PG8_SB(1, 0), b3, voffB);
;             PG8_BAR; PG8_WAIT_L(0); PG8_MMA(0, 1, At, B1); PG8_BAR;
;             PG8_LDA(At, 1, 1); PG8_STAGE(PG8_SA(1, 0), a3, voffA);
	v_mfma_f32_16x16x32_bf16 v[56:59], v[206:209], v[124:127], v[56:59]
	v_mfma_f32_16x16x32_bf16 v[52:55], v[214:217], v[124:127], v[52:55]
	s_add_i32 s68, 0, 0x18000
	v_add_u32_e32 v92, s68, v188
	ds_read_b128 v[80:83], v92
	v_mfma_f32_16x16x32_bf16 v[44:47], v[206:209], v[140:143], v[44:47]
	v_mfma_f32_16x16x32_bf16 v[36:39], v[214:217], v[140:143], v[36:39]
	ds_read_b128 v[84:87], v92 offset:1024
	v_mfma_f32_16x16x32_bf16 v[28:31], v[206:209], v[160:163], v[28:31]
	v_mfma_f32_16x16x32_bf16 v[20:23], v[214:217], v[160:163], v[20:23]
	ds_read_b128 v[88:91], v92 offset:2048
	v_mfma_f32_16x16x32_bf16 v[4:7], v[206:209], v[198:201], v[4:7]
	v_mfma_f32_16x16x32_bf16 v[0:3], v[214:217], v[198:201], v[0:3]
	ds_read_b128 v[92:95], v92 offset:3072
	v_mfma_f32_16x16x32_bf16 v[56:59], v[210:213], v[132:135], v[56:59]
	v_mfma_f32_16x16x32_bf16 v[52:55], v[218:221], v[132:135], v[52:55]
	v_mfma_f32_16x16x32_bf16 v[44:47], v[210:213], v[152:155], v[44:47]
	v_mfma_f32_16x16x32_bf16 v[36:39], v[218:221], v[152:155], v[36:39]
	v_mfma_f32_16x16x32_bf16 v[28:31], v[210:213], v[164:167], v[28:31]
	v_mfma_f32_16x16x32_bf16 v[20:23], v[218:221], v[164:167], v[20:23]
	v_mfma_f32_16x16x32_bf16 v[4:7], v[210:213], v[202:205], v[4:7]
	v_mfma_f32_16x16x32_bf16 v[0:3], v[218:221], v[202:205], v[0:3]
	s_barrier
	s_setprio 0
	s_add_u32 s46, s46, 0x80000
	s_addc_u32 s47, s47, 0
	s_mov_b32 m0, s56
	ds_read_b128 v[124:127], v190 offset:32768
	ds_read_b128 v[132:135], v190 offset:33792
	ds_read_b128 v[160:163], v190 offset:34816
	ds_read_b128 v[164:167], v190 offset:35840
	ds_read_b128 v[198:201], v190 offset:36864
	ds_read_b128 v[202:205], v190 offset:37888
	ds_read_b128 v[206:209], v190 offset:38912
	ds_read_b128 v[210:213], v190 offset:39936
	global_load_lds_dwordx4 v174, s[46:47]
	s_mov_b32 m0, s57
	s_nop 0
	global_load_lds_dwordx4 v170, s[46:47]
	s_waitcnt lgkmcnt(8)
	s_setprio 1
	s_barrier
	s_waitcnt lgkmcnt(7)
	v_mfma_f32_16x16x32_bf16 v[140:143], v[80:83], v[124:127], v[148:151]
	s_waitcnt lgkmcnt(6)
	v_mfma_f32_16x16x32_bf16 v[148:151], v[84:87], v[132:135], v[140:143]
	v_mfma_f32_16x16x32_bf16 v[140:143], v[88:91], v[124:127], v[144:147]
	s_waitcnt lgkmcnt(5)
	v_mfma_f32_16x16x32_bf16 v[136:139], v[80:83], v[160:163], v[136:139]
	v_mfma_f32_16x16x32_bf16 v[128:131], v[88:91], v[160:163], v[128:131]
	s_waitcnt lgkmcnt(3)
	v_mfma_f32_16x16x32_bf16 v[120:123], v[80:83], v[198:201], v[120:123]
	v_mfma_f32_16x16x32_bf16 v[104:107], v[88:91], v[198:201], v[104:107]
	s_waitcnt lgkmcnt(1)
	v_mfma_f32_16x16x32_bf16 v[76:79], v[80:83], v[206:209], v[76:79]
	v_mfma_f32_16x16x32_bf16 v[72:75], v[88:91], v[206:209], v[72:75]
	v_mfma_f32_16x16x32_bf16 v[144:147], v[92:95], v[132:135], v[140:143]
	v_mfma_f32_16x16x32_bf16 v[136:139], v[84:87], v[164:167], v[136:139]
	v_mfma_f32_16x16x32_bf16 v[128:131], v[92:95], v[164:167], v[128:131]
	v_mfma_f32_16x16x32_bf16 v[120:123], v[84:87], v[202:205], v[120:123]
	v_mfma_f32_16x16x32_bf16 v[104:107], v[92:95], v[202:205], v[104:107]
	s_waitcnt lgkmcnt(0)
	v_mfma_f32_16x16x32_bf16 v[76:79], v[84:87], v[210:213], v[76:79]
	v_mfma_f32_16x16x32_bf16 v[72:75], v[92:95], v[210:213], v[72:75]
	s_barrier
	s_setprio 0
	s_add_i32 s46, 0, 0x1c000
	v_add_u32_e32 v140, s46, v188
	s_add_i32 s47, s68, s54
	ds_read_b128 v[214:217], v140
	ds_read_b128 v[218:221], v140 offset:1024
	ds_read_b128 v[222:225], v140 offset:2048
	ds_read_b128 v[230:233], v140 offset:3072
	v_lshl_add_u64 v[140:141], v[184:185], 0, s[14:15]
	s_mov_b32 m0, s47
	s_nop 0
	global_load_lds_dwordx4 v[140:141], off
	v_lshl_add_u64 v[140:141], v[194:195], 0, s[14:15]
	s_add_i32 m0, s47, 0x2000
	s_nop 0
	global_load_lds_dwordx4 v[140:141], off
	s_setprio 1
	s_barrier
	s_waitcnt lgkmcnt(1)
	v_mfma_f32_16x16x32_bf16 v[96:99], v[222:225], v[124:127], v[96:99]
	v_mfma_f32_16x16x32_bf16 v[140:143], v[214:217], v[124:127], v[156:159]
	s_waitcnt lgkmcnt(0)
	v_mfma_f32_16x16x32_bf16 v[152:155], v[230:233], v[132:135], v[96:99]
	v_mfma_f32_16x16x32_bf16 v[96:99], v[214:217], v[160:163], v[100:103]
	v_mfma_f32_16x16x32_bf16 v[156:159], v[218:221], v[132:135], v[140:143]
	v_mfma_f32_16x16x32_bf16 v[140:143], v[218:221], v[164:167], v[96:99]
	v_mfma_f32_16x16x32_bf16 v[96:99], v[222:225], v[160:163], v[108:111]
	v_mfma_f32_16x16x32_bf16 v[132:135], v[230:233], v[164:167], v[96:99]
	v_mfma_f32_16x16x32_bf16 v[96:99], v[214:217], v[198:201], v[112:115]
	s_mov_b32 m0, s63
	v_mfma_f32_16x16x32_bf16 v[124:127], v[218:221], v[202:205], v[96:99]
	v_lshl_add_u64 v[184:185], v[226:227], 0, s[14:15]
	v_mfma_f32_16x16x32_bf16 v[96:99], v[222:225], v[198:201], v[116:119]
	v_mfma_f32_16x16x32_bf16 v[68:71], v[214:217], v[206:209], v[68:71]
	v_mfma_f32_16x16x32_bf16 v[64:67], v[222:225], v[206:209], v[64:67]
	v_mfma_f32_16x16x32_bf16 v[116:119], v[230:233], v[202:205], v[96:99]
	v_mfma_f32_16x16x32_bf16 v[68:71], v[218:221], v[210:213], v[68:71]
	v_mfma_f32_16x16x32_bf16 v[64:67], v[230:233], v[210:213], v[64:67]
	s_barrier
	s_setprio 0
	ds_read_b128 v[96:99], v190 offset:49152
	ds_read_b128 v[100:103], v190 offset:50176
	ds_read_b128 v[108:111], v190 offset:51200
	ds_read_b128 v[112:115], v190 offset:52224
	ds_read_b128 v[160:163], v190 offset:53248
	ds_read_b128 v[164:167], v190 offset:54272
	ds_read_b128 v[198:201], v190 offset:55296
	ds_read_b128 v[202:205], v190 offset:56320
	global_load_lds_dwordx4 v[184:185], off
	v_lshl_add_u64 v[184:185], v[234:235], 0, s[14:15]
	s_mov_b32 m0, s66
	s_nop 0
	global_load_lds_dwordx4 v[184:185], off
	s_waitcnt vmcnt(10)
	s_setprio 1
	s_barrier
; #define PG8_STAGE(bufoff, gbase, voff) do { _Pragma("unroll") for (int _i = 0; _i < 2; ++_i) \
;         __builtin_amdgcn_global_load_lds((const unsigned*)((const char*)(gbase) + (voff)[_i]), (LAS unsigned*)(lds + (bufoff) + ldsw + _i * 8192), 16, 0, 0); } while (0)
; #define PG8_LDA(dst, b, h) do { _Pragma("unroll") for (int m = 0; m < 4; ++m) _Pragma("unroll") for (int k = 0; k < 2; ++k) dst[m][k] = *(const LAS bf16x8*)(lds + PG8_SA(b, h) + aoff + m * 2048 + k * 1024); } while (0)
; #define PG8_MMA(ai, bj, At, Bt) do { __builtin_amdgcn_s_setprio(1); _Pragma("unroll") for (int m = 0; m < 4; ++m) _Pragma("unroll") for (int n = 0; n < 2; ++n) _Pragma("unroll") for (int k = 0; k < 2; ++k) \
;         acc[ai][bj][m][n] = __builtin_amdgcn_mfma_f32_16x16x32_bf16(Bt[n][k], At[m][k], acc[ai][bj][m][n], 0, 0, 0); __builtin_amdgcn_s_setprio(0); } while (0)
; #define PG8_WAIT_V(n) asm volatile("s_waitcnt vmcnt(" #n ")" ::: "memory")
; #define PG8_WAIT_L(n) asm volatile("s_waitcnt lgkmcnt(" #n ")" ::: "memory")
; #define PG8_BAR __builtin_amdgcn_s_barrier()
; #define PG8_SCHED __builtin_amdgcn_sched_barrier(0)
; template <class Map, class Epi>
; DI void gemm_phase(LAS unsigned char* lds, const Map& MP, const Epi& E, const int nM, const int nN, const int K, const int lda, const int ldb) {
;     ...
;             PG8_LDA(At, 1, 1); PG8_STAGE(PG8_SA(1, 0), a3, voffA);
;             PG8_BAR; PG8_WAIT_L(0); PG8_MMA(1, 0, At, B0); PG8_BAR; PG8_SCHED;
;             PG8_STAGE(PG8_SB(1, 1), b3 + hstepB, voffB);
;             PG8_WAIT_V(6); PG8_BAR; PG8_MMA(1, 1, At, B1); PG8_BAR;
	s_waitcnt lgkmcnt(7)
	v_mfma_f32_16x16x32_bf16 v[60:63], v[80:83], v[96:99], v[60:63]
	v_mfma_f32_16x16x32_bf16 v[48:51], v[88:91], v[96:99], v[48:51]
	s_waitcnt lgkmcnt(5)
	v_mfma_f32_16x16x32_bf16 v[40:43], v[80:83], v[108:111], v[40:43]
	v_mfma_f32_16x16x32_bf16 v[32:35], v[88:91], v[108:111], v[32:35]
	s_waitcnt lgkmcnt(3)
	v_mfma_f32_16x16x32_bf16 v[24:27], v[80:83], v[160:163], v[24:27]
	v_mfma_f32_16x16x32_bf16 v[16:19], v[88:91], v[160:163], v[16:19]
	s_waitcnt lgkmcnt(1)
	v_mfma_f32_16x16x32_bf16 v[12:15], v[80:83], v[198:201], v[12:15]
	v_mfma_f32_16x16x32_bf16 v[8:11], v[88:91], v[198:201], v[8:11]
	v_mfma_f32_16x16x32_bf16 v[60:63], v[84:87], v[100:103], v[60:63]
	v_mfma_f32_16x16x32_bf16 v[48:51], v[92:95], v[100:103], v[48:51]
	v_mfma_f32_16x16x32_bf16 v[40:43], v[84:87], v[112:115], v[40:43]
	v_mfma_f32_16x16x32_bf16 v[32:35], v[92:95], v[112:115], v[32:35]
	v_mfma_f32_16x16x32_bf16 v[24:27], v[84:87], v[164:167], v[24:27]
	v_mfma_f32_16x16x32_bf16 v[16:19], v[92:95], v[164:167], v[16:19]
	s_waitcnt lgkmcnt(0)
	v_mfma_f32_16x16x32_bf16 v[12:15], v[84:87], v[202:205], v[12:15]
	v_mfma_f32_16x16x32_bf16 v[8:11], v[92:95], v[202:205], v[8:11]
	s_barrier
	s_setprio 0
	s_add_u32 s28, s28, 0x80080
	s_addc_u32 s29, s29, 0
	s_add_i32 s46, s46, s54
	s_mov_b32 m0, s46
	s_nop 0
	global_load_lds_dwordx4 v172, s[28:29]
	s_add_i32 m0, s46, 0x2000
	s_nop 0
	global_load_lds_dwordx4 v168, s[28:29]
	s_waitcnt vmcnt(6)
	s_setprio 1
	s_barrier
	v_mfma_f32_16x16x32_bf16 v[56:59], v[214:217], v[96:99], v[56:59]
	v_mfma_f32_16x16x32_bf16 v[52:55], v[222:225], v[96:99], v[52:55]
	ds_read_b128 v[80:83], v189
	v_mfma_f32_16x16x32_bf16 v[44:47], v[214:217], v[108:111], v[44:47]
	v_mfma_f32_16x16x32_bf16 v[36:39], v[222:225], v[108:111], v[36:39]
	ds_read_b128 v[84:87], v189 offset:1024
	v_mfma_f32_16x16x32_bf16 v[28:31], v[214:217], v[160:163], v[28:31]
	v_mfma_f32_16x16x32_bf16 v[20:23], v[222:225], v[160:163], v[20:23]
	ds_read_b128 v[88:91], v189 offset:2048
	v_mfma_f32_16x16x32_bf16 v[4:7], v[214:217], v[198:201], v[4:7]
	v_mfma_f32_16x16x32_bf16 v[0:3], v[222:225], v[198:201], v[0:3]
	ds_read_b128 v[92:95], v189 offset:3072
	v_mfma_f32_16x16x32_bf16 v[56:59], v[218:221], v[100:103], v[56:59]
	s_add_i32 s3, s3, 2
	v_mfma_f32_16x16x32_bf16 v[52:55], v[230:233], v[100:103], v[52:55]
	s_add_u32 vcc_lo, vcc_lo, 0x100
	s_addc_u32 vcc_hi, vcc_hi, 0
	v_mfma_f32_16x16x32_bf16 v[44:47], v[218:221], v[112:115], v[44:47]
	s_add_u32 s42, s42, 0x100
	s_addc_u32 s43, s43, 0
	v_mfma_f32_16x16x32_bf16 v[36:39], v[230:233], v[112:115], v[36:39]
	s_cmp_gt_u32 s3, 29
	v_mfma_f32_16x16x32_bf16 v[28:31], v[218:221], v[164:167], v[28:31]
	v_mfma_f32_16x16x32_bf16 v[20:23], v[230:233], v[164:167], v[20:23]
	v_mfma_f32_16x16x32_bf16 v[4:7], v[218:221], v[202:205], v[4:7]
	v_mfma_f32_16x16x32_bf16 v[0:3], v[230:233], v[202:205], v[0:3]
	s_barrier
	s_setprio 0
	s_cbranch_scc0 .LBB1_1908
; DI float silu_mul(float g, float v) { return g * v * __builtin_amdgcn_rcpf(1.0f + __builtin_amdgcn_exp2f(-LOG2E * g)); }
;     DI void operator()(const f32x4 (&acc)[2][2][4][2], const Unit& u, int wr, int wc, int fr, int fq) const {
;         const int row0 = u.pm * BM + wr * 64 + fr, ch0 = u.pn * 128 + wc * 32 + 8 * fq;
;         f32x4 w0[2], w1[2], w2[2], bb[2];
; #pragma unroll
;         for (int n = 0; n < 2; ++n) { w0[n] = *(const f32x4*)(cw + ch0 + 4 * n); w1[n] = *(const f32x4*)(cw + DFF + ch0 + 4 * n); w2[n] = *(const f32x4*)(cw + 2 * DFF + ch0 + 4 * n); bb[n] = *(const f32x4*)(cb + ch0 + 4 * n); }
; #pragma unroll
;         for (int ai = 0; ai < 2; ++ai)
; #pragma unroll
;             for (int m = 0; m < 4; ++m) {
;                 const bool efirst = (m == 0) && (fr == 0), elast = (m == 3) && (fr == 15);
;                 const int row = row0 + ai * HALF + m * 16;
;                 f32x4 gc[2];
; #pragma unroll
;                 for (int n = 0; n < 2; ++n) {
;                     const f32x4 g = acc[ai][0][m][n];
;                     const f32x4 gprev = acc[ai][0][m > 0 ? m - 1 : 0][n], gnext = acc[ai][0][m < 3 ? m + 1 : 3][n];
;                     f32x4 up, dn;
; #pragma unroll
;                     for (int e = 0; e < 4; ++e) {
;                         const float pu = (m > 0 && fr == 15) ? gprev[e] : g[e];
;                         const float pd = (m < 3 && fr == 0) ? gnext[e] : g[e];
;                         up[e] = dpp_ror1(pu); dn[e] = dpp_ror15(pd);
;                     }
;                     if (efirst) up = (f32x4){0.f, 0.f, 0.f, 0.f};
;                     if (elast) dn = (f32x4){0.f, 0.f, 0.f, 0.f};
;                     gc[n] = w0[n] * up + w1[n] * g + w2[n] * dn + bb[n];
;                 }
;                 if (efirst || elast) {
;                     const size_t eo = (size_t)((row >> 6) * 2 + (elast ? 1 : 0)) * DFF + ch0;
; #pragma unroll
;                     for (int n = 0; n < 2; ++n) { *(f32x4*)(EP + eo + 4 * n) = gc[n]; *(f32x4*)(ER + eo + 4 * n) = acc[ai][0][m][n]; *(f32x4*)(EV + eo + 4 * n) = acc[ai][1][m][n]; }
;                 } else {
;                     const f32x4 v0 = acc[ai][1][m][0], v1 = acc[ai][1][m][1];
;                     u32x4 o;
;                     o[0] = pack2(silu_mul(gc[0][0], v0[0]), silu_mul(gc[0][1], v0[1])); o[1] = pack2(silu_mul(gc[0][2], v0[2]), silu_mul(gc[0][3], v0[3]));
	s_waitcnt lgkmcnt(0)
	s_lshl_b32 s21, s45, 7
	v_mov_b32_e32 v194, v186
	v_mov_b32_e32 v80, v187
	s_or_b32 s21, s21, s62
	v_mov_b32_e32 v160, 0
	v_lshl_add_u32 v184, v80, 3, s21
	v_ashrrev_i32_e32 v185, 31, v184
	v_lshlrev_b64 v[80:81], 2, v[184:185]
	v_lshl_add_u64 v[84:85], s[4:5], 0, v[80:81]
	v_lshl_add_u64 v[88:89], s[16:17], 0, v[80:81]
	v_lshl_add_u64 v[92:93], s[18:19], 0, v[80:81]
	v_lshl_add_u64 v[112:113], s[6:7], 0, v[80:81]
	global_load_dwordx4 v[80:83], v[84:85], off offset:16
	global_load_dwordx4 v[96:99], v[84:85], off
	s_nop 0
	global_load_dwordx4 v[84:87], v[88:89], off offset:16
	global_load_dwordx4 v[100:103], v[88:89], off
	s_nop 0
	global_load_dwordx4 v[88:91], v[92:93], off offset:16
	global_load_dwordx4 v[108:111], v[92:93], off
	s_nop 0
	global_load_dwordx4 v[92:95], v[112:113], off offset:16
	s_nop 0
	global_load_dwordx4 v[112:115], v[112:113], off
	v_cmp_eq_u32_e32 vcc, 0, v194
	v_mov_b32_e32 v164, 0
	v_mov_b32_e32 v195, 0
	v_cndmask_b32_e32 v161, v148, v136, vcc
	v_cndmask_b32_e32 v162, v149, v137, vcc
	v_cndmask_b32_e32 v163, v150, v138, vcc
	v_mov_b32_dpp v160, v161 row_ror:15 row_mask:0xf bank_mask:0xf
	v_mov_b32_e32 v161, 0
	v_mov_b32_e32 v166, 0
	v_mov_b32_e32 v167, 0
	v_mov_b32_dpp v161, v162 row_ror:15 row_mask:0xf bank_mask:0xf
	v_mov_b32_e32 v162, 0
	v_mov_b32_dpp v164, v150 row_ror:1 row_mask:0xf bank_mask:0xf
	v_cndmask_b32_e32 v165, v151, v139, vcc
	v_mov_b32_dpp v162, v163 row_ror:15 row_mask:0xf bank_mask:0xf
	v_mov_b32_dpp v195, v151 row_ror:1 row_mask:0xf bank_mask:0xf
	v_mov_b32_e32 v163, 0
	v_mov_b32_dpp v166, v148 row_ror:1 row_mask:0xf bank_mask:0xf
	v_mov_b32_dpp v167, v149 row_ror:1 row_mask:0xf bank_mask:0xf
	v_mov_b32_dpp v163, v165 row_ror:15 row_mask:0xf bank_mask:0xf
	v_cndmask_b32_e64 v165, v195, 0, vcc
	v_cndmask_b32_e64 v164, v164, 0, vcc
	v_cndmask_b32_e64 v167, v167, 0, vcc
	v_cndmask_b32_e64 v166, v166, 0, vcc
	v_mov_b32_e32 v195, 0
	v_mov_b32_e32 v196, 0
	v_mov_b32_e32 v198, 0
	v_mov_b32_e32 v200, 0
	v_mov_b32_dpp v195, v144 row_ror:1 row_mask:0xf bank_mask:0xf
	v_mov_b32_dpp v196, v145 row_ror:1 row_mask:0xf bank_mask:0xf
	v_mov_b32_dpp v198, v146 row_ror:1 row_mask:0xf bank_mask:0xf
	v_cndmask_b32_e32 v199, v147, v131, vcc
	v_mov_b32_dpp v200, v147 row_ror:1 row_mask:0xf bank_mask:0xf
	v_cndmask_b32_e64 v198, v198, 0, vcc
	v_cndmask_b32_e64 v201, v196, 0, vcc
	s_lshl_b32 s3, s44, 8
	s_add_i32 s3, s3, s49
	v_add_u32_e32 v193, s3, v194
	v_cmp_ne_u32_e64 s[46:47], 0, v194
	s_waitcnt vmcnt(0)
	v_pk_mul_f32 v[164:165], v[98:99], v[164:165]
	v_pk_mul_f32 v[166:167], v[96:97], v[166:167]
	v_pk_fma_f32 v[164:165], v[150:151], v[102:103], v[164:165]
	v_pk_fma_f32 v[166:167], v[148:149], v[100:101], v[166:167]
	v_pk_fma_f32 v[162:163], v[110:111], v[162:163], v[164:165]
	v_cndmask_b32_e32 v165, v144, v128, vcc
	v_mov_b32_e32 v164, 0
	v_pk_fma_f32 v[160:161], v[108:109], v[160:161], v[166:167]
	v_cndmask_b32_e32 v166, v145, v129, vcc
	v_mov_b32_dpp v164, v165 row_ror:15 row_mask:0xf bank_mask:0xf
	v_mov_b32_e32 v165, 0
	v_cndmask_b32_e32 v167, v146, v130, vcc
	v_pk_add_f32 v[162:163], v[114:115], v[162:163]
	v_mov_b32_dpp v165, v166 row_ror:15 row_mask:0xf bank_mask:0xf
	v_mov_b32_e32 v166, 0
	v_pk_add_f32 v[160:161], v[112:113], v[160:161]
	s_nop 0
	v_mov_b32_dpp v166, v167 row_ror:15 row_mask:0xf bank_mask:0xf
	v_mov_b32_e32 v167, 0
	s_nop 1
	v_mov_b32_dpp v167, v199 row_ror:15 row_mask:0xf bank_mask:0xf
	v_cndmask_b32_e64 v199, v200, 0, vcc
	v_cndmask_b32_e64 v200, v195, 0, vcc
	v_pk_mul_f32 v[200:201], v[80:81], v[200:201]
	v_pk_mul_f32 v[198:199], v[82:83], v[198:199]
	v_pk_fma_f32 v[200:201], v[144:145], v[84:85], v[200:201]
	v_pk_fma_f32 v[198:199], v[146:147], v[86:87], v[198:199]
	v_pk_fma_f32 v[164:165], v[88:89], v[164:165], v[200:201]
	v_pk_fma_f32 v[166:167], v[90:91], v[166:167], v[198:199]
	v_pk_add_f32 v[164:165], v[92:93], v[164:165]
	v_pk_add_f32 v[166:167], v[94:95], v[166:167]
	s_and_saveexec_b64 s[28:29], s[46:47]
	s_xor_b64 s[28:29], exec, s[28:29]
	s_cbranch_execz .LBB1_1911
	v_mul_f32_e32 v195, 0xbfb8aa3b, v160
	v_exp_f32_e32 v195, v195
	v_mul_f32_e32 v196, 0xbfb8aa3b, v161
	v_exp_f32_e32 v196, v196
	v_pk_mul_f32 v[160:161], v[156:157], v[160:161]
	v_add_f32_e32 v195, 1.0, v195
	v_rcp_f32_e32 v198, v195
	v_add_f32_e32 v196, 1.0, v196
	v_mul_f32_e32 v195, 0xbfb8aa3b, v162
	v_rcp_f32_e32 v199, v196
	v_exp_f32_e32 v195, v195
	v_mul_f32_e32 v196, 0xbfb8aa3b, v163
	v_exp_f32_e32 v196, v196
	v_pk_mul_f32 v[160:161], v[160:161], v[198:199]
	v_add_f32_e32 v195, 1.0, v195
	v_rcp_f32_e32 v200, v195
	v_add_f32_e32 v195, 1.0, v196
	v_rcp_f32_e32 v201, v195
	v_cvt_pk_bf16_f32 v160, v160, v161
	v_mul_f32_e32 v161, 0xbfb8aa3b, v164
	v_exp_f32_e32 v195, v161
	v_mul_f32_e32 v161, 0xbfb8aa3b, v165
	v_exp_f32_e32 v196, v161
	v_pk_mul_f32 v[162:163], v[158:159], v[162:163]
	v_pk_mul_f32 v[164:165], v[152:153], v[164:165]
	v_pk_mul_f32 v[162:163], v[162:163], v[200:201]
	s_nop 0
	v_cvt_pk_bf16_f32 v161, v162, v163
	v_add_f32_e32 v162, 1.0, v195
	v_mul_f32_e32 v195, 0xbfb8aa3b, v166
	v_add_f32_e32 v163, 1.0, v196
	v_exp_f32_e32 v195, v195
	v_mul_f32_e32 v196, 0xbfb8aa3b, v167
	v_exp_f32_e32 v196, v196
	v_rcp_f32_e32 v162, v162
	v_add_f32_e32 v195, 1.0, v195
	v_rcp_f32_e32 v198, v195
	v_add_f32_e32 v195, 1.0, v196
	v_rcp_f32_e32 v163, v163
	v_rcp_f32_e32 v199, v195
	v_pk_mul_f32 v[166:167], v[154:155], v[166:167]
	v_pk_mul_f32 v[162:163], v[164:165], v[162:163]
	v_pk_mul_f32 v[164:165], v[166:167], v[198:199]
	v_cvt_pk_bf16_f32 v162, v162, v163
	v_cvt_pk_bf16_f32 v163, v164, v165
	v_mov_b64_e32 v[164:165], s[52:53]
	v_mad_i64_i32 v[164:165], s[42:43], v193, s60, v[164:165]
	v_lshl_add_u64 v[164:165], v[184:185], 1, v[164:165]
	global_store_dwordx4 v[164:165], v[160:163], off

; #define PG8_STAGE(bufoff, gbase, voff) do { _Pragma("unroll") for (int _i = 0; _i < 2; ++_i) \
;         __builtin_amdgcn_global_load_lds((const unsigned*)((const char*)(gbase) + (voff)[_i]), (LAS unsigned*)(lds + (bufoff) + ldsw + _i * 8192), 16, 0, 0); } while (0)
; #define PG8_LDA(dst, b, h) do { _Pragma("unroll") for (int m = 0; m < 4; ++m) _Pragma("unroll") for (int k = 0; k < 2; ++k) dst[m][k] = *(const LAS bf16x8*)(lds + PG8_SA(b, h) + aoff + m * 2048 + k * 1024); } while (0)
; #define PG8_LDB(dst, b, h) do { _Pragma("unroll") for (int n = 0; n < 2; ++n) _Pragma("unroll") for (int k = 0; k < 2; ++k) dst[n][k] = *(const LAS bf16x8*)(lds + PG8_SB(b, h) + boff + n * 2048 + k * 1024); } while (0)
; #define PG8_MMA(ai, bj, At, Bt) do { __builtin_amdgcn_s_setprio(1); _Pragma("unroll") for (int m = 0; m < 4; ++m) _Pragma("unroll") for (int n = 0; n < 2; ++n) _Pragma("unroll") for (int k = 0; k < 2; ++k) \
;         acc[ai][bj][m][n] = __builtin_amdgcn_mfma_f32_16x16x32_bf16(Bt[n][k], At[m][k], acc[ai][bj][m][n], 0, 0, 0); __builtin_amdgcn_s_setprio(0); } while (0)
; #define PG8_WAIT_V(n) asm volatile("s_waitcnt vmcnt(" #n ")" ::: "memory")
; #define PG8_WAIT_L(n) asm volatile("s_waitcnt lgkmcnt(" #n ")" ::: "memory")
; template <class Map, class Epi>
; DI void gemm_phase(LAS unsigned char* lds, const Map& MP, const Epi& E, const int nM, const int nN, const int K, const int lda, const int ldb) {
;     ...
;         for (int t = 0; t < nt; t += 2) {
;             const bool last = (t == nt - 2);
;             const char* a1 = cA + (size_t)(t + 1) * kstep;
;             const char* a2 = last ? nA : cA + (size_t)(t + 2) * kstep; const char* b2 = last ? nB : cB + (size_t)(t + 2) * kstep;
;             const char* a3 = a2 + kstep; const char* b3 = b2 + kstep;
;             PG8_LDB(B0, 0, 0); PG8_SCHED; PG8_LDA(At, 0, 0); PG8_STAGE(PG8_SA(1, 1), a1 + hstepA, voffA);
;             PG8_WAIT_L(8); PG8_BAR; PG8_WAIT_L(0); PG8_MMA(0, 0, At, B0); PG8_BAR; PG8_SCHED;
;             PG8_LDB(B1, 0, 1); PG8_STAGE(PG8_SB(0, 0), b2, voffB);
;             PG8_BAR; PG8_WAIT_L(0); PG8_MMA(0, 1, At, B1); PG8_BAR;
;             PG8_LDA(At, 0, 1); PG8_STAGE(PG8_SA(0, 0), a2, voffA);
;             PG8_BAR; PG8_WAIT_L(0); PG8_MMA(1, 0, At, B0); PG8_BAR; PG8_SCHED;
;             PG8_STAGE(PG8_SB(0, 1), b2 + hstepB, voffB);
;             PG8_WAIT_V(6); PG8_BAR; PG8_MMA(1, 1, At, B1); PG8_BAR;
.LBB1_2078:
	s_add_u32 s10, s8, 0x100
	s_addc_u32 s11, s9, 0
	s_cmpk_eq_i32 s3, 0x54
	s_cselect_b32 s15, s43, s11
	s_cselect_b32 s14, s42, s10
	s_cselect_b32 s13, s7, s44
	s_cselect_b32 s12, s6, s39
	s_add_i32 m0, s24, 0xc000
	ds_read_b128 v[168:171], v150
	ds_read_b128 v[172:175], v150 offset:1024
	ds_read_b128 v[176:179], v150 offset:2048
	ds_read_b128 v[180:183], v150 offset:3072
	ds_read_b128 v[184:187], v150 offset:4096
	ds_read_b128 v[188:191], v150 offset:5120
	ds_read_b128 v[192:195], v150 offset:6144
	ds_read_b128 v[198:201], v150 offset:7168
	global_load_lds_dwordx4 v138, s[8:9]
	s_add_i32 m0, s24, 0xe000
	s_nop 0
	global_load_lds_dwordx4 v136, s[8:9]
	s_waitcnt lgkmcnt(8)
	s_setprio 1
	s_barrier
	s_waitcnt lgkmcnt(7)
	v_mfma_f32_16x16x32_bf16 v[124:127], v[152:155], v[168:171], v[124:127]
	v_mfma_f32_16x16x32_bf16 v[120:123], v[160:163], v[168:171], v[120:123]
	s_waitcnt lgkmcnt(5)
	v_mfma_f32_16x16x32_bf16 v[108:111], v[152:155], v[176:179], v[108:111]
	v_mfma_f32_16x16x32_bf16 v[104:107], v[160:163], v[176:179], v[104:107]
	s_waitcnt lgkmcnt(3)
	v_mfma_f32_16x16x32_bf16 v[92:95], v[152:155], v[184:187], v[92:95]
	v_mfma_f32_16x16x32_bf16 v[88:91], v[160:163], v[184:187], v[88:91]
	s_waitcnt lgkmcnt(1)
	v_mfma_f32_16x16x32_bf16 v[76:79], v[152:155], v[192:195], v[76:79]
	v_mfma_f32_16x16x32_bf16 v[72:75], v[160:163], v[192:195], v[72:75]
	v_mfma_f32_16x16x32_bf16 v[124:127], v[156:159], v[172:175], v[124:127]
	v_mfma_f32_16x16x32_bf16 v[120:123], v[164:167], v[172:175], v[120:123]
	v_mfma_f32_16x16x32_bf16 v[108:111], v[156:159], v[180:183], v[108:111]
	v_mfma_f32_16x16x32_bf16 v[104:107], v[164:167], v[180:183], v[104:107]
	v_mfma_f32_16x16x32_bf16 v[92:95], v[156:159], v[188:191], v[92:95]
	v_mfma_f32_16x16x32_bf16 v[88:91], v[164:167], v[188:191], v[88:91]
	s_waitcnt lgkmcnt(0)
	v_mfma_f32_16x16x32_bf16 v[76:79], v[156:159], v[198:201], v[76:79]
	v_mfma_f32_16x16x32_bf16 v[72:75], v[164:167], v[198:201], v[72:75]
	s_barrier
	s_setprio 0
	s_add_i32 s8, s35, s22
	v_lshl_add_u64 v[144:145], s[12:13], 0, v[132:133]
	s_mov_b32 m0, s8
	ds_read_b128 v[202:205], v151
	ds_read_b128 v[206:209], v151 offset:1024
	ds_read_b128 v[210:213], v151 offset:2048
	ds_read_b128 v[214:217], v151 offset:3072
	global_load_lds_dwordx4 v[144:145], off
	v_lshl_add_u64 v[218:219], s[12:13], 0, v[128:129]
	s_add_i32 m0, s8, 0x2000
	s_nop 0
	global_load_lds_dwordx4 v[218:219], off
	s_setprio 1
	s_barrier
	s_waitcnt lgkmcnt(3)
	v_mfma_f32_16x16x32_bf16 v[116:119], v[202:205], v[168:171], v[116:119]
	s_waitcnt lgkmcnt(1)
	v_mfma_f32_16x16x32_bf16 v[112:115], v[210:213], v[168:171], v[112:115]
	v_mfma_f32_16x16x32_bf16 v[100:103], v[202:205], v[176:179], v[100:103]
	v_mfma_f32_16x16x32_bf16 v[96:99], v[210:213], v[176:179], v[96:99]
	v_mfma_f32_16x16x32_bf16 v[84:87], v[202:205], v[184:187], v[84:87]
	v_mfma_f32_16x16x32_bf16 v[80:83], v[210:213], v[184:187], v[80:83]
	v_mfma_f32_16x16x32_bf16 v[68:71], v[202:205], v[192:195], v[68:71]
	v_mfma_f32_16x16x32_bf16 v[64:67], v[210:213], v[192:195], v[64:67]
	v_mfma_f32_16x16x32_bf16 v[116:119], v[206:209], v[172:175], v[116:119]
	s_mov_b32 m0, s24
	s_waitcnt lgkmcnt(0)
	v_mfma_f32_16x16x32_bf16 v[112:115], v[214:217], v[172:175], v[112:115]
	v_lshl_add_u64 v[220:221], s[14:15], 0, v[134:135]
	v_mfma_f32_16x16x32_bf16 v[100:103], v[206:209], v[180:183], v[100:103]
	v_mfma_f32_16x16x32_bf16 v[96:99], v[214:217], v[180:183], v[96:99]
	v_mfma_f32_16x16x32_bf16 v[84:87], v[206:209], v[188:191], v[84:87]
	v_mfma_f32_16x16x32_bf16 v[80:83], v[214:217], v[188:191], v[80:83]
	v_mfma_f32_16x16x32_bf16 v[68:71], v[206:209], v[198:201], v[68:71]
	v_mfma_f32_16x16x32_bf16 v[64:67], v[214:217], v[198:201], v[64:67]
	s_barrier
	s_setprio 0
	ds_read_b128 v[168:171], v150 offset:16384
	ds_read_b128 v[172:175], v150 offset:17408
	ds_read_b128 v[176:179], v150 offset:18432
	ds_read_b128 v[180:183], v150 offset:19456
	ds_read_b128 v[184:187], v150 offset:20480
	ds_read_b128 v[188:191], v150 offset:21504
	ds_read_b128 v[192:195], v150 offset:22528
	ds_read_b128 v[198:201], v150 offset:23552
	global_load_lds_dwordx4 v[220:221], off
	v_lshl_add_u64 v[222:223], s[14:15], 0, v[130:131]
	s_mov_b32 m0, s25
	s_nop 0
	global_load_lds_dwordx4 v[222:223], off
	s_waitcnt vmcnt(10)
	s_setprio 1
	s_barrier
	s_waitcnt lgkmcnt(7)
	v_mfma_f32_16x16x32_bf16 v[60:63], v[152:155], v[168:171], v[60:63]
	v_mfma_f32_16x16x32_bf16 v[56:59], v[160:163], v[168:171], v[56:59]
	s_waitcnt lgkmcnt(5)
	v_mfma_f32_16x16x32_bf16 v[44:47], v[152:155], v[176:179], v[44:47]
	v_mfma_f32_16x16x32_bf16 v[40:43], v[160:163], v[176:179], v[40:43]
	s_waitcnt lgkmcnt(3)
	v_mfma_f32_16x16x32_bf16 v[28:31], v[152:155], v[184:187], v[28:31]
	v_mfma_f32_16x16x32_bf16 v[24:27], v[160:163], v[184:187], v[24:27]
	s_waitcnt lgkmcnt(1)
	v_mfma_f32_16x16x32_bf16 v[12:15], v[152:155], v[192:195], v[12:15]
	v_mfma_f32_16x16x32_bf16 v[8:11], v[160:163], v[192:195], v[8:11]
	v_mfma_f32_16x16x32_bf16 v[60:63], v[156:159], v[172:175], v[60:63]
	v_mfma_f32_16x16x32_bf16 v[56:59], v[164:167], v[172:175], v[56:59]
	v_mfma_f32_16x16x32_bf16 v[44:47], v[156:159], v[180:183], v[44:47]
	v_mfma_f32_16x16x32_bf16 v[40:43], v[164:167], v[180:183], v[40:43]
	v_mfma_f32_16x16x32_bf16 v[28:31], v[156:159], v[188:191], v[28:31]
	v_mfma_f32_16x16x32_bf16 v[24:27], v[164:167], v[188:191], v[24:27]
	s_waitcnt lgkmcnt(0)
	v_mfma_f32_16x16x32_bf16 v[12:15], v[156:159], v[198:201], v[12:15]
	v_mfma_f32_16x16x32_bf16 v[8:11], v[164:167], v[198:201], v[8:11]
	s_barrier
	s_setprio 0
	s_add_u32 s8, s12, 0x160000
	s_addc_u32 s9, s13, 0
	s_add_i32 s45, s36, s22
	s_mov_b32 m0, s45
	s_nop 0
	global_load_lds_dwordx4 v132, s[8:9]
	s_add_i32 m0, s45, 0x2000
	s_nop 0
	global_load_lds_dwordx4 v128, s[8:9]
	s_waitcnt vmcnt(6)
	s_setprio 1
	s_barrier
; #define PG8_STAGE(bufoff, gbase, voff) do { _Pragma("unroll") for (int _i = 0; _i < 2; ++_i) \
;         __builtin_amdgcn_global_load_lds((const unsigned*)((const char*)(gbase) + (voff)[_i]), (LAS unsigned*)(lds + (bufoff) + ldsw + _i * 8192), 16, 0, 0); } while (0)
; #define PG8_LDA(dst, b, h) do { _Pragma("unroll") for (int m = 0; m < 4; ++m) _Pragma("unroll") for (int k = 0; k < 2; ++k) dst[m][k] = *(const LAS bf16x8*)(lds + PG8_SA(b, h) + aoff + m * 2048 + k * 1024); } while (0)
; #define PG8_LDB(dst, b, h) do { _Pragma("unroll") for (int n = 0; n < 2; ++n) _Pragma("unroll") for (int k = 0; k < 2; ++k) dst[n][k] = *(const LAS bf16x8*)(lds + PG8_SB(b, h) + boff + n * 2048 + k * 1024); } while (0)
; #define PG8_MMA(ai, bj, At, Bt) do { __builtin_amdgcn_s_setprio(1); _Pragma("unroll") for (int m = 0; m < 4; ++m) _Pragma("unroll") for (int n = 0; n < 2; ++n) _Pragma("unroll") for (int k = 0; k < 2; ++k) \
;         acc[ai][bj][m][n] = __builtin_amdgcn_mfma_f32_16x16x32_bf16(Bt[n][k], At[m][k], acc[ai][bj][m][n], 0, 0, 0); __builtin_amdgcn_s_setprio(0); } while (0)
; #define PG8_WAIT_V(n) asm volatile("s_waitcnt vmcnt(" #n ")" ::: "memory")
; #define PG8_WAIT_L(n) asm volatile("s_waitcnt lgkmcnt(" #n ")" ::: "memory")
; #define PG8_BAR __builtin_amdgcn_s_barrier()
; #define PG8_SCHED __builtin_amdgcn_sched_barrier(0)
; template <class Map, class Epi>
; DI void gemm_phase(LAS unsigned char* lds, const Map& MP, const Epi& E, const int nM, const int nN, const int K, const int lda, const int ldb) {
;     ...
;             PG8_BAR; PG8_WAIT_L(0); PG8_MMA(1, 0, At, B0); PG8_BAR; PG8_SCHED;
;             PG8_STAGE(PG8_SB(0, 1), b2 + hstepB, voffB);
;             PG8_WAIT_V(6); PG8_BAR; PG8_MMA(1, 1, At, B1); PG8_BAR;
;             PG8_LDB(B0, 1, 0); PG8_SCHED; PG8_LDA(At, 1, 0); PG8_STAGE(PG8_SA(0, 1), a2 + hstepA, voffA);
;             PG8_WAIT_L(8); PG8_BAR; PG8_WAIT_L(0); PG8_MMA(0, 0, At, B0); PG8_BAR; PG8_SCHED;
;             PG8_LDB(B1, 1, 1); PG8_STAGE(PG8_SB(1, 0), b3, voffB);
;             PG8_BAR; PG8_WAIT_L(0); PG8_MMA(0, 1, At, B1); PG8_BAR;
;             PG8_LDA(At, 1, 1); PG8_STAGE(PG8_SA(1, 0), a3, voffA);
	v_mfma_f32_16x16x32_bf16 v[52:55], v[202:205], v[168:171], v[52:55]
	v_mfma_f32_16x16x32_bf16 v[48:51], v[210:213], v[168:171], v[48:51]
	s_add_i32 s45, 0, 0x18000
	v_add_u32_e32 v164, s45, v148
	ds_read_b128 v[152:155], v164
	v_mfma_f32_16x16x32_bf16 v[36:39], v[202:205], v[176:179], v[36:39]
	v_mfma_f32_16x16x32_bf16 v[32:35], v[210:213], v[176:179], v[32:35]
	ds_read_b128 v[156:159], v164 offset:1024
	v_mfma_f32_16x16x32_bf16 v[20:23], v[202:205], v[184:187], v[20:23]
	v_mfma_f32_16x16x32_bf16 v[16:19], v[210:213], v[184:187], v[16:19]
	ds_read_b128 v[160:163], v164 offset:2048
	v_mfma_f32_16x16x32_bf16 v[4:7], v[202:205], v[192:195], v[4:7]
	v_mfma_f32_16x16x32_bf16 v[0:3], v[210:213], v[192:195], v[0:3]
	ds_read_b128 v[164:167], v164 offset:3072
	v_mfma_f32_16x16x32_bf16 v[52:55], v[206:209], v[172:175], v[52:55]
	v_mfma_f32_16x16x32_bf16 v[48:51], v[214:217], v[172:175], v[48:51]
	v_mfma_f32_16x16x32_bf16 v[36:39], v[206:209], v[180:183], v[36:39]
	v_mfma_f32_16x16x32_bf16 v[32:35], v[214:217], v[180:183], v[32:35]
	v_mfma_f32_16x16x32_bf16 v[20:23], v[206:209], v[188:191], v[20:23]
	v_mfma_f32_16x16x32_bf16 v[16:19], v[214:217], v[188:191], v[16:19]
	v_mfma_f32_16x16x32_bf16 v[4:7], v[206:209], v[198:201], v[4:7]
	v_mfma_f32_16x16x32_bf16 v[0:3], v[214:217], v[198:201], v[0:3]
	s_barrier
	s_setprio 0
	s_add_u32 s8, s14, 0x160000
	s_addc_u32 s9, s15, 0
	s_mov_b32 m0, s26
	ds_read_b128 v[168:171], v150 offset:32768
	ds_read_b128 v[172:175], v150 offset:33792
	ds_read_b128 v[176:179], v150 offset:34816
	ds_read_b128 v[180:183], v150 offset:35840
	ds_read_b128 v[184:187], v150 offset:36864
	ds_read_b128 v[188:191], v150 offset:37888
	ds_read_b128 v[192:195], v150 offset:38912
	ds_read_b128 v[198:201], v150 offset:39936
	global_load_lds_dwordx4 v134, s[8:9]
	s_mov_b32 m0, s27
	s_nop 0
	global_load_lds_dwordx4 v130, s[8:9]
	s_waitcnt lgkmcnt(8)
	s_setprio 1
	s_barrier
	s_waitcnt lgkmcnt(7)
	v_mfma_f32_16x16x32_bf16 v[124:127], v[152:155], v[168:171], v[124:127]
	v_mfma_f32_16x16x32_bf16 v[120:123], v[160:163], v[168:171], v[120:123]
	s_waitcnt lgkmcnt(5)
	v_mfma_f32_16x16x32_bf16 v[108:111], v[152:155], v[176:179], v[108:111]
	v_mfma_f32_16x16x32_bf16 v[104:107], v[160:163], v[176:179], v[104:107]
	s_waitcnt lgkmcnt(3)
	v_mfma_f32_16x16x32_bf16 v[92:95], v[152:155], v[184:187], v[92:95]
	v_mfma_f32_16x16x32_bf16 v[88:91], v[160:163], v[184:187], v[88:91]
	s_waitcnt lgkmcnt(1)
	v_mfma_f32_16x16x32_bf16 v[76:79], v[152:155], v[192:195], v[76:79]
	v_mfma_f32_16x16x32_bf16 v[72:75], v[160:163], v[192:195], v[72:75]
	v_mfma_f32_16x16x32_bf16 v[124:127], v[156:159], v[172:175], v[124:127]
	v_mfma_f32_16x16x32_bf16 v[120:123], v[164:167], v[172:175], v[120:123]
	v_mfma_f32_16x16x32_bf16 v[108:111], v[156:159], v[180:183], v[108:111]
	v_mfma_f32_16x16x32_bf16 v[104:107], v[164:167], v[180:183], v[104:107]
	v_mfma_f32_16x16x32_bf16 v[92:95], v[156:159], v[188:191], v[92:95]
	v_mfma_f32_16x16x32_bf16 v[88:91], v[164:167], v[188:191], v[88:91]
	s_waitcnt lgkmcnt(0)
	v_mfma_f32_16x16x32_bf16 v[76:79], v[156:159], v[198:201], v[76:79]
	v_mfma_f32_16x16x32_bf16 v[72:75], v[164:167], v[198:201], v[72:75]
	s_barrier
	s_setprio 0
	s_add_i32 s14, 0, 0x1c000
	s_add_i32 s8, s45, s22
	v_add_u32_e32 v196, s14, v148
	v_lshl_add_u64 v[144:145], v[144:145], 0, s[46:47]
	s_mov_b32 m0, s8
	ds_read_b128 v[202:205], v196
	ds_read_b128 v[206:209], v196 offset:1024
	ds_read_b128 v[210:213], v196 offset:2048
	ds_read_b128 v[214:217], v196 offset:3072
	global_load_lds_dwordx4 v[144:145], off
	v_lshl_add_u64 v[144:145], v[218:219], 0, s[46:47]
	s_add_i32 m0, s8, 0x2000
	s_nop 0
	global_load_lds_dwordx4 v[144:145], off
	s_setprio 1
	s_barrier
	s_waitcnt lgkmcnt(3)
	v_mfma_f32_16x16x32_bf16 v[116:119], v[202:205], v[168:171], v[116:119]
	s_waitcnt lgkmcnt(1)
	v_mfma_f32_16x16x32_bf16 v[112:115], v[210:213], v[168:171], v[112:115]
	v_mfma_f32_16x16x32_bf16 v[100:103], v[202:205], v[176:179], v[100:103]
	v_mfma_f32_16x16x32_bf16 v[96:99], v[210:213], v[176:179], v[96:99]
	v_mfma_f32_16x16x32_bf16 v[84:87], v[202:205], v[184:187], v[84:87]
	v_mfma_f32_16x16x32_bf16 v[80:83], v[210:213], v[184:187], v[80:83]
	v_mfma_f32_16x16x32_bf16 v[68:71], v[202:205], v[192:195], v[68:71]
	v_mfma_f32_16x16x32_bf16 v[64:67], v[210:213], v[192:195], v[64:67]
	v_mfma_f32_16x16x32_bf16 v[116:119], v[206:209], v[172:175], v[116:119]
	s_mov_b32 m0, s30
	s_waitcnt lgkmcnt(0)
	v_mfma_f32_16x16x32_bf16 v[112:115], v[214:217], v[172:175], v[112:115]
	v_lshl_add_u64 v[144:145], v[220:221], 0, s[46:47]
	v_mfma_f32_16x16x32_bf16 v[100:103], v[206:209], v[180:183], v[100:103]
	v_mfma_f32_16x16x32_bf16 v[96:99], v[214:217], v[180:183], v[96:99]
	v_mfma_f32_16x16x32_bf16 v[84:87], v[206:209], v[188:191], v[84:87]
	v_mfma_f32_16x16x32_bf16 v[80:83], v[214:217], v[188:191], v[80:83]
	v_mfma_f32_16x16x32_bf16 v[68:71], v[206:209], v[198:201], v[68:71]
	v_mfma_f32_16x16x32_bf16 v[64:67], v[214:217], v[198:201], v[64:67]
	s_barrier
	s_setprio 0
	ds_read_b128 v[168:171], v150 offset:49152
	ds_read_b128 v[172:175], v150 offset:50176
	ds_read_b128 v[176:179], v150 offset:51200
	ds_read_b128 v[180:183], v150 offset:52224
	ds_read_b128 v[184:187], v150 offset:53248
	ds_read_b128 v[188:191], v150 offset:54272
	ds_read_b128 v[192:195], v150 offset:55296
	ds_read_b128 v[198:201], v150 offset:56320
	global_load_lds_dwordx4 v[144:145], off
	v_lshl_add_u64 v[144:145], v[222:223], 0, s[46:47]
	s_mov_b32 m0, s31
	s_nop 0
	global_load_lds_dwordx4 v[144:145], off
	s_waitcnt vmcnt(10)
	s_setprio 1
	s_barrier
; DI unsigned pack2(float a, float b) { f32x2 v = {a, b}; hwbf16x2 r = __builtin_convertvector(v, hwbf16x2); return __builtin_bit_cast(unsigned, r); }
; DI float bflo(unsigned w) { return __uint_as_float(w << 16); }
; DI float bfhi(unsigned w) { return __uint_as_float(w & 0xffff0000u); }
; #define PG8_WAIT_V(n) asm volatile("s_waitcnt vmcnt(" #n ")" ::: "memory")
; #define PG8_WAIT_L(n) asm volatile("s_waitcnt lgkmcnt(" #n ")" ::: "memory")
;     DI void operator()(const f32x4 (&acc)[2][2][4][2], const Unit& u, int wr, int wc, int fr, int fq) const {
;         const int row0 = u.pm * BM + wr * 64 + fr, col0 = u.pn * BM + wc * 32 + 8 * fq;
;         f32x4 sc[2][2];
; #pragma unroll
;         for (int bj = 0; bj < 2; ++bj)
; #pragma unroll
;             for (int n = 0; n < 2; ++n) sc[bj][n] = scale ? *(const f32x4*)(scale + col0 + bj * HALF + 4 * n) : (f32x4){1.f, 1.f, 1.f, 1.f};
; #pragma unroll
;         for (int ai = 0; ai < 2; ++ai)
; #pragma unroll
;             for (int m = 0; m < 4; ++m) { const size_t ro = (size_t)(row0 + ai * HALF + m * 16) * D + col0;
; #pragma unroll
;                 for (int bj = 0; bj < 2; ++bj) {
;                     f32x4 x0, x1;
;                     if constexpr (IB) { const u32x4 w = *(const u32x4*)((const bf16_t*)Xin + ro + bj * HALF);
;                         x0 = (f32x4){bflo(w[0]), bfhi(w[0]), bflo(w[1]), bfhi(w[1])}; x1 = (f32x4){bflo(w[2]), bfhi(w[2]), bflo(w[3]), bfhi(w[3])}; }
;                     else { x0 = *(const f32x4*)((const float*)Xin + ro + bj * HALF); x1 = *(const f32x4*)((const float*)Xin + ro + bj * HALF + 4); }
;                     x0 += acc[ai][bj][m][0] * sc[bj][0]; x1 += acc[ai][bj][m][1] * sc[bj][1];
;                     if constexpr (OB) { u32x4 o; o[0] = pack2(x0[0], x0[1]); o[1] = pack2(x0[2], x0[3]); o[2] = pack2(x1[0], x1[1]); o[3] = pack2(x1[2], x1[3]);
;                         *(u32x4*)((bf16_t*)Xout + ro + bj * HALF) = o; }
; template <class Map, class Epi>
; DI void gemm_phase(LAS unsigned char* lds, const Map& MP, const Epi& E, const int nM, const int nN, const int K, const int lda, const int ldb) {
;     ...
;             PG8_LDA(At, 1, 1); PG8_STAGE(PG8_SA(1, 0), a3, voffA);
;             PG8_BAR; PG8_WAIT_L(0); PG8_MMA(1, 0, At, B0); PG8_BAR; PG8_SCHED;
;             PG8_STAGE(PG8_SB(1, 1), b3 + hstepB, voffB);
;             PG8_WAIT_V(6); PG8_BAR; PG8_MMA(1, 1, At, B1); PG8_BAR;
	s_waitcnt lgkmcnt(7)
	v_mfma_f32_16x16x32_bf16 v[60:63], v[152:155], v[168:171], v[60:63]
	v_mfma_f32_16x16x32_bf16 v[56:59], v[160:163], v[168:171], v[56:59]
	s_waitcnt lgkmcnt(5)
	v_mfma_f32_16x16x32_bf16 v[44:47], v[152:155], v[176:179], v[44:47]
	v_mfma_f32_16x16x32_bf16 v[40:43], v[160:163], v[176:179], v[40:43]
	s_waitcnt lgkmcnt(3)
	v_mfma_f32_16x16x32_bf16 v[28:31], v[152:155], v[184:187], v[28:31]
	v_mfma_f32_16x16x32_bf16 v[24:27], v[160:163], v[184:187], v[24:27]
	s_waitcnt lgkmcnt(1)
	v_mfma_f32_16x16x32_bf16 v[12:15], v[152:155], v[192:195], v[12:15]
	v_mfma_f32_16x16x32_bf16 v[8:11], v[160:163], v[192:195], v[8:11]
	v_mfma_f32_16x16x32_bf16 v[60:63], v[156:159], v[172:175], v[60:63]
	v_mfma_f32_16x16x32_bf16 v[56:59], v[164:167], v[172:175], v[56:59]
	v_mfma_f32_16x16x32_bf16 v[44:47], v[156:159], v[180:183], v[44:47]
	v_mfma_f32_16x16x32_bf16 v[40:43], v[164:167], v[180:183], v[40:43]
	v_mfma_f32_16x16x32_bf16 v[28:31], v[156:159], v[188:191], v[28:31]
	v_mfma_f32_16x16x32_bf16 v[24:27], v[164:167], v[188:191], v[24:27]
	s_waitcnt lgkmcnt(0)
	v_mfma_f32_16x16x32_bf16 v[12:15], v[156:159], v[198:201], v[12:15]
	v_mfma_f32_16x16x32_bf16 v[8:11], v[164:167], v[198:201], v[8:11]
	s_barrier
	s_setprio 0
	s_add_u32 s8, s12, 0x160080
	s_addc_u32 s9, s13, 0
	s_add_i32 s12, s14, s22
	s_mov_b32 m0, s12
	s_nop 0
	global_load_lds_dwordx4 v132, s[8:9]
	s_add_i32 m0, s12, 0x2000
	s_nop 0
	global_load_lds_dwordx4 v128, s[8:9]
	s_waitcnt vmcnt(6)
	s_setprio 1
	s_barrier
	v_mfma_f32_16x16x32_bf16 v[52:55], v[202:205], v[168:171], v[52:55]
	v_mfma_f32_16x16x32_bf16 v[48:51], v[210:213], v[168:171], v[48:51]
	ds_read_b128 v[152:155], v149
	v_mfma_f32_16x16x32_bf16 v[36:39], v[202:205], v[176:179], v[36:39]
	v_mfma_f32_16x16x32_bf16 v[32:35], v[210:213], v[176:179], v[32:35]
	ds_read_b128 v[156:159], v149 offset:1024
	v_mfma_f32_16x16x32_bf16 v[20:23], v[202:205], v[184:187], v[20:23]
	v_mfma_f32_16x16x32_bf16 v[16:19], v[210:213], v[184:187], v[16:19]
	ds_read_b128 v[160:163], v149 offset:2048
	v_mfma_f32_16x16x32_bf16 v[4:7], v[202:205], v[192:195], v[4:7]
	v_mfma_f32_16x16x32_bf16 v[0:3], v[210:213], v[192:195], v[0:3]
	ds_read_b128 v[164:167], v149 offset:3072
	v_mfma_f32_16x16x32_bf16 v[52:55], v[206:209], v[172:175], v[52:55]
	s_add_i32 s3, s3, 2
	v_mfma_f32_16x16x32_bf16 v[48:51], v[214:217], v[172:175], v[48:51]
	s_add_u32 s39, s39, 0x100
	s_addc_u32 s44, s44, 0
	v_mfma_f32_16x16x32_bf16 v[36:39], v[206:209], v[180:183], v[36:39]
	s_cmpk_gt_u32 s3, 0x55
	v_mfma_f32_16x16x32_bf16 v[32:35], v[214:217], v[180:183], v[32:35]
	s_mov_b64 s[8:9], s[10:11]
	v_mfma_f32_16x16x32_bf16 v[20:23], v[206:209], v[188:191], v[20:23]
	v_mfma_f32_16x16x32_bf16 v[16:19], v[214:217], v[188:191], v[16:19]
	v_mfma_f32_16x16x32_bf16 v[4:7], v[206:209], v[198:201], v[4:7]
	v_mfma_f32_16x16x32_bf16 v[0:3], v[214:217], v[198:201], v[0:3]
	s_barrier
	s_setprio 0
	s_cbranch_scc0 .LBB1_2078
	s_waitcnt lgkmcnt(0)
	v_mov_b32_e32 v152, v147
	v_mov_b32_e32 v144, v146
	s_lshl_b32 s2, s2, 8
	s_add_i32 s2, s2, s29
	s_lshl_b32 s3, s38, 8
	v_add_u32_e32 v152, s2, v152
	s_or_b32 s3, s3, s52
	v_ashrrev_i32_e32 v153, 31, v152
	v_lshl_add_u32 v144, v144, 3, s3
	v_lshlrev_b64 v[152:153], 12, v[152:153]
	v_ashrrev_i32_e32 v145, 31, v144
	v_lshl_add_u64 v[152:153], s[4:5], 0, v[152:153]
	v_lshl_add_u64 v[144:145], v[144:145], 1, v[152:153]
	global_load_dwordx4 v[160:163], v[144:145], off
	global_load_dwordx4 v[164:167], v[144:145], off offset:256
	s_mov_b64 s[98:99], 0x10000
	v_lshl_add_u64 v[154:155], v[144:145], 0, s[98:99]
	global_load_dwordx4 v[168:171], v[154:155], off
	global_load_dwordx4 v[172:175], v[154:155], off offset:256
	s_mov_b64 s[98:99], 0x20000
	v_lshl_add_u64 v[154:155], v[144:145], 0, s[98:99]
	global_load_dwordx4 v[176:179], v[154:155], off
	global_load_dwordx4 v[180:183], v[154:155], off offset:256
	s_mov_b64 s[98:99], 0x30000
	v_lshl_add_u64 v[154:155], v[144:145], 0, s[98:99]
	global_load_dwordx4 v[184:187], v[154:155], off
	global_load_dwordx4 v[188:191], v[154:155], off offset:256
	s_mov_b64 s[98:99], 0x80000
	v_lshl_add_u64 v[154:155], v[144:145], 0, s[98:99]
	global_load_dwordx4 v[192:195], v[154:155], off
	global_load_dwordx4 v[198:201], v[154:155], off offset:256
	s_mov_b64 s[98:99], 0x90000
	v_lshl_add_u64 v[154:155], v[144:145], 0, s[98:99]
	global_load_dwordx4 v[202:205], v[154:155], off
	global_load_dwordx4 v[206:209], v[154:155], off offset:256
	s_mov_b64 s[98:99], 0xa0000
	v_lshl_add_u64 v[154:155], v[144:145], 0, s[98:99]
	global_load_dwordx4 v[210:213], v[154:155], off
	global_load_dwordx4 v[214:217], v[154:155], off offset:256
	s_mov_b64 s[98:99], 0xb0000
	v_lshl_add_u64 v[154:155], v[144:145], 0, s[98:99]
	global_load_dwordx4 v[248:251], v[154:155], off
	global_load_dwordx4 v[252:255], v[154:155], off offset:256
	s_waitcnt vmcnt(15)
	s_nop 1
	v_mov_b32_e32 v152, v160
	v_mov_b32_e32 v153, v161
	v_mov_b32_e32 v154, v162
	v_mov_b32_e32 v155, v163
	s_mov_b64 s[2:3], 0x10000
	s_mov_b32 s38, s37
	s_mov_b64 s[10:11], s[6:7]
	s_mov_b64 s[8:9], s[42:43]
	s_waitcnt lgkmcnt(0)
	v_lshlrev_b32_e32 v156, 16, v152
	v_and_b32_e32 v157, 0xffff0000, v152
	v_lshlrev_b32_e32 v152, 16, v153
	v_and_b32_e32 v153, 0xffff0000, v153
	v_lshlrev_b32_e32 v158, 16, v154
	v_and_b32_e32 v159, 0xffff0000, v154
	v_lshlrev_b32_e32 v154, 16, v155
	v_and_b32_e32 v155, 0xffff0000, v155
	v_pk_add_f32 v[126:127], v[126:127], v[152:153]
	v_pk_add_f32 v[124:125], v[124:125], v[156:157]
	v_pk_add_f32 v[152:153], v[122:123], v[154:155]
	v_pk_add_f32 v[122:123], v[120:121], v[158:159]
	v_cvt_pk_bf16_f32 v120, v124, v125
	v_cvt_pk_bf16_f32 v121, v126, v127
	v_cvt_pk_bf16_f32 v122, v122, v123
	v_cvt_pk_bf16_f32 v123, v152, v153
	global_store_dwordx4 v[144:145], v[120:123], off
	s_waitcnt vmcnt(15)
; DI unsigned pack2(float a, float b) { f32x2 v = {a, b}; hwbf16x2 r = __builtin_convertvector(v, hwbf16x2); return __builtin_bit_cast(unsigned, r); }
; DI float bflo(unsigned w) { return __uint_as_float(w << 16); }
; DI float bfhi(unsigned w) { return __uint_as_float(w & 0xffff0000u); }
;     DI void operator()(const f32x4 (&acc)[2][2][4][2], const Unit& u, int wr, int wc, int fr, int fq) const {
;     ...
;         for (int ai = 0; ai < 2; ++ai)
; #pragma unroll
;             for (int m = 0; m < 4; ++m) { const size_t ro = (size_t)(row0 + ai * HALF + m * 16) * D + col0;
; #pragma unroll
;                 for (int bj = 0; bj < 2; ++bj) {
;                     f32x4 x0, x1;
;                     if constexpr (IB) { const u32x4 w = *(const u32x4*)((const bf16_t*)Xin + ro + bj * HALF);
;                         x0 = (f32x4){bflo(w[0]), bfhi(w[0]), bflo(w[1]), bfhi(w[1])}; x1 = (f32x4){bflo(w[2]), bfhi(w[2]), bflo(w[3]), bfhi(w[3])}; }
;                     else { x0 = *(const f32x4*)((const float*)Xin + ro + bj * HALF); x1 = *(const f32x4*)((const float*)Xin + ro + bj * HALF + 4); }
;                     x0 += acc[ai][bj][m][0] * sc[bj][0]; x1 += acc[ai][bj][m][1] * sc[bj][1];
;                     if constexpr (OB) { u32x4 o; o[0] = pack2(x0[0], x0[1]); o[1] = pack2(x0[2], x0[3]); o[2] = pack2(x1[0], x1[1]); o[3] = pack2(x1[2], x1[3]);
;                         *(u32x4*)((bf16_t*)Xout + ro + bj * HALF) = o; }
;                     else { *(f32x4*)((float*)Xout + ro + bj * HALF) = x0; *(f32x4*)((float*)Xout + ro + bj * HALF + 4) = x1; } } }
	s_nop 1
	v_mov_b32_e32 v120, v164
	v_mov_b32_e32 v121, v165
	v_mov_b32_e32 v122, v166
	v_mov_b32_e32 v123, v167
	s_waitcnt lgkmcnt(0)
	v_lshlrev_b32_e32 v124, 16, v120
	v_and_b32_e32 v125, 0xffff0000, v120
	v_lshlrev_b32_e32 v120, 16, v121
	v_and_b32_e32 v121, 0xffff0000, v121
	v_lshlrev_b32_e32 v126, 16, v122
	v_and_b32_e32 v127, 0xffff0000, v122
	v_lshlrev_b32_e32 v122, 16, v123
	v_and_b32_e32 v123, 0xffff0000, v123
	v_pk_add_f32 v[116:117], v[116:117], v[124:125]
	v_pk_add_f32 v[118:119], v[118:119], v[120:121]
	v_pk_add_f32 v[120:121], v[114:115], v[122:123]
	v_pk_add_f32 v[114:115], v[112:113], v[126:127]
	v_cvt_pk_bf16_f32 v112, v116, v117
	v_lshl_add_u64 v[116:117], v[144:145], 0, s[2:3]
	s_mov_b32 s2, 0x10000
	v_cvt_pk_bf16_f32 v113, v118, v119
	v_add_co_u32_e32 v118, vcc, s2, v144
	v_cvt_pk_bf16_f32 v114, v114, v115
	v_cvt_pk_bf16_f32 v115, v120, v121
	v_addc_co_u32_e32 v119, vcc, 0, v145, vcc
	global_store_dwordx4 v[144:145], v[112:115], off offset:256
	s_waitcnt vmcnt(15)
	s_nop 1
	v_mov_b32_e32 v112, v168
	v_mov_b32_e32 v113, v169
	v_mov_b32_e32 v114, v170
	v_mov_b32_e32 v115, v171
	s_mov_b64 s[2:3], 0x20000
	s_waitcnt lgkmcnt(0)
	v_lshlrev_b32_e32 v120, 16, v112
	v_and_b32_e32 v121, 0xffff0000, v112
	v_lshlrev_b32_e32 v112, 16, v113
	v_and_b32_e32 v113, 0xffff0000, v113
	v_lshlrev_b32_e32 v122, 16, v114
	v_and_b32_e32 v123, 0xffff0000, v114
	v_lshlrev_b32_e32 v114, 16, v115
	v_and_b32_e32 v115, 0xffff0000, v115
	v_pk_add_f32 v[110:111], v[110:111], v[112:113]
	v_pk_add_f32 v[108:109], v[108:109], v[120:121]
	v_pk_add_f32 v[112:113], v[106:107], v[114:115]
	v_pk_add_f32 v[106:107], v[104:105], v[122:123]
	v_cvt_pk_bf16_f32 v104, v108, v109
	v_cvt_pk_bf16_f32 v105, v110, v111
	v_cvt_pk_bf16_f32 v106, v106, v107
	v_cvt_pk_bf16_f32 v107, v112, v113
	global_store_dwordx4 v[118:119], v[104:107], off
	s_waitcnt vmcnt(15)
	s_nop 1
	v_mov_b32_e32 v104, v172
	v_mov_b32_e32 v105, v173
	v_mov_b32_e32 v106, v174
	v_mov_b32_e32 v107, v175
	s_waitcnt lgkmcnt(0)
	v_lshlrev_b32_e32 v108, 16, v104
	v_and_b32_e32 v109, 0xffff0000, v104
	v_lshlrev_b32_e32 v104, 16, v105
	v_and_b32_e32 v105, 0xffff0000, v105
	v_lshlrev_b32_e32 v110, 16, v106
	v_and_b32_e32 v111, 0xffff0000, v106
	v_lshlrev_b32_e32 v106, 16, v107
	v_and_b32_e32 v107, 0xffff0000, v107
	v_pk_add_f32 v[100:101], v[100:101], v[108:109]
	v_pk_add_f32 v[102:103], v[102:103], v[104:105]
	v_pk_add_f32 v[104:105], v[98:99], v[106:107]
	v_pk_add_f32 v[98:99], v[96:97], v[110:111]
	v_cvt_pk_bf16_f32 v96, v100, v101
	v_lshl_add_u64 v[100:101], v[144:145], 0, s[2:3]
	s_mov_b32 s2, 0x20000
	v_cvt_pk_bf16_f32 v97, v102, v103
	v_add_co_u32_e32 v102, vcc, s2, v144
	v_cvt_pk_bf16_f32 v98, v98, v99
	v_cvt_pk_bf16_f32 v99, v104, v105
	v_addc_co_u32_e32 v103, vcc, 0, v145, vcc
	global_store_dwordx4 v[116:117], v[96:99], off offset:256
	s_waitcnt vmcnt(15)
	s_nop 1
	v_mov_b32_e32 v96, v176
	v_mov_b32_e32 v97, v177
	v_mov_b32_e32 v98, v178
	v_mov_b32_e32 v99, v179
	s_mov_b64 s[2:3], 0x30000
	s_waitcnt lgkmcnt(0)
	v_lshlrev_b32_e32 v104, 16, v96
	v_and_b32_e32 v105, 0xffff0000, v96
	v_lshlrev_b32_e32 v96, 16, v97
	v_and_b32_e32 v97, 0xffff0000, v97
	v_lshlrev_b32_e32 v106, 16, v98
	v_and_b32_e32 v107, 0xffff0000, v98
	v_lshlrev_b32_e32 v98, 16, v99
	v_and_b32_e32 v99, 0xffff0000, v99
	v_pk_add_f32 v[94:95], v[94:95], v[96:97]
	v_pk_add_f32 v[92:93], v[92:93], v[104:105]
	v_pk_add_f32 v[96:97], v[90:91], v[98:99]
	v_pk_add_f32 v[90:91], v[88:89], v[106:107]
	v_cvt_pk_bf16_f32 v88, v92, v93
	v_cvt_pk_bf16_f32 v89, v94, v95
	v_cvt_pk_bf16_f32 v90, v90, v91
	v_cvt_pk_bf16_f32 v91, v96, v97
	global_store_dwordx4 v[102:103], v[88:91], off
	s_waitcnt vmcnt(15)
	s_nop 1
	v_mov_b32_e32 v88, v180
	v_mov_b32_e32 v89, v181
	v_mov_b32_e32 v90, v182
	v_mov_b32_e32 v91, v183
	s_waitcnt lgkmcnt(0)
	v_lshlrev_b32_e32 v92, 16, v88
	v_and_b32_e32 v93, 0xffff0000, v88
	v_lshlrev_b32_e32 v88, 16, v89
	v_and_b32_e32 v89, 0xffff0000, v89
	v_lshlrev_b32_e32 v94, 16, v90
	v_and_b32_e32 v95, 0xffff0000, v90
	v_lshlrev_b32_e32 v90, 16, v91
	v_and_b32_e32 v91, 0xffff0000, v91
	v_pk_add_f32 v[86:87], v[86:87], v[88:89]
	v_pk_add_f32 v[84:85], v[84:85], v[92:93]
	v_pk_add_f32 v[88:89], v[82:83], v[90:91]
	v_pk_add_f32 v[82:83], v[80:81], v[94:95]
	v_cvt_pk_bf16_f32 v80, v84, v85
	v_cvt_pk_bf16_f32 v81, v86, v87
	v_cvt_pk_bf16_f32 v82, v82, v83
	v_cvt_pk_bf16_f32 v83, v88, v89
	global_store_dwordx4 v[100:101], v[80:83], off offset:256
	s_nop 1
	v_lshl_add_u64 v[80:81], v[144:145], 0, s[2:3]
	s_mov_b32 s2, 0x30000
	v_add_co_u32_e32 v86, vcc, s2, v144
	s_mov_b64 s[2:3], 0x80000
	s_nop 0
	v_addc_co_u32_e32 v87, vcc, 0, v145, vcc
	s_waitcnt vmcnt(15)
	s_nop 1
	v_mov_b32_e32 v82, v184
	v_mov_b32_e32 v83, v185
	v_mov_b32_e32 v84, v186
	v_mov_b32_e32 v85, v187
	s_waitcnt lgkmcnt(0)
	v_lshlrev_b32_e32 v88, 16, v82
	v_and_b32_e32 v89, 0xffff0000, v82
	v_lshlrev_b32_e32 v82, 16, v83
	v_and_b32_e32 v83, 0xffff0000, v83
	v_lshlrev_b32_e32 v90, 16, v84
	v_and_b32_e32 v91, 0xffff0000, v84
	v_lshlrev_b32_e32 v84, 16, v85
	v_and_b32_e32 v85, 0xffff0000, v85
	v_pk_add_f32 v[78:79], v[78:79], v[82:83]
	v_pk_add_f32 v[76:77], v[76:77], v[88:89]
	v_pk_add_f32 v[82:83], v[74:75], v[84:85]
	v_pk_add_f32 v[74:75], v[72:73], v[90:91]
	v_cvt_pk_bf16_f32 v72, v76, v77
	v_cvt_pk_bf16_f32 v73, v78, v79
	v_cvt_pk_bf16_f32 v74, v74, v75
	v_cvt_pk_bf16_f32 v75, v82, v83
	global_store_dwordx4 v[86:87], v[72:75], off
	s_waitcnt vmcnt(15)
	s_nop 1
	v_mov_b32_e32 v72, v188
	v_mov_b32_e32 v73, v189
	v_mov_b32_e32 v74, v190
	v_mov_b32_e32 v75, v191
	s_waitcnt lgkmcnt(0)
; DI unsigned pack2(float a, float b) { f32x2 v = {a, b}; hwbf16x2 r = __builtin_convertvector(v, hwbf16x2); return __builtin_bit_cast(unsigned, r); }
; DI float bflo(unsigned w) { return __uint_as_float(w << 16); }
; DI float bfhi(unsigned w) { return __uint_as_float(w & 0xffff0000u); }
;     DI void operator()(const f32x4 (&acc)[2][2][4][2], const Unit& u, int wr, int wc, int fr, int fq) const {
;     ...
;         for (int ai = 0; ai < 2; ++ai)
; #pragma unroll
;             for (int m = 0; m < 4; ++m) { const size_t ro = (size_t)(row0 + ai * HALF + m * 16) * D + col0;
; #pragma unroll
;                 for (int bj = 0; bj < 2; ++bj) {
;                     f32x4 x0, x1;
;                     if constexpr (IB) { const u32x4 w = *(const u32x4*)((const bf16_t*)Xin + ro + bj * HALF);
;                         x0 = (f32x4){bflo(w[0]), bfhi(w[0]), bflo(w[1]), bfhi(w[1])}; x1 = (f32x4){bflo(w[2]), bfhi(w[2]), bflo(w[3]), bfhi(w[3])}; }
;                     else { x0 = *(const f32x4*)((const float*)Xin + ro + bj * HALF); x1 = *(const f32x4*)((const float*)Xin + ro + bj * HALF + 4); }
;                     x0 += acc[ai][bj][m][0] * sc[bj][0]; x1 += acc[ai][bj][m][1] * sc[bj][1];
;                     if constexpr (OB) { u32x4 o; o[0] = pack2(x0[0], x0[1]); o[1] = pack2(x0[2], x0[3]); o[2] = pack2(x1[0], x1[1]); o[3] = pack2(x1[2], x1[3]);
;                         *(u32x4*)((bf16_t*)Xout + ro + bj * HALF) = o; }
;                     else { *(f32x4*)((float*)Xout + ro + bj * HALF) = x0; *(f32x4*)((float*)Xout + ro + bj * HALF + 4) = x1; } } }
	v_lshlrev_b32_e32 v76, 16, v72
	v_and_b32_e32 v77, 0xffff0000, v72
	v_lshlrev_b32_e32 v72, 16, v73
	v_and_b32_e32 v73, 0xffff0000, v73
	v_lshlrev_b32_e32 v78, 16, v74
	v_and_b32_e32 v79, 0xffff0000, v74
	v_lshlrev_b32_e32 v74, 16, v75
	v_and_b32_e32 v75, 0xffff0000, v75
	v_pk_add_f32 v[70:71], v[70:71], v[72:73]
	v_pk_add_f32 v[68:69], v[68:69], v[76:77]
	v_pk_add_f32 v[72:73], v[66:67], v[74:75]
	v_pk_add_f32 v[66:67], v[64:65], v[78:79]
	v_cvt_pk_bf16_f32 v64, v68, v69
	v_cvt_pk_bf16_f32 v65, v70, v71
	v_cvt_pk_bf16_f32 v66, v66, v67
	v_cvt_pk_bf16_f32 v67, v72, v73
	global_store_dwordx4 v[80:81], v[64:67], off offset:256
	s_nop 1
	v_lshl_add_u64 v[64:65], v[144:145], 0, s[2:3]
	s_mov_b32 s2, 0x80000
	v_add_co_u32_e32 v70, vcc, s2, v144
	s_mov_b64 s[2:3], 0x90000
	s_nop 0
	v_addc_co_u32_e32 v71, vcc, 0, v145, vcc
	s_waitcnt vmcnt(15)
	s_nop 1
	v_mov_b32_e32 v66, v192
	v_mov_b32_e32 v67, v193
	v_mov_b32_e32 v68, v194
	v_mov_b32_e32 v69, v195
	s_waitcnt lgkmcnt(0)
	v_lshlrev_b32_e32 v72, 16, v66
	v_and_b32_e32 v73, 0xffff0000, v66
	v_lshlrev_b32_e32 v66, 16, v67
	v_and_b32_e32 v67, 0xffff0000, v67
	v_lshlrev_b32_e32 v74, 16, v68
	v_and_b32_e32 v75, 0xffff0000, v68
	v_lshlrev_b32_e32 v68, 16, v69
	v_and_b32_e32 v69, 0xffff0000, v69
	v_pk_add_f32 v[62:63], v[62:63], v[66:67]
	v_pk_add_f32 v[60:61], v[60:61], v[72:73]
	v_pk_add_f32 v[66:67], v[58:59], v[68:69]
	v_pk_add_f32 v[58:59], v[56:57], v[74:75]
	v_cvt_pk_bf16_f32 v56, v60, v61
	v_cvt_pk_bf16_f32 v57, v62, v63
	v_cvt_pk_bf16_f32 v58, v58, v59
	v_cvt_pk_bf16_f32 v59, v66, v67
	global_store_dwordx4 v[70:71], v[56:59], off
	s_waitcnt vmcnt(15)
	s_nop 1
	v_mov_b32_e32 v56, v198
	v_mov_b32_e32 v57, v199
	v_mov_b32_e32 v58, v200
	v_mov_b32_e32 v59, v201
	s_waitcnt lgkmcnt(0)
	v_lshlrev_b32_e32 v60, 16, v56
	v_and_b32_e32 v61, 0xffff0000, v56
	v_lshlrev_b32_e32 v56, 16, v57
	v_and_b32_e32 v57, 0xffff0000, v57
	v_lshlrev_b32_e32 v62, 16, v58
	v_and_b32_e32 v63, 0xffff0000, v58
	v_lshlrev_b32_e32 v58, 16, v59
	v_and_b32_e32 v59, 0xffff0000, v59
	v_pk_add_f32 v[54:55], v[54:55], v[56:57]
	v_pk_add_f32 v[52:53], v[52:53], v[60:61]
	v_pk_add_f32 v[56:57], v[50:51], v[58:59]
	v_pk_add_f32 v[50:51], v[48:49], v[62:63]
	v_cvt_pk_bf16_f32 v48, v52, v53
	v_cvt_pk_bf16_f32 v49, v54, v55
	v_cvt_pk_bf16_f32 v50, v50, v51
	v_cvt_pk_bf16_f32 v51, v56, v57
	global_store_dwordx4 v[64:65], v[48:51], off offset:256
	s_nop 1
	v_lshl_add_u64 v[48:49], v[144:145], 0, s[2:3]
	s_mov_b32 s2, 0x90000
	v_add_co_u32_e32 v54, vcc, s2, v144
	s_mov_b64 s[2:3], 0xa0000
	s_nop 0
	v_addc_co_u32_e32 v55, vcc, 0, v145, vcc
	s_waitcnt vmcnt(15)
	s_nop 1
	v_mov_b32_e32 v50, v202
	v_mov_b32_e32 v51, v203
	v_mov_b32_e32 v52, v204
	v_mov_b32_e32 v53, v205
	s_waitcnt lgkmcnt(0)
	v_lshlrev_b32_e32 v56, 16, v50
	v_and_b32_e32 v57, 0xffff0000, v50
	v_lshlrev_b32_e32 v50, 16, v51
	v_and_b32_e32 v51, 0xffff0000, v51
	v_lshlrev_b32_e32 v58, 16, v52
	v_and_b32_e32 v59, 0xffff0000, v52
	v_lshlrev_b32_e32 v52, 16, v53
	v_and_b32_e32 v53, 0xffff0000, v53
	v_pk_add_f32 v[46:47], v[46:47], v[50:51]
	v_pk_add_f32 v[44:45], v[44:45], v[56:57]
	v_pk_add_f32 v[50:51], v[42:43], v[52:53]
	v_pk_add_f32 v[42:43], v[40:41], v[58:59]
	v_cvt_pk_bf16_f32 v40, v44, v45
	v_cvt_pk_bf16_f32 v41, v46, v47
	v_cvt_pk_bf16_f32 v42, v42, v43
	v_cvt_pk_bf16_f32 v43, v50, v51
	global_store_dwordx4 v[54:55], v[40:43], off
	s_waitcnt vmcnt(15)
	s_nop 1
	v_mov_b32_e32 v40, v206
	v_mov_b32_e32 v41, v207
	v_mov_b32_e32 v42, v208
	v_mov_b32_e32 v43, v209
	s_waitcnt lgkmcnt(0)
; DI unsigned pack2(float a, float b) { f32x2 v = {a, b}; hwbf16x2 r = __builtin_convertvector(v, hwbf16x2); return __builtin_bit_cast(unsigned, r); }
; DI float bflo(unsigned w) { return __uint_as_float(w << 16); }
; DI float bfhi(unsigned w) { return __uint_as_float(w & 0xffff0000u); }
;     DI const char* a(const Unit& u) const { return (const char*)(A + (size_t)u.pm * BM * lda); }
;     DI const char* a(const Unit& u) const { return (const char*)(A + (size_t)u.pm * BM * 2048 + (u.pn >> 1) * 512); }
;     DI void operator()(const f32x4 (&acc)[2][2][4][2], const Unit& u, int wr, int wc, int fr, int fq) const {
;     ...
;         for (int ai = 0; ai < 2; ++ai)
; #pragma unroll
;             for (int m = 0; m < 4; ++m) { const size_t ro = (size_t)(row0 + ai * HALF + m * 16) * D + col0;
; #pragma unroll
;                 for (int bj = 0; bj < 2; ++bj) {
;                     f32x4 x0, x1;
;                     if constexpr (IB) { const u32x4 w = *(const u32x4*)((const bf16_t*)Xin + ro + bj * HALF);
;                         x0 = (f32x4){bflo(w[0]), bfhi(w[0]), bflo(w[1]), bfhi(w[1])}; x1 = (f32x4){bflo(w[2]), bfhi(w[2]), bflo(w[3]), bfhi(w[3])}; }
;                     else { x0 = *(const f32x4*)((const float*)Xin + ro + bj * HALF); x1 = *(const f32x4*)((const float*)Xin + ro + bj * HALF + 4); }
;                     x0 += acc[ai][bj][m][0] * sc[bj][0]; x1 += acc[ai][bj][m][1] * sc[bj][1];
;                     if constexpr (OB) { u32x4 o; o[0] = pack2(x0[0], x0[1]); o[1] = pack2(x0[2], x0[3]); o[2] = pack2(x1[0], x1[1]); o[3] = pack2(x1[2], x1[3]);
;                         *(u32x4*)((bf16_t*)Xout + ro + bj * HALF) = o; }
;                     else { *(f32x4*)((float*)Xout + ro + bj * HALF) = x0; *(f32x4*)((float*)Xout + ro + bj * HALF + 4) = x1; } } }
; template <class Map, class Epi>
; DI void gemm_phase(LAS unsigned char* lds, const Map& MP, const Epi& E, const int nM, const int nN, const int K, const int lda, const int ldb) {
;     ...
;         if (!has_next) break;
; #pragma unroll
;         for (int a = 0; a < 2; ++a)
; #pragma unroll
;             for (int b = 0; b < 2; ++b)
; #pragma unroll
;                 for (int m = 0; m < 4; ++m)
; #pragma unroll
;                     for (int n = 0; n < 2; ++n) acc[a][b][m][n] = (f32x4){0.f, 0.f, 0.f, 0.f};
;         cur = nxt; cA = nA; cB = nB; ++ui;
;     }
;     PG8_WAIT_V(0);
;     if (wr == 0) PG8_BAR;
;     PG8_BAR;
	v_lshlrev_b32_e32 v44, 16, v40
	v_and_b32_e32 v45, 0xffff0000, v40
	v_lshlrev_b32_e32 v40, 16, v41
	v_and_b32_e32 v41, 0xffff0000, v41
	v_lshlrev_b32_e32 v46, 16, v42
	v_and_b32_e32 v47, 0xffff0000, v42
	v_lshlrev_b32_e32 v42, 16, v43
	v_and_b32_e32 v43, 0xffff0000, v43
	v_pk_add_f32 v[38:39], v[38:39], v[40:41]
	v_pk_add_f32 v[36:37], v[36:37], v[44:45]
	v_pk_add_f32 v[40:41], v[34:35], v[42:43]
	v_pk_add_f32 v[34:35], v[32:33], v[46:47]
	v_cvt_pk_bf16_f32 v32, v36, v37
	v_cvt_pk_bf16_f32 v33, v38, v39
	v_cvt_pk_bf16_f32 v34, v34, v35
	v_cvt_pk_bf16_f32 v35, v40, v41
	global_store_dwordx4 v[48:49], v[32:35], off offset:256
	s_nop 1
	v_lshl_add_u64 v[32:33], v[144:145], 0, s[2:3]
	s_mov_b32 s2, 0xa0000
	v_add_co_u32_e32 v38, vcc, s2, v144
	s_mov_b64 s[2:3], 0xb0000
	s_nop 0
	v_addc_co_u32_e32 v39, vcc, 0, v145, vcc
	s_waitcnt vmcnt(15)
	s_nop 1
	v_mov_b32_e32 v34, v210
	v_mov_b32_e32 v35, v211
	v_mov_b32_e32 v36, v212
	v_mov_b32_e32 v37, v213
	s_waitcnt lgkmcnt(0)
	v_lshlrev_b32_e32 v40, 16, v34
	v_and_b32_e32 v41, 0xffff0000, v34
	v_lshlrev_b32_e32 v34, 16, v35
	v_and_b32_e32 v35, 0xffff0000, v35
	v_lshlrev_b32_e32 v42, 16, v36
	v_and_b32_e32 v43, 0xffff0000, v36
	v_lshlrev_b32_e32 v36, 16, v37
	v_and_b32_e32 v37, 0xffff0000, v37
	v_pk_add_f32 v[30:31], v[30:31], v[34:35]
	v_pk_add_f32 v[28:29], v[28:29], v[40:41]
	v_pk_add_f32 v[34:35], v[26:27], v[36:37]
	v_pk_add_f32 v[26:27], v[24:25], v[42:43]
	v_cvt_pk_bf16_f32 v24, v28, v29
	v_cvt_pk_bf16_f32 v25, v30, v31
	v_cvt_pk_bf16_f32 v26, v26, v27
	v_cvt_pk_bf16_f32 v27, v34, v35
	global_store_dwordx4 v[38:39], v[24:27], off
	s_waitcnt vmcnt(15)
	s_nop 1
	v_mov_b32_e32 v24, v214
	v_mov_b32_e32 v25, v215
	v_mov_b32_e32 v26, v216
	v_mov_b32_e32 v27, v217
	s_waitcnt lgkmcnt(0)
	v_lshlrev_b32_e32 v28, 16, v24
	v_and_b32_e32 v29, 0xffff0000, v24
	v_lshlrev_b32_e32 v24, 16, v25
	v_and_b32_e32 v25, 0xffff0000, v25
	v_lshlrev_b32_e32 v30, 16, v26
	v_and_b32_e32 v31, 0xffff0000, v26
	v_lshlrev_b32_e32 v26, 16, v27
	v_and_b32_e32 v27, 0xffff0000, v27
	v_pk_add_f32 v[22:23], v[22:23], v[24:25]
	v_pk_add_f32 v[20:21], v[20:21], v[28:29]
	v_pk_add_f32 v[24:25], v[18:19], v[26:27]
	v_pk_add_f32 v[18:19], v[16:17], v[30:31]
	v_cvt_pk_bf16_f32 v16, v20, v21
	v_cvt_pk_bf16_f32 v17, v22, v23
	v_cvt_pk_bf16_f32 v18, v18, v19
	v_cvt_pk_bf16_f32 v19, v24, v25
	global_store_dwordx4 v[32:33], v[16:19], off offset:256
	s_nop 1
	v_lshl_add_u64 v[16:17], v[144:145], 0, s[2:3]
	s_mov_b32 s2, 0xb0000
	v_add_co_u32_e32 v22, vcc, s2, v144
	s_mov_b32 s2, s53
	s_nop 0
	v_addc_co_u32_e32 v23, vcc, 0, v145, vcc
	s_waitcnt vmcnt(15)
	s_nop 1
	v_mov_b32_e32 v18, v248
	v_mov_b32_e32 v19, v249
	v_mov_b32_e32 v20, v250
	v_mov_b32_e32 v21, v251
	s_and_b64 vcc, exec, s[40:41]
	s_waitcnt lgkmcnt(0)
	v_lshlrev_b32_e32 v24, 16, v18
	v_and_b32_e32 v25, 0xffff0000, v18
	v_lshlrev_b32_e32 v18, 16, v19
	v_and_b32_e32 v19, 0xffff0000, v19
	v_lshlrev_b32_e32 v26, 16, v20
	v_and_b32_e32 v27, 0xffff0000, v20
	v_lshlrev_b32_e32 v20, 16, v21
	v_and_b32_e32 v21, 0xffff0000, v21
	v_pk_add_f32 v[14:15], v[14:15], v[18:19]
	v_pk_add_f32 v[12:13], v[12:13], v[24:25]
	v_pk_add_f32 v[18:19], v[10:11], v[20:21]
	v_pk_add_f32 v[10:11], v[8:9], v[26:27]
	v_cvt_pk_bf16_f32 v8, v12, v13
	v_cvt_pk_bf16_f32 v9, v14, v15
	v_cvt_pk_bf16_f32 v10, v10, v11
	v_cvt_pk_bf16_f32 v11, v18, v19
	global_store_dwordx4 v[22:23], v[8:11], off
	s_waitcnt vmcnt(15)
	s_nop 1
	v_mov_b32_e32 v8, v252
	v_mov_b32_e32 v9, v253
	v_mov_b32_e32 v10, v254
	v_mov_b32_e32 v11, v255
	s_waitcnt lgkmcnt(0)
	v_lshlrev_b32_e32 v12, 16, v8
	v_and_b32_e32 v13, 0xffff0000, v8
	v_lshlrev_b32_e32 v8, 16, v9
	v_and_b32_e32 v9, 0xffff0000, v9
	v_lshlrev_b32_e32 v14, 16, v10
	v_and_b32_e32 v15, 0xffff0000, v10
	v_lshlrev_b32_e32 v10, 16, v11
	v_and_b32_e32 v11, 0xffff0000, v11
	v_pk_add_f32 v[6:7], v[6:7], v[8:9]
	v_pk_add_f32 v[4:5], v[4:5], v[12:13]
	v_pk_add_f32 v[8:9], v[2:3], v[10:11]
	v_pk_add_f32 v[2:3], v[0:1], v[14:15]
	v_cvt_pk_bf16_f32 v0, v4, v5
	v_cvt_pk_bf16_f32 v1, v6, v7
	v_cvt_pk_bf16_f32 v2, v2, v3
	v_cvt_pk_bf16_f32 v3, v8, v9
	global_store_dwordx4 v[16:17], v[0:3], off offset:256
	s_cbranch_vccz .LBB1_2071
	s_waitcnt vmcnt(0)
	s_cmpk_gt_u32 s17, 0xff
	s_cbranch_scc1 .LBB1_2082
	s_barrier

; #define PG8_STAGE(bufoff, gbase, voff) do { _Pragma("unroll") for (int _i = 0; _i < 2; ++_i) \
;         __builtin_amdgcn_global_load_lds((const unsigned*)((const char*)(gbase) + (voff)[_i]), (LAS unsigned*)(lds + (bufoff) + ldsw + _i * 8192), 16, 0, 0); } while (0)
; #define PG8_LDA(dst, b, h) do { _Pragma("unroll") for (int m = 0; m < 4; ++m) _Pragma("unroll") for (int k = 0; k < 2; ++k) dst[m][k] = *(const LAS bf16x8*)(lds + PG8_SA(b, h) + aoff + m * 2048 + k * 1024); } while (0)
; #define PG8_LDB(dst, b, h) do { _Pragma("unroll") for (int n = 0; n < 2; ++n) _Pragma("unroll") for (int k = 0; k < 2; ++k) dst[n][k] = *(const LAS bf16x8*)(lds + PG8_SB(b, h) + boff + n * 2048 + k * 1024); } while (0)
; #define PG8_MMA(ai, bj, At, Bt) do { __builtin_amdgcn_s_setprio(1); _Pragma("unroll") for (int m = 0; m < 4; ++m) _Pragma("unroll") for (int n = 0; n < 2; ++n) _Pragma("unroll") for (int k = 0; k < 2; ++k) \
;         acc[ai][bj][m][n] = __builtin_amdgcn_mfma_f32_16x16x32_bf16(Bt[n][k], At[m][k], acc[ai][bj][m][n], 0, 0, 0); __builtin_amdgcn_s_setprio(0); } while (0)
; #define PG8_WAIT_V(n) asm volatile("s_waitcnt vmcnt(" #n ")" ::: "memory")
; #define PG8_WAIT_L(n) asm volatile("s_waitcnt lgkmcnt(" #n ")" ::: "memory")
; template <class Map, class Epi>
; DI void gemm_phase(LAS unsigned char* lds, const Map& MP, const Epi& E, const int nM, const int nN, const int K, const int lda, const int ldb) {
;     ...
;             const bool last = (t == nt - 2);
;             const char* a1 = cA + (size_t)(t + 1) * kstep;
;             const char* a2 = last ? nA : cA + (size_t)(t + 2) * kstep; const char* b2 = last ? nB : cB + (size_t)(t + 2) * kstep;
;             const char* a3 = a2 + kstep; const char* b3 = b2 + kstep;
;             PG8_LDB(B0, 0, 0); PG8_SCHED; PG8_LDA(At, 0, 0); PG8_STAGE(PG8_SA(1, 1), a1 + hstepA, voffA);
;             PG8_WAIT_L(8); PG8_BAR; PG8_WAIT_L(0); PG8_MMA(0, 0, At, B0); PG8_BAR; PG8_SCHED;
;             PG8_LDB(B1, 0, 1); PG8_STAGE(PG8_SB(0, 0), b2, voffB);
;             PG8_BAR; PG8_WAIT_L(0); PG8_MMA(0, 1, At, B1); PG8_BAR;
;             PG8_LDA(At, 0, 1); PG8_STAGE(PG8_SA(0, 0), a2, voffA);
;             PG8_BAR; PG8_WAIT_L(0); PG8_MMA(1, 0, At, B0); PG8_BAR; PG8_SCHED;
;             PG8_STAGE(PG8_SB(0, 1), b2 + hstepB, voffB);
;             PG8_WAIT_V(6); PG8_BAR; PG8_MMA(1, 1, At, B1); PG8_BAR;
.LBB1_2339:
	s_add_u32 s12, s10, 0xfff80080
	s_addc_u32 s13, s11, -1
	s_cmp_eq_u32 s3, 4
	s_cselect_b32 s15, s38, s13
	s_cselect_b32 s14, s39, s12
	s_cselect_b32 s13, s48, s56
	s_cselect_b32 s12, s49, s53
	s_add_i32 m0, s9, 0xc000
	ds_read_b128 v[168:171], v166
	ds_read_b128 v[172:175], v166 offset:1024
	ds_read_b128 v[176:179], v166 offset:2048
	ds_read_b128 v[180:183], v166 offset:3072
	ds_read_b128 v[184:187], v166 offset:4096
	ds_read_b128 v[188:191], v166 offset:5120
	ds_read_b128 v[192:195], v166 offset:6144
	ds_read_b128 v[198:201], v166 offset:7168
	global_load_lds_dwordx4 v154, s[10:11]
	s_add_i32 m0, s9, 0xe000
	s_nop 0
	global_load_lds_dwordx4 v152, s[10:11]
	s_waitcnt lgkmcnt(8)
	s_setprio 1
	s_barrier
	s_waitcnt lgkmcnt(7)
	v_mfma_f32_16x16x32_bf16 v[140:143], v[40:43], v[168:171], v[140:143]
	v_mfma_f32_16x16x32_bf16 v[136:139], v[56:59], v[168:171], v[136:139]
	s_waitcnt lgkmcnt(5)
	v_mfma_f32_16x16x32_bf16 v[124:127], v[40:43], v[176:179], v[124:127]
	v_mfma_f32_16x16x32_bf16 v[120:123], v[56:59], v[176:179], v[120:123]
	s_waitcnt lgkmcnt(3)
	v_mfma_f32_16x16x32_bf16 v[108:111], v[40:43], v[184:187], v[108:111]
	v_mfma_f32_16x16x32_bf16 v[104:107], v[56:59], v[184:187], v[104:107]
	s_waitcnt lgkmcnt(1)
	v_mfma_f32_16x16x32_bf16 v[92:95], v[40:43], v[192:195], v[92:95]
	v_mfma_f32_16x16x32_bf16 v[88:91], v[56:59], v[192:195], v[88:91]
	v_mfma_f32_16x16x32_bf16 v[140:143], v[44:47], v[172:175], v[140:143]
	v_mfma_f32_16x16x32_bf16 v[136:139], v[60:63], v[172:175], v[136:139]
	v_mfma_f32_16x16x32_bf16 v[124:127], v[44:47], v[180:183], v[124:127]
	v_mfma_f32_16x16x32_bf16 v[120:123], v[60:63], v[180:183], v[120:123]
	v_mfma_f32_16x16x32_bf16 v[108:111], v[44:47], v[188:191], v[108:111]
	v_mfma_f32_16x16x32_bf16 v[104:107], v[60:63], v[188:191], v[104:107]
	s_waitcnt lgkmcnt(0)
	v_mfma_f32_16x16x32_bf16 v[92:95], v[44:47], v[198:201], v[92:95]
	v_mfma_f32_16x16x32_bf16 v[88:91], v[60:63], v[198:201], v[88:91]
	s_barrier
	s_setprio 0
	s_add_i32 s57, s35, s22
	v_lshl_add_u64 v[160:161], s[12:13], 0, v[148:149]
	s_mov_b32 m0, s57
	ds_read_b128 v[202:205], v167
	ds_read_b128 v[206:209], v167 offset:1024
	ds_read_b128 v[210:213], v167 offset:2048
	ds_read_b128 v[214:217], v167 offset:3072
	global_load_lds_dwordx4 v[160:161], off
	v_lshl_add_u64 v[218:219], s[12:13], 0, v[144:145]
	s_add_i32 m0, s57, 0x2000
	s_nop 0
	global_load_lds_dwordx4 v[218:219], off
	s_setprio 1
	s_barrier
	s_waitcnt lgkmcnt(3)
	v_mfma_f32_16x16x32_bf16 v[132:135], v[202:205], v[168:171], v[132:135]
	s_waitcnt lgkmcnt(1)
	v_mfma_f32_16x16x32_bf16 v[128:131], v[210:213], v[168:171], v[128:131]
	v_mfma_f32_16x16x32_bf16 v[116:119], v[202:205], v[176:179], v[116:119]
	v_mfma_f32_16x16x32_bf16 v[112:115], v[210:213], v[176:179], v[112:115]
	v_mfma_f32_16x16x32_bf16 v[100:103], v[202:205], v[184:187], v[100:103]
	v_mfma_f32_16x16x32_bf16 v[96:99], v[210:213], v[184:187], v[96:99]
	v_mfma_f32_16x16x32_bf16 v[84:87], v[202:205], v[192:195], v[84:87]
	v_mfma_f32_16x16x32_bf16 v[80:83], v[210:213], v[192:195], v[80:83]
	v_mfma_f32_16x16x32_bf16 v[132:135], v[206:209], v[172:175], v[132:135]
	s_mov_b32 m0, s9
	s_waitcnt lgkmcnt(0)
	v_mfma_f32_16x16x32_bf16 v[128:131], v[214:217], v[172:175], v[128:131]
	v_lshl_add_u64 v[220:221], s[14:15], 0, v[150:151]
	v_mfma_f32_16x16x32_bf16 v[116:119], v[206:209], v[180:183], v[116:119]
	v_mfma_f32_16x16x32_bf16 v[112:115], v[214:217], v[180:183], v[112:115]
	v_mfma_f32_16x16x32_bf16 v[100:103], v[206:209], v[188:191], v[100:103]
	v_mfma_f32_16x16x32_bf16 v[96:99], v[214:217], v[188:191], v[96:99]
	v_mfma_f32_16x16x32_bf16 v[84:87], v[206:209], v[198:201], v[84:87]
	v_mfma_f32_16x16x32_bf16 v[80:83], v[214:217], v[198:201], v[80:83]
	s_barrier
	s_setprio 0
	ds_read_b128 v[168:171], v166 offset:16384
	ds_read_b128 v[172:175], v166 offset:17408
	ds_read_b128 v[176:179], v166 offset:18432
	ds_read_b128 v[180:183], v166 offset:19456
	ds_read_b128 v[184:187], v166 offset:20480
	ds_read_b128 v[188:191], v166 offset:21504
	ds_read_b128 v[192:195], v166 offset:22528
	ds_read_b128 v[198:201], v166 offset:23552
	global_load_lds_dwordx4 v[220:221], off
	v_lshl_add_u64 v[222:223], s[14:15], 0, v[146:147]
	s_mov_b32 m0, s24
	s_nop 0
	global_load_lds_dwordx4 v[222:223], off
	s_waitcnt vmcnt(10)
	s_setprio 1
	s_barrier
	s_waitcnt lgkmcnt(7)
	v_mfma_f32_16x16x32_bf16 v[76:79], v[40:43], v[168:171], v[76:79]
	v_mfma_f32_16x16x32_bf16 v[72:75], v[56:59], v[168:171], v[72:75]
	s_waitcnt lgkmcnt(5)
	v_mfma_f32_16x16x32_bf16 v[52:55], v[40:43], v[176:179], v[52:55]
	v_mfma_f32_16x16x32_bf16 v[48:51], v[56:59], v[176:179], v[48:51]
	s_waitcnt lgkmcnt(3)
	v_mfma_f32_16x16x32_bf16 v[28:31], v[40:43], v[184:187], v[28:31]
	v_mfma_f32_16x16x32_bf16 v[24:27], v[56:59], v[184:187], v[24:27]
	s_waitcnt lgkmcnt(1)
	v_mfma_f32_16x16x32_bf16 v[12:15], v[40:43], v[192:195], v[12:15]
	v_mfma_f32_16x16x32_bf16 v[8:11], v[56:59], v[192:195], v[8:11]
	v_mfma_f32_16x16x32_bf16 v[76:79], v[44:47], v[172:175], v[76:79]
	v_mfma_f32_16x16x32_bf16 v[72:75], v[60:63], v[172:175], v[72:75]
	v_mfma_f32_16x16x32_bf16 v[52:55], v[44:47], v[180:183], v[52:55]
	v_mfma_f32_16x16x32_bf16 v[48:51], v[60:63], v[180:183], v[48:51]
	v_mfma_f32_16x16x32_bf16 v[28:31], v[44:47], v[188:191], v[28:31]
	v_mfma_f32_16x16x32_bf16 v[24:27], v[60:63], v[188:191], v[24:27]
	s_waitcnt lgkmcnt(0)
	v_mfma_f32_16x16x32_bf16 v[12:15], v[44:47], v[198:201], v[12:15]
	v_mfma_f32_16x16x32_bf16 v[8:11], v[60:63], v[198:201], v[8:11]
	s_barrier
	s_setprio 0
	s_add_u32 s58, s12, 0x20000
	s_addc_u32 s59, s13, 0
	s_add_i32 s57, s36, s22
	s_mov_b32 m0, s57
	s_nop 0
	global_load_lds_dwordx4 v148, s[58:59]
	s_add_i32 m0, s57, 0x2000
	s_nop 0
	global_load_lds_dwordx4 v144, s[58:59]
	s_waitcnt vmcnt(6)
	s_setprio 1
	s_barrier
; #define PG8_STAGE(bufoff, gbase, voff) do { _Pragma("unroll") for (int _i = 0; _i < 2; ++_i) \
;         __builtin_amdgcn_global_load_lds((const unsigned*)((const char*)(gbase) + (voff)[_i]), (LAS unsigned*)(lds + (bufoff) + ldsw + _i * 8192), 16, 0, 0); } while (0)
; #define PG8_LDA(dst, b, h) do { _Pragma("unroll") for (int m = 0; m < 4; ++m) _Pragma("unroll") for (int k = 0; k < 2; ++k) dst[m][k] = *(const LAS bf16x8*)(lds + PG8_SA(b, h) + aoff + m * 2048 + k * 1024); } while (0)
; #define PG8_LDB(dst, b, h) do { _Pragma("unroll") for (int n = 0; n < 2; ++n) _Pragma("unroll") for (int k = 0; k < 2; ++k) dst[n][k] = *(const LAS bf16x8*)(lds + PG8_SB(b, h) + boff + n * 2048 + k * 1024); } while (0)
; #define PG8_MMA(ai, bj, At, Bt) do { __builtin_amdgcn_s_setprio(1); _Pragma("unroll") for (int m = 0; m < 4; ++m) _Pragma("unroll") for (int n = 0; n < 2; ++n) _Pragma("unroll") for (int k = 0; k < 2; ++k) \
;         acc[ai][bj][m][n] = __builtin_amdgcn_mfma_f32_16x16x32_bf16(Bt[n][k], At[m][k], acc[ai][bj][m][n], 0, 0, 0); __builtin_amdgcn_s_setprio(0); } while (0)
; #define PG8_WAIT_V(n) asm volatile("s_waitcnt vmcnt(" #n ")" ::: "memory")
; #define PG8_WAIT_L(n) asm volatile("s_waitcnt lgkmcnt(" #n ")" ::: "memory")
; #define PG8_BAR __builtin_amdgcn_s_barrier()
; #define PG8_SCHED __builtin_amdgcn_sched_barrier(0)
; template <class Map, class Epi>
; DI void gemm_phase(LAS unsigned char* lds, const Map& MP, const Epi& E, const int nM, const int nN, const int K, const int lda, const int ldb) {
;     ...
;             PG8_BAR; PG8_WAIT_L(0); PG8_MMA(1, 0, At, B0); PG8_BAR; PG8_SCHED;
;             PG8_STAGE(PG8_SB(0, 1), b2 + hstepB, voffB);
;             PG8_WAIT_V(6); PG8_BAR; PG8_MMA(1, 1, At, B1); PG8_BAR;
;             PG8_LDB(B0, 1, 0); PG8_SCHED; PG8_LDA(At, 1, 0); PG8_STAGE(PG8_SA(0, 1), a2 + hstepA, voffA);
;             PG8_WAIT_L(8); PG8_BAR; PG8_WAIT_L(0); PG8_MMA(0, 0, At, B0); PG8_BAR; PG8_SCHED;
;             PG8_LDB(B1, 1, 1); PG8_STAGE(PG8_SB(1, 0), b3, voffB);
;             PG8_BAR; PG8_WAIT_L(0); PG8_MMA(0, 1, At, B1); PG8_BAR;
;             PG8_LDA(At, 1, 1); PG8_STAGE(PG8_SA(1, 0), a3, voffA);
;             PG8_BAR; PG8_WAIT_L(0); PG8_MMA(1, 0, At, B0); PG8_BAR; PG8_SCHED;
	v_mfma_f32_16x16x32_bf16 v[36:39], v[202:205], v[176:179], v[36:39]
	v_mfma_f32_16x16x32_bf16 v[32:35], v[210:213], v[176:179], v[32:35]
	v_mfma_f32_16x16x32_bf16 v[20:23], v[202:205], v[184:187], v[20:23]
	v_mfma_f32_16x16x32_bf16 v[16:19], v[210:213], v[184:187], v[16:19]
	v_mfma_f32_16x16x32_bf16 v[4:7], v[202:205], v[192:195], v[4:7]
	v_mfma_f32_16x16x32_bf16 v[0:3], v[210:213], v[192:195], v[0:3]
	v_mfma_f32_16x16x32_bf16 v[40:43], v[202:205], v[168:171], v[68:71]
	s_add_i32 s57, 0, 0x18000
	v_add_u32_e32 v68, s57, v164
	ds_read_b128 v[56:59], v68
	ds_read_b128 v[60:63], v68 offset:1024
	v_mfma_f32_16x16x32_bf16 v[44:47], v[210:213], v[168:171], v[64:67]
	ds_read_b128 v[64:67], v68 offset:2048
	ds_read_b128 v[68:71], v68 offset:3072
	v_mfma_f32_16x16x32_bf16 v[36:39], v[206:209], v[180:183], v[36:39]
	v_mfma_f32_16x16x32_bf16 v[32:35], v[214:217], v[180:183], v[32:35]
	v_mfma_f32_16x16x32_bf16 v[20:23], v[206:209], v[188:191], v[20:23]
	v_mfma_f32_16x16x32_bf16 v[16:19], v[214:217], v[188:191], v[16:19]
	v_mfma_f32_16x16x32_bf16 v[4:7], v[206:209], v[198:201], v[4:7]
	v_mfma_f32_16x16x32_bf16 v[0:3], v[214:217], v[198:201], v[0:3]
	v_mfma_f32_16x16x32_bf16 v[40:43], v[206:209], v[172:175], v[40:43]
	v_mfma_f32_16x16x32_bf16 v[44:47], v[214:217], v[172:175], v[44:47]
	s_barrier
	s_setprio 0
	s_add_u32 s14, s14, 0x80000
	s_addc_u32 s15, s15, 0
	s_mov_b32 m0, s25
	ds_read_b128 v[168:171], v166 offset:32768
	ds_read_b128 v[172:175], v166 offset:33792
	ds_read_b128 v[176:179], v166 offset:34816
	ds_read_b128 v[180:183], v166 offset:35840
	ds_read_b128 v[184:187], v166 offset:36864
	ds_read_b128 v[188:191], v166 offset:37888
	ds_read_b128 v[192:195], v166 offset:38912
	ds_read_b128 v[198:201], v166 offset:39936
	global_load_lds_dwordx4 v150, s[14:15]
	s_mov_b32 m0, s26
	s_nop 0
	global_load_lds_dwordx4 v146, s[14:15]
	s_waitcnt lgkmcnt(8)
	s_setprio 1
	s_barrier
	s_waitcnt lgkmcnt(7)
	v_mfma_f32_16x16x32_bf16 v[140:143], v[56:59], v[168:171], v[140:143]
	v_mfma_f32_16x16x32_bf16 v[136:139], v[64:67], v[168:171], v[136:139]
	s_waitcnt lgkmcnt(5)
	v_mfma_f32_16x16x32_bf16 v[124:127], v[56:59], v[176:179], v[124:127]
	v_mfma_f32_16x16x32_bf16 v[120:123], v[64:67], v[176:179], v[120:123]
	s_waitcnt lgkmcnt(3)
	v_mfma_f32_16x16x32_bf16 v[108:111], v[56:59], v[184:187], v[108:111]
	v_mfma_f32_16x16x32_bf16 v[104:107], v[64:67], v[184:187], v[104:107]
	s_waitcnt lgkmcnt(1)
	v_mfma_f32_16x16x32_bf16 v[92:95], v[56:59], v[192:195], v[92:95]
	v_mfma_f32_16x16x32_bf16 v[88:91], v[64:67], v[192:195], v[88:91]
	v_mfma_f32_16x16x32_bf16 v[140:143], v[60:63], v[172:175], v[140:143]
	v_mfma_f32_16x16x32_bf16 v[136:139], v[68:71], v[172:175], v[136:139]
	v_mfma_f32_16x16x32_bf16 v[124:127], v[60:63], v[180:183], v[124:127]
	v_mfma_f32_16x16x32_bf16 v[120:123], v[68:71], v[180:183], v[120:123]
	v_mfma_f32_16x16x32_bf16 v[108:111], v[60:63], v[188:191], v[108:111]
	v_mfma_f32_16x16x32_bf16 v[104:107], v[68:71], v[188:191], v[104:107]
	s_waitcnt lgkmcnt(0)
	v_mfma_f32_16x16x32_bf16 v[92:95], v[60:63], v[198:201], v[92:95]
	v_mfma_f32_16x16x32_bf16 v[88:91], v[68:71], v[198:201], v[88:91]
	s_barrier
	s_setprio 0
	s_add_i32 s14, 0, 0x1c000
	s_add_i32 s15, s57, s22
	v_add_u32_e32 v196, s14, v164
	v_lshl_add_u64 v[160:161], v[160:161], 0, s[46:47]
	s_mov_b32 m0, s15
	ds_read_b128 v[202:205], v196
	ds_read_b128 v[206:209], v196 offset:1024
	ds_read_b128 v[210:213], v196 offset:2048
	ds_read_b128 v[214:217], v196 offset:3072
	global_load_lds_dwordx4 v[160:161], off
	v_lshl_add_u64 v[160:161], v[218:219], 0, s[46:47]
	s_add_i32 m0, s15, 0x2000
	s_nop 0
	global_load_lds_dwordx4 v[160:161], off
	s_setprio 1
	s_barrier
	s_waitcnt lgkmcnt(3)
	v_mfma_f32_16x16x32_bf16 v[132:135], v[202:205], v[168:171], v[132:135]
	s_waitcnt lgkmcnt(1)
	v_mfma_f32_16x16x32_bf16 v[128:131], v[210:213], v[168:171], v[128:131]
	v_mfma_f32_16x16x32_bf16 v[116:119], v[202:205], v[176:179], v[116:119]
	v_mfma_f32_16x16x32_bf16 v[112:115], v[210:213], v[176:179], v[112:115]
	v_mfma_f32_16x16x32_bf16 v[100:103], v[202:205], v[184:187], v[100:103]
	v_mfma_f32_16x16x32_bf16 v[96:99], v[210:213], v[184:187], v[96:99]
	v_mfma_f32_16x16x32_bf16 v[84:87], v[202:205], v[192:195], v[84:87]
	v_mfma_f32_16x16x32_bf16 v[80:83], v[210:213], v[192:195], v[80:83]
	v_mfma_f32_16x16x32_bf16 v[132:135], v[206:209], v[172:175], v[132:135]
	s_mov_b32 m0, s30
	s_waitcnt lgkmcnt(0)
	v_mfma_f32_16x16x32_bf16 v[128:131], v[214:217], v[172:175], v[128:131]
	v_lshl_add_u64 v[160:161], v[220:221], 0, s[46:47]
	v_mfma_f32_16x16x32_bf16 v[116:119], v[206:209], v[180:183], v[116:119]
	v_mfma_f32_16x16x32_bf16 v[112:115], v[214:217], v[180:183], v[112:115]
	v_mfma_f32_16x16x32_bf16 v[100:103], v[206:209], v[188:191], v[100:103]
	v_mfma_f32_16x16x32_bf16 v[96:99], v[214:217], v[188:191], v[96:99]
	v_mfma_f32_16x16x32_bf16 v[84:87], v[206:209], v[198:201], v[84:87]
	v_mfma_f32_16x16x32_bf16 v[80:83], v[214:217], v[198:201], v[80:83]
	s_barrier
	s_setprio 0
	ds_read_b128 v[168:171], v166 offset:49152
	ds_read_b128 v[172:175], v166 offset:50176
	ds_read_b128 v[176:179], v166 offset:51200
	ds_read_b128 v[180:183], v166 offset:52224
	ds_read_b128 v[184:187], v166 offset:53248
	ds_read_b128 v[188:191], v166 offset:54272
	ds_read_b128 v[192:195], v166 offset:55296
	ds_read_b128 v[198:201], v166 offset:56320
	global_load_lds_dwordx4 v[160:161], off
	v_lshl_add_u64 v[160:161], v[222:223], 0, s[46:47]
	s_mov_b32 m0, s31
	s_nop 0
	global_load_lds_dwordx4 v[160:161], off
	s_waitcnt vmcnt(10)
	s_setprio 1
	s_barrier
; DI float bflo(unsigned w) { return __uint_as_float(w << 16); }
; #define PG8_BAR __builtin_amdgcn_s_barrier()
;     DI void operator()(const f32x4 (&acc)[2][2][4][2], const Unit& u, int wr, int wc, int fr, int fq) const {
;         const int row0 = u.pm * BM + wr * 64 + fr, col0 = u.pn * BM + wc * 32 + 8 * fq;
;         f32x4 sc[2][2];
; #pragma unroll
;         for (int bj = 0; bj < 2; ++bj)
; #pragma unroll
;             for (int n = 0; n < 2; ++n) sc[bj][n] = scale ? *(const f32x4*)(scale + col0 + bj * HALF + 4 * n) : (f32x4){1.f, 1.f, 1.f, 1.f};
; #pragma unroll
;         for (int ai = 0; ai < 2; ++ai)
; #pragma unroll
;             for (int m = 0; m < 4; ++m) { const size_t ro = (size_t)(row0 + ai * HALF + m * 16) * D + col0;
; #pragma unroll
;                 for (int bj = 0; bj < 2; ++bj) {
;                     f32x4 x0, x1;
;                     if constexpr (IB) { const u32x4 w = *(const u32x4*)((const bf16_t*)Xin + ro + bj * HALF);
;                         x0 = (f32x4){bflo(w[0]), bfhi(w[0]), bflo(w[1]), bfhi(w[1])}; x1 = (f32x4){bflo(w[2]), bfhi(w[2]), bflo(w[3]), bfhi(w[3])}; }
;                     else { x0 = *(const f32x4*)((const float*)Xin + ro + bj * HALF); x1 = *(const f32x4*)((const float*)Xin + ro + bj * HALF + 4); }
;                     x0 += acc[ai][bj][m][0] * sc[bj][0]; x1 += acc[ai][bj][m][1] * sc[bj][1];
;                     if constexpr (OB) { u32x4 o; o[0] = pack2(x0[0], x0[1]); o[1] = pack2(x0[2], x0[3]); o[2] = pack2(x1[0], x1[1]); o[3] = pack2(x1[2], x1[3]);
;                         *(u32x4*)((bf16_t*)Xout + ro + bj * HALF) = o; }
; template <class Map, class Epi>
; DI void gemm_phase(LAS unsigned char* lds, const Map& MP, const Epi& E, const int nM, const int nN, const int K, const int lda, const int ldb) {
;     ...
;             PG8_LDB(B0, 1, 0); PG8_SCHED; PG8_LDA(At, 1, 0); PG8_STAGE(PG8_SA(0, 1), a2 + hstepA, voffA);
;             PG8_WAIT_L(8); PG8_BAR; PG8_WAIT_L(0); PG8_MMA(0, 0, At, B0); PG8_BAR; PG8_SCHED;
;             PG8_LDB(B1, 1, 1); PG8_STAGE(PG8_SB(1, 0), b3, voffB);
;             PG8_BAR; PG8_WAIT_L(0); PG8_MMA(0, 1, At, B1); PG8_BAR;
;             PG8_LDA(At, 1, 1); PG8_STAGE(PG8_SA(1, 0), a3, voffA);
;             PG8_BAR; PG8_WAIT_L(0); PG8_MMA(1, 0, At, B0); PG8_BAR; PG8_SCHED;
;             PG8_STAGE(PG8_SB(1, 1), b3 + hstepB, voffB);
;             PG8_WAIT_V(6); PG8_BAR; PG8_MMA(1, 1, At, B1); PG8_BAR;
	s_waitcnt lgkmcnt(7)
	v_mfma_f32_16x16x32_bf16 v[76:79], v[56:59], v[168:171], v[76:79]
	v_mfma_f32_16x16x32_bf16 v[72:75], v[64:67], v[168:171], v[72:75]
	s_waitcnt lgkmcnt(5)
	v_mfma_f32_16x16x32_bf16 v[52:55], v[56:59], v[176:179], v[52:55]
	v_mfma_f32_16x16x32_bf16 v[48:51], v[64:67], v[176:179], v[48:51]
	s_waitcnt lgkmcnt(3)
	v_mfma_f32_16x16x32_bf16 v[28:31], v[56:59], v[184:187], v[28:31]
	v_mfma_f32_16x16x32_bf16 v[24:27], v[64:67], v[184:187], v[24:27]
	s_waitcnt lgkmcnt(1)
	v_mfma_f32_16x16x32_bf16 v[12:15], v[56:59], v[192:195], v[12:15]
	v_mfma_f32_16x16x32_bf16 v[8:11], v[64:67], v[192:195], v[8:11]
	v_mfma_f32_16x16x32_bf16 v[76:79], v[60:63], v[172:175], v[76:79]
	v_mfma_f32_16x16x32_bf16 v[72:75], v[68:71], v[172:175], v[72:75]
	v_mfma_f32_16x16x32_bf16 v[52:55], v[60:63], v[180:183], v[52:55]
	v_mfma_f32_16x16x32_bf16 v[48:51], v[68:71], v[180:183], v[48:51]
	v_mfma_f32_16x16x32_bf16 v[28:31], v[60:63], v[188:191], v[28:31]
	v_mfma_f32_16x16x32_bf16 v[24:27], v[68:71], v[188:191], v[24:27]
	s_waitcnt lgkmcnt(0)
	v_mfma_f32_16x16x32_bf16 v[12:15], v[60:63], v[198:201], v[12:15]
	v_mfma_f32_16x16x32_bf16 v[8:11], v[68:71], v[198:201], v[8:11]
	s_barrier
	s_setprio 0
	s_add_u32 s12, s12, 0x20080
	s_addc_u32 s13, s13, 0
	s_add_i32 s14, s14, s22
	s_mov_b32 m0, s14
	s_nop 0
	global_load_lds_dwordx4 v148, s[12:13]
	s_add_i32 m0, s14, 0x2000
	s_nop 0
	global_load_lds_dwordx4 v144, s[12:13]
	s_waitcnt vmcnt(6)
	s_setprio 1
	s_barrier
	v_mfma_f32_16x16x32_bf16 v[40:43], v[202:205], v[168:171], v[40:43]
	v_mfma_f32_16x16x32_bf16 v[68:71], v[206:209], v[172:175], v[40:43]
	v_mfma_f32_16x16x32_bf16 v[40:43], v[210:213], v[168:171], v[44:47]
	v_mfma_f32_16x16x32_bf16 v[36:39], v[202:205], v[176:179], v[36:39]
	v_mfma_f32_16x16x32_bf16 v[32:35], v[210:213], v[176:179], v[32:35]
	v_mfma_f32_16x16x32_bf16 v[20:23], v[202:205], v[184:187], v[20:23]
	v_mfma_f32_16x16x32_bf16 v[16:19], v[210:213], v[184:187], v[16:19]
	v_mfma_f32_16x16x32_bf16 v[4:7], v[202:205], v[192:195], v[4:7]
	v_mfma_f32_16x16x32_bf16 v[0:3], v[210:213], v[192:195], v[0:3]
	s_add_i32 s3, s3, 2
	v_mfma_f32_16x16x32_bf16 v[64:67], v[214:217], v[172:175], v[40:43]
	s_add_u32 s53, s53, 0x100
	s_addc_u32 s56, s56, 0
	ds_read_b128 v[40:43], v165
	ds_read_b128 v[44:47], v165 offset:1024
	ds_read_b128 v[56:59], v165 offset:2048
	ds_read_b128 v[60:63], v165 offset:3072
	v_mfma_f32_16x16x32_bf16 v[36:39], v[206:209], v[180:183], v[36:39]
	s_add_u32 s10, s10, 0x100
	s_addc_u32 s11, s11, 0
	v_mfma_f32_16x16x32_bf16 v[32:35], v[214:217], v[180:183], v[32:35]
	s_cmp_gt_u32 s3, 5
	v_mfma_f32_16x16x32_bf16 v[20:23], v[206:209], v[188:191], v[20:23]
	v_mfma_f32_16x16x32_bf16 v[16:19], v[214:217], v[188:191], v[16:19]
	v_mfma_f32_16x16x32_bf16 v[4:7], v[206:209], v[198:201], v[4:7]
	v_mfma_f32_16x16x32_bf16 v[0:3], v[214:217], v[198:201], v[0:3]
	s_barrier
	s_setprio 0
	s_cbranch_scc0 .LBB1_2339
	s_waitcnt lgkmcnt(0)
	s_lshl_b32 s2, s2, 8
	v_mov_b32_e32 v40, v163
	v_mov_b32_e32 v168, v162
	s_or_b32 s2, s2, s29
	s_and_b64 vcc, exec, s[40:41]
	v_lshl_add_u32 v160, v40, 3, s2
	s_lshl_b32 s2, s8, 8
	s_add_i32 s2, s2, s28
	v_add_u32_e32 v168, s2, v168
	v_ashrrev_i32_e32 v169, 31, v168
	v_ashrrev_i32_e32 v161, 31, v160
	v_lshlrev_b64 v[168:169], 11, v[168:169]
	v_lshl_add_u64 v[44:45], v[160:161], 2, s[44:45]
	v_lshl_add_u64 v[160:161], v[168:169], 0, v[160:161]
	v_lshlrev_b64 v[160:161], 1, v[160:161]
	v_lshl_add_u64 v[172:173], s[4:5], 0, v[160:161]
	global_load_dwordx4 v[56:59], v[44:45], off offset:16
	global_load_dwordx4 v[60:63], v[44:45], off
	global_load_dwordx4 v[40:43], v[44:45], off offset:528
	s_nop 0
	global_load_dwordx4 v[44:47], v[44:45], off offset:512
	s_mov_b64 s[2:3], 0x10000
	global_load_dwordx4 v[178:181], v[172:173], off
	global_load_dwordx4 v[182:185], v[172:173], off offset:256
	s_mov_b64 s[98:99], 0x10000
	v_lshl_add_u64 v[170:171], v[172:173], 0, s[98:99]
	global_load_dwordx4 v[186:189], v[170:171], off
	global_load_dwordx4 v[190:193], v[170:171], off offset:256
	s_mov_b64 s[98:99], 0x20000
	v_lshl_add_u64 v[170:171], v[172:173], 0, s[98:99]
	global_load_dwordx4 v[198:201], v[170:171], off
	global_load_dwordx4 v[202:205], v[170:171], off offset:256
	s_mov_b64 s[98:99], 0x30000
	v_lshl_add_u64 v[170:171], v[172:173], 0, s[98:99]
	global_load_dwordx4 v[206:209], v[170:171], off
	global_load_dwordx4 v[210:213], v[170:171], off offset:256
	s_mov_b64 s[98:99], 0x80000
	v_lshl_add_u64 v[170:171], v[172:173], 0, s[98:99]
	global_load_dwordx4 v[214:217], v[170:171], off
	global_load_dwordx4 v[248:251], v[170:171], off offset:256
	s_mov_b64 s[98:99], 0x90000
	v_lshl_add_u64 v[170:171], v[172:173], 0, s[98:99]
	global_load_dwordx4 v[252:255], v[170:171], off
	s_waitcnt vmcnt(10)
	s_nop 1
	v_mov_b32_e32 v168, v178
	v_mov_b32_e32 v169, v179
	v_mov_b32_e32 v170, v180
	v_mov_b32_e32 v171, v181
	s_mov_b32 s8, s52
	s_mov_b64 s[10:11], s[54:55]
	s_mov_b64 s[12:13], s[6:7]
	s_waitcnt lgkmcnt(0)
	v_lshlrev_b32_e32 v174, 16, v168
	v_and_b32_e32 v175, 0xffff0000, v168
	v_lshlrev_b32_e32 v168, 16, v169
	v_and_b32_e32 v169, 0xffff0000, v169
	v_lshlrev_b32_e32 v176, 16, v170
	v_and_b32_e32 v177, 0xffff0000, v170
	v_lshlrev_b32_e32 v170, 16, v171
	v_and_b32_e32 v171, 0xffff0000, v171
	v_pk_fma_f32 v[142:143], v[142:143], v[62:63], v[168:169]
	v_pk_fma_f32 v[140:141], v[140:141], v[60:61], v[174:175]
	v_pk_fma_f32 v[168:169], v[138:139], v[58:59], v[170:171]
	v_pk_fma_f32 v[138:139], v[136:137], v[56:57], v[176:177]
	v_cvt_pk_bf16_f32 v136, v140, v141
	v_cvt_pk_bf16_f32 v137, v142, v143
	v_cvt_pk_bf16_f32 v138, v138, v139
	v_cvt_pk_bf16_f32 v139, v168, v169
	v_lshl_add_u64 v[140:141], s[42:43], 0, v[160:161]
	global_store_dwordx4 v[140:141], v[136:139], off
	s_waitcnt vmcnt(10)
; DI unsigned pack2(float a, float b) { f32x2 v = {a, b}; hwbf16x2 r = __builtin_convertvector(v, hwbf16x2); return __builtin_bit_cast(unsigned, r); }
; DI float bflo(unsigned w) { return __uint_as_float(w << 16); }
; DI float bfhi(unsigned w) { return __uint_as_float(w & 0xffff0000u); }
;     DI void operator()(const f32x4 (&acc)[2][2][4][2], const Unit& u, int wr, int wc, int fr, int fq) const {
;     ...
;         for (int ai = 0; ai < 2; ++ai)
; #pragma unroll
;             for (int m = 0; m < 4; ++m) { const size_t ro = (size_t)(row0 + ai * HALF + m * 16) * D + col0;
; #pragma unroll
;                 for (int bj = 0; bj < 2; ++bj) {
;                     f32x4 x0, x1;
;                     if constexpr (IB) { const u32x4 w = *(const u32x4*)((const bf16_t*)Xin + ro + bj * HALF);
;                         x0 = (f32x4){bflo(w[0]), bfhi(w[0]), bflo(w[1]), bfhi(w[1])}; x1 = (f32x4){bflo(w[2]), bfhi(w[2]), bflo(w[3]), bfhi(w[3])}; }
;                     else { x0 = *(const f32x4*)((const float*)Xin + ro + bj * HALF); x1 = *(const f32x4*)((const float*)Xin + ro + bj * HALF + 4); }
;                     x0 += acc[ai][bj][m][0] * sc[bj][0]; x1 += acc[ai][bj][m][1] * sc[bj][1];
;                     if constexpr (OB) { u32x4 o; o[0] = pack2(x0[0], x0[1]); o[1] = pack2(x0[2], x0[3]); o[2] = pack2(x1[0], x1[1]); o[3] = pack2(x1[2], x1[3]);
;                         *(u32x4*)((bf16_t*)Xout + ro + bj * HALF) = o; }
;                     else { *(f32x4*)((float*)Xout + ro + bj * HALF) = x0; *(f32x4*)((float*)Xout + ro + bj * HALF + 4) = x1; } } }
	s_nop 1
	v_mov_b32_e32 v136, v182
	v_mov_b32_e32 v137, v183
	v_mov_b32_e32 v138, v184
	v_mov_b32_e32 v139, v185
	s_waitcnt lgkmcnt(0)
	v_lshlrev_b32_e32 v142, 16, v136
	v_and_b32_e32 v143, 0xffff0000, v136
	v_lshlrev_b32_e32 v136, 16, v137
	v_and_b32_e32 v137, 0xffff0000, v137
	v_lshlrev_b32_e32 v168, 16, v138
	v_and_b32_e32 v169, 0xffff0000, v138
	v_lshlrev_b32_e32 v138, 16, v139
	v_and_b32_e32 v139, 0xffff0000, v139
	v_pk_fma_f32 v[134:135], v[134:135], v[46:47], v[136:137]
	v_pk_fma_f32 v[132:133], v[132:133], v[44:45], v[142:143]
	v_pk_fma_f32 v[136:137], v[130:131], v[42:43], v[138:139]
	v_pk_fma_f32 v[130:131], v[128:129], v[40:41], v[168:169]
	v_cvt_pk_bf16_f32 v128, v132, v133
	v_cvt_pk_bf16_f32 v129, v134, v135
	v_cvt_pk_bf16_f32 v130, v130, v131
	v_cvt_pk_bf16_f32 v131, v136, v137
	v_lshl_add_u64 v[132:133], v[160:161], 0, s[2:3]
	global_store_dwordx4 v[140:141], v[128:131], off offset:256
	v_lshl_add_u64 v[134:135], s[4:5], 0, v[132:133]
	s_waitcnt vmcnt(10)
	s_nop 1
	v_mov_b32_e32 v128, v186
	v_mov_b32_e32 v129, v187
	v_mov_b32_e32 v130, v188
	v_mov_b32_e32 v131, v189
	s_mov_b64 s[2:3], 0x20000
	s_waitcnt lgkmcnt(0)
	v_lshlrev_b32_e32 v136, 16, v128
	v_and_b32_e32 v137, 0xffff0000, v128
	v_lshlrev_b32_e32 v128, 16, v129
	v_and_b32_e32 v129, 0xffff0000, v129
	v_lshlrev_b32_e32 v138, 16, v130
	v_and_b32_e32 v139, 0xffff0000, v130
	v_lshlrev_b32_e32 v130, 16, v131
	v_and_b32_e32 v131, 0xffff0000, v131
	v_pk_fma_f32 v[126:127], v[126:127], v[62:63], v[128:129]
	v_pk_fma_f32 v[124:125], v[124:125], v[60:61], v[136:137]
	v_pk_fma_f32 v[128:129], v[122:123], v[58:59], v[130:131]
	v_pk_fma_f32 v[122:123], v[120:121], v[56:57], v[138:139]
	v_cvt_pk_bf16_f32 v120, v124, v125
	v_cvt_pk_bf16_f32 v121, v126, v127
	v_cvt_pk_bf16_f32 v122, v122, v123
	v_cvt_pk_bf16_f32 v123, v128, v129
	v_lshl_add_u64 v[124:125], s[42:43], 0, v[132:133]
	global_store_dwordx4 v[124:125], v[120:123], off
	s_waitcnt vmcnt(10)
	s_nop 1
	v_mov_b32_e32 v120, v190
	v_mov_b32_e32 v121, v191
	v_mov_b32_e32 v122, v192
	v_mov_b32_e32 v123, v193
	s_waitcnt lgkmcnt(0)
	v_lshlrev_b32_e32 v126, 16, v120
	v_and_b32_e32 v127, 0xffff0000, v120
	v_lshlrev_b32_e32 v120, 16, v121
	v_and_b32_e32 v121, 0xffff0000, v121
	v_lshlrev_b32_e32 v128, 16, v122
	v_and_b32_e32 v129, 0xffff0000, v122
	v_lshlrev_b32_e32 v122, 16, v123
	v_and_b32_e32 v123, 0xffff0000, v123
	v_pk_fma_f32 v[118:119], v[118:119], v[46:47], v[120:121]
	v_pk_fma_f32 v[116:117], v[116:117], v[44:45], v[126:127]
	v_pk_fma_f32 v[120:121], v[114:115], v[42:43], v[122:123]
	v_pk_fma_f32 v[114:115], v[112:113], v[40:41], v[128:129]
	v_cvt_pk_bf16_f32 v112, v116, v117
	v_cvt_pk_bf16_f32 v113, v118, v119
	v_cvt_pk_bf16_f32 v114, v114, v115
	v_cvt_pk_bf16_f32 v115, v120, v121
	v_lshl_add_u64 v[116:117], v[160:161], 0, s[2:3]
	global_store_dwordx4 v[124:125], v[112:115], off offset:256
	v_lshl_add_u64 v[118:119], s[4:5], 0, v[116:117]
	s_waitcnt vmcnt(10)
	s_nop 1
	v_mov_b32_e32 v112, v198
	v_mov_b32_e32 v113, v199
	v_mov_b32_e32 v114, v200
	v_mov_b32_e32 v115, v201
	s_mov_b64 s[2:3], 0x30000
	s_waitcnt lgkmcnt(0)
	v_lshlrev_b32_e32 v120, 16, v112
	v_and_b32_e32 v121, 0xffff0000, v112
	v_lshlrev_b32_e32 v112, 16, v113
	v_and_b32_e32 v113, 0xffff0000, v113
	v_lshlrev_b32_e32 v122, 16, v114
	v_and_b32_e32 v123, 0xffff0000, v114
	v_lshlrev_b32_e32 v114, 16, v115
	v_and_b32_e32 v115, 0xffff0000, v115
	v_pk_fma_f32 v[110:111], v[110:111], v[62:63], v[112:113]
	v_pk_fma_f32 v[108:109], v[108:109], v[60:61], v[120:121]
	v_pk_fma_f32 v[112:113], v[106:107], v[58:59], v[114:115]
	v_pk_fma_f32 v[106:107], v[104:105], v[56:57], v[122:123]
	v_cvt_pk_bf16_f32 v104, v108, v109
	v_cvt_pk_bf16_f32 v105, v110, v111
	v_cvt_pk_bf16_f32 v106, v106, v107
	v_cvt_pk_bf16_f32 v107, v112, v113
	v_lshl_add_u64 v[108:109], s[42:43], 0, v[116:117]
	global_store_dwordx4 v[108:109], v[104:107], off
	s_waitcnt vmcnt(10)
	s_nop 1
	v_mov_b32_e32 v104, v202
	v_mov_b32_e32 v105, v203
	v_mov_b32_e32 v106, v204
	v_mov_b32_e32 v107, v205
	s_waitcnt lgkmcnt(0)
	v_lshlrev_b32_e32 v110, 16, v104
	v_and_b32_e32 v111, 0xffff0000, v104
	v_lshlrev_b32_e32 v104, 16, v105
	v_and_b32_e32 v105, 0xffff0000, v105
	v_lshlrev_b32_e32 v112, 16, v106
	v_and_b32_e32 v113, 0xffff0000, v106
	v_lshlrev_b32_e32 v106, 16, v107
	v_and_b32_e32 v107, 0xffff0000, v107
	v_pk_fma_f32 v[102:103], v[102:103], v[46:47], v[104:105]
	v_pk_fma_f32 v[100:101], v[100:101], v[44:45], v[110:111]
	v_pk_fma_f32 v[104:105], v[98:99], v[42:43], v[106:107]
	v_pk_fma_f32 v[98:99], v[96:97], v[40:41], v[112:113]
	v_cvt_pk_bf16_f32 v96, v100, v101
	v_cvt_pk_bf16_f32 v97, v102, v103
	v_cvt_pk_bf16_f32 v98, v98, v99
	v_cvt_pk_bf16_f32 v99, v104, v105
	v_lshl_add_u64 v[100:101], v[160:161], 0, s[2:3]
	global_store_dwordx4 v[108:109], v[96:99], off offset:256
	v_lshl_add_u64 v[102:103], s[4:5], 0, v[100:101]
	s_waitcnt vmcnt(10)
	s_nop 1
	v_mov_b32_e32 v96, v206
	v_mov_b32_e32 v97, v207
	v_mov_b32_e32 v98, v208
	v_mov_b32_e32 v99, v209
	s_mov_b64 s[2:3], 0x80000
	s_waitcnt lgkmcnt(0)
	v_lshlrev_b32_e32 v104, 16, v96
	v_and_b32_e32 v105, 0xffff0000, v96
	v_lshlrev_b32_e32 v96, 16, v97
	v_and_b32_e32 v97, 0xffff0000, v97
	v_lshlrev_b32_e32 v106, 16, v98
	v_and_b32_e32 v107, 0xffff0000, v98
	v_lshlrev_b32_e32 v98, 16, v99
	v_and_b32_e32 v99, 0xffff0000, v99
	v_pk_fma_f32 v[94:95], v[94:95], v[62:63], v[96:97]
	v_pk_fma_f32 v[92:93], v[92:93], v[60:61], v[104:105]
	v_pk_fma_f32 v[96:97], v[90:91], v[58:59], v[98:99]
	v_pk_fma_f32 v[90:91], v[88:89], v[56:57], v[106:107]
	v_cvt_pk_bf16_f32 v88, v92, v93
	v_cvt_pk_bf16_f32 v89, v94, v95
	v_cvt_pk_bf16_f32 v90, v90, v91
	v_cvt_pk_bf16_f32 v91, v96, v97
	v_lshl_add_u64 v[92:93], s[42:43], 0, v[100:101]
	global_store_dwordx4 v[92:93], v[88:91], off
	s_waitcnt vmcnt(10)
; DI unsigned pack2(float a, float b) { f32x2 v = {a, b}; hwbf16x2 r = __builtin_convertvector(v, hwbf16x2); return __builtin_bit_cast(unsigned, r); }
; DI float bflo(unsigned w) { return __uint_as_float(w << 16); }
; DI float bfhi(unsigned w) { return __uint_as_float(w & 0xffff0000u); }
;     DI void operator()(const f32x4 (&acc)[2][2][4][2], const Unit& u, int wr, int wc, int fr, int fq) const {
;     ...
;         for (int ai = 0; ai < 2; ++ai)
; #pragma unroll
;             for (int m = 0; m < 4; ++m) { const size_t ro = (size_t)(row0 + ai * HALF + m * 16) * D + col0;
; #pragma unroll
;                 for (int bj = 0; bj < 2; ++bj) {
;                     f32x4 x0, x1;
;                     if constexpr (IB) { const u32x4 w = *(const u32x4*)((const bf16_t*)Xin + ro + bj * HALF);
;                         x0 = (f32x4){bflo(w[0]), bfhi(w[0]), bflo(w[1]), bfhi(w[1])}; x1 = (f32x4){bflo(w[2]), bfhi(w[2]), bflo(w[3]), bfhi(w[3])}; }
;                     else { x0 = *(const f32x4*)((const float*)Xin + ro + bj * HALF); x1 = *(const f32x4*)((const float*)Xin + ro + bj * HALF + 4); }
;                     x0 += acc[ai][bj][m][0] * sc[bj][0]; x1 += acc[ai][bj][m][1] * sc[bj][1];
;                     if constexpr (OB) { u32x4 o; o[0] = pack2(x0[0], x0[1]); o[1] = pack2(x0[2], x0[3]); o[2] = pack2(x1[0], x1[1]); o[3] = pack2(x1[2], x1[3]);
;                         *(u32x4*)((bf16_t*)Xout + ro + bj * HALF) = o; }
;                     else { *(f32x4*)((float*)Xout + ro + bj * HALF) = x0; *(f32x4*)((float*)Xout + ro + bj * HALF + 4) = x1; } } }
	s_nop 1
	v_mov_b32_e32 v88, v210
	v_mov_b32_e32 v89, v211
	v_mov_b32_e32 v90, v212
	v_mov_b32_e32 v91, v213
	s_waitcnt lgkmcnt(0)
	v_lshlrev_b32_e32 v94, 16, v88
	v_and_b32_e32 v95, 0xffff0000, v88
	v_lshlrev_b32_e32 v88, 16, v89
	v_and_b32_e32 v89, 0xffff0000, v89
	v_lshlrev_b32_e32 v96, 16, v90
	v_and_b32_e32 v97, 0xffff0000, v90
	v_lshlrev_b32_e32 v90, 16, v91
	v_and_b32_e32 v91, 0xffff0000, v91
	v_pk_fma_f32 v[86:87], v[86:87], v[46:47], v[88:89]
	v_pk_fma_f32 v[84:85], v[84:85], v[44:45], v[94:95]
	v_pk_fma_f32 v[88:89], v[82:83], v[42:43], v[90:91]
	v_pk_fma_f32 v[82:83], v[80:81], v[40:41], v[96:97]
	v_cvt_pk_bf16_f32 v80, v84, v85
	v_cvt_pk_bf16_f32 v81, v86, v87
	v_cvt_pk_bf16_f32 v82, v82, v83
	v_cvt_pk_bf16_f32 v83, v88, v89
	v_lshl_add_u64 v[84:85], v[160:161], 0, s[2:3]
	global_store_dwordx4 v[92:93], v[80:83], off offset:256
	v_lshl_add_u64 v[86:87], s[4:5], 0, v[84:85]
	s_waitcnt vmcnt(10)
	s_nop 1
	v_mov_b32_e32 v80, v214
	v_mov_b32_e32 v81, v215
	v_mov_b32_e32 v82, v216
	v_mov_b32_e32 v83, v217
	s_mov_b64 s[2:3], 0x90000
	s_waitcnt lgkmcnt(0)
	v_lshlrev_b32_e32 v88, 16, v80
	v_and_b32_e32 v89, 0xffff0000, v80
	v_lshlrev_b32_e32 v80, 16, v81
	v_and_b32_e32 v81, 0xffff0000, v81
	v_lshlrev_b32_e32 v90, 16, v82
	v_and_b32_e32 v91, 0xffff0000, v82
	v_lshlrev_b32_e32 v82, 16, v83
	v_and_b32_e32 v83, 0xffff0000, v83
	v_pk_fma_f32 v[78:79], v[78:79], v[62:63], v[80:81]
	v_pk_fma_f32 v[76:77], v[76:77], v[60:61], v[88:89]
	v_pk_fma_f32 v[80:81], v[74:75], v[58:59], v[82:83]
	v_pk_fma_f32 v[74:75], v[72:73], v[56:57], v[90:91]
	v_cvt_pk_bf16_f32 v72, v76, v77
	v_cvt_pk_bf16_f32 v73, v78, v79
	v_cvt_pk_bf16_f32 v74, v74, v75
	v_cvt_pk_bf16_f32 v75, v80, v81
	v_lshl_add_u64 v[76:77], s[42:43], 0, v[84:85]
	global_store_dwordx4 v[76:77], v[72:75], off
	s_waitcnt vmcnt(10)
	s_nop 1
	v_mov_b32_e32 v72, v248
	v_mov_b32_e32 v73, v249
	v_mov_b32_e32 v74, v250
	v_mov_b32_e32 v75, v251
	s_waitcnt lgkmcnt(0)
	v_lshlrev_b32_e32 v78, 16, v72
	v_and_b32_e32 v79, 0xffff0000, v72
	v_lshlrev_b32_e32 v72, 16, v73
	v_and_b32_e32 v73, 0xffff0000, v73
	v_lshlrev_b32_e32 v80, 16, v74
	v_and_b32_e32 v81, 0xffff0000, v74
	v_lshlrev_b32_e32 v74, 16, v75
	v_and_b32_e32 v75, 0xffff0000, v75
	v_pk_fma_f32 v[70:71], v[70:71], v[46:47], v[72:73]
	v_pk_fma_f32 v[68:69], v[68:69], v[44:45], v[78:79]
	v_pk_fma_f32 v[72:73], v[66:67], v[42:43], v[74:75]
	v_pk_fma_f32 v[66:67], v[64:65], v[40:41], v[80:81]
	v_cvt_pk_bf16_f32 v64, v68, v69
	v_cvt_pk_bf16_f32 v65, v70, v71
	v_cvt_pk_bf16_f32 v66, v66, v67
	v_cvt_pk_bf16_f32 v67, v72, v73
	v_lshl_add_u64 v[68:69], v[160:161], 0, s[2:3]
	global_store_dwordx4 v[76:77], v[64:67], off offset:256
	v_lshl_add_u64 v[70:71], s[4:5], 0, v[68:69]
	s_waitcnt vmcnt(10)
	s_nop 1
	v_mov_b32_e32 v64, v252
	v_mov_b32_e32 v65, v253
	v_mov_b32_e32 v66, v254
	v_mov_b32_e32 v67, v255
	s_mov_b64 s[2:3], 0xa0000
	s_waitcnt lgkmcnt(0)
	v_lshlrev_b32_e32 v72, 16, v64
	v_and_b32_e32 v73, 0xffff0000, v64
	v_lshlrev_b32_e32 v64, 16, v65
	v_and_b32_e32 v65, 0xffff0000, v65
	v_lshlrev_b32_e32 v74, 16, v66
	v_and_b32_e32 v75, 0xffff0000, v66
	v_lshlrev_b32_e32 v66, 16, v67
	v_and_b32_e32 v67, 0xffff0000, v67
	v_pk_fma_f32 v[54:55], v[54:55], v[62:63], v[64:65]
	v_pk_fma_f32 v[52:53], v[52:53], v[60:61], v[72:73]
	v_pk_fma_f32 v[64:65], v[50:51], v[58:59], v[66:67]
	v_pk_fma_f32 v[50:51], v[48:49], v[56:57], v[74:75]
	v_cvt_pk_bf16_f32 v48, v52, v53
	v_cvt_pk_bf16_f32 v49, v54, v55
	v_cvt_pk_bf16_f32 v50, v50, v51
	v_cvt_pk_bf16_f32 v51, v64, v65
	v_lshl_add_u64 v[52:53], s[42:43], 0, v[68:69]
	global_store_dwordx4 v[52:53], v[48:51], off
	global_load_dwordx4 v[48:51], v[70:71], off offset:256
	s_waitcnt vmcnt(0) lgkmcnt(0)
; DI unsigned pack2(float a, float b) { f32x2 v = {a, b}; hwbf16x2 r = __builtin_convertvector(v, hwbf16x2); return __builtin_bit_cast(unsigned, r); }
; DI float bflo(unsigned w) { return __uint_as_float(w << 16); }
; DI float bfhi(unsigned w) { return __uint_as_float(w & 0xffff0000u); }
;     DI const char* a(const Unit& u) const { return (const char*)(A + (size_t)u.pm * BM * lda); }
;     DI const char* a(const Unit& u) const { return (const char*)(A + (size_t)u.pm * BM * 2048 + (u.pn >> 1) * 512); }
;     DI void operator()(const f32x4 (&acc)[2][2][4][2], const Unit& u, int wr, int wc, int fr, int fq) const {
;     ...
;         for (int ai = 0; ai < 2; ++ai)
; #pragma unroll
;             for (int m = 0; m < 4; ++m) { const size_t ro = (size_t)(row0 + ai * HALF + m * 16) * D + col0;
; #pragma unroll
;                 for (int bj = 0; bj < 2; ++bj) {
;                     f32x4 x0, x1;
;                     if constexpr (IB) { const u32x4 w = *(const u32x4*)((const bf16_t*)Xin + ro + bj * HALF);
;                         x0 = (f32x4){bflo(w[0]), bfhi(w[0]), bflo(w[1]), bfhi(w[1])}; x1 = (f32x4){bflo(w[2]), bfhi(w[2]), bflo(w[3]), bfhi(w[3])}; }
;                     else { x0 = *(const f32x4*)((const float*)Xin + ro + bj * HALF); x1 = *(const f32x4*)((const float*)Xin + ro + bj * HALF + 4); }
;                     x0 += acc[ai][bj][m][0] * sc[bj][0]; x1 += acc[ai][bj][m][1] * sc[bj][1];
;                     if constexpr (OB) { u32x4 o; o[0] = pack2(x0[0], x0[1]); o[1] = pack2(x0[2], x0[3]); o[2] = pack2(x1[0], x1[1]); o[3] = pack2(x1[2], x1[3]);
;                         *(u32x4*)((bf16_t*)Xout + ro + bj * HALF) = o; }
;                     else { *(f32x4*)((float*)Xout + ro + bj * HALF) = x0; *(f32x4*)((float*)Xout + ro + bj * HALF + 4) = x1; } } }
; template <class Map, class Epi>
; DI void gemm_phase(LAS unsigned char* lds, const Map& MP, const Epi& E, const int nM, const int nN, const int K, const int lda, const int ldb) {
;     ...
;         if (!has_next) break;
; #pragma unroll
;         for (int a = 0; a < 2; ++a)
; #pragma unroll
;             for (int b = 0; b < 2; ++b)
; #pragma unroll
;                 for (int m = 0; m < 4; ++m)
; #pragma unroll
;                     for (int n = 0; n < 2; ++n) acc[a][b][m][n] = (f32x4){0.f, 0.f, 0.f, 0.f};
;         cur = nxt; cA = nA; cB = nB; ++ui;
;     }
;     PG8_WAIT_V(0);
;     if (wr == 0) PG8_BAR;
;     PG8_BAR;
	v_lshlrev_b32_e32 v54, 16, v48
	v_and_b32_e32 v55, 0xffff0000, v48
	v_lshlrev_b32_e32 v48, 16, v49
	v_and_b32_e32 v49, 0xffff0000, v49
	v_lshlrev_b32_e32 v64, 16, v50
	v_and_b32_e32 v65, 0xffff0000, v50
	v_lshlrev_b32_e32 v50, 16, v51
	v_and_b32_e32 v51, 0xffff0000, v51
	v_pk_fma_f32 v[38:39], v[38:39], v[46:47], v[48:49]
	v_pk_fma_f32 v[36:37], v[36:37], v[44:45], v[54:55]
	v_pk_fma_f32 v[48:49], v[34:35], v[42:43], v[50:51]
	v_pk_fma_f32 v[34:35], v[32:33], v[40:41], v[64:65]
	v_cvt_pk_bf16_f32 v32, v36, v37
	v_cvt_pk_bf16_f32 v33, v38, v39
	v_cvt_pk_bf16_f32 v34, v34, v35
	v_cvt_pk_bf16_f32 v35, v48, v49
	v_lshl_add_u64 v[36:37], v[160:161], 0, s[2:3]
	global_store_dwordx4 v[52:53], v[32:35], off offset:256
	v_lshl_add_u64 v[38:39], s[4:5], 0, v[36:37]
	global_load_dwordx4 v[32:35], v[38:39], off
	s_mov_b64 s[2:3], 0xb0000
	s_waitcnt vmcnt(0) lgkmcnt(0)
	v_lshlrev_b32_e32 v48, 16, v32
	v_and_b32_e32 v49, 0xffff0000, v32
	v_lshlrev_b32_e32 v32, 16, v33
	v_and_b32_e32 v33, 0xffff0000, v33
	v_lshlrev_b32_e32 v50, 16, v34
	v_and_b32_e32 v51, 0xffff0000, v34
	v_lshlrev_b32_e32 v34, 16, v35
	v_and_b32_e32 v35, 0xffff0000, v35
	v_pk_fma_f32 v[30:31], v[30:31], v[62:63], v[32:33]
	v_pk_fma_f32 v[28:29], v[28:29], v[60:61], v[48:49]
	v_pk_fma_f32 v[32:33], v[26:27], v[58:59], v[34:35]
	v_pk_fma_f32 v[26:27], v[24:25], v[56:57], v[50:51]
	v_cvt_pk_bf16_f32 v24, v28, v29
	v_cvt_pk_bf16_f32 v25, v30, v31
	v_cvt_pk_bf16_f32 v26, v26, v27
	v_cvt_pk_bf16_f32 v27, v32, v33
	v_lshl_add_u64 v[28:29], s[42:43], 0, v[36:37]
	global_store_dwordx4 v[28:29], v[24:27], off
	global_load_dwordx4 v[24:27], v[38:39], off offset:256
	s_waitcnt vmcnt(0) lgkmcnt(0)
	v_lshlrev_b32_e32 v30, 16, v24
	v_and_b32_e32 v31, 0xffff0000, v24
	v_lshlrev_b32_e32 v24, 16, v25
	v_and_b32_e32 v25, 0xffff0000, v25
	v_lshlrev_b32_e32 v32, 16, v26
	v_and_b32_e32 v33, 0xffff0000, v26
	v_lshlrev_b32_e32 v26, 16, v27
	v_and_b32_e32 v27, 0xffff0000, v27
	v_pk_fma_f32 v[22:23], v[22:23], v[46:47], v[24:25]
	v_pk_fma_f32 v[20:21], v[20:21], v[44:45], v[30:31]
	v_pk_fma_f32 v[24:25], v[18:19], v[42:43], v[26:27]
	v_pk_fma_f32 v[18:19], v[16:17], v[40:41], v[32:33]
	v_cvt_pk_bf16_f32 v16, v20, v21
	v_cvt_pk_bf16_f32 v17, v22, v23
	v_cvt_pk_bf16_f32 v18, v18, v19
	v_cvt_pk_bf16_f32 v19, v24, v25
	v_lshl_add_u64 v[20:21], v[160:161], 0, s[2:3]
	global_store_dwordx4 v[28:29], v[16:19], off offset:256
	v_lshl_add_u64 v[22:23], s[4:5], 0, v[20:21]
	global_load_dwordx4 v[16:19], v[22:23], off
	s_mov_b32 s2, s37
	s_waitcnt vmcnt(0) lgkmcnt(0)
	v_lshlrev_b32_e32 v24, 16, v16
	v_and_b32_e32 v25, 0xffff0000, v16
	v_lshlrev_b32_e32 v16, 16, v17
	v_and_b32_e32 v17, 0xffff0000, v17
	v_lshlrev_b32_e32 v26, 16, v18
	v_and_b32_e32 v27, 0xffff0000, v18
	v_lshlrev_b32_e32 v18, 16, v19
	v_and_b32_e32 v19, 0xffff0000, v19
	v_pk_fma_f32 v[14:15], v[14:15], v[62:63], v[16:17]
	v_pk_fma_f32 v[12:13], v[12:13], v[60:61], v[24:25]
	v_pk_fma_f32 v[16:17], v[10:11], v[58:59], v[18:19]
	v_pk_fma_f32 v[10:11], v[8:9], v[56:57], v[26:27]
	v_cvt_pk_bf16_f32 v8, v12, v13
	v_cvt_pk_bf16_f32 v9, v14, v15
	v_cvt_pk_bf16_f32 v10, v10, v11
	v_cvt_pk_bf16_f32 v11, v16, v17
	v_lshl_add_u64 v[12:13], s[42:43], 0, v[20:21]
	global_store_dwordx4 v[12:13], v[8:11], off
	global_load_dwordx4 v[8:11], v[22:23], off offset:256
	s_waitcnt vmcnt(0) lgkmcnt(0)
	v_lshlrev_b32_e32 v14, 16, v8
	v_and_b32_e32 v15, 0xffff0000, v8
	v_lshlrev_b32_e32 v8, 16, v9
	v_and_b32_e32 v9, 0xffff0000, v9
	v_lshlrev_b32_e32 v16, 16, v10
	v_and_b32_e32 v17, 0xffff0000, v10
	v_lshlrev_b32_e32 v10, 16, v11
	v_and_b32_e32 v11, 0xffff0000, v11
	v_pk_fma_f32 v[6:7], v[6:7], v[46:47], v[8:9]
	v_pk_fma_f32 v[4:5], v[4:5], v[44:45], v[14:15]
	v_pk_fma_f32 v[8:9], v[2:3], v[42:43], v[10:11]
	v_pk_fma_f32 v[2:3], v[0:1], v[40:41], v[16:17]
	v_cvt_pk_bf16_f32 v0, v4, v5
	v_cvt_pk_bf16_f32 v1, v6, v7
	v_cvt_pk_bf16_f32 v2, v2, v3
	v_cvt_pk_bf16_f32 v3, v8, v9
	global_store_dwordx4 v[12:13], v[0:3], off offset:256
	s_cbranch_vccz .LBB1_2336
	s_waitcnt vmcnt(0)
	s_cmpk_gt_u32 s17, 0xff
	s_cbranch_scc1 .LBB1_2343
	s_barrier

; #define PG8_STAGE(bufoff, gbase, voff) do { _Pragma("unroll") for (int _i = 0; _i < 2; ++_i) \
;         __builtin_amdgcn_global_load_lds((const unsigned*)((const char*)(gbase) + (voff)[_i]), (LAS unsigned*)(lds + (bufoff) + ldsw + _i * 8192), 16, 0, 0); } while (0)
; #define PG8_LDA(dst, b, h) do { _Pragma("unroll") for (int m = 0; m < 4; ++m) _Pragma("unroll") for (int k = 0; k < 2; ++k) dst[m][k] = *(const LAS bf16x8*)(lds + PG8_SA(b, h) + aoff + m * 2048 + k * 1024); } while (0)
; #define PG8_LDB(dst, b, h) do { _Pragma("unroll") for (int n = 0; n < 2; ++n) _Pragma("unroll") for (int k = 0; k < 2; ++k) dst[n][k] = *(const LAS bf16x8*)(lds + PG8_SB(b, h) + boff + n * 2048 + k * 1024); } while (0)
; #define PG8_MMA(ai, bj, At, Bt) do { __builtin_amdgcn_s_setprio(1); _Pragma("unroll") for (int m = 0; m < 4; ++m) _Pragma("unroll") for (int n = 0; n < 2; ++n) _Pragma("unroll") for (int k = 0; k < 2; ++k) \
;         acc[ai][bj][m][n] = __builtin_amdgcn_mfma_f32_16x16x32_bf16(Bt[n][k], At[m][k], acc[ai][bj][m][n], 0, 0, 0); __builtin_amdgcn_s_setprio(0); } while (0)
; #define PG8_WAIT_V(n) asm volatile("s_waitcnt vmcnt(" #n ")" ::: "memory")
; #define PG8_WAIT_L(n) asm volatile("s_waitcnt lgkmcnt(" #n ")" ::: "memory")
; template <class Map, class Epi>
; DI void gemm_phase(LAS unsigned char* lds, const Map& MP, const Epi& E, const int nM, const int nN, const int K, const int lda, const int ldb) {
;     ...
;             const bool last = (t == nt - 2);
;             const char* a1 = cA + (size_t)(t + 1) * kstep;
;             const char* a2 = last ? nA : cA + (size_t)(t + 2) * kstep; const char* b2 = last ? nB : cB + (size_t)(t + 2) * kstep;
;             const char* a3 = a2 + kstep; const char* b3 = b2 + kstep;
;             PG8_LDB(B0, 0, 0); PG8_SCHED; PG8_LDA(At, 0, 0); PG8_STAGE(PG8_SA(1, 1), a1 + hstepA, voffA);
;             PG8_WAIT_L(8); PG8_BAR; PG8_WAIT_L(0); PG8_MMA(0, 0, At, B0); PG8_BAR; PG8_SCHED;
;             PG8_LDB(B1, 0, 1); PG8_STAGE(PG8_SB(0, 0), b2, voffB);
;             PG8_BAR; PG8_WAIT_L(0); PG8_MMA(0, 1, At, B1); PG8_BAR;
;             PG8_LDA(At, 0, 1); PG8_STAGE(PG8_SA(0, 0), a2, voffA);
;             PG8_BAR; PG8_WAIT_L(0); PG8_MMA(1, 0, At, B0); PG8_BAR; PG8_SCHED;
;             PG8_STAGE(PG8_SB(0, 1), b2 + hstepB, voffB);
;             PG8_WAIT_V(6); PG8_BAR; PG8_MMA(1, 1, At, B1); PG8_BAR;
.LBB1_2483:
	s_add_u32 s28, s42, 0xfff80080
	s_addc_u32 s29, s43, -1
	s_cmp_eq_u32 s3, 28
	s_cselect_b32 s47, s23, s29
	s_cselect_b32 s46, s58, s28
	s_cselect_b32 s29, s21, vcc_hi
	s_cselect_b32 s28, s59, vcc_lo
	s_add_i32 m0, s38, 0xc000
	ds_read_b128 v[96:99], v190
	ds_read_b128 v[100:103], v190 offset:1024
	ds_read_b128 v[108:111], v190 offset:2048
	ds_read_b128 v[112:115], v190 offset:3072
	ds_read_b128 v[160:163], v190 offset:4096
	ds_read_b128 v[164:167], v190 offset:5120
	ds_read_b128 v[198:201], v190 offset:6144
	ds_read_b128 v[202:205], v190 offset:7168
	global_load_lds_dwordx4 v178, s[42:43]
	s_add_i32 m0, s38, 0xe000
	s_nop 0
	global_load_lds_dwordx4 v176, s[42:43]
	s_waitcnt lgkmcnt(8)
	s_setprio 1
	s_barrier
	s_waitcnt lgkmcnt(7)
	v_mfma_f32_16x16x32_bf16 v[148:151], v[80:83], v[96:99], v[148:151]
	v_mfma_f32_16x16x32_bf16 v[144:147], v[88:91], v[96:99], v[144:147]
	s_waitcnt lgkmcnt(5)
	v_mfma_f32_16x16x32_bf16 v[136:139], v[80:83], v[108:111], v[136:139]
	v_mfma_f32_16x16x32_bf16 v[128:131], v[88:91], v[108:111], v[128:131]
	s_waitcnt lgkmcnt(3)
	v_mfma_f32_16x16x32_bf16 v[120:123], v[80:83], v[160:163], v[120:123]
	v_mfma_f32_16x16x32_bf16 v[104:107], v[88:91], v[160:163], v[104:107]
	s_waitcnt lgkmcnt(1)
	v_mfma_f32_16x16x32_bf16 v[76:79], v[80:83], v[198:201], v[76:79]
	v_mfma_f32_16x16x32_bf16 v[72:75], v[88:91], v[198:201], v[72:75]
	v_mfma_f32_16x16x32_bf16 v[148:151], v[84:87], v[100:103], v[148:151]
	v_mfma_f32_16x16x32_bf16 v[144:147], v[92:95], v[100:103], v[144:147]
	v_mfma_f32_16x16x32_bf16 v[136:139], v[84:87], v[112:115], v[136:139]
	v_mfma_f32_16x16x32_bf16 v[128:131], v[92:95], v[112:115], v[128:131]
	v_mfma_f32_16x16x32_bf16 v[120:123], v[84:87], v[164:167], v[120:123]
	v_mfma_f32_16x16x32_bf16 v[104:107], v[92:95], v[164:167], v[104:107]
	s_waitcnt lgkmcnt(0)
	v_mfma_f32_16x16x32_bf16 v[76:79], v[84:87], v[202:205], v[76:79]
	v_mfma_f32_16x16x32_bf16 v[72:75], v[92:95], v[202:205], v[72:75]
	s_barrier
	s_setprio 0
	s_add_i32 s68, s2, s37
	v_lshl_add_u64 v[184:185], s[28:29], 0, v[172:173]
	s_mov_b32 m0, s68
	ds_read_b128 v[206:209], v191
	ds_read_b128 v[210:213], v191 offset:1024
	ds_read_b128 v[214:217], v191 offset:2048
	ds_read_b128 v[218:221], v191 offset:3072
	global_load_lds_dwordx4 v[184:185], off
	v_lshl_add_u64 v[194:195], s[28:29], 0, v[168:169]
	s_add_i32 m0, s68, 0x2000
	s_nop 0
	global_load_lds_dwordx4 v[194:195], off
	s_setprio 1
	s_barrier
	s_waitcnt lgkmcnt(3)
	v_mfma_f32_16x16x32_bf16 v[156:159], v[206:209], v[96:99], v[156:159]
	s_waitcnt lgkmcnt(1)
	v_mfma_f32_16x16x32_bf16 v[96:99], v[214:217], v[96:99], v[152:155]
	v_mfma_f32_16x16x32_bf16 v[156:159], v[210:213], v[100:103], v[156:159]
	s_waitcnt lgkmcnt(0)
	v_mfma_f32_16x16x32_bf16 v[96:99], v[218:221], v[100:103], v[96:99]
	v_mfma_f32_16x16x32_bf16 v[100:103], v[206:209], v[108:111], v[140:143]
	v_mfma_f32_16x16x32_bf16 v[108:111], v[214:217], v[108:111], v[132:135]
	v_mfma_f32_16x16x32_bf16 v[116:119], v[214:217], v[160:163], v[116:119]
	v_mfma_f32_16x16x32_bf16 v[68:71], v[206:209], v[198:201], v[68:71]
	v_mfma_f32_16x16x32_bf16 v[64:67], v[214:217], v[198:201], v[64:67]
	s_mov_b32 m0, s38
	v_mfma_f32_16x16x32_bf16 v[100:103], v[210:213], v[112:115], v[100:103]
	v_lshl_add_u64 v[230:231], s[46:47], 0, v[174:175]
	v_mfma_f32_16x16x32_bf16 v[108:111], v[218:221], v[112:115], v[108:111]
	v_mfma_f32_16x16x32_bf16 v[112:115], v[206:209], v[160:163], v[124:127]
	v_mfma_f32_16x16x32_bf16 v[116:119], v[218:221], v[164:167], v[116:119]
	v_mfma_f32_16x16x32_bf16 v[68:71], v[210:213], v[202:205], v[68:71]
	v_mfma_f32_16x16x32_bf16 v[64:67], v[218:221], v[202:205], v[64:67]
	v_mfma_f32_16x16x32_bf16 v[112:115], v[210:213], v[164:167], v[112:115]
	s_barrier
	s_setprio 0
	ds_read_b128 v[124:127], v190 offset:16384
	ds_read_b128 v[132:135], v190 offset:17408
	ds_read_b128 v[140:143], v190 offset:18432
	ds_read_b128 v[152:155], v190 offset:19456
	ds_read_b128 v[160:163], v190 offset:20480
	ds_read_b128 v[164:167], v190 offset:21504
	ds_read_b128 v[198:201], v190 offset:22528
	ds_read_b128 v[202:205], v190 offset:23552
	global_load_lds_dwordx4 v[230:231], off
	v_lshl_add_u64 v[232:233], s[46:47], 0, v[170:171]
	s_mov_b32 m0, s39
	s_nop 0
	global_load_lds_dwordx4 v[232:233], off
	s_waitcnt vmcnt(10)
	s_setprio 1
	s_barrier
	s_waitcnt lgkmcnt(7)
	v_mfma_f32_16x16x32_bf16 v[60:63], v[80:83], v[124:127], v[60:63]
	v_mfma_f32_16x16x32_bf16 v[48:51], v[88:91], v[124:127], v[48:51]
	s_waitcnt lgkmcnt(5)
	v_mfma_f32_16x16x32_bf16 v[40:43], v[80:83], v[140:143], v[40:43]
	v_mfma_f32_16x16x32_bf16 v[32:35], v[88:91], v[140:143], v[32:35]
	s_waitcnt lgkmcnt(3)
	v_mfma_f32_16x16x32_bf16 v[24:27], v[80:83], v[160:163], v[24:27]
	v_mfma_f32_16x16x32_bf16 v[16:19], v[88:91], v[160:163], v[16:19]
	s_waitcnt lgkmcnt(1)
	v_mfma_f32_16x16x32_bf16 v[12:15], v[80:83], v[198:201], v[12:15]
	v_mfma_f32_16x16x32_bf16 v[8:11], v[88:91], v[198:201], v[8:11]
	v_mfma_f32_16x16x32_bf16 v[60:63], v[84:87], v[132:135], v[60:63]
	v_mfma_f32_16x16x32_bf16 v[48:51], v[92:95], v[132:135], v[48:51]
	v_mfma_f32_16x16x32_bf16 v[40:43], v[84:87], v[152:155], v[40:43]
	v_mfma_f32_16x16x32_bf16 v[32:35], v[92:95], v[152:155], v[32:35]
	v_mfma_f32_16x16x32_bf16 v[24:27], v[84:87], v[164:167], v[24:27]
	v_mfma_f32_16x16x32_bf16 v[16:19], v[92:95], v[164:167], v[16:19]
	s_waitcnt lgkmcnt(0)
	v_mfma_f32_16x16x32_bf16 v[12:15], v[84:87], v[202:205], v[12:15]
	v_mfma_f32_16x16x32_bf16 v[8:11], v[92:95], v[202:205], v[8:11]
	s_barrier
	s_setprio 0
	s_add_u32 s68, s28, 0x80000
	s_addc_u32 s69, s29, 0
	s_add_i32 s70, s67, s37
	s_mov_b32 m0, s70
	s_nop 0
	global_load_lds_dwordx4 v172, s[68:69]
	s_add_i32 m0, s70, 0x2000
	s_nop 0
	global_load_lds_dwordx4 v168, s[68:69]
	s_waitcnt vmcnt(6)
	s_setprio 1
	s_barrier
; #define PG8_STAGE(bufoff, gbase, voff) do { _Pragma("unroll") for (int _i = 0; _i < 2; ++_i) \
;         __builtin_amdgcn_global_load_lds((const unsigned*)((const char*)(gbase) + (voff)[_i]), (LAS unsigned*)(lds + (bufoff) + ldsw + _i * 8192), 16, 0, 0); } while (0)
; #define PG8_LDA(dst, b, h) do { _Pragma("unroll") for (int m = 0; m < 4; ++m) _Pragma("unroll") for (int k = 0; k < 2; ++k) dst[m][k] = *(const LAS bf16x8*)(lds + PG8_SA(b, h) + aoff + m * 2048 + k * 1024); } while (0)
; #define PG8_LDB(dst, b, h) do { _Pragma("unroll") for (int n = 0; n < 2; ++n) _Pragma("unroll") for (int k = 0; k < 2; ++k) dst[n][k] = *(const LAS bf16x8*)(lds + PG8_SB(b, h) + boff + n * 2048 + k * 1024); } while (0)
; #define PG8_MMA(ai, bj, At, Bt) do { __builtin_amdgcn_s_setprio(1); _Pragma("unroll") for (int m = 0; m < 4; ++m) _Pragma("unroll") for (int n = 0; n < 2; ++n) _Pragma("unroll") for (int k = 0; k < 2; ++k) \
;         acc[ai][bj][m][n] = __builtin_amdgcn_mfma_f32_16x16x32_bf16(Bt[n][k], At[m][k], acc[ai][bj][m][n], 0, 0, 0); __builtin_amdgcn_s_setprio(0); } while (0)
; #define PG8_WAIT_V(n) asm volatile("s_waitcnt vmcnt(" #n ")" ::: "memory")
; #define PG8_WAIT_L(n) asm volatile("s_waitcnt lgkmcnt(" #n ")" ::: "memory")
; #define PG8_BAR __builtin_amdgcn_s_barrier()
; #define PG8_SCHED __builtin_amdgcn_sched_barrier(0)
; template <class Map, class Epi>
; DI void gemm_phase(LAS unsigned char* lds, const Map& MP, const Epi& E, const int nM, const int nN, const int K, const int lda, const int ldb) {
;     ...
;             PG8_BAR; PG8_WAIT_L(0); PG8_MMA(1, 0, At, B0); PG8_BAR; PG8_SCHED;
;             PG8_STAGE(PG8_SB(0, 1), b2 + hstepB, voffB);
;             PG8_WAIT_V(6); PG8_BAR; PG8_MMA(1, 1, At, B1); PG8_BAR;
;             PG8_LDB(B0, 1, 0); PG8_SCHED; PG8_LDA(At, 1, 0); PG8_STAGE(PG8_SA(0, 1), a2 + hstepA, voffA);
;             PG8_WAIT_L(8); PG8_BAR; PG8_WAIT_L(0); PG8_MMA(0, 0, At, B0); PG8_BAR; PG8_SCHED;
;             PG8_LDB(B1, 1, 1); PG8_STAGE(PG8_SB(1, 0), b3, voffB);
;             PG8_BAR; PG8_WAIT_L(0); PG8_MMA(0, 1, At, B1); PG8_BAR;
;             PG8_LDA(At, 1, 1); PG8_STAGE(PG8_SA(1, 0), a3, voffA);
;             PG8_BAR; PG8_WAIT_L(0); PG8_MMA(1, 0, At, B0); PG8_BAR; PG8_SCHED;
	v_mfma_f32_16x16x32_bf16 v[56:59], v[206:209], v[124:127], v[56:59]
	v_mfma_f32_16x16x32_bf16 v[52:55], v[214:217], v[124:127], v[52:55]
	s_add_i32 s68, 0, 0x18000
	v_add_u32_e32 v92, s68, v188
	ds_read_b128 v[80:83], v92
	v_mfma_f32_16x16x32_bf16 v[44:47], v[206:209], v[140:143], v[44:47]
	v_mfma_f32_16x16x32_bf16 v[36:39], v[214:217], v[140:143], v[36:39]
	ds_read_b128 v[84:87], v92 offset:1024
	v_mfma_f32_16x16x32_bf16 v[28:31], v[206:209], v[160:163], v[28:31]
	v_mfma_f32_16x16x32_bf16 v[20:23], v[214:217], v[160:163], v[20:23]
	ds_read_b128 v[88:91], v92 offset:2048
	v_mfma_f32_16x16x32_bf16 v[4:7], v[206:209], v[198:201], v[4:7]
	v_mfma_f32_16x16x32_bf16 v[0:3], v[214:217], v[198:201], v[0:3]
	ds_read_b128 v[92:95], v92 offset:3072
	v_mfma_f32_16x16x32_bf16 v[56:59], v[210:213], v[132:135], v[56:59]
	v_mfma_f32_16x16x32_bf16 v[52:55], v[218:221], v[132:135], v[52:55]
	v_mfma_f32_16x16x32_bf16 v[44:47], v[210:213], v[152:155], v[44:47]
	v_mfma_f32_16x16x32_bf16 v[36:39], v[218:221], v[152:155], v[36:39]
	v_mfma_f32_16x16x32_bf16 v[28:31], v[210:213], v[164:167], v[28:31]
	v_mfma_f32_16x16x32_bf16 v[20:23], v[218:221], v[164:167], v[20:23]
	v_mfma_f32_16x16x32_bf16 v[4:7], v[210:213], v[202:205], v[4:7]
	v_mfma_f32_16x16x32_bf16 v[0:3], v[218:221], v[202:205], v[0:3]
	s_barrier
	s_setprio 0
	s_add_u32 s46, s46, 0x80000
	s_addc_u32 s47, s47, 0
	s_mov_b32 m0, s55
	ds_read_b128 v[124:127], v190 offset:32768
	ds_read_b128 v[132:135], v190 offset:33792
	ds_read_b128 v[160:163], v190 offset:34816
	ds_read_b128 v[164:167], v190 offset:35840
	ds_read_b128 v[198:201], v190 offset:36864
	ds_read_b128 v[202:205], v190 offset:37888
	ds_read_b128 v[206:209], v190 offset:38912
	ds_read_b128 v[210:213], v190 offset:39936
	global_load_lds_dwordx4 v174, s[46:47]
	s_mov_b32 m0, s56
	s_nop 0
	global_load_lds_dwordx4 v170, s[46:47]
	s_waitcnt lgkmcnt(8)
	s_setprio 1
	s_barrier
	s_waitcnt lgkmcnt(7)
	v_mfma_f32_16x16x32_bf16 v[140:143], v[80:83], v[124:127], v[148:151]
	s_waitcnt lgkmcnt(6)
	v_mfma_f32_16x16x32_bf16 v[148:151], v[84:87], v[132:135], v[140:143]
	v_mfma_f32_16x16x32_bf16 v[140:143], v[88:91], v[124:127], v[144:147]
	s_waitcnt lgkmcnt(5)
	v_mfma_f32_16x16x32_bf16 v[136:139], v[80:83], v[160:163], v[136:139]
	v_mfma_f32_16x16x32_bf16 v[128:131], v[88:91], v[160:163], v[128:131]
	s_waitcnt lgkmcnt(3)
	v_mfma_f32_16x16x32_bf16 v[120:123], v[80:83], v[198:201], v[120:123]
	v_mfma_f32_16x16x32_bf16 v[104:107], v[88:91], v[198:201], v[104:107]
	s_waitcnt lgkmcnt(1)
	v_mfma_f32_16x16x32_bf16 v[76:79], v[80:83], v[206:209], v[76:79]
	v_mfma_f32_16x16x32_bf16 v[72:75], v[88:91], v[206:209], v[72:75]
	v_mfma_f32_16x16x32_bf16 v[144:147], v[92:95], v[132:135], v[140:143]
	v_mfma_f32_16x16x32_bf16 v[136:139], v[84:87], v[164:167], v[136:139]
	v_mfma_f32_16x16x32_bf16 v[128:131], v[92:95], v[164:167], v[128:131]
	v_mfma_f32_16x16x32_bf16 v[120:123], v[84:87], v[202:205], v[120:123]
	v_mfma_f32_16x16x32_bf16 v[104:107], v[92:95], v[202:205], v[104:107]
	s_waitcnt lgkmcnt(0)
	v_mfma_f32_16x16x32_bf16 v[76:79], v[84:87], v[210:213], v[76:79]
	v_mfma_f32_16x16x32_bf16 v[72:75], v[92:95], v[210:213], v[72:75]
	s_barrier
	s_setprio 0
	s_add_i32 s46, 0, 0x1c000
	v_add_u32_e32 v140, s46, v188
	s_add_i32 s47, s68, s37
	ds_read_b128 v[214:217], v140
	ds_read_b128 v[218:221], v140 offset:1024
	ds_read_b128 v[222:225], v140 offset:2048
	ds_read_b128 v[226:229], v140 offset:3072
	v_lshl_add_u64 v[140:141], v[184:185], 0, s[14:15]
	s_mov_b32 m0, s47
	s_nop 0
	global_load_lds_dwordx4 v[140:141], off
	v_lshl_add_u64 v[140:141], v[194:195], 0, s[14:15]
	s_add_i32 m0, s47, 0x2000
	s_nop 0
	global_load_lds_dwordx4 v[140:141], off
	s_setprio 1
	s_barrier
	s_waitcnt lgkmcnt(1)
	v_mfma_f32_16x16x32_bf16 v[96:99], v[222:225], v[124:127], v[96:99]
	v_mfma_f32_16x16x32_bf16 v[140:143], v[214:217], v[124:127], v[156:159]
	s_waitcnt lgkmcnt(0)
	v_mfma_f32_16x16x32_bf16 v[152:155], v[226:229], v[132:135], v[96:99]
	v_mfma_f32_16x16x32_bf16 v[96:99], v[214:217], v[160:163], v[100:103]
	v_mfma_f32_16x16x32_bf16 v[156:159], v[218:221], v[132:135], v[140:143]
	v_mfma_f32_16x16x32_bf16 v[140:143], v[218:221], v[164:167], v[96:99]
	v_mfma_f32_16x16x32_bf16 v[96:99], v[222:225], v[160:163], v[108:111]
	v_mfma_f32_16x16x32_bf16 v[132:135], v[226:229], v[164:167], v[96:99]
	v_mfma_f32_16x16x32_bf16 v[96:99], v[214:217], v[198:201], v[112:115]
	s_mov_b32 m0, s62
	v_mfma_f32_16x16x32_bf16 v[124:127], v[218:221], v[202:205], v[96:99]
	v_lshl_add_u64 v[184:185], v[230:231], 0, s[14:15]
	v_mfma_f32_16x16x32_bf16 v[96:99], v[222:225], v[198:201], v[116:119]
	v_mfma_f32_16x16x32_bf16 v[68:71], v[214:217], v[206:209], v[68:71]
	v_mfma_f32_16x16x32_bf16 v[64:67], v[222:225], v[206:209], v[64:67]
	v_mfma_f32_16x16x32_bf16 v[116:119], v[226:229], v[202:205], v[96:99]
	v_mfma_f32_16x16x32_bf16 v[68:71], v[218:221], v[210:213], v[68:71]
	v_mfma_f32_16x16x32_bf16 v[64:67], v[226:229], v[210:213], v[64:67]
	s_barrier
	s_setprio 0
	ds_read_b128 v[96:99], v190 offset:49152
	ds_read_b128 v[100:103], v190 offset:50176
	ds_read_b128 v[108:111], v190 offset:51200
	ds_read_b128 v[112:115], v190 offset:52224
	ds_read_b128 v[160:163], v190 offset:53248
	ds_read_b128 v[164:167], v190 offset:54272
	ds_read_b128 v[198:201], v190 offset:55296
	ds_read_b128 v[202:205], v190 offset:56320
	global_load_lds_dwordx4 v[184:185], off
	v_lshl_add_u64 v[184:185], v[232:233], 0, s[14:15]
	s_mov_b32 m0, s63
	s_nop 0
	global_load_lds_dwordx4 v[184:185], off
	s_waitcnt vmcnt(10)
	s_setprio 1
	s_barrier
; #define PG8_STAGE(bufoff, gbase, voff) do { _Pragma("unroll") for (int _i = 0; _i < 2; ++_i) \
;         __builtin_amdgcn_global_load_lds((const unsigned*)((const char*)(gbase) + (voff)[_i]), (LAS unsigned*)(lds + (bufoff) + ldsw + _i * 8192), 16, 0, 0); } while (0)
; #define PG8_LDA(dst, b, h) do { _Pragma("unroll") for (int m = 0; m < 4; ++m) _Pragma("unroll") for (int k = 0; k < 2; ++k) dst[m][k] = *(const LAS bf16x8*)(lds + PG8_SA(b, h) + aoff + m * 2048 + k * 1024); } while (0)
; #define PG8_MMA(ai, bj, At, Bt) do { __builtin_amdgcn_s_setprio(1); _Pragma("unroll") for (int m = 0; m < 4; ++m) _Pragma("unroll") for (int n = 0; n < 2; ++n) _Pragma("unroll") for (int k = 0; k < 2; ++k) \
;         acc[ai][bj][m][n] = __builtin_amdgcn_mfma_f32_16x16x32_bf16(Bt[n][k], At[m][k], acc[ai][bj][m][n], 0, 0, 0); __builtin_amdgcn_s_setprio(0); } while (0)
; #define PG8_WAIT_V(n) asm volatile("s_waitcnt vmcnt(" #n ")" ::: "memory")
; #define PG8_WAIT_L(n) asm volatile("s_waitcnt lgkmcnt(" #n ")" ::: "memory")
; #define PG8_BAR __builtin_amdgcn_s_barrier()
; #define PG8_SCHED __builtin_amdgcn_sched_barrier(0)
; template <class Map, class Epi>
; DI void gemm_phase(LAS unsigned char* lds, const Map& MP, const Epi& E, const int nM, const int nN, const int K, const int lda, const int ldb) {
;     ...
;             PG8_LDA(At, 1, 1); PG8_STAGE(PG8_SA(1, 0), a3, voffA);
;             PG8_BAR; PG8_WAIT_L(0); PG8_MMA(1, 0, At, B0); PG8_BAR; PG8_SCHED;
;             PG8_STAGE(PG8_SB(1, 1), b3 + hstepB, voffB);
;             PG8_WAIT_V(6); PG8_BAR; PG8_MMA(1, 1, At, B1); PG8_BAR;
	s_waitcnt lgkmcnt(7)
	v_mfma_f32_16x16x32_bf16 v[60:63], v[80:83], v[96:99], v[60:63]
	v_mfma_f32_16x16x32_bf16 v[48:51], v[88:91], v[96:99], v[48:51]
	s_waitcnt lgkmcnt(5)
	v_mfma_f32_16x16x32_bf16 v[40:43], v[80:83], v[108:111], v[40:43]
	v_mfma_f32_16x16x32_bf16 v[32:35], v[88:91], v[108:111], v[32:35]
	s_waitcnt lgkmcnt(3)
	v_mfma_f32_16x16x32_bf16 v[24:27], v[80:83], v[160:163], v[24:27]
	v_mfma_f32_16x16x32_bf16 v[16:19], v[88:91], v[160:163], v[16:19]
	s_waitcnt lgkmcnt(1)
	v_mfma_f32_16x16x32_bf16 v[12:15], v[80:83], v[198:201], v[12:15]
	v_mfma_f32_16x16x32_bf16 v[8:11], v[88:91], v[198:201], v[8:11]
	v_mfma_f32_16x16x32_bf16 v[60:63], v[84:87], v[100:103], v[60:63]
	v_mfma_f32_16x16x32_bf16 v[48:51], v[92:95], v[100:103], v[48:51]
	v_mfma_f32_16x16x32_bf16 v[40:43], v[84:87], v[112:115], v[40:43]
	v_mfma_f32_16x16x32_bf16 v[32:35], v[92:95], v[112:115], v[32:35]
	v_mfma_f32_16x16x32_bf16 v[24:27], v[84:87], v[164:167], v[24:27]
	v_mfma_f32_16x16x32_bf16 v[16:19], v[92:95], v[164:167], v[16:19]
	s_waitcnt lgkmcnt(0)
	v_mfma_f32_16x16x32_bf16 v[12:15], v[84:87], v[202:205], v[12:15]
	v_mfma_f32_16x16x32_bf16 v[8:11], v[92:95], v[202:205], v[8:11]
	s_barrier
	s_setprio 0
	s_add_u32 s28, s28, 0x80080
	s_addc_u32 s29, s29, 0
	s_add_i32 s46, s46, s37
	s_mov_b32 m0, s46
	s_nop 0
	global_load_lds_dwordx4 v172, s[28:29]
	s_add_i32 m0, s46, 0x2000
	s_nop 0
	global_load_lds_dwordx4 v168, s[28:29]
	s_waitcnt vmcnt(6)
	s_setprio 1
	s_barrier
	v_mfma_f32_16x16x32_bf16 v[56:59], v[214:217], v[96:99], v[56:59]
	v_mfma_f32_16x16x32_bf16 v[52:55], v[222:225], v[96:99], v[52:55]
	ds_read_b128 v[80:83], v189
	v_mfma_f32_16x16x32_bf16 v[44:47], v[214:217], v[108:111], v[44:47]
	v_mfma_f32_16x16x32_bf16 v[36:39], v[222:225], v[108:111], v[36:39]
	ds_read_b128 v[84:87], v189 offset:1024
	v_mfma_f32_16x16x32_bf16 v[28:31], v[214:217], v[160:163], v[28:31]
	v_mfma_f32_16x16x32_bf16 v[20:23], v[222:225], v[160:163], v[20:23]
	ds_read_b128 v[88:91], v189 offset:2048
	v_mfma_f32_16x16x32_bf16 v[4:7], v[214:217], v[198:201], v[4:7]
	v_mfma_f32_16x16x32_bf16 v[0:3], v[222:225], v[198:201], v[0:3]
	ds_read_b128 v[92:95], v189 offset:3072
	v_mfma_f32_16x16x32_bf16 v[56:59], v[218:221], v[100:103], v[56:59]
	s_add_i32 s3, s3, 2
	v_mfma_f32_16x16x32_bf16 v[52:55], v[226:229], v[100:103], v[52:55]
	s_add_u32 vcc_lo, vcc_lo, 0x100
	s_addc_u32 vcc_hi, vcc_hi, 0
	v_mfma_f32_16x16x32_bf16 v[44:47], v[218:221], v[112:115], v[44:47]
	s_add_u32 s42, s42, 0x100
	s_addc_u32 s43, s43, 0
	v_mfma_f32_16x16x32_bf16 v[36:39], v[226:229], v[112:115], v[36:39]
	s_cmp_gt_u32 s3, 29
	v_mfma_f32_16x16x32_bf16 v[28:31], v[218:221], v[164:167], v[28:31]
	v_mfma_f32_16x16x32_bf16 v[20:23], v[226:229], v[164:167], v[20:23]
	v_mfma_f32_16x16x32_bf16 v[4:7], v[218:221], v[202:205], v[4:7]
	v_mfma_f32_16x16x32_bf16 v[0:3], v[226:229], v[202:205], v[0:3]
	s_barrier
	s_setprio 0
	s_cbranch_scc0 .LBB1_2483
; DI float silu_mul(float g, float v) { return g * v * __builtin_amdgcn_rcpf(1.0f + __builtin_amdgcn_exp2f(-LOG2E * g)); }
;     DI void operator()(const f32x4 (&acc)[2][2][4][2], const Unit& u, int wr, int wc, int fr, int fq) const {
;         const int row0 = u.pm * BM + wr * 64 + fr, ch0 = u.pn * 128 + wc * 32 + 8 * fq;
;         f32x4 w0[2], w1[2], w2[2], bb[2];
; #pragma unroll
;         for (int n = 0; n < 2; ++n) { w0[n] = *(const f32x4*)(cw + ch0 + 4 * n); w1[n] = *(const f32x4*)(cw + DFF + ch0 + 4 * n); w2[n] = *(const f32x4*)(cw + 2 * DFF + ch0 + 4 * n); bb[n] = *(const f32x4*)(cb + ch0 + 4 * n); }
; #pragma unroll
;         for (int ai = 0; ai < 2; ++ai)
; #pragma unroll
;             for (int m = 0; m < 4; ++m) {
;                 const bool efirst = (m == 0) && (fr == 0), elast = (m == 3) && (fr == 15);
;                 const int row = row0 + ai * HALF + m * 16;
;                 f32x4 gc[2];
; #pragma unroll
;                 for (int n = 0; n < 2; ++n) {
;                     const f32x4 g = acc[ai][0][m][n];
;                     const f32x4 gprev = acc[ai][0][m > 0 ? m - 1 : 0][n], gnext = acc[ai][0][m < 3 ? m + 1 : 3][n];
;                     f32x4 up, dn;
; #pragma unroll
;                     for (int e = 0; e < 4; ++e) {
;                         const float pu = (m > 0 && fr == 15) ? gprev[e] : g[e];
;                         const float pd = (m < 3 && fr == 0) ? gnext[e] : g[e];
;                         up[e] = dpp_ror1(pu); dn[e] = dpp_ror15(pd);
;                     }
;                     if (efirst) up = (f32x4){0.f, 0.f, 0.f, 0.f};
;                     if (elast) dn = (f32x4){0.f, 0.f, 0.f, 0.f};
;                     gc[n] = w0[n] * up + w1[n] * g + w2[n] * dn + bb[n];
;                 }
;                 if (efirst || elast) {
;                     const size_t eo = (size_t)((row >> 6) * 2 + (elast ? 1 : 0)) * DFF + ch0;
; #pragma unroll
;                     for (int n = 0; n < 2; ++n) { *(f32x4*)(EP + eo + 4 * n) = gc[n]; *(f32x4*)(ER + eo + 4 * n) = acc[ai][0][m][n]; *(f32x4*)(EV + eo + 4 * n) = acc[ai][1][m][n]; }
;                 } else {
;                     const f32x4 v0 = acc[ai][1][m][0], v1 = acc[ai][1][m][1];
;                     u32x4 o;
;                     o[0] = pack2(silu_mul(gc[0][0], v0[0]), silu_mul(gc[0][1], v0[1])); o[1] = pack2(silu_mul(gc[0][2], v0[2]), silu_mul(gc[0][3], v0[3]));
	s_waitcnt lgkmcnt(0)
	s_lshl_b32 s21, s45, 7
	v_mov_b32_e32 v80, v187
	v_mov_b32_e32 v194, v186
	s_or_b32 s21, s21, s57
	v_mov_b32_e32 v160, 0
	v_lshl_add_u32 v184, v80, 3, s21
	v_ashrrev_i32_e32 v185, 31, v184
	v_lshlrev_b64 v[80:81], 2, v[184:185]
	v_lshl_add_u64 v[84:85], s[4:5], 0, v[80:81]
	v_lshl_add_u64 v[88:89], s[16:17], 0, v[80:81]
	v_lshl_add_u64 v[92:93], s[18:19], 0, v[80:81]
	v_lshl_add_u64 v[112:113], s[6:7], 0, v[80:81]
	global_load_dwordx4 v[80:83], v[84:85], off offset:16
	global_load_dwordx4 v[96:99], v[84:85], off
	s_nop 0
	global_load_dwordx4 v[84:87], v[88:89], off offset:16
	global_load_dwordx4 v[100:103], v[88:89], off
	s_nop 0
	global_load_dwordx4 v[88:91], v[92:93], off offset:16
	global_load_dwordx4 v[108:111], v[92:93], off
	s_nop 0
	global_load_dwordx4 v[92:95], v[112:113], off offset:16
	s_nop 0
	global_load_dwordx4 v[112:115], v[112:113], off
	v_cmp_eq_u32_e32 vcc, 0, v194
	v_mov_b32_e32 v164, 0
	v_mov_b32_e32 v195, 0
	v_cndmask_b32_e32 v161, v148, v136, vcc
	v_cndmask_b32_e32 v162, v149, v137, vcc
	v_cndmask_b32_e32 v163, v150, v138, vcc
	v_mov_b32_dpp v160, v161 row_ror:15 row_mask:0xf bank_mask:0xf
	v_mov_b32_e32 v161, 0
	v_mov_b32_e32 v166, 0
	v_mov_b32_e32 v167, 0
	v_mov_b32_dpp v161, v162 row_ror:15 row_mask:0xf bank_mask:0xf
	v_mov_b32_e32 v162, 0
	v_mov_b32_dpp v164, v150 row_ror:1 row_mask:0xf bank_mask:0xf
	v_cndmask_b32_e32 v165, v151, v139, vcc
	v_mov_b32_dpp v162, v163 row_ror:15 row_mask:0xf bank_mask:0xf
	v_mov_b32_dpp v195, v151 row_ror:1 row_mask:0xf bank_mask:0xf
	v_mov_b32_e32 v163, 0
	v_mov_b32_dpp v166, v148 row_ror:1 row_mask:0xf bank_mask:0xf
	v_mov_b32_dpp v167, v149 row_ror:1 row_mask:0xf bank_mask:0xf
	v_mov_b32_dpp v163, v165 row_ror:15 row_mask:0xf bank_mask:0xf
	v_cndmask_b32_e64 v165, v195, 0, vcc
	v_cndmask_b32_e64 v164, v164, 0, vcc
	v_cndmask_b32_e64 v167, v167, 0, vcc
	v_cndmask_b32_e64 v166, v166, 0, vcc
	v_mov_b32_e32 v195, 0
	v_mov_b32_e32 v196, 0
	v_mov_b32_e32 v198, 0
	v_mov_b32_e32 v200, 0
	v_mov_b32_dpp v195, v144 row_ror:1 row_mask:0xf bank_mask:0xf
	v_mov_b32_dpp v196, v145 row_ror:1 row_mask:0xf bank_mask:0xf
	v_mov_b32_dpp v198, v146 row_ror:1 row_mask:0xf bank_mask:0xf
	v_cndmask_b32_e32 v199, v147, v131, vcc
	v_mov_b32_dpp v200, v147 row_ror:1 row_mask:0xf bank_mask:0xf
	v_cndmask_b32_e64 v198, v198, 0, vcc
	v_cndmask_b32_e64 v201, v196, 0, vcc
	s_lshl_b32 s3, s44, 8
	s_add_i32 s3, s3, s49
	v_add_u32_e32 v193, s3, v194
	v_cmp_ne_u32_e64 s[46:47], 0, v194
	s_waitcnt vmcnt(0)
	v_pk_mul_f32 v[164:165], v[98:99], v[164:165]
	v_pk_mul_f32 v[166:167], v[96:97], v[166:167]
	v_pk_fma_f32 v[164:165], v[150:151], v[102:103], v[164:165]
	v_pk_fma_f32 v[166:167], v[148:149], v[100:101], v[166:167]
	v_pk_fma_f32 v[162:163], v[110:111], v[162:163], v[164:165]
	v_cndmask_b32_e32 v165, v144, v128, vcc
	v_mov_b32_e32 v164, 0
	v_pk_fma_f32 v[160:161], v[108:109], v[160:161], v[166:167]
	v_cndmask_b32_e32 v166, v145, v129, vcc
	v_mov_b32_dpp v164, v165 row_ror:15 row_mask:0xf bank_mask:0xf
	v_mov_b32_e32 v165, 0
	v_cndmask_b32_e32 v167, v146, v130, vcc
	v_pk_add_f32 v[162:163], v[114:115], v[162:163]
	v_mov_b32_dpp v165, v166 row_ror:15 row_mask:0xf bank_mask:0xf
	v_mov_b32_e32 v166, 0
	v_pk_add_f32 v[160:161], v[112:113], v[160:161]
	s_nop 0
	v_mov_b32_dpp v166, v167 row_ror:15 row_mask:0xf bank_mask:0xf
	v_mov_b32_e32 v167, 0
	s_nop 1
	v_mov_b32_dpp v167, v199 row_ror:15 row_mask:0xf bank_mask:0xf
	v_cndmask_b32_e64 v199, v200, 0, vcc
	v_cndmask_b32_e64 v200, v195, 0, vcc
	v_pk_mul_f32 v[200:201], v[80:81], v[200:201]
	v_pk_mul_f32 v[198:199], v[82:83], v[198:199]
	v_pk_fma_f32 v[200:201], v[144:145], v[84:85], v[200:201]
	v_pk_fma_f32 v[198:199], v[146:147], v[86:87], v[198:199]
	v_pk_fma_f32 v[164:165], v[88:89], v[164:165], v[200:201]
	v_pk_fma_f32 v[166:167], v[90:91], v[166:167], v[198:199]
	v_pk_add_f32 v[164:165], v[92:93], v[164:165]
	v_pk_add_f32 v[166:167], v[94:95], v[166:167]
	s_and_saveexec_b64 s[28:29], s[46:47]
	s_xor_b64 s[28:29], exec, s[28:29]
	s_cbranch_execz .LBB1_2486
	v_mul_f32_e32 v195, 0xbfb8aa3b, v160
	v_exp_f32_e32 v195, v195
	v_mul_f32_e32 v196, 0xbfb8aa3b, v161
	v_exp_f32_e32 v196, v196
	v_pk_mul_f32 v[160:161], v[156:157], v[160:161]
	v_add_f32_e32 v195, 1.0, v195
	v_rcp_f32_e32 v198, v195
	v_add_f32_e32 v196, 1.0, v196
	v_mul_f32_e32 v195, 0xbfb8aa3b, v162
	v_rcp_f32_e32 v199, v196
	v_exp_f32_e32 v195, v195
	v_mul_f32_e32 v196, 0xbfb8aa3b, v163
	v_exp_f32_e32 v196, v196
	v_pk_mul_f32 v[160:161], v[160:161], v[198:199]
	v_add_f32_e32 v195, 1.0, v195
	v_rcp_f32_e32 v200, v195
	v_add_f32_e32 v195, 1.0, v196
	v_rcp_f32_e32 v201, v195
	v_cvt_pk_bf16_f32 v160, v160, v161
	v_mul_f32_e32 v161, 0xbfb8aa3b, v164
	v_exp_f32_e32 v195, v161
	v_mul_f32_e32 v161, 0xbfb8aa3b, v165
	v_exp_f32_e32 v196, v161
	v_pk_mul_f32 v[162:163], v[158:159], v[162:163]
	v_pk_mul_f32 v[164:165], v[152:153], v[164:165]
	v_pk_mul_f32 v[162:163], v[162:163], v[200:201]
	s_nop 0
	v_cvt_pk_bf16_f32 v161, v162, v163
	v_add_f32_e32 v162, 1.0, v195
	v_mul_f32_e32 v195, 0xbfb8aa3b, v166
	v_add_f32_e32 v163, 1.0, v196
	v_exp_f32_e32 v195, v195
	v_mul_f32_e32 v196, 0xbfb8aa3b, v167
	v_exp_f32_e32 v196, v196
	v_rcp_f32_e32 v162, v162
	v_add_f32_e32 v195, 1.0, v195
	v_rcp_f32_e32 v198, v195
	v_add_f32_e32 v195, 1.0, v196
	v_rcp_f32_e32 v163, v163
	v_rcp_f32_e32 v199, v195
	v_pk_mul_f32 v[166:167], v[154:155], v[166:167]
	v_pk_mul_f32 v[162:163], v[164:165], v[162:163]
	v_pk_mul_f32 v[164:165], v[166:167], v[198:199]
	v_cvt_pk_bf16_f32 v162, v162, v163
	v_cvt_pk_bf16_f32 v163, v164, v165
	v_mov_b64_e32 v[164:165], s[52:53]
	v_mad_i64_i32 v[164:165], s[42:43], v193, s60, v[164:165]
	v_lshl_add_u64 v[164:165], v[184:185], 1, v[164:165]
	global_store_dwordx4 v[164:165], v[160:163], off

; #define PG8_STAGE(bufoff, gbase, voff) do { _Pragma("unroll") for (int _i = 0; _i < 2; ++_i) \
;         __builtin_amdgcn_global_load_lds((const unsigned*)((const char*)(gbase) + (voff)[_i]), (LAS unsigned*)(lds + (bufoff) + ldsw + _i * 8192), 16, 0, 0); } while (0)
; #define PG8_LDA(dst, b, h) do { _Pragma("unroll") for (int m = 0; m < 4; ++m) _Pragma("unroll") for (int k = 0; k < 2; ++k) dst[m][k] = *(const LAS bf16x8*)(lds + PG8_SA(b, h) + aoff + m * 2048 + k * 1024); } while (0)
; #define PG8_LDB(dst, b, h) do { _Pragma("unroll") for (int n = 0; n < 2; ++n) _Pragma("unroll") for (int k = 0; k < 2; ++k) dst[n][k] = *(const LAS bf16x8*)(lds + PG8_SB(b, h) + boff + n * 2048 + k * 1024); } while (0)
; #define PG8_MMA(ai, bj, At, Bt) do { __builtin_amdgcn_s_setprio(1); _Pragma("unroll") for (int m = 0; m < 4; ++m) _Pragma("unroll") for (int n = 0; n < 2; ++n) _Pragma("unroll") for (int k = 0; k < 2; ++k) \
;         acc[ai][bj][m][n] = __builtin_amdgcn_mfma_f32_16x16x32_bf16(Bt[n][k], At[m][k], acc[ai][bj][m][n], 0, 0, 0); __builtin_amdgcn_s_setprio(0); } while (0)
; #define PG8_WAIT_V(n) asm volatile("s_waitcnt vmcnt(" #n ")" ::: "memory")
; #define PG8_WAIT_L(n) asm volatile("s_waitcnt lgkmcnt(" #n ")" ::: "memory")
; template <class Map, class Epi>
; DI void gemm_phase(LAS unsigned char* lds, const Map& MP, const Epi& E, const int nM, const int nN, const int K, const int lda, const int ldb) {
;     ...
;             const bool last = (t == nt - 2);
;             const char* a1 = cA + (size_t)(t + 1) * kstep;
;             const char* a2 = last ? nA : cA + (size_t)(t + 2) * kstep; const char* b2 = last ? nB : cB + (size_t)(t + 2) * kstep;
;             const char* a3 = a2 + kstep; const char* b3 = b2 + kstep;
;             PG8_LDB(B0, 0, 0); PG8_SCHED; PG8_LDA(At, 0, 0); PG8_STAGE(PG8_SA(1, 1), a1 + hstepA, voffA);
;             PG8_WAIT_L(8); PG8_BAR; PG8_WAIT_L(0); PG8_MMA(0, 0, At, B0); PG8_BAR; PG8_SCHED;
;             PG8_LDB(B1, 0, 1); PG8_STAGE(PG8_SB(0, 0), b2, voffB);
;             PG8_BAR; PG8_WAIT_L(0); PG8_MMA(0, 1, At, B1); PG8_BAR;
;             PG8_LDA(At, 0, 1); PG8_STAGE(PG8_SA(0, 0), a2, voffA);
;             PG8_BAR; PG8_WAIT_L(0); PG8_MMA(1, 0, At, B0); PG8_BAR; PG8_SCHED;
;             PG8_STAGE(PG8_SB(0, 1), b2 + hstepB, voffB);
;             PG8_WAIT_V(6); PG8_BAR; PG8_MMA(1, 1, At, B1); PG8_BAR;
.LBB1_2653:
	s_add_u32 s10, s8, 0x100
	s_addc_u32 s11, s9, 0
	s_cmpk_eq_i32 s48, 0x54
	s_cselect_b32 s15, s43, s11
	s_cselect_b32 s14, s42, s10
	s_cselect_b32 s13, s45, s39
	s_cselect_b32 s12, s44, s38
	s_add_i32 m0, s22, 0xc000
	ds_read_b128 v[168:171], v150
	ds_read_b128 v[172:175], v150 offset:1024
	ds_read_b128 v[176:179], v150 offset:2048
	ds_read_b128 v[180:183], v150 offset:3072
	ds_read_b128 v[184:187], v150 offset:4096
	ds_read_b128 v[188:191], v150 offset:5120
	ds_read_b128 v[192:195], v150 offset:6144
	ds_read_b128 v[196:199], v150 offset:7168
	global_load_lds_dwordx4 v138, s[8:9]
	s_add_i32 m0, s22, 0xe000
	s_nop 0
	global_load_lds_dwordx4 v136, s[8:9]
	s_waitcnt lgkmcnt(8)
	s_setprio 1
	s_barrier
	s_waitcnt lgkmcnt(7)
	v_mfma_f32_16x16x32_bf16 v[124:127], v[152:155], v[168:171], v[124:127]
	v_mfma_f32_16x16x32_bf16 v[120:123], v[160:163], v[168:171], v[120:123]
	s_waitcnt lgkmcnt(5)
	v_mfma_f32_16x16x32_bf16 v[108:111], v[152:155], v[176:179], v[108:111]
	v_mfma_f32_16x16x32_bf16 v[104:107], v[160:163], v[176:179], v[104:107]
	s_waitcnt lgkmcnt(3)
	v_mfma_f32_16x16x32_bf16 v[92:95], v[152:155], v[184:187], v[92:95]
	v_mfma_f32_16x16x32_bf16 v[88:91], v[160:163], v[184:187], v[88:91]
	s_waitcnt lgkmcnt(1)
	v_mfma_f32_16x16x32_bf16 v[76:79], v[152:155], v[192:195], v[76:79]
	v_mfma_f32_16x16x32_bf16 v[72:75], v[160:163], v[192:195], v[72:75]
	v_mfma_f32_16x16x32_bf16 v[124:127], v[156:159], v[172:175], v[124:127]
	v_mfma_f32_16x16x32_bf16 v[120:123], v[164:167], v[172:175], v[120:123]
	v_mfma_f32_16x16x32_bf16 v[108:111], v[156:159], v[180:183], v[108:111]
	v_mfma_f32_16x16x32_bf16 v[104:107], v[164:167], v[180:183], v[104:107]
	v_mfma_f32_16x16x32_bf16 v[92:95], v[156:159], v[188:191], v[92:95]
	v_mfma_f32_16x16x32_bf16 v[88:91], v[164:167], v[188:191], v[88:91]
	s_waitcnt lgkmcnt(0)
	v_mfma_f32_16x16x32_bf16 v[76:79], v[156:159], v[196:199], v[76:79]
	v_mfma_f32_16x16x32_bf16 v[72:75], v[164:167], v[196:199], v[72:75]
	s_barrier
	s_setprio 0
	s_add_i32 s8, s33, s20
	v_lshl_add_u64 v[144:145], s[12:13], 0, v[132:133]
	s_mov_b32 m0, s8
	ds_read_b128 v[200:203], v151
	ds_read_b128 v[204:207], v151 offset:1024
	ds_read_b128 v[208:211], v151 offset:2048
	ds_read_b128 v[212:215], v151 offset:3072
	global_load_lds_dwordx4 v[144:145], off
	v_lshl_add_u64 v[216:217], s[12:13], 0, v[128:129]
	s_add_i32 m0, s8, 0x2000
	s_nop 0
	global_load_lds_dwordx4 v[216:217], off
	s_setprio 1
	s_barrier
	s_waitcnt lgkmcnt(3)
	v_mfma_f32_16x16x32_bf16 v[116:119], v[200:203], v[168:171], v[116:119]
	s_waitcnt lgkmcnt(1)
	v_mfma_f32_16x16x32_bf16 v[112:115], v[208:211], v[168:171], v[112:115]
	v_mfma_f32_16x16x32_bf16 v[100:103], v[200:203], v[176:179], v[100:103]
	v_mfma_f32_16x16x32_bf16 v[96:99], v[208:211], v[176:179], v[96:99]
	v_mfma_f32_16x16x32_bf16 v[84:87], v[200:203], v[184:187], v[84:87]
	v_mfma_f32_16x16x32_bf16 v[80:83], v[208:211], v[184:187], v[80:83]
	v_mfma_f32_16x16x32_bf16 v[68:71], v[200:203], v[192:195], v[68:71]
	v_mfma_f32_16x16x32_bf16 v[64:67], v[208:211], v[192:195], v[64:67]
	v_mfma_f32_16x16x32_bf16 v[116:119], v[204:207], v[172:175], v[116:119]
	s_mov_b32 m0, s22
	s_waitcnt lgkmcnt(0)
	v_mfma_f32_16x16x32_bf16 v[112:115], v[212:215], v[172:175], v[112:115]
	v_lshl_add_u64 v[218:219], s[14:15], 0, v[134:135]
	v_mfma_f32_16x16x32_bf16 v[100:103], v[204:207], v[180:183], v[100:103]
	v_mfma_f32_16x16x32_bf16 v[96:99], v[212:215], v[180:183], v[96:99]
	v_mfma_f32_16x16x32_bf16 v[84:87], v[204:207], v[188:191], v[84:87]
	v_mfma_f32_16x16x32_bf16 v[80:83], v[212:215], v[188:191], v[80:83]
	v_mfma_f32_16x16x32_bf16 v[68:71], v[204:207], v[196:199], v[68:71]
	v_mfma_f32_16x16x32_bf16 v[64:67], v[212:215], v[196:199], v[64:67]
	s_barrier
	s_setprio 0
	ds_read_b128 v[168:171], v150 offset:16384
	ds_read_b128 v[172:175], v150 offset:17408
	ds_read_b128 v[176:179], v150 offset:18432
	ds_read_b128 v[180:183], v150 offset:19456
	ds_read_b128 v[184:187], v150 offset:20480
	ds_read_b128 v[188:191], v150 offset:21504
	ds_read_b128 v[192:195], v150 offset:22528
	ds_read_b128 v[196:199], v150 offset:23552
	global_load_lds_dwordx4 v[218:219], off
	v_lshl_add_u64 v[220:221], s[14:15], 0, v[130:131]
	s_mov_b32 m0, s23
	s_nop 0
	global_load_lds_dwordx4 v[220:221], off
	s_waitcnt vmcnt(10)
	s_setprio 1
	s_barrier
	s_waitcnt lgkmcnt(7)
	v_mfma_f32_16x16x32_bf16 v[60:63], v[152:155], v[168:171], v[60:63]
	v_mfma_f32_16x16x32_bf16 v[56:59], v[160:163], v[168:171], v[56:59]
	s_waitcnt lgkmcnt(5)
	v_mfma_f32_16x16x32_bf16 v[44:47], v[152:155], v[176:179], v[44:47]
	v_mfma_f32_16x16x32_bf16 v[40:43], v[160:163], v[176:179], v[40:43]
	s_waitcnt lgkmcnt(3)
	v_mfma_f32_16x16x32_bf16 v[28:31], v[152:155], v[184:187], v[28:31]
	v_mfma_f32_16x16x32_bf16 v[24:27], v[160:163], v[184:187], v[24:27]
	s_waitcnt lgkmcnt(1)
	v_mfma_f32_16x16x32_bf16 v[12:15], v[152:155], v[192:195], v[12:15]
	v_mfma_f32_16x16x32_bf16 v[8:11], v[160:163], v[192:195], v[8:11]
	v_mfma_f32_16x16x32_bf16 v[60:63], v[156:159], v[172:175], v[60:63]
	v_mfma_f32_16x16x32_bf16 v[56:59], v[164:167], v[172:175], v[56:59]
	v_mfma_f32_16x16x32_bf16 v[44:47], v[156:159], v[180:183], v[44:47]
	v_mfma_f32_16x16x32_bf16 v[40:43], v[164:167], v[180:183], v[40:43]
	v_mfma_f32_16x16x32_bf16 v[28:31], v[156:159], v[188:191], v[28:31]
	v_mfma_f32_16x16x32_bf16 v[24:27], v[164:167], v[188:191], v[24:27]
	s_waitcnt lgkmcnt(0)
	v_mfma_f32_16x16x32_bf16 v[12:15], v[156:159], v[196:199], v[12:15]
	v_mfma_f32_16x16x32_bf16 v[8:11], v[164:167], v[196:199], v[8:11]
	s_barrier
; #define PG8_STAGE(bufoff, gbase, voff) do { _Pragma("unroll") for (int _i = 0; _i < 2; ++_i) \
;         __builtin_amdgcn_global_load_lds((const unsigned*)((const char*)(gbase) + (voff)[_i]), (LAS unsigned*)(lds + (bufoff) + ldsw + _i * 8192), 16, 0, 0); } while (0)
; #define PG8_LDA(dst, b, h) do { _Pragma("unroll") for (int m = 0; m < 4; ++m) _Pragma("unroll") for (int k = 0; k < 2; ++k) dst[m][k] = *(const LAS bf16x8*)(lds + PG8_SA(b, h) + aoff + m * 2048 + k * 1024); } while (0)
; #define PG8_LDB(dst, b, h) do { _Pragma("unroll") for (int n = 0; n < 2; ++n) _Pragma("unroll") for (int k = 0; k < 2; ++k) dst[n][k] = *(const LAS bf16x8*)(lds + PG8_SB(b, h) + boff + n * 2048 + k * 1024); } while (0)
; #define PG8_MMA(ai, bj, At, Bt) do { __builtin_amdgcn_s_setprio(1); _Pragma("unroll") for (int m = 0; m < 4; ++m) _Pragma("unroll") for (int n = 0; n < 2; ++n) _Pragma("unroll") for (int k = 0; k < 2; ++k) \
;         acc[ai][bj][m][n] = __builtin_amdgcn_mfma_f32_16x16x32_bf16(Bt[n][k], At[m][k], acc[ai][bj][m][n], 0, 0, 0); __builtin_amdgcn_s_setprio(0); } while (0)
; #define PG8_WAIT_V(n) asm volatile("s_waitcnt vmcnt(" #n ")" ::: "memory")
; #define PG8_WAIT_L(n) asm volatile("s_waitcnt lgkmcnt(" #n ")" ::: "memory")
; #define PG8_BAR __builtin_amdgcn_s_barrier()
; #define PG8_SCHED __builtin_amdgcn_sched_barrier(0)
; template <class Map, class Epi>
; DI void gemm_phase(LAS unsigned char* lds, const Map& MP, const Epi& E, const int nM, const int nN, const int K, const int lda, const int ldb) {
;     ...
;             PG8_LDA(At, 0, 1); PG8_STAGE(PG8_SA(0, 0), a2, voffA);
;             PG8_BAR; PG8_WAIT_L(0); PG8_MMA(1, 0, At, B0); PG8_BAR; PG8_SCHED;
;             PG8_STAGE(PG8_SB(0, 1), b2 + hstepB, voffB);
;             PG8_WAIT_V(6); PG8_BAR; PG8_MMA(1, 1, At, B1); PG8_BAR;
;             PG8_LDB(B0, 1, 0); PG8_SCHED; PG8_LDA(At, 1, 0); PG8_STAGE(PG8_SA(0, 1), a2 + hstepA, voffA);
;             PG8_WAIT_L(8); PG8_BAR; PG8_WAIT_L(0); PG8_MMA(0, 0, At, B0); PG8_BAR; PG8_SCHED;
;             PG8_LDB(B1, 1, 1); PG8_STAGE(PG8_SB(1, 0), b3, voffB);
;             PG8_BAR; PG8_WAIT_L(0); PG8_MMA(0, 1, At, B1); PG8_BAR;
;             PG8_LDA(At, 1, 1); PG8_STAGE(PG8_SA(1, 0), a3, voffA);
;             PG8_BAR; PG8_WAIT_L(0); PG8_MMA(1, 0, At, B0); PG8_BAR; PG8_SCHED;
	s_setprio 0
	s_add_u32 s8, s12, 0x160000
	s_addc_u32 s9, s13, 0
	s_add_i32 s49, s34, s20
	s_mov_b32 m0, s49
	s_nop 0
	global_load_lds_dwordx4 v132, s[8:9]
	s_add_i32 m0, s49, 0x2000
	s_nop 0
	global_load_lds_dwordx4 v128, s[8:9]
	s_waitcnt vmcnt(6)
	s_setprio 1
	s_barrier
	v_mfma_f32_16x16x32_bf16 v[52:55], v[200:203], v[168:171], v[52:55]
	v_mfma_f32_16x16x32_bf16 v[48:51], v[208:211], v[168:171], v[48:51]
	s_add_i32 s49, 0, 0x18000
	v_add_u32_e32 v164, s49, v148
	ds_read_b128 v[152:155], v164
	v_mfma_f32_16x16x32_bf16 v[36:39], v[200:203], v[176:179], v[36:39]
	v_mfma_f32_16x16x32_bf16 v[32:35], v[208:211], v[176:179], v[32:35]
	ds_read_b128 v[156:159], v164 offset:1024
	v_mfma_f32_16x16x32_bf16 v[20:23], v[200:203], v[184:187], v[20:23]
	v_mfma_f32_16x16x32_bf16 v[16:19], v[208:211], v[184:187], v[16:19]
	ds_read_b128 v[160:163], v164 offset:2048
	v_mfma_f32_16x16x32_bf16 v[4:7], v[200:203], v[192:195], v[4:7]
	v_mfma_f32_16x16x32_bf16 v[0:3], v[208:211], v[192:195], v[0:3]
	ds_read_b128 v[164:167], v164 offset:3072
	v_mfma_f32_16x16x32_bf16 v[52:55], v[204:207], v[172:175], v[52:55]
	v_mfma_f32_16x16x32_bf16 v[48:51], v[212:215], v[172:175], v[48:51]
	v_mfma_f32_16x16x32_bf16 v[36:39], v[204:207], v[180:183], v[36:39]
	v_mfma_f32_16x16x32_bf16 v[32:35], v[212:215], v[180:183], v[32:35]
	v_mfma_f32_16x16x32_bf16 v[20:23], v[204:207], v[188:191], v[20:23]
	v_mfma_f32_16x16x32_bf16 v[16:19], v[212:215], v[188:191], v[16:19]
	v_mfma_f32_16x16x32_bf16 v[4:7], v[204:207], v[196:199], v[4:7]
	v_mfma_f32_16x16x32_bf16 v[0:3], v[212:215], v[196:199], v[0:3]
	s_barrier
	s_setprio 0
	s_add_u32 s8, s14, 0x160000
	s_addc_u32 s9, s15, 0
	s_mov_b32 m0, s24
	ds_read_b128 v[168:171], v150 offset:32768
	ds_read_b128 v[172:175], v150 offset:33792
	ds_read_b128 v[176:179], v150 offset:34816
	ds_read_b128 v[180:183], v150 offset:35840
	ds_read_b128 v[184:187], v150 offset:36864
	ds_read_b128 v[188:191], v150 offset:37888
	ds_read_b128 v[192:195], v150 offset:38912
	ds_read_b128 v[196:199], v150 offset:39936
	global_load_lds_dwordx4 v134, s[8:9]
	s_mov_b32 m0, s25
	s_nop 0
	global_load_lds_dwordx4 v130, s[8:9]
	s_waitcnt lgkmcnt(8)
	s_setprio 1
	s_barrier
	s_waitcnt lgkmcnt(7)
	v_mfma_f32_16x16x32_bf16 v[124:127], v[152:155], v[168:171], v[124:127]
	v_mfma_f32_16x16x32_bf16 v[120:123], v[160:163], v[168:171], v[120:123]
	s_waitcnt lgkmcnt(5)
	v_mfma_f32_16x16x32_bf16 v[108:111], v[152:155], v[176:179], v[108:111]
	v_mfma_f32_16x16x32_bf16 v[104:107], v[160:163], v[176:179], v[104:107]
	s_waitcnt lgkmcnt(3)
	v_mfma_f32_16x16x32_bf16 v[92:95], v[152:155], v[184:187], v[92:95]
	v_mfma_f32_16x16x32_bf16 v[88:91], v[160:163], v[184:187], v[88:91]
	s_waitcnt lgkmcnt(1)
	v_mfma_f32_16x16x32_bf16 v[76:79], v[152:155], v[192:195], v[76:79]
	v_mfma_f32_16x16x32_bf16 v[72:75], v[160:163], v[192:195], v[72:75]
	v_mfma_f32_16x16x32_bf16 v[124:127], v[156:159], v[172:175], v[124:127]
	v_mfma_f32_16x16x32_bf16 v[120:123], v[164:167], v[172:175], v[120:123]
	v_mfma_f32_16x16x32_bf16 v[108:111], v[156:159], v[180:183], v[108:111]
	v_mfma_f32_16x16x32_bf16 v[104:107], v[164:167], v[180:183], v[104:107]
	v_mfma_f32_16x16x32_bf16 v[92:95], v[156:159], v[188:191], v[92:95]
	v_mfma_f32_16x16x32_bf16 v[88:91], v[164:167], v[188:191], v[88:91]
	s_waitcnt lgkmcnt(0)
	v_mfma_f32_16x16x32_bf16 v[76:79], v[156:159], v[196:199], v[76:79]
	v_mfma_f32_16x16x32_bf16 v[72:75], v[164:167], v[196:199], v[72:75]
	s_barrier
	s_setprio 0
	s_add_i32 s14, 0, 0x1c000
	s_add_i32 s8, s49, s20
	v_add_u32_e32 v212, s14, v148
	v_lshl_add_u64 v[144:145], v[144:145], 0, s[46:47]
	s_mov_b32 m0, s8
	ds_read_b128 v[200:203], v212
	ds_read_b128 v[204:207], v212 offset:1024
	ds_read_b128 v[208:211], v212 offset:2048
	ds_read_b128 v[212:215], v212 offset:3072
	global_load_lds_dwordx4 v[144:145], off
	v_lshl_add_u64 v[144:145], v[216:217], 0, s[46:47]
	s_add_i32 m0, s8, 0x2000
	s_nop 0
	global_load_lds_dwordx4 v[144:145], off
	s_setprio 1
	s_barrier
	s_waitcnt lgkmcnt(3)
	v_mfma_f32_16x16x32_bf16 v[116:119], v[200:203], v[168:171], v[116:119]
	s_waitcnt lgkmcnt(1)
	v_mfma_f32_16x16x32_bf16 v[112:115], v[208:211], v[168:171], v[112:115]
	v_mfma_f32_16x16x32_bf16 v[100:103], v[200:203], v[176:179], v[100:103]
	v_mfma_f32_16x16x32_bf16 v[96:99], v[208:211], v[176:179], v[96:99]
	v_mfma_f32_16x16x32_bf16 v[84:87], v[200:203], v[184:187], v[84:87]
	v_mfma_f32_16x16x32_bf16 v[80:83], v[208:211], v[184:187], v[80:83]
	v_mfma_f32_16x16x32_bf16 v[68:71], v[200:203], v[192:195], v[68:71]
	v_mfma_f32_16x16x32_bf16 v[64:67], v[208:211], v[192:195], v[64:67]
	v_mfma_f32_16x16x32_bf16 v[116:119], v[204:207], v[172:175], v[116:119]
	s_mov_b32 m0, s29
	s_waitcnt lgkmcnt(0)
	v_mfma_f32_16x16x32_bf16 v[112:115], v[212:215], v[172:175], v[112:115]
	v_lshl_add_u64 v[144:145], v[218:219], 0, s[46:47]
	v_mfma_f32_16x16x32_bf16 v[100:103], v[204:207], v[180:183], v[100:103]
	v_mfma_f32_16x16x32_bf16 v[96:99], v[212:215], v[180:183], v[96:99]
	v_mfma_f32_16x16x32_bf16 v[84:87], v[204:207], v[188:191], v[84:87]
	v_mfma_f32_16x16x32_bf16 v[80:83], v[212:215], v[188:191], v[80:83]
	v_mfma_f32_16x16x32_bf16 v[68:71], v[204:207], v[196:199], v[68:71]
	v_mfma_f32_16x16x32_bf16 v[64:67], v[212:215], v[196:199], v[64:67]
	s_barrier
	s_setprio 0
	ds_read_b128 v[168:171], v150 offset:49152
	ds_read_b128 v[172:175], v150 offset:50176
	ds_read_b128 v[176:179], v150 offset:51200
	ds_read_b128 v[180:183], v150 offset:52224
	ds_read_b128 v[184:187], v150 offset:53248
	ds_read_b128 v[188:191], v150 offset:54272
	ds_read_b128 v[192:195], v150 offset:55296
	ds_read_b128 v[196:199], v150 offset:56320
	global_load_lds_dwordx4 v[144:145], off
	v_lshl_add_u64 v[144:145], v[220:221], 0, s[46:47]
	s_mov_b32 m0, s30
	s_nop 0
	global_load_lds_dwordx4 v[144:145], off
	s_waitcnt vmcnt(10)
	s_setprio 1
	s_barrier
; DI unsigned pack2(float a, float b) { f32x2 v = {a, b}; hwbf16x2 r = __builtin_convertvector(v, hwbf16x2); return __builtin_bit_cast(unsigned, r); }
; DI float bflo(unsigned w) { return __uint_as_float(w << 16); }
; DI float bfhi(unsigned w) { return __uint_as_float(w & 0xffff0000u); }
;     DI void operator()(const f32x4 (&acc)[2][2][4][2], const Unit& u, int wr, int wc, int fr, int fq) const {
;         const int row0 = u.pm * BM + wr * 64 + fr, col0 = u.pn * BM + wc * 32 + 8 * fq;
;         f32x4 sc[2][2];
; #pragma unroll
;         for (int bj = 0; bj < 2; ++bj)
; #pragma unroll
;             for (int n = 0; n < 2; ++n) sc[bj][n] = scale ? *(const f32x4*)(scale + col0 + bj * HALF + 4 * n) : (f32x4){1.f, 1.f, 1.f, 1.f};
; #pragma unroll
;         for (int ai = 0; ai < 2; ++ai)
; #pragma unroll
;             for (int m = 0; m < 4; ++m) { const size_t ro = (size_t)(row0 + ai * HALF + m * 16) * D + col0;
; #pragma unroll
;                 for (int bj = 0; bj < 2; ++bj) {
;                     f32x4 x0, x1;
;                     if constexpr (IB) { const u32x4 w = *(const u32x4*)((const bf16_t*)Xin + ro + bj * HALF);
;                         x0 = (f32x4){bflo(w[0]), bfhi(w[0]), bflo(w[1]), bfhi(w[1])}; x1 = (f32x4){bflo(w[2]), bfhi(w[2]), bflo(w[3]), bfhi(w[3])}; }
;                     else { x0 = *(const f32x4*)((const float*)Xin + ro + bj * HALF); x1 = *(const f32x4*)((const float*)Xin + ro + bj * HALF + 4); }
;                     x0 += acc[ai][bj][m][0] * sc[bj][0]; x1 += acc[ai][bj][m][1] * sc[bj][1];
;                     if constexpr (OB) { u32x4 o; o[0] = pack2(x0[0], x0[1]); o[1] = pack2(x0[2], x0[3]); o[2] = pack2(x1[0], x1[1]); o[3] = pack2(x1[2], x1[3]);
;                         *(u32x4*)((bf16_t*)Xout + ro + bj * HALF) = o; }
;                     else { *(f32x4*)((float*)Xout + ro + bj * HALF) = x0; *(f32x4*)((float*)Xout + ro + bj * HALF + 4) = x1; } } }
; template <class Map, class Epi>
; DI void gemm_phase(LAS unsigned char* lds, const Map& MP, const Epi& E, const int nM, const int nN, const int K, const int lda, const int ldb) {
;     ...
;             PG8_LDA(At, 1, 1); PG8_STAGE(PG8_SA(1, 0), a3, voffA);
;             PG8_BAR; PG8_WAIT_L(0); PG8_MMA(1, 0, At, B0); PG8_BAR; PG8_SCHED;
;             PG8_STAGE(PG8_SB(1, 1), b3 + hstepB, voffB);
;             PG8_WAIT_V(6); PG8_BAR; PG8_MMA(1, 1, At, B1); PG8_BAR;
	s_waitcnt lgkmcnt(7)
	v_mfma_f32_16x16x32_bf16 v[60:63], v[152:155], v[168:171], v[60:63]
	v_mfma_f32_16x16x32_bf16 v[56:59], v[160:163], v[168:171], v[56:59]
	s_waitcnt lgkmcnt(5)
	v_mfma_f32_16x16x32_bf16 v[44:47], v[152:155], v[176:179], v[44:47]
	v_mfma_f32_16x16x32_bf16 v[40:43], v[160:163], v[176:179], v[40:43]
	s_waitcnt lgkmcnt(3)
	v_mfma_f32_16x16x32_bf16 v[28:31], v[152:155], v[184:187], v[28:31]
	v_mfma_f32_16x16x32_bf16 v[24:27], v[160:163], v[184:187], v[24:27]
	s_waitcnt lgkmcnt(1)
	v_mfma_f32_16x16x32_bf16 v[12:15], v[152:155], v[192:195], v[12:15]
	v_mfma_f32_16x16x32_bf16 v[8:11], v[160:163], v[192:195], v[8:11]
	v_mfma_f32_16x16x32_bf16 v[60:63], v[156:159], v[172:175], v[60:63]
	v_mfma_f32_16x16x32_bf16 v[56:59], v[164:167], v[172:175], v[56:59]
	v_mfma_f32_16x16x32_bf16 v[44:47], v[156:159], v[180:183], v[44:47]
	v_mfma_f32_16x16x32_bf16 v[40:43], v[164:167], v[180:183], v[40:43]
	v_mfma_f32_16x16x32_bf16 v[28:31], v[156:159], v[188:191], v[28:31]
	v_mfma_f32_16x16x32_bf16 v[24:27], v[164:167], v[188:191], v[24:27]
	s_waitcnt lgkmcnt(0)
	v_mfma_f32_16x16x32_bf16 v[12:15], v[156:159], v[196:199], v[12:15]
	v_mfma_f32_16x16x32_bf16 v[8:11], v[164:167], v[196:199], v[8:11]
	s_barrier
	s_setprio 0
	s_add_u32 s8, s12, 0x160080
	s_addc_u32 s9, s13, 0
	s_add_i32 s12, s14, s20
	s_mov_b32 m0, s12
	s_nop 0
	global_load_lds_dwordx4 v132, s[8:9]
	s_add_i32 m0, s12, 0x2000
	s_nop 0
	global_load_lds_dwordx4 v128, s[8:9]
	s_waitcnt vmcnt(6)
	s_setprio 1
	s_barrier
	v_mfma_f32_16x16x32_bf16 v[52:55], v[200:203], v[168:171], v[52:55]
	v_mfma_f32_16x16x32_bf16 v[48:51], v[208:211], v[168:171], v[48:51]
	ds_read_b128 v[152:155], v149
	v_mfma_f32_16x16x32_bf16 v[36:39], v[200:203], v[176:179], v[36:39]
	v_mfma_f32_16x16x32_bf16 v[32:35], v[208:211], v[176:179], v[32:35]
	ds_read_b128 v[156:159], v149 offset:1024
	v_mfma_f32_16x16x32_bf16 v[20:23], v[200:203], v[184:187], v[20:23]
	v_mfma_f32_16x16x32_bf16 v[16:19], v[208:211], v[184:187], v[16:19]
	ds_read_b128 v[160:163], v149 offset:2048
	v_mfma_f32_16x16x32_bf16 v[4:7], v[200:203], v[192:195], v[4:7]
	v_mfma_f32_16x16x32_bf16 v[0:3], v[208:211], v[192:195], v[0:3]
	ds_read_b128 v[164:167], v149 offset:3072
	v_mfma_f32_16x16x32_bf16 v[52:55], v[204:207], v[172:175], v[52:55]
	s_add_i32 s48, s48, 2
	v_mfma_f32_16x16x32_bf16 v[48:51], v[212:215], v[172:175], v[48:51]
	s_add_u32 s38, s38, 0x100
	s_addc_u32 s39, s39, 0
	v_mfma_f32_16x16x32_bf16 v[36:39], v[204:207], v[180:183], v[36:39]
	s_cmpk_gt_u32 s48, 0x55
	v_mfma_f32_16x16x32_bf16 v[32:35], v[212:215], v[180:183], v[32:35]
	s_mov_b64 s[8:9], s[10:11]
	v_mfma_f32_16x16x32_bf16 v[20:23], v[204:207], v[188:191], v[20:23]
	v_mfma_f32_16x16x32_bf16 v[16:19], v[212:215], v[188:191], v[16:19]
	v_mfma_f32_16x16x32_bf16 v[4:7], v[204:207], v[196:199], v[4:7]
	v_mfma_f32_16x16x32_bf16 v[0:3], v[212:215], v[196:199], v[0:3]
	s_barrier
	s_setprio 0
	s_cbranch_scc0 .LBB1_2653
	s_waitcnt lgkmcnt(0)
	v_mov_b32_e32 v144, v147
	v_mov_b32_e32 v152, v146
	s_lshl_b32 s2, s2, 8
	s_lshl_b32 s8, s37, 8
	s_add_i32 s2, s2, s27
	s_or_b32 s8, s8, s28
	v_add_u32_e32 v152, s2, v152
	v_lshl_add_u32 v144, v144, 3, s8
	v_ashrrev_i32_e32 v153, 31, v152
	v_ashrrev_i32_e32 v145, 31, v144
	v_lshlrev_b64 v[152:153], 11, v[152:153]
	v_lshl_add_u64 v[144:145], v[152:153], 0, v[144:145]
	v_lshl_add_u64 v[156:157], v[144:145], 1, s[6:7]
	global_load_dwordx4 v[162:165], v[156:157], off
	global_load_dwordx4 v[166:169], v[156:157], off offset:256
	s_mov_b64 s[98:99], 0x10000
	v_lshl_add_u64 v[154:155], v[156:157], 0, s[98:99]
	global_load_dwordx4 v[170:173], v[154:155], off
	global_load_dwordx4 v[174:177], v[154:155], off offset:256
	s_mov_b64 s[98:99], 0x20000
	v_lshl_add_u64 v[154:155], v[156:157], 0, s[98:99]
	global_load_dwordx4 v[178:181], v[154:155], off
	global_load_dwordx4 v[182:185], v[154:155], off offset:256
	s_mov_b64 s[98:99], 0x30000
	v_lshl_add_u64 v[154:155], v[156:157], 0, s[98:99]
	global_load_dwordx4 v[186:189], v[154:155], off
	global_load_dwordx4 v[190:193], v[154:155], off offset:256
	s_mov_b64 s[98:99], 0x80000
	v_lshl_add_u64 v[154:155], v[156:157], 0, s[98:99]
	global_load_dwordx4 v[194:197], v[154:155], off
	global_load_dwordx4 v[198:201], v[154:155], off offset:256
	s_mov_b64 s[98:99], 0x90000
	v_lshl_add_u64 v[154:155], v[156:157], 0, s[98:99]
	global_load_dwordx4 v[202:205], v[154:155], off
	global_load_dwordx4 v[206:209], v[154:155], off offset:256
	s_mov_b64 s[98:99], 0xa0000
	v_lshl_add_u64 v[154:155], v[156:157], 0, s[98:99]
	global_load_dwordx4 v[210:213], v[154:155], off
	global_load_dwordx4 v[248:251], v[154:155], off offset:256
	s_mov_b64 s[98:99], 0xb0000
	v_lshl_add_u64 v[154:155], v[156:157], 0, s[98:99]
	global_load_dwordx4 v[252:255], v[154:155], off
	s_waitcnt vmcnt(14)
	s_nop 1
	v_mov_b32_e32 v152, v162
	v_mov_b32_e32 v153, v163
	v_mov_b32_e32 v154, v164
	v_mov_b32_e32 v155, v165
	s_mov_b64 s[8:9], 0x8000
	s_and_b64 vcc, exec, s[40:41]
	s_mov_b32 s37, s35
	s_mov_b32 s2, s36
	s_mov_b64 s[10:11], s[44:45]
	s_waitcnt lgkmcnt(0)
	v_lshlrev_b32_e32 v158, 16, v152
	v_and_b32_e32 v159, 0xffff0000, v152
	v_lshlrev_b32_e32 v152, 16, v153
	v_and_b32_e32 v153, 0xffff0000, v153
	v_lshlrev_b32_e32 v160, 16, v154
	v_and_b32_e32 v161, 0xffff0000, v154
	v_lshlrev_b32_e32 v154, 16, v155
	v_and_b32_e32 v155, 0xffff0000, v155
	v_pk_add_f32 v[126:127], v[126:127], v[152:153]
	v_pk_add_f32 v[124:125], v[124:125], v[158:159]
	v_lshl_add_u64 v[152:153], v[144:145], 2, s[4:5]
	v_pk_add_f32 v[122:123], v[122:123], v[154:155]
	v_pk_add_f32 v[120:121], v[120:121], v[160:161]
	global_store_dwordx4 v[152:153], v[124:127], off
	global_store_dwordx4 v[152:153], v[120:123], off offset:16
	s_waitcnt vmcnt(15)
; DI unsigned pack2(float a, float b) { f32x2 v = {a, b}; hwbf16x2 r = __builtin_convertvector(v, hwbf16x2); return __builtin_bit_cast(unsigned, r); }
; DI float bflo(unsigned w) { return __uint_as_float(w << 16); }
; DI float bfhi(unsigned w) { return __uint_as_float(w & 0xffff0000u); }
;     DI void operator()(const f32x4 (&acc)[2][2][4][2], const Unit& u, int wr, int wc, int fr, int fq) const {
;     ...
;         for (int ai = 0; ai < 2; ++ai)
; #pragma unroll
;             for (int m = 0; m < 4; ++m) { const size_t ro = (size_t)(row0 + ai * HALF + m * 16) * D + col0;
; #pragma unroll
;                 for (int bj = 0; bj < 2; ++bj) {
;                     f32x4 x0, x1;
;                     if constexpr (IB) { const u32x4 w = *(const u32x4*)((const bf16_t*)Xin + ro + bj * HALF);
;                         x0 = (f32x4){bflo(w[0]), bfhi(w[0]), bflo(w[1]), bfhi(w[1])}; x1 = (f32x4){bflo(w[2]), bfhi(w[2]), bflo(w[3]), bfhi(w[3])}; }
;                     else { x0 = *(const f32x4*)((const float*)Xin + ro + bj * HALF); x1 = *(const f32x4*)((const float*)Xin + ro + bj * HALF + 4); }
;                     x0 += acc[ai][bj][m][0] * sc[bj][0]; x1 += acc[ai][bj][m][1] * sc[bj][1];
;                     if constexpr (OB) { u32x4 o; o[0] = pack2(x0[0], x0[1]); o[1] = pack2(x0[2], x0[3]); o[2] = pack2(x1[0], x1[1]); o[3] = pack2(x1[2], x1[3]);
;                         *(u32x4*)((bf16_t*)Xout + ro + bj * HALF) = o; }
;                     else { *(f32x4*)((float*)Xout + ro + bj * HALF) = x0; *(f32x4*)((float*)Xout + ro + bj * HALF + 4) = x1; } } }
	s_nop 1
	v_mov_b32_e32 v120, v166
	v_mov_b32_e32 v121, v167
	v_mov_b32_e32 v122, v168
	v_mov_b32_e32 v123, v169
	s_waitcnt lgkmcnt(0)
	v_lshlrev_b32_e32 v124, 16, v120
	v_and_b32_e32 v125, 0xffff0000, v120
	v_lshlrev_b32_e32 v120, 16, v121
	v_and_b32_e32 v121, 0xffff0000, v121
	v_lshlrev_b32_e32 v126, 16, v122
	v_and_b32_e32 v127, 0xffff0000, v122
	v_lshlrev_b32_e32 v122, 16, v123
	v_and_b32_e32 v123, 0xffff0000, v123
	v_pk_add_f32 v[118:119], v[118:119], v[120:121]
	v_pk_add_f32 v[116:117], v[116:117], v[124:125]
	v_pk_add_f32 v[114:115], v[114:115], v[122:123]
	v_pk_add_f32 v[112:113], v[112:113], v[126:127]
	global_store_dwordx4 v[152:153], v[116:119], off offset:512
	global_store_dwordx4 v[152:153], v[112:115], off offset:528
	s_nop 0
	v_lshl_add_u64 v[116:117], v[144:145], 0, s[8:9]
	v_lshl_add_u64 v[118:119], v[116:117], 1, s[6:7]
	s_waitcnt vmcnt(16)
	s_nop 1
	v_mov_b32_e32 v112, v170
	v_mov_b32_e32 v113, v171
	v_mov_b32_e32 v114, v172
	v_mov_b32_e32 v115, v173
	s_mov_b64 s[8:9], 0x10000
	s_waitcnt lgkmcnt(0)
	v_lshlrev_b32_e32 v120, 16, v112
	v_and_b32_e32 v121, 0xffff0000, v112
	v_lshlrev_b32_e32 v112, 16, v113
	v_and_b32_e32 v113, 0xffff0000, v113
	v_lshlrev_b32_e32 v122, 16, v114
	v_and_b32_e32 v123, 0xffff0000, v114
	v_lshlrev_b32_e32 v114, 16, v115
	v_and_b32_e32 v115, 0xffff0000, v115
	v_pk_add_f32 v[110:111], v[110:111], v[112:113]
	v_pk_add_f32 v[108:109], v[108:109], v[120:121]
	v_lshl_add_u64 v[112:113], v[116:117], 2, s[4:5]
	v_pk_add_f32 v[106:107], v[106:107], v[114:115]
	v_pk_add_f32 v[104:105], v[104:105], v[122:123]
	global_store_dwordx4 v[112:113], v[108:111], off
	global_store_dwordx4 v[112:113], v[104:107], off offset:16
	s_waitcnt vmcnt(17)
	s_nop 1
	v_mov_b32_e32 v104, v174
	v_mov_b32_e32 v105, v175
	v_mov_b32_e32 v106, v176
	v_mov_b32_e32 v107, v177
	s_waitcnt lgkmcnt(0)
	v_lshlrev_b32_e32 v108, 16, v104
	v_and_b32_e32 v109, 0xffff0000, v104
	v_lshlrev_b32_e32 v104, 16, v105
	v_and_b32_e32 v105, 0xffff0000, v105
	v_lshlrev_b32_e32 v110, 16, v106
	v_and_b32_e32 v111, 0xffff0000, v106
	v_lshlrev_b32_e32 v106, 16, v107
	v_and_b32_e32 v107, 0xffff0000, v107
	v_pk_add_f32 v[102:103], v[102:103], v[104:105]
	v_pk_add_f32 v[100:101], v[100:101], v[108:109]
	v_pk_add_f32 v[98:99], v[98:99], v[106:107]
	v_pk_add_f32 v[96:97], v[96:97], v[110:111]
	global_store_dwordx4 v[112:113], v[100:103], off offset:512
	global_store_dwordx4 v[112:113], v[96:99], off offset:528
	s_nop 0
	v_lshl_add_u64 v[100:101], v[144:145], 0, s[8:9]
	v_lshl_add_u64 v[102:103], v[100:101], 1, s[6:7]
	s_waitcnt vmcnt(18)
	s_nop 1
	v_mov_b32_e32 v96, v178
	v_mov_b32_e32 v97, v179
	v_mov_b32_e32 v98, v180
	v_mov_b32_e32 v99, v181
	s_mov_b64 s[8:9], 0x18000
	s_waitcnt lgkmcnt(0)
	v_lshlrev_b32_e32 v104, 16, v96
	v_and_b32_e32 v105, 0xffff0000, v96
	v_lshlrev_b32_e32 v96, 16, v97
	v_and_b32_e32 v97, 0xffff0000, v97
	v_lshlrev_b32_e32 v106, 16, v98
	v_and_b32_e32 v107, 0xffff0000, v98
	v_lshlrev_b32_e32 v98, 16, v99
	v_and_b32_e32 v99, 0xffff0000, v99
	v_pk_add_f32 v[94:95], v[94:95], v[96:97]
	v_pk_add_f32 v[92:93], v[92:93], v[104:105]
	v_lshl_add_u64 v[96:97], v[100:101], 2, s[4:5]
	v_pk_add_f32 v[90:91], v[90:91], v[98:99]
	v_pk_add_f32 v[88:89], v[88:89], v[106:107]
	global_store_dwordx4 v[96:97], v[92:95], off
	global_store_dwordx4 v[96:97], v[88:91], off offset:16
	s_waitcnt vmcnt(19)
	s_nop 1
	v_mov_b32_e32 v88, v182
	v_mov_b32_e32 v89, v183
	v_mov_b32_e32 v90, v184
	v_mov_b32_e32 v91, v185
	s_waitcnt lgkmcnt(0)
	v_lshlrev_b32_e32 v92, 16, v88
	v_and_b32_e32 v93, 0xffff0000, v88
	v_lshlrev_b32_e32 v88, 16, v89
	v_and_b32_e32 v89, 0xffff0000, v89
	v_lshlrev_b32_e32 v94, 16, v90
	v_and_b32_e32 v95, 0xffff0000, v90
	v_lshlrev_b32_e32 v90, 16, v91
	v_and_b32_e32 v91, 0xffff0000, v91
	v_pk_add_f32 v[86:87], v[86:87], v[88:89]
	v_pk_add_f32 v[84:85], v[84:85], v[92:93]
	v_pk_add_f32 v[82:83], v[82:83], v[90:91]
	v_pk_add_f32 v[80:81], v[80:81], v[94:95]
	global_store_dwordx4 v[96:97], v[84:87], off offset:512
	global_store_dwordx4 v[96:97], v[80:83], off offset:528
	s_nop 0
	v_lshl_add_u64 v[84:85], v[144:145], 0, s[8:9]
	v_lshl_add_u64 v[86:87], v[84:85], 1, s[6:7]
	s_waitcnt vmcnt(20)
	s_nop 1
	v_mov_b32_e32 v80, v186
	v_mov_b32_e32 v81, v187
	v_mov_b32_e32 v82, v188
	v_mov_b32_e32 v83, v189
	s_mov_b64 s[8:9], 0x40000
	s_waitcnt lgkmcnt(0)
	v_lshlrev_b32_e32 v88, 16, v80
	v_and_b32_e32 v89, 0xffff0000, v80
	v_lshlrev_b32_e32 v80, 16, v81
	v_and_b32_e32 v81, 0xffff0000, v81
	v_lshlrev_b32_e32 v90, 16, v82
	v_and_b32_e32 v91, 0xffff0000, v82
	v_lshlrev_b32_e32 v82, 16, v83
	v_and_b32_e32 v83, 0xffff0000, v83
	v_pk_add_f32 v[78:79], v[78:79], v[80:81]
	v_pk_add_f32 v[76:77], v[76:77], v[88:89]
	v_lshl_add_u64 v[80:81], v[84:85], 2, s[4:5]
	v_pk_add_f32 v[74:75], v[74:75], v[82:83]
	v_pk_add_f32 v[72:73], v[72:73], v[90:91]
	global_store_dwordx4 v[80:81], v[76:79], off
	global_store_dwordx4 v[80:81], v[72:75], off offset:16
	s_waitcnt vmcnt(21)
	s_nop 1
	v_mov_b32_e32 v72, v190
	v_mov_b32_e32 v73, v191
	v_mov_b32_e32 v74, v192
	v_mov_b32_e32 v75, v193
	s_waitcnt lgkmcnt(0)
	v_lshlrev_b32_e32 v76, 16, v72
	v_and_b32_e32 v77, 0xffff0000, v72
	v_lshlrev_b32_e32 v72, 16, v73
	v_and_b32_e32 v73, 0xffff0000, v73
	v_lshlrev_b32_e32 v78, 16, v74
	v_and_b32_e32 v79, 0xffff0000, v74
	v_lshlrev_b32_e32 v74, 16, v75
	v_and_b32_e32 v75, 0xffff0000, v75
	v_pk_add_f32 v[70:71], v[70:71], v[72:73]
	v_pk_add_f32 v[68:69], v[68:69], v[76:77]
	v_pk_add_f32 v[66:67], v[66:67], v[74:75]
	v_pk_add_f32 v[64:65], v[64:65], v[78:79]
	global_store_dwordx4 v[80:81], v[68:71], off offset:512
	global_store_dwordx4 v[80:81], v[64:67], off offset:528
	s_nop 0
	v_lshl_add_u64 v[68:69], v[144:145], 0, s[8:9]
	v_lshl_add_u64 v[70:71], v[68:69], 1, s[6:7]
	s_waitcnt vmcnt(22)
; DI unsigned pack2(float a, float b) { f32x2 v = {a, b}; hwbf16x2 r = __builtin_convertvector(v, hwbf16x2); return __builtin_bit_cast(unsigned, r); }
; DI float bflo(unsigned w) { return __uint_as_float(w << 16); }
; DI float bfhi(unsigned w) { return __uint_as_float(w & 0xffff0000u); }
;     DI const char* a(const Unit& u) const { return (const char*)(A + (size_t)u.pm * BM * lda); }
;     DI const char* a(const Unit& u) const { return (const char*)(A + (size_t)u.pm * BM * 2048 + (u.pn >> 1) * 512); }
;     DI void operator()(const f32x4 (&acc)[2][2][4][2], const Unit& u, int wr, int wc, int fr, int fq) const {
;     ...
;         for (int ai = 0; ai < 2; ++ai)
; #pragma unroll
;             for (int m = 0; m < 4; ++m) { const size_t ro = (size_t)(row0 + ai * HALF + m * 16) * D + col0;
; #pragma unroll
;                 for (int bj = 0; bj < 2; ++bj) {
;                     f32x4 x0, x1;
;                     if constexpr (IB) { const u32x4 w = *(const u32x4*)((const bf16_t*)Xin + ro + bj * HALF);
;                         x0 = (f32x4){bflo(w[0]), bfhi(w[0]), bflo(w[1]), bfhi(w[1])}; x1 = (f32x4){bflo(w[2]), bfhi(w[2]), bflo(w[3]), bfhi(w[3])}; }
;                     else { x0 = *(const f32x4*)((const float*)Xin + ro + bj * HALF); x1 = *(const f32x4*)((const float*)Xin + ro + bj * HALF + 4); }
;                     x0 += acc[ai][bj][m][0] * sc[bj][0]; x1 += acc[ai][bj][m][1] * sc[bj][1];
;                     if constexpr (OB) { u32x4 o; o[0] = pack2(x0[0], x0[1]); o[1] = pack2(x0[2], x0[3]); o[2] = pack2(x1[0], x1[1]); o[3] = pack2(x1[2], x1[3]);
;                         *(u32x4*)((bf16_t*)Xout + ro + bj * HALF) = o; }
;                     else { *(f32x4*)((float*)Xout + ro + bj * HALF) = x0; *(f32x4*)((float*)Xout + ro + bj * HALF + 4) = x1; } } }
; template <class Map, class Epi>
; DI void gemm_phase(LAS unsigned char* lds, const Map& MP, const Epi& E, const int nM, const int nN, const int K, const int lda, const int ldb) {
;     ...
;         if (!has_next) break;
; #pragma unroll
;         for (int a = 0; a < 2; ++a)
; #pragma unroll
;             for (int b = 0; b < 2; ++b)
; #pragma unroll
;                 for (int m = 0; m < 4; ++m)
; #pragma unroll
;                     for (int n = 0; n < 2; ++n) acc[a][b][m][n] = (f32x4){0.f, 0.f, 0.f, 0.f};
;         cur = nxt; cA = nA; cB = nB; ++ui;
;     }
;     PG8_WAIT_V(0);
;     if (wr == 0) PG8_BAR;
;     PG8_BAR;
	s_nop 1
	v_mov_b32_e32 v64, v194
	v_mov_b32_e32 v65, v195
	v_mov_b32_e32 v66, v196
	v_mov_b32_e32 v67, v197
	s_mov_b64 s[8:9], 0x48000
	s_waitcnt lgkmcnt(0)
	v_lshlrev_b32_e32 v72, 16, v64
	v_and_b32_e32 v73, 0xffff0000, v64
	v_lshlrev_b32_e32 v64, 16, v65
	v_and_b32_e32 v65, 0xffff0000, v65
	v_lshlrev_b32_e32 v74, 16, v66
	v_and_b32_e32 v75, 0xffff0000, v66
	v_lshlrev_b32_e32 v66, 16, v67
	v_and_b32_e32 v67, 0xffff0000, v67
	v_pk_add_f32 v[62:63], v[62:63], v[64:65]
	v_pk_add_f32 v[60:61], v[60:61], v[72:73]
	v_lshl_add_u64 v[64:65], v[68:69], 2, s[4:5]
	v_pk_add_f32 v[58:59], v[58:59], v[66:67]
	v_pk_add_f32 v[56:57], v[56:57], v[74:75]
	global_store_dwordx4 v[64:65], v[60:63], off
	global_store_dwordx4 v[64:65], v[56:59], off offset:16
	s_waitcnt vmcnt(23)
	s_nop 1
	v_mov_b32_e32 v56, v198
	v_mov_b32_e32 v57, v199
	v_mov_b32_e32 v58, v200
	v_mov_b32_e32 v59, v201
	s_waitcnt lgkmcnt(0)
	v_lshlrev_b32_e32 v60, 16, v56
	v_and_b32_e32 v61, 0xffff0000, v56
	v_lshlrev_b32_e32 v56, 16, v57
	v_and_b32_e32 v57, 0xffff0000, v57
	v_lshlrev_b32_e32 v62, 16, v58
	v_and_b32_e32 v63, 0xffff0000, v58
	v_lshlrev_b32_e32 v58, 16, v59
	v_and_b32_e32 v59, 0xffff0000, v59
	v_pk_add_f32 v[54:55], v[54:55], v[56:57]
	v_pk_add_f32 v[52:53], v[52:53], v[60:61]
	v_pk_add_f32 v[50:51], v[50:51], v[58:59]
	v_pk_add_f32 v[48:49], v[48:49], v[62:63]
	global_store_dwordx4 v[64:65], v[52:55], off offset:512
	global_store_dwordx4 v[64:65], v[48:51], off offset:528
	s_nop 0
	v_lshl_add_u64 v[52:53], v[144:145], 0, s[8:9]
	v_lshl_add_u64 v[54:55], v[52:53], 1, s[6:7]
	s_waitcnt vmcnt(24)
	s_nop 1
	v_mov_b32_e32 v48, v202
	v_mov_b32_e32 v49, v203
	v_mov_b32_e32 v50, v204
	v_mov_b32_e32 v51, v205
	s_mov_b64 s[8:9], 0x50000
	s_waitcnt lgkmcnt(0)
	v_lshlrev_b32_e32 v56, 16, v48
	v_and_b32_e32 v57, 0xffff0000, v48
	v_lshlrev_b32_e32 v48, 16, v49
	v_and_b32_e32 v49, 0xffff0000, v49
	v_lshlrev_b32_e32 v58, 16, v50
	v_and_b32_e32 v59, 0xffff0000, v50
	v_lshlrev_b32_e32 v50, 16, v51
	v_and_b32_e32 v51, 0xffff0000, v51
	v_pk_add_f32 v[46:47], v[46:47], v[48:49]
	v_pk_add_f32 v[44:45], v[44:45], v[56:57]
	v_lshl_add_u64 v[48:49], v[52:53], 2, s[4:5]
	v_pk_add_f32 v[42:43], v[42:43], v[50:51]
	v_pk_add_f32 v[40:41], v[40:41], v[58:59]
	global_store_dwordx4 v[48:49], v[44:47], off
	global_store_dwordx4 v[48:49], v[40:43], off offset:16
	s_waitcnt vmcnt(25)
	s_nop 1
	v_mov_b32_e32 v40, v206
	v_mov_b32_e32 v41, v207
	v_mov_b32_e32 v42, v208
	v_mov_b32_e32 v43, v209
	s_waitcnt lgkmcnt(0)
	v_lshlrev_b32_e32 v44, 16, v40
	v_and_b32_e32 v45, 0xffff0000, v40
	v_lshlrev_b32_e32 v40, 16, v41
	v_and_b32_e32 v41, 0xffff0000, v41
	v_lshlrev_b32_e32 v46, 16, v42
	v_and_b32_e32 v47, 0xffff0000, v42
	v_lshlrev_b32_e32 v42, 16, v43
	v_and_b32_e32 v43, 0xffff0000, v43
	v_pk_add_f32 v[38:39], v[38:39], v[40:41]
	v_pk_add_f32 v[36:37], v[36:37], v[44:45]
	v_pk_add_f32 v[34:35], v[34:35], v[42:43]
	v_pk_add_f32 v[32:33], v[32:33], v[46:47]
	global_store_dwordx4 v[48:49], v[36:39], off offset:512
	global_store_dwordx4 v[48:49], v[32:35], off offset:528
	s_nop 0
	v_lshl_add_u64 v[36:37], v[144:145], 0, s[8:9]
	v_lshl_add_u64 v[38:39], v[36:37], 1, s[6:7]
	s_waitcnt vmcnt(26)
	s_nop 1
	v_mov_b32_e32 v32, v210
	v_mov_b32_e32 v33, v211
	v_mov_b32_e32 v34, v212
	v_mov_b32_e32 v35, v213
	s_mov_b64 s[8:9], 0x58000
	s_waitcnt lgkmcnt(0)
	v_lshlrev_b32_e32 v40, 16, v32
	v_and_b32_e32 v41, 0xffff0000, v32
	v_lshlrev_b32_e32 v32, 16, v33
	v_and_b32_e32 v33, 0xffff0000, v33
	v_lshlrev_b32_e32 v42, 16, v34
	v_and_b32_e32 v43, 0xffff0000, v34
	v_lshlrev_b32_e32 v34, 16, v35
	v_and_b32_e32 v35, 0xffff0000, v35
	v_pk_add_f32 v[30:31], v[30:31], v[32:33]
	v_pk_add_f32 v[28:29], v[28:29], v[40:41]
	v_lshl_add_u64 v[32:33], v[36:37], 2, s[4:5]
	v_pk_add_f32 v[26:27], v[26:27], v[34:35]
	v_pk_add_f32 v[24:25], v[24:25], v[42:43]
	global_store_dwordx4 v[32:33], v[28:31], off
	global_store_dwordx4 v[32:33], v[24:27], off offset:16
	s_waitcnt vmcnt(27)
	s_nop 1
	v_mov_b32_e32 v24, v248
	v_mov_b32_e32 v25, v249
	v_mov_b32_e32 v26, v250
	v_mov_b32_e32 v27, v251
	s_waitcnt lgkmcnt(0)
	v_lshlrev_b32_e32 v28, 16, v24
	v_and_b32_e32 v29, 0xffff0000, v24
	v_lshlrev_b32_e32 v24, 16, v25
	v_and_b32_e32 v25, 0xffff0000, v25
	v_lshlrev_b32_e32 v30, 16, v26
	v_and_b32_e32 v31, 0xffff0000, v26
	v_lshlrev_b32_e32 v26, 16, v27
	v_and_b32_e32 v27, 0xffff0000, v27
	v_pk_add_f32 v[22:23], v[22:23], v[24:25]
	v_pk_add_f32 v[20:21], v[20:21], v[28:29]
	v_pk_add_f32 v[18:19], v[18:19], v[26:27]
	v_pk_add_f32 v[16:17], v[16:17], v[30:31]
	global_store_dwordx4 v[32:33], v[20:23], off offset:512
	global_store_dwordx4 v[32:33], v[16:19], off offset:528
	s_nop 0
	v_lshl_add_u64 v[20:21], v[144:145], 0, s[8:9]
	v_lshl_add_u64 v[22:23], v[20:21], 1, s[6:7]
	s_waitcnt vmcnt(28)
	s_nop 1
	v_mov_b32_e32 v16, v252
	v_mov_b32_e32 v17, v253
	v_mov_b32_e32 v18, v254
	v_mov_b32_e32 v19, v255
	s_mov_b64 s[8:9], s[42:43]
	s_waitcnt lgkmcnt(0)
	v_lshlrev_b32_e32 v24, 16, v16
	v_and_b32_e32 v25, 0xffff0000, v16
	v_lshlrev_b32_e32 v16, 16, v17
	v_and_b32_e32 v17, 0xffff0000, v17
	v_lshlrev_b32_e32 v26, 16, v18
	v_and_b32_e32 v27, 0xffff0000, v18
	v_lshlrev_b32_e32 v18, 16, v19
	v_and_b32_e32 v19, 0xffff0000, v19
	v_pk_add_f32 v[14:15], v[14:15], v[16:17]
	v_pk_add_f32 v[12:13], v[12:13], v[24:25]
	v_lshl_add_u64 v[16:17], v[20:21], 2, s[4:5]
	v_pk_add_f32 v[10:11], v[10:11], v[18:19]
	v_pk_add_f32 v[8:9], v[8:9], v[26:27]
	global_store_dwordx4 v[16:17], v[12:15], off
	global_store_dwordx4 v[16:17], v[8:11], off offset:16
	global_load_dwordx4 v[8:11], v[22:23], off offset:256
	s_waitcnt vmcnt(0) lgkmcnt(0)
	v_lshlrev_b32_e32 v12, 16, v8
	v_and_b32_e32 v13, 0xffff0000, v8
	v_lshlrev_b32_e32 v8, 16, v9
	v_and_b32_e32 v9, 0xffff0000, v9
	v_lshlrev_b32_e32 v14, 16, v10
	v_and_b32_e32 v15, 0xffff0000, v10
	v_lshlrev_b32_e32 v10, 16, v11
	v_and_b32_e32 v11, 0xffff0000, v11
	v_pk_add_f32 v[6:7], v[6:7], v[8:9]
	v_pk_add_f32 v[4:5], v[4:5], v[12:13]
	v_pk_add_f32 v[2:3], v[2:3], v[10:11]
	v_pk_add_f32 v[0:1], v[0:1], v[14:15]
	global_store_dwordx4 v[16:17], v[4:7], off offset:512
	global_store_dwordx4 v[16:17], v[0:3], off offset:528
	s_cbranch_vccz .LBB1_2646
	s_waitcnt vmcnt(0)
	s_cmpk_gt_u32 s3, 0xff
	s_cbranch_scc1 .LBB1_2657
	s_barrier
